# on top of v15: in all 28 GEMM K-loops the post-MFMA-block s_barrier moved one MFMA earlier, the duplicate lgkmcnt(0) after the pre-MFMA barrier and the mid-block setprio 0/1 pair removed
# baseline (speedup 1.0000x reference)
.LBB0_274:
	ds_read_b128 v[146:149], v153
	ds_read_b128 v[156:159], v153 offset:1024
	ds_read_b128 v[160:163], v153 offset:2048
	ds_read_b128 v[164:167], v153 offset:3072
	ds_read_b128 v[168:171], v154
	ds_read_b128 v[172:175], v154 offset:1024
	ds_read_b128 v[176:179], v154 offset:2048
	ds_read_b128 v[180:183], v154 offset:3072
	s_add_u32 s34, s76, 0xfff80080
	s_addc_u32 s35, s77, -1
	s_cmp_eq_u32 s85, 28
	s_cselect_b32 s79, s0, s35
	s_cselect_b32 s78, s1, s34
	s_cselect_b32 s35, s67, s84
	s_cselect_b32 s34, s69, s83
	v_lshl_add_u64 v[218:219], s[76:77], 0, v[138:139]
	s_add_i32 m0, s54, 0xc000
	ds_read_b128 v[184:187], v155
	ds_read_b128 v[188:191], v155 offset:1024
	ds_read_b128 v[192:195], v155 offset:2048
	ds_read_b128 v[196:199], v155 offset:3072
	ds_read_b128 v[200:203], v155 offset:4096
	ds_read_b128 v[204:207], v155 offset:5120
	ds_read_b128 v[208:211], v155 offset:6144
	ds_read_b128 v[212:215], v155 offset:7168
	global_load_lds_dwordx4 v[218:219], off
	v_lshl_add_u64 v[218:219], s[76:77], 0, v[140:141]
	s_add_i32 m0, s54, 0xe000
	s_nop 0
	global_load_lds_dwordx4 v[218:219], off
	s_waitcnt vmcnt(8)
	s_waitcnt lgkmcnt(0)
	s_barrier
	s_setprio 1
	v_mfma_f32_16x16x32_bf16 v[126:129], v[146:149], v[184:187], v[126:129]
	v_mfma_f32_16x16x32_bf16 v[118:121], v[160:163], v[184:187], v[118:121]
	v_mfma_f32_16x16x32_bf16 v[110:113], v[146:149], v[192:195], v[110:113]
	v_mfma_f32_16x16x32_bf16 v[102:105], v[160:163], v[192:195], v[102:105]
	v_mfma_f32_16x16x32_bf16 v[94:97], v[146:149], v[200:203], v[94:97]
	v_mfma_f32_16x16x32_bf16 v[86:89], v[160:163], v[200:203], v[86:89]
	v_mfma_f32_16x16x32_bf16 v[78:81], v[146:149], v[208:211], v[78:81]
	v_mfma_f32_16x16x32_bf16 v[70:73], v[160:163], v[208:211], v[70:73]
	v_mfma_f32_16x16x32_bf16 v[126:129], v[156:159], v[188:191], v[126:129]
	v_mfma_f32_16x16x32_bf16 v[118:121], v[164:167], v[188:191], v[118:121]
	v_mfma_f32_16x16x32_bf16 v[110:113], v[156:159], v[196:199], v[110:113]
	v_mfma_f32_16x16x32_bf16 v[102:105], v[164:167], v[196:199], v[102:105]
	v_mfma_f32_16x16x32_bf16 v[94:97], v[156:159], v[204:207], v[94:97]
	v_mfma_f32_16x16x32_bf16 v[86:89], v[164:167], v[204:207], v[86:89]
	v_mfma_f32_16x16x32_bf16 v[78:81], v[156:159], v[212:215], v[78:81]
	v_mfma_f32_16x16x32_bf16 v[70:73], v[164:167], v[212:215], v[70:73]
	v_mfma_f32_16x16x32_bf16 v[122:125], v[168:171], v[184:187], v[122:125]
	v_mfma_f32_16x16x32_bf16 v[114:117], v[176:179], v[184:187], v[114:117]
	v_mfma_f32_16x16x32_bf16 v[106:109], v[168:171], v[192:195], v[106:109]
	v_mfma_f32_16x16x32_bf16 v[98:101], v[176:179], v[192:195], v[98:101]
	v_mfma_f32_16x16x32_bf16 v[90:93], v[168:171], v[200:203], v[90:93]
	v_mfma_f32_16x16x32_bf16 v[82:85], v[176:179], v[200:203], v[82:85]
	v_mfma_f32_16x16x32_bf16 v[74:77], v[168:171], v[208:211], v[74:77]
	v_mfma_f32_16x16x32_bf16 v[66:69], v[176:179], v[208:211], v[66:69]
	v_mfma_f32_16x16x32_bf16 v[122:125], v[172:175], v[188:191], v[122:125]
	v_mfma_f32_16x16x32_bf16 v[114:117], v[180:183], v[188:191], v[114:117]
	v_mfma_f32_16x16x32_bf16 v[106:109], v[172:175], v[196:199], v[106:109]
	v_mfma_f32_16x16x32_bf16 v[98:101], v[180:183], v[196:199], v[98:101]
	v_mfma_f32_16x16x32_bf16 v[90:93], v[172:175], v[204:207], v[90:93]
	v_mfma_f32_16x16x32_bf16 v[82:85], v[180:183], v[204:207], v[82:85]
	v_mfma_f32_16x16x32_bf16 v[74:77], v[172:175], v[212:215], v[74:77]
	s_barrier
	v_mfma_f32_16x16x32_bf16 v[66:69], v[180:183], v[212:215], v[66:69]
	s_setprio 0
	s_add_i32 s62, s75, s33
	v_lshl_add_u64 v[218:219], s[34:35], 0, v[134:135]
	s_mov_b32 m0, s62
	ds_read_b128 v[184:187], v155 offset:16384
	ds_read_b128 v[188:191], v155 offset:17408
	ds_read_b128 v[192:195], v155 offset:18432
	ds_read_b128 v[196:199], v155 offset:19456
	ds_read_b128 v[200:203], v155 offset:20480
	ds_read_b128 v[204:207], v155 offset:21504
	ds_read_b128 v[208:211], v155 offset:22528
	ds_read_b128 v[212:215], v155 offset:23552
	global_load_lds_dwordx4 v[218:219], off
	s_add_i32 m0, s62, 0x2000
	s_add_u32 s62, s34, 0x80000
	v_lshl_add_u64 v[220:221], s[34:35], 0, v[130:131]
	s_addc_u32 s63, s35, 0
	s_add_i32 s86, s80, s33
	global_load_lds_dwordx4 v[220:221], off
	v_lshl_add_u64 v[222:223], s[62:63], 0, v[134:135]
	s_mov_b32 m0, s86
	v_lshl_add_u64 v[224:225], s[78:79], 0, v[132:133]
	global_load_lds_dwordx4 v[222:223], off
	v_lshl_add_u64 v[222:223], s[62:63], 0, v[130:131]
	s_add_i32 m0, s86, 0x2000
	s_nop 0
	global_load_lds_dwordx4 v[222:223], off
	v_lshl_add_u64 v[222:223], s[78:79], 0, v[136:137]
	s_mov_b32 m0, s54
	s_nop 0
	global_load_lds_dwordx4 v[222:223], off
	s_mov_b32 m0, s55
	s_nop 0
	global_load_lds_dwordx4 v[224:225], off
	s_waitcnt vmcnt(8)
	s_waitcnt lgkmcnt(0)
	s_barrier
	s_setprio 1
	v_mfma_f32_16x16x32_bf16 v[62:65], v[146:149], v[184:187], v[62:65]
	v_mfma_f32_16x16x32_bf16 v[54:57], v[160:163], v[184:187], v[54:57]
	v_mfma_f32_16x16x32_bf16 v[46:49], v[146:149], v[192:195], v[46:49]
	v_mfma_f32_16x16x32_bf16 v[38:41], v[160:163], v[192:195], v[38:41]
	v_mfma_f32_16x16x32_bf16 v[30:33], v[146:149], v[200:203], v[30:33]
	v_mfma_f32_16x16x32_bf16 v[22:25], v[160:163], v[200:203], v[22:25]
	v_mfma_f32_16x16x32_bf16 v[14:17], v[146:149], v[208:211], v[14:17]
	v_mfma_f32_16x16x32_bf16 v[6:9], v[160:163], v[208:211], v[6:9]
	v_mfma_f32_16x16x32_bf16 v[62:65], v[156:159], v[188:191], v[62:65]
	v_mfma_f32_16x16x32_bf16 v[54:57], v[164:167], v[188:191], v[54:57]
	v_mfma_f32_16x16x32_bf16 v[46:49], v[156:159], v[196:199], v[46:49]
	v_mfma_f32_16x16x32_bf16 v[38:41], v[164:167], v[196:199], v[38:41]
	v_mfma_f32_16x16x32_bf16 v[30:33], v[156:159], v[204:207], v[30:33]
	v_mfma_f32_16x16x32_bf16 v[22:25], v[164:167], v[204:207], v[22:25]
	v_mfma_f32_16x16x32_bf16 v[14:17], v[156:159], v[212:215], v[14:17]
	v_mfma_f32_16x16x32_bf16 v[6:9], v[164:167], v[212:215], v[6:9]
	v_mfma_f32_16x16x32_bf16 v[58:61], v[168:171], v[184:187], v[58:61]
	v_mfma_f32_16x16x32_bf16 v[50:53], v[176:179], v[184:187], v[50:53]
	v_mfma_f32_16x16x32_bf16 v[42:45], v[168:171], v[192:195], v[42:45]
	v_mfma_f32_16x16x32_bf16 v[34:37], v[176:179], v[192:195], v[34:37]
	v_mfma_f32_16x16x32_bf16 v[26:29], v[168:171], v[200:203], v[26:29]
	v_mfma_f32_16x16x32_bf16 v[18:21], v[176:179], v[200:203], v[18:21]
	v_mfma_f32_16x16x32_bf16 v[10:13], v[168:171], v[208:211], v[10:13]
	v_mfma_f32_16x16x32_bf16 v[2:5], v[176:179], v[208:211], v[2:5]
	v_mfma_f32_16x16x32_bf16 v[58:61], v[172:175], v[188:191], v[58:61]
	v_mfma_f32_16x16x32_bf16 v[50:53], v[180:183], v[188:191], v[50:53]
	v_mfma_f32_16x16x32_bf16 v[42:45], v[172:175], v[196:199], v[42:45]
	v_mfma_f32_16x16x32_bf16 v[34:37], v[180:183], v[196:199], v[34:37]
	v_mfma_f32_16x16x32_bf16 v[26:29], v[172:175], v[204:207], v[26:29]
	v_mfma_f32_16x16x32_bf16 v[18:21], v[180:183], v[204:207], v[18:21]
	v_mfma_f32_16x16x32_bf16 v[10:13], v[172:175], v[212:215], v[10:13]
	s_barrier
	v_mfma_f32_16x16x32_bf16 v[2:5], v[180:183], v[212:215], v[2:5]
	s_setprio 0
	s_add_i32 s86, 0, 0x18000
	s_add_i32 s87, 0, 0x1c000
	v_add_u32_e32 v164, s86, v151
	v_add_u32_e32 v180, s87, v151
	ds_read_b128 v[146:149], v164
	ds_read_b128 v[156:159], v164 offset:1024
	ds_read_b128 v[160:163], v164 offset:2048
	ds_read_b128 v[164:167], v164 offset:3072
	ds_read_b128 v[168:171], v180
	ds_read_b128 v[172:175], v180 offset:1024
	ds_read_b128 v[176:179], v180 offset:2048
	ds_read_b128 v[180:183], v180 offset:3072
	s_add_u32 s62, s78, 0x80000
	s_addc_u32 s63, s79, 0
	s_mov_b32 m0, s56
	v_lshl_add_u64 v[226:227], s[62:63], 0, v[136:137]
	ds_read_b128 v[184:187], v155 offset:32768
	ds_read_b128 v[188:191], v155 offset:33792
	ds_read_b128 v[192:195], v155 offset:34816
	ds_read_b128 v[196:199], v155 offset:35840
	ds_read_b128 v[200:203], v155 offset:36864
	ds_read_b128 v[204:207], v155 offset:37888
	ds_read_b128 v[208:211], v155 offset:38912
	ds_read_b128 v[212:215], v155 offset:39936
	global_load_lds_dwordx4 v[226:227], off
	v_lshl_add_u64 v[226:227], s[62:63], 0, v[132:133]
	s_mov_b32 m0, s57
	s_nop 0
	global_load_lds_dwordx4 v[226:227], off
	s_waitcnt vmcnt(8)
	s_waitcnt lgkmcnt(0)
	s_barrier
	s_setprio 1
	v_mfma_f32_16x16x32_bf16 v[126:129], v[146:149], v[184:187], v[126:129]
	v_mfma_f32_16x16x32_bf16 v[118:121], v[160:163], v[184:187], v[118:121]
	v_mfma_f32_16x16x32_bf16 v[110:113], v[146:149], v[192:195], v[110:113]
	v_mfma_f32_16x16x32_bf16 v[102:105], v[160:163], v[192:195], v[102:105]
	v_mfma_f32_16x16x32_bf16 v[94:97], v[146:149], v[200:203], v[94:97]
	v_mfma_f32_16x16x32_bf16 v[86:89], v[160:163], v[200:203], v[86:89]
	v_mfma_f32_16x16x32_bf16 v[78:81], v[146:149], v[208:211], v[78:81]
	v_mfma_f32_16x16x32_bf16 v[70:73], v[160:163], v[208:211], v[70:73]
	v_mfma_f32_16x16x32_bf16 v[126:129], v[156:159], v[188:191], v[126:129]
	v_mfma_f32_16x16x32_bf16 v[118:121], v[164:167], v[188:191], v[118:121]
	v_mfma_f32_16x16x32_bf16 v[110:113], v[156:159], v[196:199], v[110:113]
	v_mfma_f32_16x16x32_bf16 v[102:105], v[164:167], v[196:199], v[102:105]
	v_mfma_f32_16x16x32_bf16 v[94:97], v[156:159], v[204:207], v[94:97]
	v_mfma_f32_16x16x32_bf16 v[86:89], v[164:167], v[204:207], v[86:89]
	v_mfma_f32_16x16x32_bf16 v[78:81], v[156:159], v[212:215], v[78:81]
	v_mfma_f32_16x16x32_bf16 v[70:73], v[164:167], v[212:215], v[70:73]
	v_mfma_f32_16x16x32_bf16 v[122:125], v[168:171], v[184:187], v[122:125]
	v_mfma_f32_16x16x32_bf16 v[114:117], v[176:179], v[184:187], v[114:117]
	v_mfma_f32_16x16x32_bf16 v[106:109], v[168:171], v[192:195], v[106:109]
	v_mfma_f32_16x16x32_bf16 v[98:101], v[176:179], v[192:195], v[98:101]
	v_mfma_f32_16x16x32_bf16 v[90:93], v[168:171], v[200:203], v[90:93]
	v_mfma_f32_16x16x32_bf16 v[82:85], v[176:179], v[200:203], v[82:85]
	v_mfma_f32_16x16x32_bf16 v[74:77], v[168:171], v[208:211], v[74:77]
	v_mfma_f32_16x16x32_bf16 v[66:69], v[176:179], v[208:211], v[66:69]
	v_mfma_f32_16x16x32_bf16 v[122:125], v[172:175], v[188:191], v[122:125]
	v_mfma_f32_16x16x32_bf16 v[114:117], v[180:183], v[188:191], v[114:117]
	v_mfma_f32_16x16x32_bf16 v[106:109], v[172:175], v[196:199], v[106:109]
	v_mfma_f32_16x16x32_bf16 v[98:101], v[180:183], v[196:199], v[98:101]
	v_mfma_f32_16x16x32_bf16 v[90:93], v[172:175], v[204:207], v[90:93]
	v_mfma_f32_16x16x32_bf16 v[82:85], v[180:183], v[204:207], v[82:85]
	v_mfma_f32_16x16x32_bf16 v[74:77], v[172:175], v[212:215], v[74:77]
	s_barrier
	v_mfma_f32_16x16x32_bf16 v[66:69], v[180:183], v[212:215], v[66:69]
	s_setprio 0
	s_add_i32 s62, s86, s33
	v_lshl_add_u64 v[218:219], v[218:219], 0, s[8:9]
	s_mov_b32 m0, s62
	ds_read_b128 v[184:187], v155 offset:49152
	ds_read_b128 v[188:191], v155 offset:50176
	ds_read_b128 v[192:195], v155 offset:51200
	ds_read_b128 v[196:199], v155 offset:52224
	ds_read_b128 v[200:203], v155 offset:53248
	ds_read_b128 v[204:207], v155 offset:54272
	ds_read_b128 v[208:211], v155 offset:55296
	ds_read_b128 v[212:215], v155 offset:56320
	global_load_lds_dwordx4 v[218:219], off
	s_add_i32 m0, s62, 0x2000
	s_add_u32 s34, s34, 0x80080
	v_lshl_add_u64 v[218:219], v[220:221], 0, s[8:9]
	s_addc_u32 s35, s35, 0
	s_add_i32 s62, s87, s33
	global_load_lds_dwordx4 v[218:219], off
	v_lshl_add_u64 v[218:219], s[34:35], 0, v[134:135]
	s_mov_b32 m0, s62
	s_nop 0
	global_load_lds_dwordx4 v[218:219], off
	v_lshl_add_u64 v[218:219], s[34:35], 0, v[130:131]
	s_add_i32 m0, s62, 0x2000
	s_nop 0
	global_load_lds_dwordx4 v[218:219], off
	v_lshl_add_u64 v[218:219], v[222:223], 0, s[8:9]
	s_mov_b32 m0, s59
	s_nop 0
	global_load_lds_dwordx4 v[218:219], off
	v_lshl_add_u64 v[218:219], v[224:225], 0, s[8:9]
	s_mov_b32 m0, s60
	s_nop 0
	global_load_lds_dwordx4 v[218:219], off
	s_waitcnt vmcnt(8)
	s_waitcnt lgkmcnt(0)
	s_barrier
	s_setprio 1
	v_mfma_f32_16x16x32_bf16 v[62:65], v[146:149], v[184:187], v[62:65]
	v_mfma_f32_16x16x32_bf16 v[54:57], v[160:163], v[184:187], v[54:57]
	v_mfma_f32_16x16x32_bf16 v[46:49], v[146:149], v[192:195], v[46:49]
	v_mfma_f32_16x16x32_bf16 v[38:41], v[160:163], v[192:195], v[38:41]
	v_mfma_f32_16x16x32_bf16 v[30:33], v[146:149], v[200:203], v[30:33]
	v_mfma_f32_16x16x32_bf16 v[22:25], v[160:163], v[200:203], v[22:25]
	v_mfma_f32_16x16x32_bf16 v[14:17], v[146:149], v[208:211], v[14:17]
	v_mfma_f32_16x16x32_bf16 v[6:9], v[160:163], v[208:211], v[6:9]
	v_mfma_f32_16x16x32_bf16 v[62:65], v[156:159], v[188:191], v[62:65]
	v_mfma_f32_16x16x32_bf16 v[54:57], v[164:167], v[188:191], v[54:57]
	v_mfma_f32_16x16x32_bf16 v[46:49], v[156:159], v[196:199], v[46:49]
	v_mfma_f32_16x16x32_bf16 v[38:41], v[164:167], v[196:199], v[38:41]
	v_mfma_f32_16x16x32_bf16 v[30:33], v[156:159], v[204:207], v[30:33]
	v_mfma_f32_16x16x32_bf16 v[22:25], v[164:167], v[204:207], v[22:25]
	v_mfma_f32_16x16x32_bf16 v[14:17], v[156:159], v[212:215], v[14:17]
	v_mfma_f32_16x16x32_bf16 v[6:9], v[164:167], v[212:215], v[6:9]
	v_mfma_f32_16x16x32_bf16 v[58:61], v[168:171], v[184:187], v[58:61]
	v_mfma_f32_16x16x32_bf16 v[50:53], v[176:179], v[184:187], v[50:53]
	v_mfma_f32_16x16x32_bf16 v[42:45], v[168:171], v[192:195], v[42:45]
	v_mfma_f32_16x16x32_bf16 v[34:37], v[176:179], v[192:195], v[34:37]
	v_mfma_f32_16x16x32_bf16 v[26:29], v[168:171], v[200:203], v[26:29]
	v_mfma_f32_16x16x32_bf16 v[18:21], v[176:179], v[200:203], v[18:21]
	v_mfma_f32_16x16x32_bf16 v[10:13], v[168:171], v[208:211], v[10:13]
	v_mfma_f32_16x16x32_bf16 v[2:5], v[176:179], v[208:211], v[2:5]
	v_mfma_f32_16x16x32_bf16 v[58:61], v[172:175], v[188:191], v[58:61]
	v_mfma_f32_16x16x32_bf16 v[50:53], v[180:183], v[188:191], v[50:53]
	v_mfma_f32_16x16x32_bf16 v[42:45], v[172:175], v[196:199], v[42:45]
	v_mfma_f32_16x16x32_bf16 v[34:37], v[180:183], v[196:199], v[34:37]
	v_mfma_f32_16x16x32_bf16 v[26:29], v[172:175], v[204:207], v[26:29]
	v_mfma_f32_16x16x32_bf16 v[18:21], v[180:183], v[204:207], v[18:21]
	v_mfma_f32_16x16x32_bf16 v[10:13], v[172:175], v[212:215], v[10:13]
	s_barrier
	v_mfma_f32_16x16x32_bf16 v[2:5], v[180:183], v[212:215], v[2:5]
	s_setprio 0
	s_add_i32 s85, s85, 2
	s_add_u32 s76, s76, 0x100
	s_addc_u32 s77, s77, 0
	s_add_u32 s83, s83, 0x100
	s_addc_u32 s84, s84, 0
	s_cmp_gt_u32 s85, 29
	s_cbranch_scc0 .LBB0_274
	s_and_b64 vcc, exec, s[64:65]
	s_cbranch_vccz .LBB0_277
	s_barrier

.LBB0_387:
	ds_read_b128 v[146:149], v154
	ds_read_b128 v[158:161], v154 offset:1024
	ds_read_b128 v[162:165], v154 offset:2048
	ds_read_b128 v[166:169], v154 offset:3072
	ds_read_b128 v[170:173], v155
	ds_read_b128 v[174:177], v155 offset:1024
	ds_read_b128 v[178:181], v155 offset:2048
	ds_read_b128 v[182:185], v155 offset:3072
	s_add_u32 s34, s72, 0xffea0080
	s_addc_u32 s35, s73, -1
	s_cmpk_eq_i32 s81, 0x54
	s_cselect_b32 s75, s5, s35
	s_cselect_b32 s74, s4, s34
	s_cselect_b32 s35, s71, s1
	s_cselect_b32 s34, s70, s0
	v_lshl_add_u64 v[150:151], s[72:73], 0, v[138:139]
	s_add_i32 m0, s53, 0xc000
	ds_read_b128 v[186:189], v156
	ds_read_b128 v[190:193], v156 offset:1024
	ds_read_b128 v[194:197], v156 offset:2048
	ds_read_b128 v[198:201], v156 offset:3072
	ds_read_b128 v[202:205], v156 offset:4096
	ds_read_b128 v[206:209], v156 offset:5120
	ds_read_b128 v[210:213], v156 offset:6144
	ds_read_b128 v[218:221], v156 offset:7168
	global_load_lds_dwordx4 v[150:151], off
	v_lshl_add_u64 v[150:151], s[72:73], 0, v[140:141]
	s_add_i32 m0, s53, 0xe000
	s_nop 0
	global_load_lds_dwordx4 v[150:151], off
	s_waitcnt vmcnt(8)
	s_waitcnt lgkmcnt(0)
	s_barrier
	s_setprio 1
	v_mfma_f32_16x16x32_bf16 v[126:129], v[146:149], v[186:189], v[126:129]
	v_mfma_f32_16x16x32_bf16 v[122:125], v[162:165], v[186:189], v[122:125]
	v_mfma_f32_16x16x32_bf16 v[118:121], v[146:149], v[194:197], v[118:121]
	v_mfma_f32_16x16x32_bf16 v[114:117], v[162:165], v[194:197], v[114:117]
	v_mfma_f32_16x16x32_bf16 v[94:97], v[146:149], v[202:205], v[94:97]
	v_mfma_f32_16x16x32_bf16 v[90:93], v[162:165], v[202:205], v[90:93]
	v_mfma_f32_16x16x32_bf16 v[86:89], v[146:149], v[210:213], v[86:89]
	v_mfma_f32_16x16x32_bf16 v[82:85], v[162:165], v[210:213], v[82:85]
	v_mfma_f32_16x16x32_bf16 v[126:129], v[158:161], v[190:193], v[126:129]
	v_mfma_f32_16x16x32_bf16 v[122:125], v[166:169], v[190:193], v[122:125]
	v_mfma_f32_16x16x32_bf16 v[118:121], v[158:161], v[198:201], v[118:121]
	v_mfma_f32_16x16x32_bf16 v[114:117], v[166:169], v[198:201], v[114:117]
	v_mfma_f32_16x16x32_bf16 v[94:97], v[158:161], v[206:209], v[94:97]
	v_mfma_f32_16x16x32_bf16 v[90:93], v[166:169], v[206:209], v[90:93]
	v_mfma_f32_16x16x32_bf16 v[86:89], v[158:161], v[218:221], v[86:89]
	v_mfma_f32_16x16x32_bf16 v[82:85], v[166:169], v[218:221], v[82:85]
	v_mfma_f32_16x16x32_bf16 v[110:113], v[170:173], v[186:189], v[110:113]
	v_mfma_f32_16x16x32_bf16 v[106:109], v[178:181], v[186:189], v[106:109]
	v_mfma_f32_16x16x32_bf16 v[102:105], v[170:173], v[194:197], v[102:105]
	v_mfma_f32_16x16x32_bf16 v[98:101], v[178:181], v[194:197], v[98:101]
	v_mfma_f32_16x16x32_bf16 v[78:81], v[170:173], v[202:205], v[78:81]
	v_mfma_f32_16x16x32_bf16 v[74:77], v[178:181], v[202:205], v[74:77]
	v_mfma_f32_16x16x32_bf16 v[70:73], v[170:173], v[210:213], v[70:73]
	v_mfma_f32_16x16x32_bf16 v[66:69], v[178:181], v[210:213], v[66:69]
	v_mfma_f32_16x16x32_bf16 v[110:113], v[174:177], v[190:193], v[110:113]
	v_mfma_f32_16x16x32_bf16 v[106:109], v[182:185], v[190:193], v[106:109]
	v_mfma_f32_16x16x32_bf16 v[102:105], v[174:177], v[198:201], v[102:105]
	v_mfma_f32_16x16x32_bf16 v[98:101], v[182:185], v[198:201], v[98:101]
	v_mfma_f32_16x16x32_bf16 v[78:81], v[174:177], v[206:209], v[78:81]
	v_mfma_f32_16x16x32_bf16 v[74:77], v[182:185], v[206:209], v[74:77]
	v_mfma_f32_16x16x32_bf16 v[70:73], v[174:177], v[218:221], v[70:73]
	s_barrier
	v_mfma_f32_16x16x32_bf16 v[66:69], v[182:185], v[218:221], v[66:69]
	s_setprio 0
	s_add_i32 s62, s61, s52
	v_lshl_add_u64 v[150:151], s[34:35], 0, v[132:133]
	s_mov_b32 m0, s62
	ds_read_b128 v[186:189], v156 offset:16384
	ds_read_b128 v[190:193], v156 offset:17408
	ds_read_b128 v[194:197], v156 offset:18432
	ds_read_b128 v[198:201], v156 offset:19456
	ds_read_b128 v[202:205], v156 offset:20480
	ds_read_b128 v[206:209], v156 offset:21504
	ds_read_b128 v[210:213], v156 offset:22528
	ds_read_b128 v[218:221], v156 offset:23552
	global_load_lds_dwordx4 v[150:151], off
	s_add_i32 m0, s62, 0x2000
	s_add_u32 s62, s34, 0x160000
	v_lshl_add_u64 v[214:215], s[34:35], 0, v[136:137]
	s_addc_u32 s63, s35, 0
	s_add_i32 s82, s76, s52
	global_load_lds_dwordx4 v[214:215], off
	v_lshl_add_u64 v[222:223], s[62:63], 0, v[132:133]
	s_mov_b32 m0, s82
	v_lshl_add_u64 v[224:225], s[74:75], 0, v[134:135]
	global_load_lds_dwordx4 v[222:223], off
	v_lshl_add_u64 v[222:223], s[62:63], 0, v[136:137]
	s_add_i32 m0, s82, 0x2000
	s_nop 0
	global_load_lds_dwordx4 v[222:223], off
	v_lshl_add_u64 v[222:223], s[74:75], 0, v[130:131]
	s_mov_b32 m0, s53
	s_nop 0
	global_load_lds_dwordx4 v[222:223], off
	s_mov_b32 m0, s54
	s_nop 0
	global_load_lds_dwordx4 v[224:225], off
	s_waitcnt vmcnt(8)
	s_waitcnt lgkmcnt(0)
	s_barrier
	s_setprio 1
	v_mfma_f32_16x16x32_bf16 v[62:65], v[146:149], v[186:189], v[62:65]
	v_mfma_f32_16x16x32_bf16 v[58:61], v[162:165], v[186:189], v[58:61]
	v_mfma_f32_16x16x32_bf16 v[54:57], v[146:149], v[194:197], v[54:57]
	v_mfma_f32_16x16x32_bf16 v[50:53], v[162:165], v[194:197], v[50:53]
	v_mfma_f32_16x16x32_bf16 v[30:33], v[146:149], v[202:205], v[30:33]
	v_mfma_f32_16x16x32_bf16 v[26:29], v[162:165], v[202:205], v[26:29]
	v_mfma_f32_16x16x32_bf16 v[22:25], v[146:149], v[210:213], v[22:25]
	v_mfma_f32_16x16x32_bf16 v[18:21], v[162:165], v[210:213], v[18:21]
	v_mfma_f32_16x16x32_bf16 v[62:65], v[158:161], v[190:193], v[62:65]
	v_mfma_f32_16x16x32_bf16 v[58:61], v[166:169], v[190:193], v[58:61]
	v_mfma_f32_16x16x32_bf16 v[54:57], v[158:161], v[198:201], v[54:57]
	v_mfma_f32_16x16x32_bf16 v[50:53], v[166:169], v[198:201], v[50:53]
	v_mfma_f32_16x16x32_bf16 v[30:33], v[158:161], v[206:209], v[30:33]
	v_mfma_f32_16x16x32_bf16 v[26:29], v[166:169], v[206:209], v[26:29]
	v_mfma_f32_16x16x32_bf16 v[22:25], v[158:161], v[218:221], v[22:25]
	v_mfma_f32_16x16x32_bf16 v[18:21], v[166:169], v[218:221], v[18:21]
	v_mfma_f32_16x16x32_bf16 v[46:49], v[170:173], v[186:189], v[46:49]
	v_mfma_f32_16x16x32_bf16 v[42:45], v[178:181], v[186:189], v[42:45]
	v_mfma_f32_16x16x32_bf16 v[38:41], v[170:173], v[194:197], v[38:41]
	v_mfma_f32_16x16x32_bf16 v[34:37], v[178:181], v[194:197], v[34:37]
	v_mfma_f32_16x16x32_bf16 v[14:17], v[170:173], v[202:205], v[14:17]
	v_mfma_f32_16x16x32_bf16 v[10:13], v[178:181], v[202:205], v[10:13]
	v_mfma_f32_16x16x32_bf16 v[6:9], v[170:173], v[210:213], v[6:9]
	v_mfma_f32_16x16x32_bf16 v[2:5], v[178:181], v[210:213], v[2:5]
	v_mfma_f32_16x16x32_bf16 v[46:49], v[174:177], v[190:193], v[46:49]
	v_mfma_f32_16x16x32_bf16 v[42:45], v[182:185], v[190:193], v[42:45]
	v_mfma_f32_16x16x32_bf16 v[38:41], v[174:177], v[198:201], v[38:41]
	v_mfma_f32_16x16x32_bf16 v[34:37], v[182:185], v[198:201], v[34:37]
	v_mfma_f32_16x16x32_bf16 v[14:17], v[174:177], v[206:209], v[14:17]
	v_mfma_f32_16x16x32_bf16 v[10:13], v[182:185], v[206:209], v[10:13]
	v_mfma_f32_16x16x32_bf16 v[6:9], v[174:177], v[218:221], v[6:9]
	s_barrier
	v_mfma_f32_16x16x32_bf16 v[2:5], v[182:185], v[218:221], v[2:5]
	s_setprio 0
	s_add_i32 s82, 0, 0x18000
	v_add_u32_e32 v157, s82, v152
	s_add_i32 s83, 0, 0x1c000
	ds_read_b128 v[146:149], v157
	ds_read_b128 v[158:161], v157 offset:1024
	ds_read_b128 v[162:165], v157 offset:2048
	ds_read_b128 v[166:169], v157 offset:3072
	v_add_u32_e32 v157, s83, v152
	ds_read_b128 v[170:173], v157
	ds_read_b128 v[174:177], v157 offset:1024
	ds_read_b128 v[178:181], v157 offset:2048
	ds_read_b128 v[182:185], v157 offset:3072
	s_add_u32 s62, s74, 0x160000
	s_addc_u32 s63, s75, 0
	s_mov_b32 m0, s55
	v_lshl_add_u64 v[226:227], s[62:63], 0, v[130:131]
	ds_read_b128 v[186:189], v156 offset:32768
	ds_read_b128 v[190:193], v156 offset:33792
	ds_read_b128 v[194:197], v156 offset:34816
	ds_read_b128 v[198:201], v156 offset:35840
	ds_read_b128 v[202:205], v156 offset:36864
	ds_read_b128 v[206:209], v156 offset:37888
	ds_read_b128 v[210:213], v156 offset:38912
	ds_read_b128 v[218:221], v156 offset:39936
	global_load_lds_dwordx4 v[226:227], off
	v_lshl_add_u64 v[226:227], s[62:63], 0, v[134:135]
	s_mov_b32 m0, s56
	s_nop 0
	global_load_lds_dwordx4 v[226:227], off
	s_waitcnt vmcnt(8)
	s_waitcnt lgkmcnt(0)
	s_barrier
	s_setprio 1
	v_mfma_f32_16x16x32_bf16 v[126:129], v[146:149], v[186:189], v[126:129]
	v_mfma_f32_16x16x32_bf16 v[122:125], v[162:165], v[186:189], v[122:125]
	v_mfma_f32_16x16x32_bf16 v[118:121], v[146:149], v[194:197], v[118:121]
	v_mfma_f32_16x16x32_bf16 v[114:117], v[162:165], v[194:197], v[114:117]
	v_mfma_f32_16x16x32_bf16 v[94:97], v[146:149], v[202:205], v[94:97]
	v_mfma_f32_16x16x32_bf16 v[90:93], v[162:165], v[202:205], v[90:93]
	v_mfma_f32_16x16x32_bf16 v[86:89], v[146:149], v[210:213], v[86:89]
	v_mfma_f32_16x16x32_bf16 v[82:85], v[162:165], v[210:213], v[82:85]
	v_mfma_f32_16x16x32_bf16 v[126:129], v[158:161], v[190:193], v[126:129]
	v_mfma_f32_16x16x32_bf16 v[122:125], v[166:169], v[190:193], v[122:125]
	v_mfma_f32_16x16x32_bf16 v[118:121], v[158:161], v[198:201], v[118:121]
	v_mfma_f32_16x16x32_bf16 v[114:117], v[166:169], v[198:201], v[114:117]
	v_mfma_f32_16x16x32_bf16 v[94:97], v[158:161], v[206:209], v[94:97]
	v_mfma_f32_16x16x32_bf16 v[90:93], v[166:169], v[206:209], v[90:93]
	v_mfma_f32_16x16x32_bf16 v[86:89], v[158:161], v[218:221], v[86:89]
	v_mfma_f32_16x16x32_bf16 v[82:85], v[166:169], v[218:221], v[82:85]
	v_mfma_f32_16x16x32_bf16 v[110:113], v[170:173], v[186:189], v[110:113]
	v_mfma_f32_16x16x32_bf16 v[106:109], v[178:181], v[186:189], v[106:109]
	v_mfma_f32_16x16x32_bf16 v[102:105], v[170:173], v[194:197], v[102:105]
	v_mfma_f32_16x16x32_bf16 v[98:101], v[178:181], v[194:197], v[98:101]
	v_mfma_f32_16x16x32_bf16 v[78:81], v[170:173], v[202:205], v[78:81]
	v_mfma_f32_16x16x32_bf16 v[74:77], v[178:181], v[202:205], v[74:77]
	v_mfma_f32_16x16x32_bf16 v[70:73], v[170:173], v[210:213], v[70:73]
	v_mfma_f32_16x16x32_bf16 v[66:69], v[178:181], v[210:213], v[66:69]
	v_mfma_f32_16x16x32_bf16 v[110:113], v[174:177], v[190:193], v[110:113]
	v_mfma_f32_16x16x32_bf16 v[106:109], v[182:185], v[190:193], v[106:109]
	v_mfma_f32_16x16x32_bf16 v[102:105], v[174:177], v[198:201], v[102:105]
	v_mfma_f32_16x16x32_bf16 v[98:101], v[182:185], v[198:201], v[98:101]
	v_mfma_f32_16x16x32_bf16 v[78:81], v[174:177], v[206:209], v[78:81]
	v_mfma_f32_16x16x32_bf16 v[74:77], v[182:185], v[206:209], v[74:77]
	v_mfma_f32_16x16x32_bf16 v[70:73], v[174:177], v[218:221], v[70:73]
	s_barrier
	v_mfma_f32_16x16x32_bf16 v[66:69], v[182:185], v[218:221], v[66:69]
	s_setprio 0
	s_add_i32 s62, s82, s52
	v_lshl_add_u64 v[150:151], v[150:151], 0, s[66:67]
	s_mov_b32 m0, s62
	ds_read_b128 v[186:189], v156 offset:49152
	ds_read_b128 v[190:193], v156 offset:50176
	ds_read_b128 v[194:197], v156 offset:51200
	ds_read_b128 v[198:201], v156 offset:52224
	ds_read_b128 v[202:205], v156 offset:53248
	ds_read_b128 v[206:209], v156 offset:54272
	ds_read_b128 v[210:213], v156 offset:55296
	ds_read_b128 v[218:221], v156 offset:56320
	global_load_lds_dwordx4 v[150:151], off
	s_add_i32 m0, s62, 0x2000
	s_add_u32 s34, s34, 0x160080
	v_lshl_add_u64 v[150:151], v[214:215], 0, s[66:67]
	s_addc_u32 s35, s35, 0
	s_add_i32 s62, s83, s52
	global_load_lds_dwordx4 v[150:151], off
	v_lshl_add_u64 v[150:151], s[34:35], 0, v[132:133]
	s_mov_b32 m0, s62
	s_nop 0
	global_load_lds_dwordx4 v[150:151], off
	v_lshl_add_u64 v[150:151], s[34:35], 0, v[136:137]
	s_add_i32 m0, s62, 0x2000
	s_nop 0
	global_load_lds_dwordx4 v[150:151], off
	v_lshl_add_u64 v[150:151], v[222:223], 0, s[66:67]
	s_mov_b32 m0, s58
	s_nop 0
	global_load_lds_dwordx4 v[150:151], off
	v_lshl_add_u64 v[150:151], v[224:225], 0, s[66:67]
	s_mov_b32 m0, s59
	s_nop 0
	global_load_lds_dwordx4 v[150:151], off
	s_waitcnt vmcnt(8)
	s_waitcnt lgkmcnt(0)
	s_barrier
	s_setprio 1
	v_mfma_f32_16x16x32_bf16 v[62:65], v[146:149], v[186:189], v[62:65]
	v_mfma_f32_16x16x32_bf16 v[58:61], v[162:165], v[186:189], v[58:61]
	v_mfma_f32_16x16x32_bf16 v[54:57], v[146:149], v[194:197], v[54:57]
	v_mfma_f32_16x16x32_bf16 v[50:53], v[162:165], v[194:197], v[50:53]
	v_mfma_f32_16x16x32_bf16 v[30:33], v[146:149], v[202:205], v[30:33]
	v_mfma_f32_16x16x32_bf16 v[26:29], v[162:165], v[202:205], v[26:29]
	v_mfma_f32_16x16x32_bf16 v[22:25], v[146:149], v[210:213], v[22:25]
	v_mfma_f32_16x16x32_bf16 v[18:21], v[162:165], v[210:213], v[18:21]
	v_mfma_f32_16x16x32_bf16 v[62:65], v[158:161], v[190:193], v[62:65]
	v_mfma_f32_16x16x32_bf16 v[58:61], v[166:169], v[190:193], v[58:61]
	v_mfma_f32_16x16x32_bf16 v[54:57], v[158:161], v[198:201], v[54:57]
	v_mfma_f32_16x16x32_bf16 v[50:53], v[166:169], v[198:201], v[50:53]
	v_mfma_f32_16x16x32_bf16 v[30:33], v[158:161], v[206:209], v[30:33]
	v_mfma_f32_16x16x32_bf16 v[26:29], v[166:169], v[206:209], v[26:29]
	v_mfma_f32_16x16x32_bf16 v[22:25], v[158:161], v[218:221], v[22:25]
	v_mfma_f32_16x16x32_bf16 v[18:21], v[166:169], v[218:221], v[18:21]
	v_mfma_f32_16x16x32_bf16 v[46:49], v[170:173], v[186:189], v[46:49]
	v_mfma_f32_16x16x32_bf16 v[42:45], v[178:181], v[186:189], v[42:45]
	v_mfma_f32_16x16x32_bf16 v[38:41], v[170:173], v[194:197], v[38:41]
	v_mfma_f32_16x16x32_bf16 v[34:37], v[178:181], v[194:197], v[34:37]
	v_mfma_f32_16x16x32_bf16 v[14:17], v[170:173], v[202:205], v[14:17]
	v_mfma_f32_16x16x32_bf16 v[10:13], v[178:181], v[202:205], v[10:13]
	v_mfma_f32_16x16x32_bf16 v[6:9], v[170:173], v[210:213], v[6:9]
	v_mfma_f32_16x16x32_bf16 v[2:5], v[178:181], v[210:213], v[2:5]
	v_mfma_f32_16x16x32_bf16 v[46:49], v[174:177], v[190:193], v[46:49]
	v_mfma_f32_16x16x32_bf16 v[42:45], v[182:185], v[190:193], v[42:45]
	v_mfma_f32_16x16x32_bf16 v[38:41], v[174:177], v[198:201], v[38:41]
	v_mfma_f32_16x16x32_bf16 v[34:37], v[182:185], v[198:201], v[34:37]
	v_mfma_f32_16x16x32_bf16 v[14:17], v[174:177], v[206:209], v[14:17]
	v_mfma_f32_16x16x32_bf16 v[10:13], v[182:185], v[206:209], v[10:13]
	v_mfma_f32_16x16x32_bf16 v[6:9], v[174:177], v[218:221], v[6:9]
	s_barrier
	v_mfma_f32_16x16x32_bf16 v[2:5], v[182:185], v[218:221], v[2:5]
	s_setprio 0
	s_add_i32 s81, s81, 2
	s_add_u32 s72, s72, 0x100
	s_addc_u32 s73, s73, 0
	s_add_u32 s0, s0, 0x100
	s_addc_u32 s1, s1, 0
	s_cmpk_gt_u32 s81, 0x55
	s_cbranch_scc0 .LBB0_387
	s_and_b64 vcc, exec, s[68:69]
	s_cbranch_vccz .LBB0_390
	s_barrier

.LBB0_518:
	ds_read_b128 v[160:163], v155
	ds_read_b128 v[164:167], v155 offset:1024
	ds_read_b128 v[168:171], v155 offset:2048
	ds_read_b128 v[172:175], v155 offset:3072
	ds_read_b128 v[176:179], v156
	ds_read_b128 v[180:183], v156 offset:1024
	ds_read_b128 v[184:187], v156 offset:2048
	ds_read_b128 v[188:191], v156 offset:3072
	s_add_u32 s34, s90, 0xfff80080
	s_addc_u32 s35, s91, -1
	s_cmp_eq_u32 s83, 28
	s_cselect_b32 s93, s0, s35
	s_cselect_b32 s92, s1, s34
	s_cselect_b32 s35, s7, s68
	s_cselect_b32 s34, s9, s52
	v_lshl_add_u64 v[152:153], s[90:91], 0, v[144:145]
	s_add_i32 m0, s56, 0xc000
	ds_read_b128 v[192:195], v157
	ds_read_b128 v[196:199], v157 offset:1024
	ds_read_b128 v[200:203], v157 offset:2048
	ds_read_b128 v[204:207], v157 offset:3072
	ds_read_b128 v[208:211], v157 offset:4096
	ds_read_b128 v[212:215], v157 offset:5120
	ds_read_b128 v[218:221], v157 offset:6144
	ds_read_b128 v[222:225], v157 offset:7168
	global_load_lds_dwordx4 v[152:153], off
	v_lshl_add_u64 v[152:153], s[90:91], 0, v[146:147]
	s_add_i32 m0, s56, 0xe000
	s_nop 0
	global_load_lds_dwordx4 v[152:153], off
	s_waitcnt vmcnt(8)
	s_waitcnt lgkmcnt(0)
	s_barrier
	s_setprio 1
	v_mfma_f32_16x16x32_bf16 v[126:129], v[160:163], v[192:195], v[126:129]
	v_mfma_f32_16x16x32_bf16 v[122:125], v[168:171], v[192:195], v[122:125]
	v_mfma_f32_16x16x32_bf16 v[110:113], v[160:163], v[200:203], v[110:113]
	v_mfma_f32_16x16x32_bf16 v[106:109], v[168:171], v[200:203], v[106:109]
	v_mfma_f32_16x16x32_bf16 v[94:97], v[160:163], v[208:211], v[94:97]
	v_mfma_f32_16x16x32_bf16 v[90:93], v[168:171], v[208:211], v[90:93]
	v_mfma_f32_16x16x32_bf16 v[78:81], v[160:163], v[218:221], v[78:81]
	v_mfma_f32_16x16x32_bf16 v[74:77], v[168:171], v[218:221], v[74:77]
	v_mfma_f32_16x16x32_bf16 v[126:129], v[164:167], v[196:199], v[126:129]
	v_mfma_f32_16x16x32_bf16 v[122:125], v[172:175], v[196:199], v[122:125]
	v_mfma_f32_16x16x32_bf16 v[110:113], v[164:167], v[204:207], v[110:113]
	v_mfma_f32_16x16x32_bf16 v[106:109], v[172:175], v[204:207], v[106:109]
	v_mfma_f32_16x16x32_bf16 v[94:97], v[164:167], v[212:215], v[94:97]
	v_mfma_f32_16x16x32_bf16 v[90:93], v[172:175], v[212:215], v[90:93]
	v_mfma_f32_16x16x32_bf16 v[78:81], v[164:167], v[222:225], v[78:81]
	v_mfma_f32_16x16x32_bf16 v[74:77], v[172:175], v[222:225], v[74:77]
	v_mfma_f32_16x16x32_bf16 v[118:121], v[176:179], v[192:195], v[118:121]
	v_mfma_f32_16x16x32_bf16 v[114:117], v[184:187], v[192:195], v[114:117]
	v_mfma_f32_16x16x32_bf16 v[102:105], v[176:179], v[200:203], v[102:105]
	v_mfma_f32_16x16x32_bf16 v[98:101], v[184:187], v[200:203], v[98:101]
	v_mfma_f32_16x16x32_bf16 v[86:89], v[176:179], v[208:211], v[86:89]
	v_mfma_f32_16x16x32_bf16 v[82:85], v[184:187], v[208:211], v[82:85]
	v_mfma_f32_16x16x32_bf16 v[70:73], v[176:179], v[218:221], v[70:73]
	v_mfma_f32_16x16x32_bf16 v[66:69], v[184:187], v[218:221], v[66:69]
	v_mfma_f32_16x16x32_bf16 v[118:121], v[180:183], v[196:199], v[118:121]
	v_mfma_f32_16x16x32_bf16 v[114:117], v[188:191], v[196:199], v[114:117]
	v_mfma_f32_16x16x32_bf16 v[102:105], v[180:183], v[204:207], v[102:105]
	v_mfma_f32_16x16x32_bf16 v[98:101], v[188:191], v[204:207], v[98:101]
	v_mfma_f32_16x16x32_bf16 v[86:89], v[180:183], v[212:215], v[86:89]
	v_mfma_f32_16x16x32_bf16 v[82:85], v[188:191], v[212:215], v[82:85]
	v_mfma_f32_16x16x32_bf16 v[70:73], v[180:183], v[222:225], v[70:73]
	s_barrier
	v_mfma_f32_16x16x32_bf16 v[66:69], v[188:191], v[222:225], v[66:69]
	s_setprio 0
	s_add_i32 s53, s75, s30
	v_lshl_add_u64 v[152:153], s[34:35], 0, v[132:133]
	s_mov_b32 m0, s53
	ds_read_b128 v[192:195], v157 offset:16384
	ds_read_b128 v[196:199], v157 offset:17408
	ds_read_b128 v[200:203], v157 offset:18432
	ds_read_b128 v[204:207], v157 offset:19456
	ds_read_b128 v[208:211], v157 offset:20480
	ds_read_b128 v[212:215], v157 offset:21504
	ds_read_b128 v[218:221], v157 offset:22528
	ds_read_b128 v[222:225], v157 offset:23552
	global_load_lds_dwordx4 v[152:153], off
	s_add_i32 m0, s53, 0x2000
	s_add_u32 s54, s34, 0x80000
	v_lshl_add_u64 v[226:227], s[34:35], 0, v[136:137]
	s_addc_u32 s55, s35, 0
	s_add_i32 s53, s94, s30
	global_load_lds_dwordx4 v[226:227], off
	v_lshl_add_u64 v[228:229], s[54:55], 0, v[132:133]
	s_mov_b32 m0, s53
	v_lshl_add_u64 v[230:231], s[92:93], 0, v[134:135]
	global_load_lds_dwordx4 v[228:229], off
	v_lshl_add_u64 v[228:229], s[54:55], 0, v[136:137]
	s_add_i32 m0, s53, 0x2000
	s_nop 0
	global_load_lds_dwordx4 v[228:229], off
	v_lshl_add_u64 v[228:229], s[92:93], 0, v[130:131]
	s_mov_b32 m0, s56
	s_nop 0
	global_load_lds_dwordx4 v[228:229], off
	s_mov_b32 m0, s57
	s_nop 0
	global_load_lds_dwordx4 v[230:231], off
	s_waitcnt vmcnt(8)
	s_waitcnt lgkmcnt(0)
	s_barrier
	s_setprio 1
	v_mfma_f32_16x16x32_bf16 v[62:65], v[160:163], v[192:195], v[62:65]
	v_mfma_f32_16x16x32_bf16 v[58:61], v[168:171], v[192:195], v[58:61]
	v_mfma_f32_16x16x32_bf16 v[46:49], v[160:163], v[200:203], v[46:49]
	v_mfma_f32_16x16x32_bf16 v[42:45], v[168:171], v[200:203], v[42:45]
	v_mfma_f32_16x16x32_bf16 v[30:33], v[160:163], v[208:211], v[30:33]
	v_mfma_f32_16x16x32_bf16 v[26:29], v[168:171], v[208:211], v[26:29]
	v_mfma_f32_16x16x32_bf16 v[14:17], v[160:163], v[218:221], v[14:17]
	v_mfma_f32_16x16x32_bf16 v[10:13], v[168:171], v[218:221], v[10:13]
	v_mfma_f32_16x16x32_bf16 v[62:65], v[164:167], v[196:199], v[62:65]
	v_mfma_f32_16x16x32_bf16 v[58:61], v[172:175], v[196:199], v[58:61]
	v_mfma_f32_16x16x32_bf16 v[46:49], v[164:167], v[204:207], v[46:49]
	v_mfma_f32_16x16x32_bf16 v[42:45], v[172:175], v[204:207], v[42:45]
	v_mfma_f32_16x16x32_bf16 v[30:33], v[164:167], v[212:215], v[30:33]
	v_mfma_f32_16x16x32_bf16 v[26:29], v[172:175], v[212:215], v[26:29]
	v_mfma_f32_16x16x32_bf16 v[14:17], v[164:167], v[222:225], v[14:17]
	v_mfma_f32_16x16x32_bf16 v[10:13], v[172:175], v[222:225], v[10:13]
	v_mfma_f32_16x16x32_bf16 v[54:57], v[176:179], v[192:195], v[54:57]
	v_mfma_f32_16x16x32_bf16 v[50:53], v[184:187], v[192:195], v[50:53]
	v_mfma_f32_16x16x32_bf16 v[38:41], v[176:179], v[200:203], v[38:41]
	v_mfma_f32_16x16x32_bf16 v[34:37], v[184:187], v[200:203], v[34:37]
	v_mfma_f32_16x16x32_bf16 v[22:25], v[176:179], v[208:211], v[22:25]
	v_mfma_f32_16x16x32_bf16 v[18:21], v[184:187], v[208:211], v[18:21]
	v_mfma_f32_16x16x32_bf16 v[6:9], v[176:179], v[218:221], v[6:9]
	v_mfma_f32_16x16x32_bf16 v[2:5], v[184:187], v[218:221], v[2:5]
	v_mfma_f32_16x16x32_bf16 v[54:57], v[180:183], v[196:199], v[54:57]
	v_mfma_f32_16x16x32_bf16 v[50:53], v[188:191], v[196:199], v[50:53]
	v_mfma_f32_16x16x32_bf16 v[38:41], v[180:183], v[204:207], v[38:41]
	v_mfma_f32_16x16x32_bf16 v[34:37], v[188:191], v[204:207], v[34:37]
	v_mfma_f32_16x16x32_bf16 v[22:25], v[180:183], v[212:215], v[22:25]
	v_mfma_f32_16x16x32_bf16 v[18:21], v[188:191], v[212:215], v[18:21]
	v_mfma_f32_16x16x32_bf16 v[6:9], v[180:183], v[222:225], v[6:9]
	s_barrier
	v_mfma_f32_16x16x32_bf16 v[2:5], v[188:191], v[222:225], v[2:5]
	s_setprio 0
	s_add_i32 s53, 0, 0x18000
	v_add_u32_e32 v138, s53, v154
	s_add_i32 s62, 0, 0x1c000
	ds_read_b128 v[160:163], v138
	ds_read_b128 v[164:167], v138 offset:1024
	ds_read_b128 v[168:171], v138 offset:2048
	ds_read_b128 v[172:175], v138 offset:3072
	v_add_u32_e32 v138, s62, v154
	ds_read_b128 v[176:179], v138
	ds_read_b128 v[180:183], v138 offset:1024
	ds_read_b128 v[184:187], v138 offset:2048
	ds_read_b128 v[188:191], v138 offset:3072
	s_add_u32 s54, s92, 0x80000
	s_addc_u32 s55, s93, 0
	s_mov_b32 m0, s58
	v_lshl_add_u64 v[232:233], s[54:55], 0, v[130:131]
	ds_read_b128 v[192:195], v157 offset:32768
	ds_read_b128 v[196:199], v157 offset:33792
	ds_read_b128 v[200:203], v157 offset:34816
	ds_read_b128 v[204:207], v157 offset:35840
	ds_read_b128 v[208:211], v157 offset:36864
	ds_read_b128 v[212:215], v157 offset:37888
	ds_read_b128 v[218:221], v157 offset:38912
	ds_read_b128 v[222:225], v157 offset:39936
	global_load_lds_dwordx4 v[232:233], off
	v_lshl_add_u64 v[232:233], s[54:55], 0, v[134:135]
	s_mov_b32 m0, s59
	s_nop 0
	global_load_lds_dwordx4 v[232:233], off
	s_waitcnt vmcnt(8)
	s_waitcnt lgkmcnt(0)
	s_barrier
	s_setprio 1
	v_mfma_f32_16x16x32_bf16 v[126:129], v[160:163], v[192:195], v[126:129]
	v_mfma_f32_16x16x32_bf16 v[122:125], v[168:171], v[192:195], v[122:125]
	v_mfma_f32_16x16x32_bf16 v[110:113], v[160:163], v[200:203], v[110:113]
	v_mfma_f32_16x16x32_bf16 v[106:109], v[168:171], v[200:203], v[106:109]
	v_mfma_f32_16x16x32_bf16 v[94:97], v[160:163], v[208:211], v[94:97]
	v_mfma_f32_16x16x32_bf16 v[90:93], v[168:171], v[208:211], v[90:93]
	v_mfma_f32_16x16x32_bf16 v[78:81], v[160:163], v[218:221], v[78:81]
	v_mfma_f32_16x16x32_bf16 v[74:77], v[168:171], v[218:221], v[74:77]
	v_mfma_f32_16x16x32_bf16 v[126:129], v[164:167], v[196:199], v[126:129]
	v_mfma_f32_16x16x32_bf16 v[122:125], v[172:175], v[196:199], v[122:125]
	v_mfma_f32_16x16x32_bf16 v[110:113], v[164:167], v[204:207], v[110:113]
	v_mfma_f32_16x16x32_bf16 v[106:109], v[172:175], v[204:207], v[106:109]
	v_mfma_f32_16x16x32_bf16 v[94:97], v[164:167], v[212:215], v[94:97]
	v_mfma_f32_16x16x32_bf16 v[90:93], v[172:175], v[212:215], v[90:93]
	v_mfma_f32_16x16x32_bf16 v[78:81], v[164:167], v[222:225], v[78:81]
	v_mfma_f32_16x16x32_bf16 v[74:77], v[172:175], v[222:225], v[74:77]
	v_mfma_f32_16x16x32_bf16 v[118:121], v[176:179], v[192:195], v[118:121]
	v_mfma_f32_16x16x32_bf16 v[114:117], v[184:187], v[192:195], v[114:117]
	v_mfma_f32_16x16x32_bf16 v[102:105], v[176:179], v[200:203], v[102:105]
	v_mfma_f32_16x16x32_bf16 v[98:101], v[184:187], v[200:203], v[98:101]
	v_mfma_f32_16x16x32_bf16 v[86:89], v[176:179], v[208:211], v[86:89]
	v_mfma_f32_16x16x32_bf16 v[82:85], v[184:187], v[208:211], v[82:85]
	v_mfma_f32_16x16x32_bf16 v[70:73], v[176:179], v[218:221], v[70:73]
	v_mfma_f32_16x16x32_bf16 v[66:69], v[184:187], v[218:221], v[66:69]
	v_mfma_f32_16x16x32_bf16 v[118:121], v[180:183], v[196:199], v[118:121]
	v_mfma_f32_16x16x32_bf16 v[114:117], v[188:191], v[196:199], v[114:117]
	v_mfma_f32_16x16x32_bf16 v[102:105], v[180:183], v[204:207], v[102:105]
	v_mfma_f32_16x16x32_bf16 v[98:101], v[188:191], v[204:207], v[98:101]
	v_mfma_f32_16x16x32_bf16 v[86:89], v[180:183], v[212:215], v[86:89]
	v_mfma_f32_16x16x32_bf16 v[82:85], v[188:191], v[212:215], v[82:85]
	v_mfma_f32_16x16x32_bf16 v[70:73], v[180:183], v[222:225], v[70:73]
	s_barrier
	v_mfma_f32_16x16x32_bf16 v[66:69], v[188:191], v[222:225], v[66:69]
	s_setprio 0
	s_add_i32 s53, s53, s30
	v_lshl_add_u64 v[152:153], v[152:153], 0, s[76:77]
	s_mov_b32 m0, s53
	ds_read_b128 v[192:195], v157 offset:49152
	ds_read_b128 v[196:199], v157 offset:50176
	ds_read_b128 v[200:203], v157 offset:51200
	ds_read_b128 v[204:207], v157 offset:52224
	ds_read_b128 v[208:211], v157 offset:53248
	ds_read_b128 v[212:215], v157 offset:54272
	ds_read_b128 v[218:221], v157 offset:55296
	ds_read_b128 v[222:225], v157 offset:56320
	global_load_lds_dwordx4 v[152:153], off
	s_add_i32 m0, s53, 0x2000
	s_add_u32 s34, s34, 0x80080
	v_lshl_add_u64 v[152:153], v[226:227], 0, s[76:77]
	s_addc_u32 s35, s35, 0
	s_add_i32 s53, s62, s30
	global_load_lds_dwordx4 v[152:153], off
	v_lshl_add_u64 v[152:153], s[34:35], 0, v[132:133]
	s_mov_b32 m0, s53
	s_nop 0
	global_load_lds_dwordx4 v[152:153], off
	v_lshl_add_u64 v[152:153], s[34:35], 0, v[136:137]
	s_add_i32 m0, s53, 0x2000
	s_nop 0
	global_load_lds_dwordx4 v[152:153], off
	v_lshl_add_u64 v[152:153], v[228:229], 0, s[76:77]
	s_mov_b32 m0, s61
	s_nop 0
	global_load_lds_dwordx4 v[152:153], off
	v_lshl_add_u64 v[152:153], v[230:231], 0, s[76:77]
	s_mov_b32 m0, s72
	s_nop 0
	global_load_lds_dwordx4 v[152:153], off
	s_waitcnt vmcnt(8)
	s_waitcnt lgkmcnt(0)
	s_barrier
	s_setprio 1
	v_mfma_f32_16x16x32_bf16 v[62:65], v[160:163], v[192:195], v[62:65]
	v_mfma_f32_16x16x32_bf16 v[58:61], v[168:171], v[192:195], v[58:61]
	v_mfma_f32_16x16x32_bf16 v[46:49], v[160:163], v[200:203], v[46:49]
	v_mfma_f32_16x16x32_bf16 v[42:45], v[168:171], v[200:203], v[42:45]
	v_mfma_f32_16x16x32_bf16 v[30:33], v[160:163], v[208:211], v[30:33]
	v_mfma_f32_16x16x32_bf16 v[26:29], v[168:171], v[208:211], v[26:29]
	v_mfma_f32_16x16x32_bf16 v[14:17], v[160:163], v[218:221], v[14:17]
	v_mfma_f32_16x16x32_bf16 v[10:13], v[168:171], v[218:221], v[10:13]
	v_mfma_f32_16x16x32_bf16 v[62:65], v[164:167], v[196:199], v[62:65]
	v_mfma_f32_16x16x32_bf16 v[58:61], v[172:175], v[196:199], v[58:61]
	v_mfma_f32_16x16x32_bf16 v[46:49], v[164:167], v[204:207], v[46:49]
	v_mfma_f32_16x16x32_bf16 v[42:45], v[172:175], v[204:207], v[42:45]
	v_mfma_f32_16x16x32_bf16 v[30:33], v[164:167], v[212:215], v[30:33]
	v_mfma_f32_16x16x32_bf16 v[26:29], v[172:175], v[212:215], v[26:29]
	v_mfma_f32_16x16x32_bf16 v[14:17], v[164:167], v[222:225], v[14:17]
	v_mfma_f32_16x16x32_bf16 v[10:13], v[172:175], v[222:225], v[10:13]
	v_mfma_f32_16x16x32_bf16 v[54:57], v[176:179], v[192:195], v[54:57]
	v_mfma_f32_16x16x32_bf16 v[50:53], v[184:187], v[192:195], v[50:53]
	v_mfma_f32_16x16x32_bf16 v[38:41], v[176:179], v[200:203], v[38:41]
	v_mfma_f32_16x16x32_bf16 v[34:37], v[184:187], v[200:203], v[34:37]
	v_mfma_f32_16x16x32_bf16 v[22:25], v[176:179], v[208:211], v[22:25]
	v_mfma_f32_16x16x32_bf16 v[18:21], v[184:187], v[208:211], v[18:21]
	v_mfma_f32_16x16x32_bf16 v[6:9], v[176:179], v[218:221], v[6:9]
	v_mfma_f32_16x16x32_bf16 v[2:5], v[184:187], v[218:221], v[2:5]
	v_mfma_f32_16x16x32_bf16 v[54:57], v[180:183], v[196:199], v[54:57]
	v_mfma_f32_16x16x32_bf16 v[50:53], v[188:191], v[196:199], v[50:53]
	v_mfma_f32_16x16x32_bf16 v[38:41], v[180:183], v[204:207], v[38:41]
	v_mfma_f32_16x16x32_bf16 v[34:37], v[188:191], v[204:207], v[34:37]
	v_mfma_f32_16x16x32_bf16 v[22:25], v[180:183], v[212:215], v[22:25]
	v_mfma_f32_16x16x32_bf16 v[18:21], v[188:191], v[212:215], v[18:21]
	v_mfma_f32_16x16x32_bf16 v[6:9], v[180:183], v[222:225], v[6:9]
	s_barrier
	v_mfma_f32_16x16x32_bf16 v[2:5], v[188:191], v[222:225], v[2:5]
	s_setprio 0
	s_add_i32 s83, s83, 2
	s_add_u32 s90, s90, 0x100
	s_addc_u32 s91, s91, 0
	s_add_u32 s52, s52, 0x100
	s_addc_u32 s68, s68, 0
	s_cmp_gt_u32 s83, 29
	s_cbranch_scc0 .LBB0_518
	s_and_b64 vcc, exec, s[78:79]
	s_cbranch_vccz .LBB0_521
	s_barrier

.LBB0_685:
	ds_read_b128 v[146:149], v165
	ds_read_b128 v[150:153], v165 offset:1024
	ds_read_b128 v[168:171], v165 offset:2048
	ds_read_b128 v[172:175], v165 offset:3072
	ds_read_b128 v[176:179], v166
	ds_read_b128 v[180:183], v166 offset:1024
	ds_read_b128 v[184:187], v166 offset:2048
	ds_read_b128 v[188:191], v166 offset:3072
	s_add_u32 s34, s84, 0xfffe0080
	s_addc_u32 s35, s85, -1
	s_cmp_eq_u32 s89, 4
	s_cselect_b32 s87, s0, s35
	s_cselect_b32 s86, s1, s34
	s_cselect_b32 s35, s52, s88
	s_cselect_b32 s34, s71, s77
	v_lshl_add_u64 v[226:227], s[84:85], 0, v[138:139]
	s_add_i32 m0, s33, 0xc000
	ds_read_b128 v[192:195], v167
	ds_read_b128 v[196:199], v167 offset:1024
	ds_read_b128 v[200:203], v167 offset:2048
	ds_read_b128 v[204:207], v167 offset:3072
	ds_read_b128 v[208:211], v167 offset:4096
	ds_read_b128 v[212:215], v167 offset:5120
	ds_read_b128 v[218:221], v167 offset:6144
	ds_read_b128 v[222:225], v167 offset:7168
	global_load_lds_dwordx4 v[226:227], off
	v_lshl_add_u64 v[226:227], s[84:85], 0, v[140:141]
	s_add_i32 m0, s33, 0xe000
	s_nop 0
	global_load_lds_dwordx4 v[226:227], off
	s_waitcnt vmcnt(8)
	s_waitcnt lgkmcnt(0)
	s_barrier
	s_setprio 1
	v_mfma_f32_16x16x32_bf16 v[126:129], v[146:149], v[192:195], v[126:129]
	v_mfma_f32_16x16x32_bf16 v[122:125], v[168:171], v[192:195], v[122:125]
	v_mfma_f32_16x16x32_bf16 v[114:117], v[146:149], v[200:203], v[114:117]
	v_mfma_f32_16x16x32_bf16 v[106:109], v[168:171], v[200:203], v[106:109]
	v_mfma_f32_16x16x32_bf16 v[98:101], v[146:149], v[208:211], v[98:101]
	v_mfma_f32_16x16x32_bf16 v[90:93], v[168:171], v[208:211], v[90:93]
	v_mfma_f32_16x16x32_bf16 v[82:85], v[146:149], v[218:221], v[82:85]
	v_mfma_f32_16x16x32_bf16 v[74:77], v[168:171], v[218:221], v[74:77]
	v_mfma_f32_16x16x32_bf16 v[126:129], v[150:153], v[196:199], v[126:129]
	v_mfma_f32_16x16x32_bf16 v[122:125], v[172:175], v[196:199], v[122:125]
	v_mfma_f32_16x16x32_bf16 v[114:117], v[150:153], v[204:207], v[114:117]
	v_mfma_f32_16x16x32_bf16 v[106:109], v[172:175], v[204:207], v[106:109]
	v_mfma_f32_16x16x32_bf16 v[98:101], v[150:153], v[212:215], v[98:101]
	v_mfma_f32_16x16x32_bf16 v[90:93], v[172:175], v[212:215], v[90:93]
	v_mfma_f32_16x16x32_bf16 v[82:85], v[150:153], v[222:225], v[82:85]
	v_mfma_f32_16x16x32_bf16 v[74:77], v[172:175], v[222:225], v[74:77]
	v_mfma_f32_16x16x32_bf16 v[118:121], v[176:179], v[192:195], v[118:121]
	v_mfma_f32_16x16x32_bf16 v[110:113], v[184:187], v[192:195], v[110:113]
	v_mfma_f32_16x16x32_bf16 v[102:105], v[176:179], v[200:203], v[102:105]
	v_mfma_f32_16x16x32_bf16 v[94:97], v[184:187], v[200:203], v[94:97]
	v_mfma_f32_16x16x32_bf16 v[86:89], v[176:179], v[208:211], v[86:89]
	v_mfma_f32_16x16x32_bf16 v[78:81], v[184:187], v[208:211], v[78:81]
	v_mfma_f32_16x16x32_bf16 v[70:73], v[176:179], v[218:221], v[70:73]
	v_mfma_f32_16x16x32_bf16 v[66:69], v[184:187], v[218:221], v[66:69]
	v_mfma_f32_16x16x32_bf16 v[118:121], v[180:183], v[196:199], v[118:121]
	v_mfma_f32_16x16x32_bf16 v[110:113], v[188:191], v[196:199], v[110:113]
	v_mfma_f32_16x16x32_bf16 v[102:105], v[180:183], v[204:207], v[102:105]
	v_mfma_f32_16x16x32_bf16 v[94:97], v[188:191], v[204:207], v[94:97]
	v_mfma_f32_16x16x32_bf16 v[86:89], v[180:183], v[212:215], v[86:89]
	v_mfma_f32_16x16x32_bf16 v[78:81], v[188:191], v[212:215], v[78:81]
	v_mfma_f32_16x16x32_bf16 v[70:73], v[180:183], v[222:225], v[70:73]
	s_barrier
	v_mfma_f32_16x16x32_bf16 v[66:69], v[188:191], v[222:225], v[66:69]
	s_setprio 0
	s_add_i32 s53, s73, s12
	v_lshl_add_u64 v[226:227], s[34:35], 0, v[132:133]
	s_mov_b32 m0, s53
	ds_read_b128 v[192:195], v167 offset:16384
	ds_read_b128 v[196:199], v167 offset:17408
	ds_read_b128 v[200:203], v167 offset:18432
	ds_read_b128 v[204:207], v167 offset:19456
	ds_read_b128 v[208:211], v167 offset:20480
	ds_read_b128 v[212:215], v167 offset:21504
	ds_read_b128 v[218:221], v167 offset:22528
	ds_read_b128 v[222:225], v167 offset:23552
	global_load_lds_dwordx4 v[226:227], off
	s_add_i32 m0, s53, 0x2000
	s_add_u32 s54, s34, 0x20000
	v_lshl_add_u64 v[228:229], s[34:35], 0, v[136:137]
	s_addc_u32 s55, s35, 0
	s_add_i32 s53, s74, s12
	global_load_lds_dwordx4 v[228:229], off
	v_lshl_add_u64 v[230:231], s[54:55], 0, v[132:133]
	s_mov_b32 m0, s53
	v_lshl_add_u64 v[232:233], s[86:87], 0, v[134:135]
	global_load_lds_dwordx4 v[230:231], off
	v_lshl_add_u64 v[230:231], s[54:55], 0, v[136:137]
	s_add_i32 m0, s53, 0x2000
	s_nop 0
	global_load_lds_dwordx4 v[230:231], off
	v_lshl_add_u64 v[230:231], s[86:87], 0, v[130:131]
	s_mov_b32 m0, s33
	s_nop 0
	global_load_lds_dwordx4 v[230:231], off
	s_mov_b32 m0, s56
	s_nop 0
	global_load_lds_dwordx4 v[232:233], off
	s_waitcnt vmcnt(8)
	s_waitcnt lgkmcnt(0)
	s_barrier
	s_setprio 1
	v_mfma_f32_16x16x32_bf16 v[62:65], v[146:149], v[192:195], v[62:65]
	v_mfma_f32_16x16x32_bf16 v[58:61], v[168:171], v[192:195], v[58:61]
	v_mfma_f32_16x16x32_bf16 v[50:53], v[146:149], v[200:203], v[50:53]
	v_mfma_f32_16x16x32_bf16 v[42:45], v[168:171], v[200:203], v[42:45]
	v_mfma_f32_16x16x32_bf16 v[34:37], v[146:149], v[208:211], v[34:37]
	v_mfma_f32_16x16x32_bf16 v[26:29], v[168:171], v[208:211], v[26:29]
	v_mfma_f32_16x16x32_bf16 v[18:21], v[146:149], v[218:221], v[18:21]
	v_mfma_f32_16x16x32_bf16 v[10:13], v[168:171], v[218:221], v[10:13]
	v_mfma_f32_16x16x32_bf16 v[62:65], v[150:153], v[196:199], v[62:65]
	v_mfma_f32_16x16x32_bf16 v[58:61], v[172:175], v[196:199], v[58:61]
	v_mfma_f32_16x16x32_bf16 v[50:53], v[150:153], v[204:207], v[50:53]
	v_mfma_f32_16x16x32_bf16 v[42:45], v[172:175], v[204:207], v[42:45]
	v_mfma_f32_16x16x32_bf16 v[34:37], v[150:153], v[212:215], v[34:37]
	v_mfma_f32_16x16x32_bf16 v[26:29], v[172:175], v[212:215], v[26:29]
	v_mfma_f32_16x16x32_bf16 v[18:21], v[150:153], v[222:225], v[18:21]
	v_mfma_f32_16x16x32_bf16 v[10:13], v[172:175], v[222:225], v[10:13]
	v_mfma_f32_16x16x32_bf16 v[54:57], v[176:179], v[192:195], v[54:57]
	v_mfma_f32_16x16x32_bf16 v[46:49], v[184:187], v[192:195], v[46:49]
	v_mfma_f32_16x16x32_bf16 v[38:41], v[176:179], v[200:203], v[38:41]
	v_mfma_f32_16x16x32_bf16 v[30:33], v[184:187], v[200:203], v[30:33]
	v_mfma_f32_16x16x32_bf16 v[22:25], v[176:179], v[208:211], v[22:25]
	v_mfma_f32_16x16x32_bf16 v[14:17], v[184:187], v[208:211], v[14:17]
	v_mfma_f32_16x16x32_bf16 v[6:9], v[176:179], v[218:221], v[6:9]
	v_mfma_f32_16x16x32_bf16 v[2:5], v[184:187], v[218:221], v[2:5]
	v_mfma_f32_16x16x32_bf16 v[54:57], v[180:183], v[196:199], v[54:57]
	v_mfma_f32_16x16x32_bf16 v[46:49], v[188:191], v[196:199], v[46:49]
	v_mfma_f32_16x16x32_bf16 v[38:41], v[180:183], v[204:207], v[38:41]
	v_mfma_f32_16x16x32_bf16 v[30:33], v[188:191], v[204:207], v[30:33]
	v_mfma_f32_16x16x32_bf16 v[22:25], v[180:183], v[212:215], v[22:25]
	v_mfma_f32_16x16x32_bf16 v[14:17], v[188:191], v[212:215], v[14:17]
	v_mfma_f32_16x16x32_bf16 v[6:9], v[180:183], v[222:225], v[6:9]
	s_barrier
	v_mfma_f32_16x16x32_bf16 v[2:5], v[188:191], v[222:225], v[2:5]
	s_setprio 0
	s_add_i32 s53, 0, 0x18000
	s_add_i32 s62, 0, 0x1c000
	v_add_u32_e32 v172, s53, v162
	v_add_u32_e32 v188, s62, v162
	ds_read_b128 v[146:149], v172
	ds_read_b128 v[150:153], v172 offset:1024
	ds_read_b128 v[168:171], v172 offset:2048
	ds_read_b128 v[172:175], v172 offset:3072
	ds_read_b128 v[176:179], v188
	ds_read_b128 v[180:183], v188 offset:1024
	ds_read_b128 v[184:187], v188 offset:2048
	ds_read_b128 v[188:191], v188 offset:3072
	s_add_u32 s54, s86, 0x20000
	s_addc_u32 s55, s87, 0
	s_mov_b32 m0, s57
	v_lshl_add_u64 v[234:235], s[54:55], 0, v[130:131]
	ds_read_b128 v[192:195], v167 offset:32768
	ds_read_b128 v[196:199], v167 offset:33792
	ds_read_b128 v[200:203], v167 offset:34816
	ds_read_b128 v[204:207], v167 offset:35840
	ds_read_b128 v[208:211], v167 offset:36864
	ds_read_b128 v[212:215], v167 offset:37888
	ds_read_b128 v[218:221], v167 offset:38912
	ds_read_b128 v[222:225], v167 offset:39936
	global_load_lds_dwordx4 v[234:235], off
	v_lshl_add_u64 v[234:235], s[54:55], 0, v[134:135]
	s_mov_b32 m0, s58
	s_nop 0
	global_load_lds_dwordx4 v[234:235], off
	s_waitcnt vmcnt(8)
	s_waitcnt lgkmcnt(0)
	s_barrier
	s_setprio 1
	v_mfma_f32_16x16x32_bf16 v[126:129], v[146:149], v[192:195], v[126:129]
	v_mfma_f32_16x16x32_bf16 v[122:125], v[168:171], v[192:195], v[122:125]
	v_mfma_f32_16x16x32_bf16 v[114:117], v[146:149], v[200:203], v[114:117]
	v_mfma_f32_16x16x32_bf16 v[106:109], v[168:171], v[200:203], v[106:109]
	v_mfma_f32_16x16x32_bf16 v[98:101], v[146:149], v[208:211], v[98:101]
	v_mfma_f32_16x16x32_bf16 v[90:93], v[168:171], v[208:211], v[90:93]
	v_mfma_f32_16x16x32_bf16 v[82:85], v[146:149], v[218:221], v[82:85]
	v_mfma_f32_16x16x32_bf16 v[74:77], v[168:171], v[218:221], v[74:77]
	v_mfma_f32_16x16x32_bf16 v[126:129], v[150:153], v[196:199], v[126:129]
	v_mfma_f32_16x16x32_bf16 v[122:125], v[172:175], v[196:199], v[122:125]
	v_mfma_f32_16x16x32_bf16 v[114:117], v[150:153], v[204:207], v[114:117]
	v_mfma_f32_16x16x32_bf16 v[106:109], v[172:175], v[204:207], v[106:109]
	v_mfma_f32_16x16x32_bf16 v[98:101], v[150:153], v[212:215], v[98:101]
	v_mfma_f32_16x16x32_bf16 v[90:93], v[172:175], v[212:215], v[90:93]
	v_mfma_f32_16x16x32_bf16 v[82:85], v[150:153], v[222:225], v[82:85]
	v_mfma_f32_16x16x32_bf16 v[74:77], v[172:175], v[222:225], v[74:77]
	v_mfma_f32_16x16x32_bf16 v[118:121], v[176:179], v[192:195], v[118:121]
	v_mfma_f32_16x16x32_bf16 v[110:113], v[184:187], v[192:195], v[110:113]
	v_mfma_f32_16x16x32_bf16 v[102:105], v[176:179], v[200:203], v[102:105]
	v_mfma_f32_16x16x32_bf16 v[94:97], v[184:187], v[200:203], v[94:97]
	v_mfma_f32_16x16x32_bf16 v[86:89], v[176:179], v[208:211], v[86:89]
	v_mfma_f32_16x16x32_bf16 v[78:81], v[184:187], v[208:211], v[78:81]
	v_mfma_f32_16x16x32_bf16 v[70:73], v[176:179], v[218:221], v[70:73]
	v_mfma_f32_16x16x32_bf16 v[66:69], v[184:187], v[218:221], v[66:69]
	v_mfma_f32_16x16x32_bf16 v[118:121], v[180:183], v[196:199], v[118:121]
	v_mfma_f32_16x16x32_bf16 v[110:113], v[188:191], v[196:199], v[110:113]
	v_mfma_f32_16x16x32_bf16 v[102:105], v[180:183], v[204:207], v[102:105]
	v_mfma_f32_16x16x32_bf16 v[94:97], v[188:191], v[204:207], v[94:97]
	v_mfma_f32_16x16x32_bf16 v[86:89], v[180:183], v[212:215], v[86:89]
	v_mfma_f32_16x16x32_bf16 v[78:81], v[188:191], v[212:215], v[78:81]
	v_mfma_f32_16x16x32_bf16 v[70:73], v[180:183], v[222:225], v[70:73]
	s_barrier
	v_mfma_f32_16x16x32_bf16 v[66:69], v[188:191], v[222:225], v[66:69]
	s_setprio 0
	s_add_i32 s53, s53, s12
	v_lshl_add_u64 v[226:227], v[226:227], 0, s[8:9]
	s_mov_b32 m0, s53
	ds_read_b128 v[192:195], v167 offset:49152
	ds_read_b128 v[196:199], v167 offset:50176
	ds_read_b128 v[200:203], v167 offset:51200
	ds_read_b128 v[204:207], v167 offset:52224
	ds_read_b128 v[208:211], v167 offset:53248
	ds_read_b128 v[212:215], v167 offset:54272
	ds_read_b128 v[218:221], v167 offset:55296
	ds_read_b128 v[222:225], v167 offset:56320
	global_load_lds_dwordx4 v[226:227], off
	s_add_i32 m0, s53, 0x2000
	s_add_u32 s34, s34, 0x20080
	v_lshl_add_u64 v[226:227], v[228:229], 0, s[8:9]
	s_addc_u32 s35, s35, 0
	s_add_i32 s53, s62, s12
	global_load_lds_dwordx4 v[226:227], off
	v_lshl_add_u64 v[226:227], s[34:35], 0, v[132:133]
	s_mov_b32 m0, s53
	s_nop 0
	global_load_lds_dwordx4 v[226:227], off
	v_lshl_add_u64 v[226:227], s[34:35], 0, v[136:137]
	s_add_i32 m0, s53, 0x2000
	s_nop 0
	global_load_lds_dwordx4 v[226:227], off
	v_lshl_add_u64 v[226:227], v[230:231], 0, s[8:9]
	s_mov_b32 m0, s60
	s_nop 0
	global_load_lds_dwordx4 v[226:227], off
	v_lshl_add_u64 v[226:227], v[232:233], 0, s[8:9]
	s_mov_b32 m0, s61
	s_nop 0
	global_load_lds_dwordx4 v[226:227], off
	s_waitcnt vmcnt(8)
	s_waitcnt lgkmcnt(0)
	s_barrier
	s_setprio 1
	v_mfma_f32_16x16x32_bf16 v[62:65], v[146:149], v[192:195], v[62:65]
	v_mfma_f32_16x16x32_bf16 v[58:61], v[168:171], v[192:195], v[58:61]
	v_mfma_f32_16x16x32_bf16 v[50:53], v[146:149], v[200:203], v[50:53]
	v_mfma_f32_16x16x32_bf16 v[42:45], v[168:171], v[200:203], v[42:45]
	v_mfma_f32_16x16x32_bf16 v[34:37], v[146:149], v[208:211], v[34:37]
	v_mfma_f32_16x16x32_bf16 v[26:29], v[168:171], v[208:211], v[26:29]
	v_mfma_f32_16x16x32_bf16 v[18:21], v[146:149], v[218:221], v[18:21]
	v_mfma_f32_16x16x32_bf16 v[10:13], v[168:171], v[218:221], v[10:13]
	v_mfma_f32_16x16x32_bf16 v[62:65], v[150:153], v[196:199], v[62:65]
	v_mfma_f32_16x16x32_bf16 v[58:61], v[172:175], v[196:199], v[58:61]
	v_mfma_f32_16x16x32_bf16 v[50:53], v[150:153], v[204:207], v[50:53]
	v_mfma_f32_16x16x32_bf16 v[42:45], v[172:175], v[204:207], v[42:45]
	v_mfma_f32_16x16x32_bf16 v[34:37], v[150:153], v[212:215], v[34:37]
	v_mfma_f32_16x16x32_bf16 v[26:29], v[172:175], v[212:215], v[26:29]
	v_mfma_f32_16x16x32_bf16 v[18:21], v[150:153], v[222:225], v[18:21]
	v_mfma_f32_16x16x32_bf16 v[10:13], v[172:175], v[222:225], v[10:13]
	v_mfma_f32_16x16x32_bf16 v[54:57], v[176:179], v[192:195], v[54:57]
	v_mfma_f32_16x16x32_bf16 v[46:49], v[184:187], v[192:195], v[46:49]
	v_mfma_f32_16x16x32_bf16 v[38:41], v[176:179], v[200:203], v[38:41]
	v_mfma_f32_16x16x32_bf16 v[30:33], v[184:187], v[200:203], v[30:33]
	v_mfma_f32_16x16x32_bf16 v[22:25], v[176:179], v[208:211], v[22:25]
	v_mfma_f32_16x16x32_bf16 v[14:17], v[184:187], v[208:211], v[14:17]
	v_mfma_f32_16x16x32_bf16 v[6:9], v[176:179], v[218:221], v[6:9]
	v_mfma_f32_16x16x32_bf16 v[2:5], v[184:187], v[218:221], v[2:5]
	v_mfma_f32_16x16x32_bf16 v[54:57], v[180:183], v[196:199], v[54:57]
	v_mfma_f32_16x16x32_bf16 v[46:49], v[188:191], v[196:199], v[46:49]
	v_mfma_f32_16x16x32_bf16 v[38:41], v[180:183], v[204:207], v[38:41]
	v_mfma_f32_16x16x32_bf16 v[30:33], v[188:191], v[204:207], v[30:33]
	v_mfma_f32_16x16x32_bf16 v[22:25], v[180:183], v[212:215], v[22:25]
	v_mfma_f32_16x16x32_bf16 v[14:17], v[188:191], v[212:215], v[14:17]
	v_mfma_f32_16x16x32_bf16 v[6:9], v[180:183], v[222:225], v[6:9]
	s_barrier
	v_mfma_f32_16x16x32_bf16 v[2:5], v[188:191], v[222:225], v[2:5]
	s_setprio 0
	s_add_i32 s89, s89, 2
	s_add_u32 s84, s84, 0x100
	s_addc_u32 s85, s85, 0
	s_add_u32 s77, s77, 0x100
	s_addc_u32 s88, s88, 0
	s_cmp_gt_u32 s89, 5
	s_cbranch_scc0 .LBB0_685
	s_and_b64 vcc, exec, s[66:67]
	s_cbranch_vccz .LBB0_688
	s_barrier

.LBB0_715:
	ds_read_b128 v[146:149], v1
	ds_read_b128 v[160:163], v1 offset:1024
	ds_read_b128 v[164:167], v1 offset:2048
	ds_read_b128 v[168:171], v1 offset:3072
	ds_read_b128 v[172:175], v154
	ds_read_b128 v[176:179], v154 offset:1024
	ds_read_b128 v[180:183], v154 offset:2048
	ds_read_b128 v[184:187], v154 offset:3072
	s_add_u32 s34, s84, 0xfffe0080
	s_addc_u32 s35, s85, -1
	s_cmp_eq_u32 s88, 4
	s_cselect_b32 s87, s0, s35
	s_cselect_b32 s86, s1, s34
	s_cselect_b32 s35, s52, s83
	s_cselect_b32 s34, s71, s77
	v_lshl_add_u64 v[150:151], s[84:85], 0, v[138:139]
	s_add_i32 m0, s33, 0xc000
	ds_read_b128 v[188:191], v155
	ds_read_b128 v[192:195], v155 offset:1024
	ds_read_b128 v[196:199], v155 offset:2048
	ds_read_b128 v[200:203], v155 offset:3072
	ds_read_b128 v[204:207], v155 offset:4096
	ds_read_b128 v[208:211], v155 offset:5120
	ds_read_b128 v[212:215], v155 offset:6144
	ds_read_b128 v[218:221], v155 offset:7168
	global_load_lds_dwordx4 v[150:151], off
	v_lshl_add_u64 v[150:151], s[84:85], 0, v[140:141]
	s_add_i32 m0, s33, 0xe000
	s_nop 0
	global_load_lds_dwordx4 v[150:151], off
	s_waitcnt vmcnt(8)
	s_waitcnt lgkmcnt(0)
	s_barrier
	s_setprio 1
	v_mfma_f32_16x16x32_bf16 v[126:129], v[146:149], v[188:191], v[126:129]
	v_mfma_f32_16x16x32_bf16 v[122:125], v[164:167], v[188:191], v[122:125]
	v_mfma_f32_16x16x32_bf16 v[110:113], v[146:149], v[196:199], v[110:113]
	v_mfma_f32_16x16x32_bf16 v[106:109], v[164:167], v[196:199], v[106:109]
	v_mfma_f32_16x16x32_bf16 v[94:97], v[146:149], v[204:207], v[94:97]
	v_mfma_f32_16x16x32_bf16 v[90:93], v[164:167], v[204:207], v[90:93]
	v_mfma_f32_16x16x32_bf16 v[78:81], v[146:149], v[212:215], v[78:81]
	v_mfma_f32_16x16x32_bf16 v[74:77], v[164:167], v[212:215], v[74:77]
	v_mfma_f32_16x16x32_bf16 v[126:129], v[160:163], v[192:195], v[126:129]
	v_mfma_f32_16x16x32_bf16 v[122:125], v[168:171], v[192:195], v[122:125]
	v_mfma_f32_16x16x32_bf16 v[110:113], v[160:163], v[200:203], v[110:113]
	v_mfma_f32_16x16x32_bf16 v[106:109], v[168:171], v[200:203], v[106:109]
	v_mfma_f32_16x16x32_bf16 v[94:97], v[160:163], v[208:211], v[94:97]
	v_mfma_f32_16x16x32_bf16 v[90:93], v[168:171], v[208:211], v[90:93]
	v_mfma_f32_16x16x32_bf16 v[78:81], v[160:163], v[218:221], v[78:81]
	v_mfma_f32_16x16x32_bf16 v[74:77], v[168:171], v[218:221], v[74:77]
	v_mfma_f32_16x16x32_bf16 v[118:121], v[172:175], v[188:191], v[118:121]
	v_mfma_f32_16x16x32_bf16 v[114:117], v[180:183], v[188:191], v[114:117]
	v_mfma_f32_16x16x32_bf16 v[102:105], v[172:175], v[196:199], v[102:105]
	v_mfma_f32_16x16x32_bf16 v[98:101], v[180:183], v[196:199], v[98:101]
	v_mfma_f32_16x16x32_bf16 v[86:89], v[172:175], v[204:207], v[86:89]
	v_mfma_f32_16x16x32_bf16 v[82:85], v[180:183], v[204:207], v[82:85]
	v_mfma_f32_16x16x32_bf16 v[70:73], v[172:175], v[212:215], v[70:73]
	v_mfma_f32_16x16x32_bf16 v[66:69], v[180:183], v[212:215], v[66:69]
	v_mfma_f32_16x16x32_bf16 v[118:121], v[176:179], v[192:195], v[118:121]
	v_mfma_f32_16x16x32_bf16 v[114:117], v[184:187], v[192:195], v[114:117]
	v_mfma_f32_16x16x32_bf16 v[102:105], v[176:179], v[200:203], v[102:105]
	v_mfma_f32_16x16x32_bf16 v[98:101], v[184:187], v[200:203], v[98:101]
	v_mfma_f32_16x16x32_bf16 v[86:89], v[176:179], v[208:211], v[86:89]
	v_mfma_f32_16x16x32_bf16 v[82:85], v[184:187], v[208:211], v[82:85]
	v_mfma_f32_16x16x32_bf16 v[70:73], v[176:179], v[218:221], v[70:73]
	s_barrier
	v_mfma_f32_16x16x32_bf16 v[66:69], v[184:187], v[218:221], v[66:69]
	s_setprio 0
	s_add_i32 s53, s73, s13
	v_lshl_add_u64 v[150:151], s[34:35], 0, v[132:133]
	s_mov_b32 m0, s53
	ds_read_b128 v[188:191], v155 offset:16384
	ds_read_b128 v[192:195], v155 offset:17408
	ds_read_b128 v[196:199], v155 offset:18432
	ds_read_b128 v[200:203], v155 offset:19456
	ds_read_b128 v[204:207], v155 offset:20480
	ds_read_b128 v[208:211], v155 offset:21504
	ds_read_b128 v[212:215], v155 offset:22528
	ds_read_b128 v[218:221], v155 offset:23552
	global_load_lds_dwordx4 v[150:151], off
	s_add_i32 m0, s53, 0x2000
	s_add_u32 s54, s34, 0x20000
	v_lshl_add_u64 v[222:223], s[34:35], 0, v[136:137]
	s_addc_u32 s55, s35, 0
	s_add_i32 s53, s74, s13
	global_load_lds_dwordx4 v[222:223], off
	v_lshl_add_u64 v[224:225], s[54:55], 0, v[132:133]
	s_mov_b32 m0, s53
	v_lshl_add_u64 v[226:227], s[86:87], 0, v[134:135]
	global_load_lds_dwordx4 v[224:225], off
	v_lshl_add_u64 v[224:225], s[54:55], 0, v[136:137]
	s_add_i32 m0, s53, 0x2000
	s_nop 0
	global_load_lds_dwordx4 v[224:225], off
	v_lshl_add_u64 v[224:225], s[86:87], 0, v[130:131]
	s_mov_b32 m0, s33
	s_nop 0
	global_load_lds_dwordx4 v[224:225], off
	s_mov_b32 m0, s56
	s_nop 0
	global_load_lds_dwordx4 v[226:227], off
	s_waitcnt vmcnt(8)
	s_waitcnt lgkmcnt(0)
	s_barrier
	s_setprio 1
	v_mfma_f32_16x16x32_bf16 v[62:65], v[146:149], v[188:191], v[62:65]
	v_mfma_f32_16x16x32_bf16 v[58:61], v[164:167], v[188:191], v[58:61]
	v_mfma_f32_16x16x32_bf16 v[50:53], v[146:149], v[196:199], v[50:53]
	v_mfma_f32_16x16x32_bf16 v[42:45], v[164:167], v[196:199], v[42:45]
	v_mfma_f32_16x16x32_bf16 v[34:37], v[146:149], v[204:207], v[34:37]
	v_mfma_f32_16x16x32_bf16 v[26:29], v[164:167], v[204:207], v[26:29]
	v_mfma_f32_16x16x32_bf16 v[18:21], v[146:149], v[212:215], v[18:21]
	v_mfma_f32_16x16x32_bf16 v[10:13], v[164:167], v[212:215], v[10:13]
	v_mfma_f32_16x16x32_bf16 v[62:65], v[160:163], v[192:195], v[62:65]
	v_mfma_f32_16x16x32_bf16 v[58:61], v[168:171], v[192:195], v[58:61]
	v_mfma_f32_16x16x32_bf16 v[50:53], v[160:163], v[200:203], v[50:53]
	v_mfma_f32_16x16x32_bf16 v[42:45], v[168:171], v[200:203], v[42:45]
	v_mfma_f32_16x16x32_bf16 v[34:37], v[160:163], v[208:211], v[34:37]
	v_mfma_f32_16x16x32_bf16 v[26:29], v[168:171], v[208:211], v[26:29]
	v_mfma_f32_16x16x32_bf16 v[18:21], v[160:163], v[218:221], v[18:21]
	v_mfma_f32_16x16x32_bf16 v[10:13], v[168:171], v[218:221], v[10:13]
	v_mfma_f32_16x16x32_bf16 v[54:57], v[172:175], v[188:191], v[54:57]
	v_mfma_f32_16x16x32_bf16 v[46:49], v[180:183], v[188:191], v[46:49]
	v_mfma_f32_16x16x32_bf16 v[38:41], v[172:175], v[196:199], v[38:41]
	v_mfma_f32_16x16x32_bf16 v[30:33], v[180:183], v[196:199], v[30:33]
	v_mfma_f32_16x16x32_bf16 v[22:25], v[172:175], v[204:207], v[22:25]
	v_mfma_f32_16x16x32_bf16 v[14:17], v[180:183], v[204:207], v[14:17]
	v_mfma_f32_16x16x32_bf16 v[6:9], v[172:175], v[212:215], v[6:9]
	v_mfma_f32_16x16x32_bf16 v[2:5], v[180:183], v[212:215], v[2:5]
	v_mfma_f32_16x16x32_bf16 v[54:57], v[176:179], v[192:195], v[54:57]
	v_mfma_f32_16x16x32_bf16 v[46:49], v[184:187], v[192:195], v[46:49]
	v_mfma_f32_16x16x32_bf16 v[38:41], v[176:179], v[200:203], v[38:41]
	v_mfma_f32_16x16x32_bf16 v[30:33], v[184:187], v[200:203], v[30:33]
	v_mfma_f32_16x16x32_bf16 v[22:25], v[176:179], v[208:211], v[22:25]
	v_mfma_f32_16x16x32_bf16 v[14:17], v[184:187], v[208:211], v[14:17]
	v_mfma_f32_16x16x32_bf16 v[6:9], v[176:179], v[218:221], v[6:9]
	s_barrier
	v_mfma_f32_16x16x32_bf16 v[2:5], v[184:187], v[218:221], v[2:5]
	s_setprio 0
	s_add_i32 s53, 0, 0x18000
	v_add_u32_e32 v156, s53, v153
	s_add_i32 s62, 0, 0x1c000
	ds_read_b128 v[146:149], v156
	ds_read_b128 v[160:163], v156 offset:1024
	ds_read_b128 v[164:167], v156 offset:2048
	ds_read_b128 v[168:171], v156 offset:3072
	v_add_u32_e32 v156, s62, v153
	ds_read_b128 v[172:175], v156
	ds_read_b128 v[176:179], v156 offset:1024
	ds_read_b128 v[180:183], v156 offset:2048
	ds_read_b128 v[184:187], v156 offset:3072
	s_add_u32 s54, s86, 0x20000
	s_addc_u32 s55, s87, 0
	s_mov_b32 m0, s57
	v_lshl_add_u64 v[228:229], s[54:55], 0, v[130:131]
	ds_read_b128 v[188:191], v155 offset:32768
	ds_read_b128 v[192:195], v155 offset:33792
	ds_read_b128 v[196:199], v155 offset:34816
	ds_read_b128 v[200:203], v155 offset:35840
	ds_read_b128 v[204:207], v155 offset:36864
	ds_read_b128 v[208:211], v155 offset:37888
	ds_read_b128 v[212:215], v155 offset:38912
	ds_read_b128 v[218:221], v155 offset:39936
	global_load_lds_dwordx4 v[228:229], off
	v_lshl_add_u64 v[228:229], s[54:55], 0, v[134:135]
	s_mov_b32 m0, s58
	s_nop 0
	global_load_lds_dwordx4 v[228:229], off
	s_waitcnt vmcnt(8)
	s_waitcnt lgkmcnt(0)
	s_barrier
	s_setprio 1
	v_mfma_f32_16x16x32_bf16 v[126:129], v[146:149], v[188:191], v[126:129]
	v_mfma_f32_16x16x32_bf16 v[122:125], v[164:167], v[188:191], v[122:125]
	v_mfma_f32_16x16x32_bf16 v[110:113], v[146:149], v[196:199], v[110:113]
	v_mfma_f32_16x16x32_bf16 v[106:109], v[164:167], v[196:199], v[106:109]
	v_mfma_f32_16x16x32_bf16 v[94:97], v[146:149], v[204:207], v[94:97]
	v_mfma_f32_16x16x32_bf16 v[90:93], v[164:167], v[204:207], v[90:93]
	v_mfma_f32_16x16x32_bf16 v[78:81], v[146:149], v[212:215], v[78:81]
	v_mfma_f32_16x16x32_bf16 v[74:77], v[164:167], v[212:215], v[74:77]
	v_mfma_f32_16x16x32_bf16 v[126:129], v[160:163], v[192:195], v[126:129]
	v_mfma_f32_16x16x32_bf16 v[122:125], v[168:171], v[192:195], v[122:125]
	v_mfma_f32_16x16x32_bf16 v[110:113], v[160:163], v[200:203], v[110:113]
	v_mfma_f32_16x16x32_bf16 v[106:109], v[168:171], v[200:203], v[106:109]
	v_mfma_f32_16x16x32_bf16 v[94:97], v[160:163], v[208:211], v[94:97]
	v_mfma_f32_16x16x32_bf16 v[90:93], v[168:171], v[208:211], v[90:93]
	v_mfma_f32_16x16x32_bf16 v[78:81], v[160:163], v[218:221], v[78:81]
	v_mfma_f32_16x16x32_bf16 v[74:77], v[168:171], v[218:221], v[74:77]
	v_mfma_f32_16x16x32_bf16 v[118:121], v[172:175], v[188:191], v[118:121]
	v_mfma_f32_16x16x32_bf16 v[114:117], v[180:183], v[188:191], v[114:117]
	v_mfma_f32_16x16x32_bf16 v[102:105], v[172:175], v[196:199], v[102:105]
	v_mfma_f32_16x16x32_bf16 v[98:101], v[180:183], v[196:199], v[98:101]
	v_mfma_f32_16x16x32_bf16 v[86:89], v[172:175], v[204:207], v[86:89]
	v_mfma_f32_16x16x32_bf16 v[82:85], v[180:183], v[204:207], v[82:85]
	v_mfma_f32_16x16x32_bf16 v[70:73], v[172:175], v[212:215], v[70:73]
	v_mfma_f32_16x16x32_bf16 v[66:69], v[180:183], v[212:215], v[66:69]
	v_mfma_f32_16x16x32_bf16 v[118:121], v[176:179], v[192:195], v[118:121]
	v_mfma_f32_16x16x32_bf16 v[114:117], v[184:187], v[192:195], v[114:117]
	v_mfma_f32_16x16x32_bf16 v[102:105], v[176:179], v[200:203], v[102:105]
	v_mfma_f32_16x16x32_bf16 v[98:101], v[184:187], v[200:203], v[98:101]
	v_mfma_f32_16x16x32_bf16 v[86:89], v[176:179], v[208:211], v[86:89]
	v_mfma_f32_16x16x32_bf16 v[82:85], v[184:187], v[208:211], v[82:85]
	v_mfma_f32_16x16x32_bf16 v[70:73], v[176:179], v[218:221], v[70:73]
	s_barrier
	v_mfma_f32_16x16x32_bf16 v[66:69], v[184:187], v[218:221], v[66:69]
	s_setprio 0
	s_add_i32 s53, s53, s13
	v_lshl_add_u64 v[150:151], v[150:151], 0, s[8:9]
	s_mov_b32 m0, s53
	ds_read_b128 v[188:191], v155 offset:49152
	ds_read_b128 v[192:195], v155 offset:50176
	ds_read_b128 v[196:199], v155 offset:51200
	ds_read_b128 v[200:203], v155 offset:52224
	ds_read_b128 v[204:207], v155 offset:53248
	ds_read_b128 v[208:211], v155 offset:54272
	ds_read_b128 v[212:215], v155 offset:55296
	ds_read_b128 v[218:221], v155 offset:56320
	global_load_lds_dwordx4 v[150:151], off
	s_add_i32 m0, s53, 0x2000
	s_add_u32 s34, s34, 0x20080
	v_lshl_add_u64 v[150:151], v[222:223], 0, s[8:9]
	s_addc_u32 s35, s35, 0
	s_add_i32 s53, s62, s13
	global_load_lds_dwordx4 v[150:151], off
	v_lshl_add_u64 v[150:151], s[34:35], 0, v[132:133]
	s_mov_b32 m0, s53
	s_nop 0
	global_load_lds_dwordx4 v[150:151], off
	v_lshl_add_u64 v[150:151], s[34:35], 0, v[136:137]
	s_add_i32 m0, s53, 0x2000
	s_nop 0
	global_load_lds_dwordx4 v[150:151], off
	v_lshl_add_u64 v[150:151], v[224:225], 0, s[8:9]
	s_mov_b32 m0, s60
	s_nop 0
	global_load_lds_dwordx4 v[150:151], off
	v_lshl_add_u64 v[150:151], v[226:227], 0, s[8:9]
	s_mov_b32 m0, s61
	s_nop 0
	global_load_lds_dwordx4 v[150:151], off
	s_waitcnt vmcnt(8)
	s_waitcnt lgkmcnt(0)
	s_barrier
	s_setprio 1
	v_mfma_f32_16x16x32_bf16 v[62:65], v[146:149], v[188:191], v[62:65]
	v_mfma_f32_16x16x32_bf16 v[58:61], v[164:167], v[188:191], v[58:61]
	v_mfma_f32_16x16x32_bf16 v[50:53], v[146:149], v[196:199], v[50:53]
	v_mfma_f32_16x16x32_bf16 v[42:45], v[164:167], v[196:199], v[42:45]
	v_mfma_f32_16x16x32_bf16 v[34:37], v[146:149], v[204:207], v[34:37]
	v_mfma_f32_16x16x32_bf16 v[26:29], v[164:167], v[204:207], v[26:29]
	v_mfma_f32_16x16x32_bf16 v[18:21], v[146:149], v[212:215], v[18:21]
	v_mfma_f32_16x16x32_bf16 v[10:13], v[164:167], v[212:215], v[10:13]
	v_mfma_f32_16x16x32_bf16 v[62:65], v[160:163], v[192:195], v[62:65]
	v_mfma_f32_16x16x32_bf16 v[58:61], v[168:171], v[192:195], v[58:61]
	v_mfma_f32_16x16x32_bf16 v[50:53], v[160:163], v[200:203], v[50:53]
	v_mfma_f32_16x16x32_bf16 v[42:45], v[168:171], v[200:203], v[42:45]
	v_mfma_f32_16x16x32_bf16 v[34:37], v[160:163], v[208:211], v[34:37]
	v_mfma_f32_16x16x32_bf16 v[26:29], v[168:171], v[208:211], v[26:29]
	v_mfma_f32_16x16x32_bf16 v[18:21], v[160:163], v[218:221], v[18:21]
	v_mfma_f32_16x16x32_bf16 v[10:13], v[168:171], v[218:221], v[10:13]
	v_mfma_f32_16x16x32_bf16 v[54:57], v[172:175], v[188:191], v[54:57]
	v_mfma_f32_16x16x32_bf16 v[46:49], v[180:183], v[188:191], v[46:49]
	v_mfma_f32_16x16x32_bf16 v[38:41], v[172:175], v[196:199], v[38:41]
	v_mfma_f32_16x16x32_bf16 v[30:33], v[180:183], v[196:199], v[30:33]
	v_mfma_f32_16x16x32_bf16 v[22:25], v[172:175], v[204:207], v[22:25]
	v_mfma_f32_16x16x32_bf16 v[14:17], v[180:183], v[204:207], v[14:17]
	v_mfma_f32_16x16x32_bf16 v[6:9], v[172:175], v[212:215], v[6:9]
	v_mfma_f32_16x16x32_bf16 v[2:5], v[180:183], v[212:215], v[2:5]
	v_mfma_f32_16x16x32_bf16 v[54:57], v[176:179], v[192:195], v[54:57]
	v_mfma_f32_16x16x32_bf16 v[46:49], v[184:187], v[192:195], v[46:49]
	v_mfma_f32_16x16x32_bf16 v[38:41], v[176:179], v[200:203], v[38:41]
	v_mfma_f32_16x16x32_bf16 v[30:33], v[184:187], v[200:203], v[30:33]
	v_mfma_f32_16x16x32_bf16 v[22:25], v[176:179], v[208:211], v[22:25]
	v_mfma_f32_16x16x32_bf16 v[14:17], v[184:187], v[208:211], v[14:17]
	v_mfma_f32_16x16x32_bf16 v[6:9], v[176:179], v[218:221], v[6:9]
	s_barrier
	v_mfma_f32_16x16x32_bf16 v[2:5], v[184:187], v[218:221], v[2:5]
	s_setprio 0
	s_add_i32 s88, s88, 2
	s_add_u32 s84, s84, 0x100
	s_addc_u32 s85, s85, 0
	s_add_u32 s77, s77, 0x100
	s_addc_u32 s83, s83, 0
	s_cmp_gt_u32 s88, 5
	s_cbranch_scc0 .LBB0_715
	s_and_b64 vcc, exec, s[66:67]
	s_cbranch_vccz .LBB0_718
	s_barrier

.LBB0_995:
	ds_read_b128 v[146:149], v164
	ds_read_b128 v[150:153], v164 offset:1024
	ds_read_b128 v[154:157], v164 offset:2048
	ds_read_b128 v[158:161], v164 offset:3072
	ds_read_b128 v[168:171], v165
	ds_read_b128 v[172:175], v165 offset:1024
	ds_read_b128 v[176:179], v165 offset:2048
	ds_read_b128 v[180:183], v165 offset:3072
	s_add_u32 s34, s88, 0xfff80080
	s_addc_u32 s35, s89, -1
	s_cmp_eq_u32 s81, 28
	s_cselect_b32 s91, s0, s35
	s_cselect_b32 s90, s1, s34
	s_cselect_b32 s35, s52, s77
	s_cselect_b32 s34, s74, s75
	v_lshl_add_u64 v[218:219], s[88:89], 0, v[138:139]
	s_add_i32 m0, s33, 0xc000
	ds_read_b128 v[184:187], v166
	ds_read_b128 v[188:191], v166 offset:1024
	ds_read_b128 v[192:195], v166 offset:2048
	ds_read_b128 v[196:199], v166 offset:3072
	ds_read_b128 v[200:203], v166 offset:4096
	ds_read_b128 v[204:207], v166 offset:5120
	ds_read_b128 v[208:211], v166 offset:6144
	ds_read_b128 v[212:215], v166 offset:7168
	global_load_lds_dwordx4 v[218:219], off
	v_lshl_add_u64 v[218:219], s[88:89], 0, v[140:141]
	s_add_i32 m0, s33, 0xe000
	s_nop 0
	global_load_lds_dwordx4 v[218:219], off
	s_waitcnt vmcnt(8)
	s_waitcnt lgkmcnt(0)
	s_barrier
	s_setprio 1
	v_mfma_f32_16x16x32_bf16 v[126:129], v[146:149], v[184:187], v[126:129]
	v_mfma_f32_16x16x32_bf16 v[122:125], v[154:157], v[184:187], v[122:125]
	v_mfma_f32_16x16x32_bf16 v[110:113], v[146:149], v[192:195], v[110:113]
	v_mfma_f32_16x16x32_bf16 v[106:109], v[154:157], v[192:195], v[106:109]
	v_mfma_f32_16x16x32_bf16 v[94:97], v[146:149], v[200:203], v[94:97]
	v_mfma_f32_16x16x32_bf16 v[90:93], v[154:157], v[200:203], v[90:93]
	v_mfma_f32_16x16x32_bf16 v[78:81], v[146:149], v[208:211], v[78:81]
	v_mfma_f32_16x16x32_bf16 v[74:77], v[154:157], v[208:211], v[74:77]
	v_mfma_f32_16x16x32_bf16 v[126:129], v[150:153], v[188:191], v[126:129]
	v_mfma_f32_16x16x32_bf16 v[122:125], v[158:161], v[188:191], v[122:125]
	v_mfma_f32_16x16x32_bf16 v[110:113], v[150:153], v[196:199], v[110:113]
	v_mfma_f32_16x16x32_bf16 v[106:109], v[158:161], v[196:199], v[106:109]
	v_mfma_f32_16x16x32_bf16 v[94:97], v[150:153], v[204:207], v[94:97]
	v_mfma_f32_16x16x32_bf16 v[90:93], v[158:161], v[204:207], v[90:93]
	v_mfma_f32_16x16x32_bf16 v[78:81], v[150:153], v[212:215], v[78:81]
	v_mfma_f32_16x16x32_bf16 v[74:77], v[158:161], v[212:215], v[74:77]
	v_mfma_f32_16x16x32_bf16 v[118:121], v[168:171], v[184:187], v[118:121]
	v_mfma_f32_16x16x32_bf16 v[114:117], v[176:179], v[184:187], v[114:117]
	v_mfma_f32_16x16x32_bf16 v[102:105], v[168:171], v[192:195], v[102:105]
	v_mfma_f32_16x16x32_bf16 v[98:101], v[176:179], v[192:195], v[98:101]
	v_mfma_f32_16x16x32_bf16 v[86:89], v[168:171], v[200:203], v[86:89]
	v_mfma_f32_16x16x32_bf16 v[82:85], v[176:179], v[200:203], v[82:85]
	v_mfma_f32_16x16x32_bf16 v[70:73], v[168:171], v[208:211], v[70:73]
	v_mfma_f32_16x16x32_bf16 v[66:69], v[176:179], v[208:211], v[66:69]
	v_mfma_f32_16x16x32_bf16 v[118:121], v[172:175], v[188:191], v[118:121]
	v_mfma_f32_16x16x32_bf16 v[114:117], v[180:183], v[188:191], v[114:117]
	v_mfma_f32_16x16x32_bf16 v[102:105], v[172:175], v[196:199], v[102:105]
	v_mfma_f32_16x16x32_bf16 v[98:101], v[180:183], v[196:199], v[98:101]
	v_mfma_f32_16x16x32_bf16 v[86:89], v[172:175], v[204:207], v[86:89]
	v_mfma_f32_16x16x32_bf16 v[82:85], v[180:183], v[204:207], v[82:85]
	v_mfma_f32_16x16x32_bf16 v[70:73], v[172:175], v[212:215], v[70:73]
	s_barrier
	v_mfma_f32_16x16x32_bf16 v[66:69], v[180:183], v[212:215], v[66:69]
	s_setprio 0
	s_add_i32 s53, s71, s31
	v_lshl_add_u64 v[218:219], s[34:35], 0, v[132:133]
	s_mov_b32 m0, s53
	ds_read_b128 v[184:187], v166 offset:16384
	ds_read_b128 v[188:191], v166 offset:17408
	ds_read_b128 v[192:195], v166 offset:18432
	ds_read_b128 v[196:199], v166 offset:19456
	ds_read_b128 v[200:203], v166 offset:20480
	ds_read_b128 v[204:207], v166 offset:21504
	ds_read_b128 v[208:211], v166 offset:22528
	ds_read_b128 v[212:215], v166 offset:23552
	global_load_lds_dwordx4 v[218:219], off
	s_add_i32 m0, s53, 0x2000
	s_add_u32 s54, s34, 0x80000
	v_lshl_add_u64 v[220:221], s[34:35], 0, v[136:137]
	s_addc_u32 s55, s35, 0
	s_add_i32 s53, s72, s31
	global_load_lds_dwordx4 v[220:221], off
	v_lshl_add_u64 v[222:223], s[54:55], 0, v[132:133]
	s_mov_b32 m0, s53
	v_lshl_add_u64 v[224:225], s[90:91], 0, v[134:135]
	global_load_lds_dwordx4 v[222:223], off
	v_lshl_add_u64 v[222:223], s[54:55], 0, v[136:137]
	s_add_i32 m0, s53, 0x2000
	s_nop 0
	global_load_lds_dwordx4 v[222:223], off
	v_lshl_add_u64 v[222:223], s[90:91], 0, v[130:131]
	s_mov_b32 m0, s33
	s_nop 0
	global_load_lds_dwordx4 v[222:223], off
	s_mov_b32 m0, s56
	s_nop 0
	global_load_lds_dwordx4 v[224:225], off
	s_waitcnt vmcnt(8)
	s_waitcnt lgkmcnt(0)
	s_barrier
	s_setprio 1
	v_mfma_f32_16x16x32_bf16 v[62:65], v[146:149], v[184:187], v[62:65]
	v_mfma_f32_16x16x32_bf16 v[58:61], v[154:157], v[184:187], v[58:61]
	v_mfma_f32_16x16x32_bf16 v[46:49], v[146:149], v[192:195], v[46:49]
	v_mfma_f32_16x16x32_bf16 v[42:45], v[154:157], v[192:195], v[42:45]
	v_mfma_f32_16x16x32_bf16 v[30:33], v[146:149], v[200:203], v[30:33]
	v_mfma_f32_16x16x32_bf16 v[26:29], v[154:157], v[200:203], v[26:29]
	v_mfma_f32_16x16x32_bf16 v[14:17], v[146:149], v[208:211], v[14:17]
	v_mfma_f32_16x16x32_bf16 v[10:13], v[154:157], v[208:211], v[10:13]
	v_mfma_f32_16x16x32_bf16 v[62:65], v[150:153], v[188:191], v[62:65]
	v_mfma_f32_16x16x32_bf16 v[58:61], v[158:161], v[188:191], v[58:61]
	v_mfma_f32_16x16x32_bf16 v[46:49], v[150:153], v[196:199], v[46:49]
	v_mfma_f32_16x16x32_bf16 v[42:45], v[158:161], v[196:199], v[42:45]
	v_mfma_f32_16x16x32_bf16 v[30:33], v[150:153], v[204:207], v[30:33]
	v_mfma_f32_16x16x32_bf16 v[26:29], v[158:161], v[204:207], v[26:29]
	v_mfma_f32_16x16x32_bf16 v[14:17], v[150:153], v[212:215], v[14:17]
	v_mfma_f32_16x16x32_bf16 v[10:13], v[158:161], v[212:215], v[10:13]
	v_mfma_f32_16x16x32_bf16 v[54:57], v[168:171], v[184:187], v[54:57]
	v_mfma_f32_16x16x32_bf16 v[50:53], v[176:179], v[184:187], v[50:53]
	v_mfma_f32_16x16x32_bf16 v[38:41], v[168:171], v[192:195], v[38:41]
	v_mfma_f32_16x16x32_bf16 v[34:37], v[176:179], v[192:195], v[34:37]
	v_mfma_f32_16x16x32_bf16 v[22:25], v[168:171], v[200:203], v[22:25]
	v_mfma_f32_16x16x32_bf16 v[18:21], v[176:179], v[200:203], v[18:21]
	v_mfma_f32_16x16x32_bf16 v[6:9], v[168:171], v[208:211], v[6:9]
	v_mfma_f32_16x16x32_bf16 v[2:5], v[176:179], v[208:211], v[2:5]
	v_mfma_f32_16x16x32_bf16 v[54:57], v[172:175], v[188:191], v[54:57]
	v_mfma_f32_16x16x32_bf16 v[50:53], v[180:183], v[188:191], v[50:53]
	v_mfma_f32_16x16x32_bf16 v[38:41], v[172:175], v[196:199], v[38:41]
	v_mfma_f32_16x16x32_bf16 v[34:37], v[180:183], v[196:199], v[34:37]
	v_mfma_f32_16x16x32_bf16 v[22:25], v[172:175], v[204:207], v[22:25]
	v_mfma_f32_16x16x32_bf16 v[18:21], v[180:183], v[204:207], v[18:21]
	v_mfma_f32_16x16x32_bf16 v[6:9], v[172:175], v[212:215], v[6:9]
	s_barrier
	v_mfma_f32_16x16x32_bf16 v[2:5], v[180:183], v[212:215], v[2:5]
	s_setprio 0
	s_add_i32 s53, 0, 0x18000
	s_add_i32 s62, 0, 0x1c000
	v_add_u32_e32 v158, s53, v162
	v_add_u32_e32 v167, s62, v162
	ds_read_b128 v[146:149], v158
	ds_read_b128 v[150:153], v158 offset:1024
	ds_read_b128 v[154:157], v158 offset:2048
	ds_read_b128 v[158:161], v158 offset:3072
	ds_read_b128 v[168:171], v167
	ds_read_b128 v[172:175], v167 offset:1024
	ds_read_b128 v[176:179], v167 offset:2048
	ds_read_b128 v[180:183], v167 offset:3072
	s_add_u32 s54, s90, 0x80000
	s_addc_u32 s55, s91, 0
	s_mov_b32 m0, s57
	v_lshl_add_u64 v[226:227], s[54:55], 0, v[130:131]
	ds_read_b128 v[184:187], v166 offset:32768
	ds_read_b128 v[188:191], v166 offset:33792
	ds_read_b128 v[192:195], v166 offset:34816
	ds_read_b128 v[196:199], v166 offset:35840
	ds_read_b128 v[200:203], v166 offset:36864
	ds_read_b128 v[204:207], v166 offset:37888
	ds_read_b128 v[208:211], v166 offset:38912
	ds_read_b128 v[212:215], v166 offset:39936
	global_load_lds_dwordx4 v[226:227], off
	v_lshl_add_u64 v[226:227], s[54:55], 0, v[134:135]
	s_mov_b32 m0, s58
	s_nop 0
	global_load_lds_dwordx4 v[226:227], off
	s_waitcnt vmcnt(8)
	s_waitcnt lgkmcnt(0)
	s_barrier
	s_setprio 1
	v_mfma_f32_16x16x32_bf16 v[126:129], v[146:149], v[184:187], v[126:129]
	v_mfma_f32_16x16x32_bf16 v[122:125], v[154:157], v[184:187], v[122:125]
	v_mfma_f32_16x16x32_bf16 v[110:113], v[146:149], v[192:195], v[110:113]
	v_mfma_f32_16x16x32_bf16 v[106:109], v[154:157], v[192:195], v[106:109]
	v_mfma_f32_16x16x32_bf16 v[94:97], v[146:149], v[200:203], v[94:97]
	v_mfma_f32_16x16x32_bf16 v[90:93], v[154:157], v[200:203], v[90:93]
	v_mfma_f32_16x16x32_bf16 v[78:81], v[146:149], v[208:211], v[78:81]
	v_mfma_f32_16x16x32_bf16 v[74:77], v[154:157], v[208:211], v[74:77]
	v_mfma_f32_16x16x32_bf16 v[126:129], v[150:153], v[188:191], v[126:129]
	v_mfma_f32_16x16x32_bf16 v[122:125], v[158:161], v[188:191], v[122:125]
	v_mfma_f32_16x16x32_bf16 v[110:113], v[150:153], v[196:199], v[110:113]
	v_mfma_f32_16x16x32_bf16 v[106:109], v[158:161], v[196:199], v[106:109]
	v_mfma_f32_16x16x32_bf16 v[94:97], v[150:153], v[204:207], v[94:97]
	v_mfma_f32_16x16x32_bf16 v[90:93], v[158:161], v[204:207], v[90:93]
	v_mfma_f32_16x16x32_bf16 v[78:81], v[150:153], v[212:215], v[78:81]
	v_mfma_f32_16x16x32_bf16 v[74:77], v[158:161], v[212:215], v[74:77]
	v_mfma_f32_16x16x32_bf16 v[118:121], v[168:171], v[184:187], v[118:121]
	v_mfma_f32_16x16x32_bf16 v[114:117], v[176:179], v[184:187], v[114:117]
	v_mfma_f32_16x16x32_bf16 v[102:105], v[168:171], v[192:195], v[102:105]
	v_mfma_f32_16x16x32_bf16 v[98:101], v[176:179], v[192:195], v[98:101]
	v_mfma_f32_16x16x32_bf16 v[86:89], v[168:171], v[200:203], v[86:89]
	v_mfma_f32_16x16x32_bf16 v[82:85], v[176:179], v[200:203], v[82:85]
	v_mfma_f32_16x16x32_bf16 v[70:73], v[168:171], v[208:211], v[70:73]
	v_mfma_f32_16x16x32_bf16 v[66:69], v[176:179], v[208:211], v[66:69]
	v_mfma_f32_16x16x32_bf16 v[118:121], v[172:175], v[188:191], v[118:121]
	v_mfma_f32_16x16x32_bf16 v[114:117], v[180:183], v[188:191], v[114:117]
	v_mfma_f32_16x16x32_bf16 v[102:105], v[172:175], v[196:199], v[102:105]
	v_mfma_f32_16x16x32_bf16 v[98:101], v[180:183], v[196:199], v[98:101]
	v_mfma_f32_16x16x32_bf16 v[86:89], v[172:175], v[204:207], v[86:89]
	v_mfma_f32_16x16x32_bf16 v[82:85], v[180:183], v[204:207], v[82:85]
	v_mfma_f32_16x16x32_bf16 v[70:73], v[172:175], v[212:215], v[70:73]
	s_barrier
	v_mfma_f32_16x16x32_bf16 v[66:69], v[180:183], v[212:215], v[66:69]
	s_setprio 0
	s_add_i32 s53, s53, s31
	v_lshl_add_u64 v[218:219], v[218:219], 0, s[8:9]
	s_mov_b32 m0, s53
	ds_read_b128 v[184:187], v166 offset:49152
	ds_read_b128 v[188:191], v166 offset:50176
	ds_read_b128 v[192:195], v166 offset:51200
	ds_read_b128 v[196:199], v166 offset:52224
	ds_read_b128 v[200:203], v166 offset:53248
	ds_read_b128 v[204:207], v166 offset:54272
	ds_read_b128 v[208:211], v166 offset:55296
	ds_read_b128 v[212:215], v166 offset:56320
	global_load_lds_dwordx4 v[218:219], off
	s_add_i32 m0, s53, 0x2000
	s_add_u32 s34, s34, 0x80080
	v_lshl_add_u64 v[218:219], v[220:221], 0, s[8:9]
	s_addc_u32 s35, s35, 0
	s_add_i32 s53, s62, s31
	global_load_lds_dwordx4 v[218:219], off
	v_lshl_add_u64 v[218:219], s[34:35], 0, v[132:133]
	s_mov_b32 m0, s53
	s_nop 0
	global_load_lds_dwordx4 v[218:219], off
	v_lshl_add_u64 v[218:219], s[34:35], 0, v[136:137]
	s_add_i32 m0, s53, 0x2000
	s_nop 0
	global_load_lds_dwordx4 v[218:219], off
	v_lshl_add_u64 v[218:219], v[222:223], 0, s[8:9]
	s_mov_b32 m0, s60
	s_nop 0
	global_load_lds_dwordx4 v[218:219], off
	v_lshl_add_u64 v[218:219], v[224:225], 0, s[8:9]
	s_mov_b32 m0, s61
	s_nop 0
	global_load_lds_dwordx4 v[218:219], off
	s_waitcnt vmcnt(8)
	s_waitcnt lgkmcnt(0)
	s_barrier
	s_setprio 1
	v_mfma_f32_16x16x32_bf16 v[62:65], v[146:149], v[184:187], v[62:65]
	v_mfma_f32_16x16x32_bf16 v[58:61], v[154:157], v[184:187], v[58:61]
	v_mfma_f32_16x16x32_bf16 v[46:49], v[146:149], v[192:195], v[46:49]
	v_mfma_f32_16x16x32_bf16 v[42:45], v[154:157], v[192:195], v[42:45]
	v_mfma_f32_16x16x32_bf16 v[30:33], v[146:149], v[200:203], v[30:33]
	v_mfma_f32_16x16x32_bf16 v[26:29], v[154:157], v[200:203], v[26:29]
	v_mfma_f32_16x16x32_bf16 v[14:17], v[146:149], v[208:211], v[14:17]
	v_mfma_f32_16x16x32_bf16 v[10:13], v[154:157], v[208:211], v[10:13]
	v_mfma_f32_16x16x32_bf16 v[62:65], v[150:153], v[188:191], v[62:65]
	v_mfma_f32_16x16x32_bf16 v[58:61], v[158:161], v[188:191], v[58:61]
	v_mfma_f32_16x16x32_bf16 v[46:49], v[150:153], v[196:199], v[46:49]
	v_mfma_f32_16x16x32_bf16 v[42:45], v[158:161], v[196:199], v[42:45]
	v_mfma_f32_16x16x32_bf16 v[30:33], v[150:153], v[204:207], v[30:33]
	v_mfma_f32_16x16x32_bf16 v[26:29], v[158:161], v[204:207], v[26:29]
	v_mfma_f32_16x16x32_bf16 v[14:17], v[150:153], v[212:215], v[14:17]
	v_mfma_f32_16x16x32_bf16 v[10:13], v[158:161], v[212:215], v[10:13]
	v_mfma_f32_16x16x32_bf16 v[54:57], v[168:171], v[184:187], v[54:57]
	v_mfma_f32_16x16x32_bf16 v[50:53], v[176:179], v[184:187], v[50:53]
	v_mfma_f32_16x16x32_bf16 v[38:41], v[168:171], v[192:195], v[38:41]
	v_mfma_f32_16x16x32_bf16 v[34:37], v[176:179], v[192:195], v[34:37]
	v_mfma_f32_16x16x32_bf16 v[22:25], v[168:171], v[200:203], v[22:25]
	v_mfma_f32_16x16x32_bf16 v[18:21], v[176:179], v[200:203], v[18:21]
	v_mfma_f32_16x16x32_bf16 v[6:9], v[168:171], v[208:211], v[6:9]
	v_mfma_f32_16x16x32_bf16 v[2:5], v[176:179], v[208:211], v[2:5]
	v_mfma_f32_16x16x32_bf16 v[54:57], v[172:175], v[188:191], v[54:57]
	v_mfma_f32_16x16x32_bf16 v[50:53], v[180:183], v[188:191], v[50:53]
	v_mfma_f32_16x16x32_bf16 v[38:41], v[172:175], v[196:199], v[38:41]
	v_mfma_f32_16x16x32_bf16 v[34:37], v[180:183], v[196:199], v[34:37]
	v_mfma_f32_16x16x32_bf16 v[22:25], v[172:175], v[204:207], v[22:25]
	v_mfma_f32_16x16x32_bf16 v[18:21], v[180:183], v[204:207], v[18:21]
	v_mfma_f32_16x16x32_bf16 v[6:9], v[172:175], v[212:215], v[6:9]
	s_barrier
	v_mfma_f32_16x16x32_bf16 v[2:5], v[180:183], v[212:215], v[2:5]
	s_setprio 0
	s_add_i32 s81, s81, 2
	s_add_u32 s88, s88, 0x100
	s_addc_u32 s89, s89, 0
	s_add_u32 s75, s75, 0x100
	s_addc_u32 s77, s77, 0
	s_cmp_gt_u32 s81, 29
	s_cbranch_scc0 .LBB0_995
	s_and_b64 vcc, exec, s[78:79]
	s_cbranch_vccz .LBB0_998
	s_barrier

.LBB0_1124:
	ds_read_b128 v[146:149], v153
	ds_read_b128 v[156:159], v153 offset:1024
	ds_read_b128 v[160:163], v153 offset:2048
	ds_read_b128 v[164:167], v153 offset:3072
	ds_read_b128 v[168:171], v154
	ds_read_b128 v[172:175], v154 offset:1024
	ds_read_b128 v[176:179], v154 offset:2048
	ds_read_b128 v[180:183], v154 offset:3072
	s_add_u32 s34, s88, 0xfff80080
	s_addc_u32 s35, s89, -1
	s_cmp_eq_u32 s92, 28
	s_cselect_b32 s91, s0, s35
	s_cselect_b32 s90, s1, s34
	s_cselect_b32 s35, s52, s83
	s_cselect_b32 s34, s77, s81
	v_lshl_add_u64 v[218:219], s[88:89], 0, v[138:139]
	s_add_i32 m0, s56, 0xc000
	ds_read_b128 v[184:187], v155
	ds_read_b128 v[188:191], v155 offset:1024
	ds_read_b128 v[192:195], v155 offset:2048
	ds_read_b128 v[196:199], v155 offset:3072
	ds_read_b128 v[200:203], v155 offset:4096
	ds_read_b128 v[204:207], v155 offset:5120
	ds_read_b128 v[208:211], v155 offset:6144
	ds_read_b128 v[212:215], v155 offset:7168
	global_load_lds_dwordx4 v[218:219], off
	v_lshl_add_u64 v[218:219], s[88:89], 0, v[140:141]
	s_add_i32 m0, s56, 0xe000
	s_nop 0
	global_load_lds_dwordx4 v[218:219], off
	s_waitcnt vmcnt(8)
	s_waitcnt lgkmcnt(0)
	s_barrier
	s_setprio 1
	v_mfma_f32_16x16x32_bf16 v[126:129], v[146:149], v[184:187], v[126:129]
	v_mfma_f32_16x16x32_bf16 v[118:121], v[160:163], v[184:187], v[118:121]
	v_mfma_f32_16x16x32_bf16 v[110:113], v[146:149], v[192:195], v[110:113]
	v_mfma_f32_16x16x32_bf16 v[102:105], v[160:163], v[192:195], v[102:105]
	v_mfma_f32_16x16x32_bf16 v[94:97], v[146:149], v[200:203], v[94:97]
	v_mfma_f32_16x16x32_bf16 v[86:89], v[160:163], v[200:203], v[86:89]
	v_mfma_f32_16x16x32_bf16 v[78:81], v[146:149], v[208:211], v[78:81]
	v_mfma_f32_16x16x32_bf16 v[70:73], v[160:163], v[208:211], v[70:73]
	v_mfma_f32_16x16x32_bf16 v[126:129], v[156:159], v[188:191], v[126:129]
	v_mfma_f32_16x16x32_bf16 v[118:121], v[164:167], v[188:191], v[118:121]
	v_mfma_f32_16x16x32_bf16 v[110:113], v[156:159], v[196:199], v[110:113]
	v_mfma_f32_16x16x32_bf16 v[102:105], v[164:167], v[196:199], v[102:105]
	v_mfma_f32_16x16x32_bf16 v[94:97], v[156:159], v[204:207], v[94:97]
	v_mfma_f32_16x16x32_bf16 v[86:89], v[164:167], v[204:207], v[86:89]
	v_mfma_f32_16x16x32_bf16 v[78:81], v[156:159], v[212:215], v[78:81]
	v_mfma_f32_16x16x32_bf16 v[70:73], v[164:167], v[212:215], v[70:73]
	v_mfma_f32_16x16x32_bf16 v[122:125], v[168:171], v[184:187], v[122:125]
	v_mfma_f32_16x16x32_bf16 v[114:117], v[176:179], v[184:187], v[114:117]
	v_mfma_f32_16x16x32_bf16 v[106:109], v[168:171], v[192:195], v[106:109]
	v_mfma_f32_16x16x32_bf16 v[98:101], v[176:179], v[192:195], v[98:101]
	v_mfma_f32_16x16x32_bf16 v[90:93], v[168:171], v[200:203], v[90:93]
	v_mfma_f32_16x16x32_bf16 v[82:85], v[176:179], v[200:203], v[82:85]
	v_mfma_f32_16x16x32_bf16 v[74:77], v[168:171], v[208:211], v[74:77]
	v_mfma_f32_16x16x32_bf16 v[66:69], v[176:179], v[208:211], v[66:69]
	v_mfma_f32_16x16x32_bf16 v[122:125], v[172:175], v[188:191], v[122:125]
	v_mfma_f32_16x16x32_bf16 v[114:117], v[180:183], v[188:191], v[114:117]
	v_mfma_f32_16x16x32_bf16 v[106:109], v[172:175], v[196:199], v[106:109]
	v_mfma_f32_16x16x32_bf16 v[98:101], v[180:183], v[196:199], v[98:101]
	v_mfma_f32_16x16x32_bf16 v[90:93], v[172:175], v[204:207], v[90:93]
	v_mfma_f32_16x16x32_bf16 v[82:85], v[180:183], v[204:207], v[82:85]
	v_mfma_f32_16x16x32_bf16 v[74:77], v[172:175], v[212:215], v[74:77]
	s_barrier
	v_mfma_f32_16x16x32_bf16 v[66:69], v[180:183], v[212:215], v[66:69]
	s_setprio 0
	s_add_i32 s53, s72, s30
	v_lshl_add_u64 v[218:219], s[34:35], 0, v[134:135]
	s_mov_b32 m0, s53
	ds_read_b128 v[184:187], v155 offset:16384
	ds_read_b128 v[188:191], v155 offset:17408
	ds_read_b128 v[192:195], v155 offset:18432
	ds_read_b128 v[196:199], v155 offset:19456
	ds_read_b128 v[200:203], v155 offset:20480
	ds_read_b128 v[204:207], v155 offset:21504
	ds_read_b128 v[208:211], v155 offset:22528
	ds_read_b128 v[212:215], v155 offset:23552
	global_load_lds_dwordx4 v[218:219], off
	s_add_i32 m0, s53, 0x2000
	s_add_u32 s54, s34, 0x80000
	v_lshl_add_u64 v[220:221], s[34:35], 0, v[130:131]
	s_addc_u32 s55, s35, 0
	s_add_i32 s53, s73, s30
	global_load_lds_dwordx4 v[220:221], off
	v_lshl_add_u64 v[222:223], s[54:55], 0, v[134:135]
	s_mov_b32 m0, s53
	v_lshl_add_u64 v[224:225], s[90:91], 0, v[132:133]
	global_load_lds_dwordx4 v[222:223], off
	v_lshl_add_u64 v[222:223], s[54:55], 0, v[130:131]
	s_add_i32 m0, s53, 0x2000
	s_nop 0
	global_load_lds_dwordx4 v[222:223], off
	v_lshl_add_u64 v[222:223], s[90:91], 0, v[136:137]
	s_mov_b32 m0, s56
	s_nop 0
	global_load_lds_dwordx4 v[222:223], off
	s_mov_b32 m0, s57
	s_nop 0
	global_load_lds_dwordx4 v[224:225], off
	s_waitcnt vmcnt(8)
	s_waitcnt lgkmcnt(0)
	s_barrier
	s_setprio 1
	v_mfma_f32_16x16x32_bf16 v[62:65], v[146:149], v[184:187], v[62:65]
	v_mfma_f32_16x16x32_bf16 v[54:57], v[160:163], v[184:187], v[54:57]
	v_mfma_f32_16x16x32_bf16 v[46:49], v[146:149], v[192:195], v[46:49]
	v_mfma_f32_16x16x32_bf16 v[38:41], v[160:163], v[192:195], v[38:41]
	v_mfma_f32_16x16x32_bf16 v[30:33], v[146:149], v[200:203], v[30:33]
	v_mfma_f32_16x16x32_bf16 v[22:25], v[160:163], v[200:203], v[22:25]
	v_mfma_f32_16x16x32_bf16 v[14:17], v[146:149], v[208:211], v[14:17]
	v_mfma_f32_16x16x32_bf16 v[6:9], v[160:163], v[208:211], v[6:9]
	v_mfma_f32_16x16x32_bf16 v[62:65], v[156:159], v[188:191], v[62:65]
	v_mfma_f32_16x16x32_bf16 v[54:57], v[164:167], v[188:191], v[54:57]
	v_mfma_f32_16x16x32_bf16 v[46:49], v[156:159], v[196:199], v[46:49]
	v_mfma_f32_16x16x32_bf16 v[38:41], v[164:167], v[196:199], v[38:41]
	v_mfma_f32_16x16x32_bf16 v[30:33], v[156:159], v[204:207], v[30:33]
	v_mfma_f32_16x16x32_bf16 v[22:25], v[164:167], v[204:207], v[22:25]
	v_mfma_f32_16x16x32_bf16 v[14:17], v[156:159], v[212:215], v[14:17]
	v_mfma_f32_16x16x32_bf16 v[6:9], v[164:167], v[212:215], v[6:9]
	v_mfma_f32_16x16x32_bf16 v[58:61], v[168:171], v[184:187], v[58:61]
	v_mfma_f32_16x16x32_bf16 v[50:53], v[176:179], v[184:187], v[50:53]
	v_mfma_f32_16x16x32_bf16 v[42:45], v[168:171], v[192:195], v[42:45]
	v_mfma_f32_16x16x32_bf16 v[34:37], v[176:179], v[192:195], v[34:37]
	v_mfma_f32_16x16x32_bf16 v[26:29], v[168:171], v[200:203], v[26:29]
	v_mfma_f32_16x16x32_bf16 v[18:21], v[176:179], v[200:203], v[18:21]
	v_mfma_f32_16x16x32_bf16 v[10:13], v[168:171], v[208:211], v[10:13]
	v_mfma_f32_16x16x32_bf16 v[2:5], v[176:179], v[208:211], v[2:5]
	v_mfma_f32_16x16x32_bf16 v[58:61], v[172:175], v[188:191], v[58:61]
	v_mfma_f32_16x16x32_bf16 v[50:53], v[180:183], v[188:191], v[50:53]
	v_mfma_f32_16x16x32_bf16 v[42:45], v[172:175], v[196:199], v[42:45]
	v_mfma_f32_16x16x32_bf16 v[34:37], v[180:183], v[196:199], v[34:37]
	v_mfma_f32_16x16x32_bf16 v[26:29], v[172:175], v[204:207], v[26:29]
	v_mfma_f32_16x16x32_bf16 v[18:21], v[180:183], v[204:207], v[18:21]
	v_mfma_f32_16x16x32_bf16 v[10:13], v[172:175], v[212:215], v[10:13]
	s_barrier
	v_mfma_f32_16x16x32_bf16 v[2:5], v[180:183], v[212:215], v[2:5]
	s_setprio 0
	s_add_i32 s53, 0, 0x18000
	s_add_i32 s62, 0, 0x1c000
	v_add_u32_e32 v164, s53, v151
	v_add_u32_e32 v180, s62, v151
	ds_read_b128 v[146:149], v164
	ds_read_b128 v[156:159], v164 offset:1024
	ds_read_b128 v[160:163], v164 offset:2048
	ds_read_b128 v[164:167], v164 offset:3072
	ds_read_b128 v[168:171], v180
	ds_read_b128 v[172:175], v180 offset:1024
	ds_read_b128 v[176:179], v180 offset:2048
	ds_read_b128 v[180:183], v180 offset:3072
	s_add_u32 s54, s90, 0x80000
	s_addc_u32 s55, s91, 0
	s_mov_b32 m0, s58
	v_lshl_add_u64 v[226:227], s[54:55], 0, v[136:137]
	ds_read_b128 v[184:187], v155 offset:32768
	ds_read_b128 v[188:191], v155 offset:33792
	ds_read_b128 v[192:195], v155 offset:34816
	ds_read_b128 v[196:199], v155 offset:35840
	ds_read_b128 v[200:203], v155 offset:36864
	ds_read_b128 v[204:207], v155 offset:37888
	ds_read_b128 v[208:211], v155 offset:38912
	ds_read_b128 v[212:215], v155 offset:39936
	global_load_lds_dwordx4 v[226:227], off
	v_lshl_add_u64 v[226:227], s[54:55], 0, v[132:133]
	s_mov_b32 m0, s59
	s_nop 0
	global_load_lds_dwordx4 v[226:227], off
	s_waitcnt vmcnt(8)
	s_waitcnt lgkmcnt(0)
	s_barrier
	s_setprio 1
	v_mfma_f32_16x16x32_bf16 v[126:129], v[146:149], v[184:187], v[126:129]
	v_mfma_f32_16x16x32_bf16 v[118:121], v[160:163], v[184:187], v[118:121]
	v_mfma_f32_16x16x32_bf16 v[110:113], v[146:149], v[192:195], v[110:113]
	v_mfma_f32_16x16x32_bf16 v[102:105], v[160:163], v[192:195], v[102:105]
	v_mfma_f32_16x16x32_bf16 v[94:97], v[146:149], v[200:203], v[94:97]
	v_mfma_f32_16x16x32_bf16 v[86:89], v[160:163], v[200:203], v[86:89]
	v_mfma_f32_16x16x32_bf16 v[78:81], v[146:149], v[208:211], v[78:81]
	v_mfma_f32_16x16x32_bf16 v[70:73], v[160:163], v[208:211], v[70:73]
	v_mfma_f32_16x16x32_bf16 v[126:129], v[156:159], v[188:191], v[126:129]
	v_mfma_f32_16x16x32_bf16 v[118:121], v[164:167], v[188:191], v[118:121]
	v_mfma_f32_16x16x32_bf16 v[110:113], v[156:159], v[196:199], v[110:113]
	v_mfma_f32_16x16x32_bf16 v[102:105], v[164:167], v[196:199], v[102:105]
	v_mfma_f32_16x16x32_bf16 v[94:97], v[156:159], v[204:207], v[94:97]
	v_mfma_f32_16x16x32_bf16 v[86:89], v[164:167], v[204:207], v[86:89]
	v_mfma_f32_16x16x32_bf16 v[78:81], v[156:159], v[212:215], v[78:81]
	v_mfma_f32_16x16x32_bf16 v[70:73], v[164:167], v[212:215], v[70:73]
	v_mfma_f32_16x16x32_bf16 v[122:125], v[168:171], v[184:187], v[122:125]
	v_mfma_f32_16x16x32_bf16 v[114:117], v[176:179], v[184:187], v[114:117]
	v_mfma_f32_16x16x32_bf16 v[106:109], v[168:171], v[192:195], v[106:109]
	v_mfma_f32_16x16x32_bf16 v[98:101], v[176:179], v[192:195], v[98:101]
	v_mfma_f32_16x16x32_bf16 v[90:93], v[168:171], v[200:203], v[90:93]
	v_mfma_f32_16x16x32_bf16 v[82:85], v[176:179], v[200:203], v[82:85]
	v_mfma_f32_16x16x32_bf16 v[74:77], v[168:171], v[208:211], v[74:77]
	v_mfma_f32_16x16x32_bf16 v[66:69], v[176:179], v[208:211], v[66:69]
	v_mfma_f32_16x16x32_bf16 v[122:125], v[172:175], v[188:191], v[122:125]
	v_mfma_f32_16x16x32_bf16 v[114:117], v[180:183], v[188:191], v[114:117]
	v_mfma_f32_16x16x32_bf16 v[106:109], v[172:175], v[196:199], v[106:109]
	v_mfma_f32_16x16x32_bf16 v[98:101], v[180:183], v[196:199], v[98:101]
	v_mfma_f32_16x16x32_bf16 v[90:93], v[172:175], v[204:207], v[90:93]
	v_mfma_f32_16x16x32_bf16 v[82:85], v[180:183], v[204:207], v[82:85]
	v_mfma_f32_16x16x32_bf16 v[74:77], v[172:175], v[212:215], v[74:77]
	s_barrier
	v_mfma_f32_16x16x32_bf16 v[66:69], v[180:183], v[212:215], v[66:69]
	s_setprio 0
	s_add_i32 s53, s53, s30
	v_lshl_add_u64 v[218:219], v[218:219], 0, s[8:9]
	s_mov_b32 m0, s53
	ds_read_b128 v[184:187], v155 offset:49152
	ds_read_b128 v[188:191], v155 offset:50176
	ds_read_b128 v[192:195], v155 offset:51200
	ds_read_b128 v[196:199], v155 offset:52224
	ds_read_b128 v[200:203], v155 offset:53248
	ds_read_b128 v[204:207], v155 offset:54272
	ds_read_b128 v[208:211], v155 offset:55296
	ds_read_b128 v[212:215], v155 offset:56320
	global_load_lds_dwordx4 v[218:219], off
	s_add_i32 m0, s53, 0x2000
	s_add_u32 s34, s34, 0x80080
	v_lshl_add_u64 v[218:219], v[220:221], 0, s[8:9]
	s_addc_u32 s35, s35, 0
	s_add_i32 s53, s62, s30
	global_load_lds_dwordx4 v[218:219], off
	v_lshl_add_u64 v[218:219], s[34:35], 0, v[134:135]
	s_mov_b32 m0, s53
	s_nop 0
	global_load_lds_dwordx4 v[218:219], off
	v_lshl_add_u64 v[218:219], s[34:35], 0, v[130:131]
	s_add_i32 m0, s53, 0x2000
	s_nop 0
	global_load_lds_dwordx4 v[218:219], off
	v_lshl_add_u64 v[218:219], v[222:223], 0, s[8:9]
	s_mov_b32 m0, s61
	s_nop 0
	global_load_lds_dwordx4 v[218:219], off
	v_lshl_add_u64 v[218:219], v[224:225], 0, s[8:9]
	s_mov_b32 m0, s70
	s_nop 0
	global_load_lds_dwordx4 v[218:219], off
	s_waitcnt vmcnt(8)
	s_waitcnt lgkmcnt(0)
	s_barrier
	s_setprio 1
	v_mfma_f32_16x16x32_bf16 v[62:65], v[146:149], v[184:187], v[62:65]
	v_mfma_f32_16x16x32_bf16 v[54:57], v[160:163], v[184:187], v[54:57]
	v_mfma_f32_16x16x32_bf16 v[46:49], v[146:149], v[192:195], v[46:49]
	v_mfma_f32_16x16x32_bf16 v[38:41], v[160:163], v[192:195], v[38:41]
	v_mfma_f32_16x16x32_bf16 v[30:33], v[146:149], v[200:203], v[30:33]
	v_mfma_f32_16x16x32_bf16 v[22:25], v[160:163], v[200:203], v[22:25]
	v_mfma_f32_16x16x32_bf16 v[14:17], v[146:149], v[208:211], v[14:17]
	v_mfma_f32_16x16x32_bf16 v[6:9], v[160:163], v[208:211], v[6:9]
	v_mfma_f32_16x16x32_bf16 v[62:65], v[156:159], v[188:191], v[62:65]
	v_mfma_f32_16x16x32_bf16 v[54:57], v[164:167], v[188:191], v[54:57]
	v_mfma_f32_16x16x32_bf16 v[46:49], v[156:159], v[196:199], v[46:49]
	v_mfma_f32_16x16x32_bf16 v[38:41], v[164:167], v[196:199], v[38:41]
	v_mfma_f32_16x16x32_bf16 v[30:33], v[156:159], v[204:207], v[30:33]
	v_mfma_f32_16x16x32_bf16 v[22:25], v[164:167], v[204:207], v[22:25]
	v_mfma_f32_16x16x32_bf16 v[14:17], v[156:159], v[212:215], v[14:17]
	v_mfma_f32_16x16x32_bf16 v[6:9], v[164:167], v[212:215], v[6:9]
	v_mfma_f32_16x16x32_bf16 v[58:61], v[168:171], v[184:187], v[58:61]
	v_mfma_f32_16x16x32_bf16 v[50:53], v[176:179], v[184:187], v[50:53]
	v_mfma_f32_16x16x32_bf16 v[42:45], v[168:171], v[192:195], v[42:45]
	v_mfma_f32_16x16x32_bf16 v[34:37], v[176:179], v[192:195], v[34:37]
	v_mfma_f32_16x16x32_bf16 v[26:29], v[168:171], v[200:203], v[26:29]
	v_mfma_f32_16x16x32_bf16 v[18:21], v[176:179], v[200:203], v[18:21]
	v_mfma_f32_16x16x32_bf16 v[10:13], v[168:171], v[208:211], v[10:13]
	v_mfma_f32_16x16x32_bf16 v[2:5], v[176:179], v[208:211], v[2:5]
	v_mfma_f32_16x16x32_bf16 v[58:61], v[172:175], v[188:191], v[58:61]
	v_mfma_f32_16x16x32_bf16 v[50:53], v[180:183], v[188:191], v[50:53]
	v_mfma_f32_16x16x32_bf16 v[42:45], v[172:175], v[196:199], v[42:45]
	v_mfma_f32_16x16x32_bf16 v[34:37], v[180:183], v[196:199], v[34:37]
	v_mfma_f32_16x16x32_bf16 v[26:29], v[172:175], v[204:207], v[26:29]
	v_mfma_f32_16x16x32_bf16 v[18:21], v[180:183], v[204:207], v[18:21]
	v_mfma_f32_16x16x32_bf16 v[10:13], v[172:175], v[212:215], v[10:13]
	s_barrier
	v_mfma_f32_16x16x32_bf16 v[2:5], v[180:183], v[212:215], v[2:5]
	s_setprio 0
	s_add_i32 s92, s92, 2
	s_add_u32 s88, s88, 0x100
	s_addc_u32 s89, s89, 0
	s_add_u32 s81, s81, 0x100
	s_addc_u32 s83, s83, 0
	s_cmp_gt_u32 s92, 29
	s_cbranch_scc0 .LBB0_1124
	s_and_b64 vcc, exec, s[78:79]
	s_cbranch_vccz .LBB0_1127
	s_barrier

.LBB0_1237:
	ds_read_b128 v[146:149], v164
	ds_read_b128 v[150:153], v164 offset:1024
	ds_read_b128 v[154:157], v164 offset:2048
	ds_read_b128 v[158:161], v164 offset:3072
	ds_read_b128 v[168:171], v165
	ds_read_b128 v[172:175], v165 offset:1024
	ds_read_b128 v[176:179], v165 offset:2048
	ds_read_b128 v[180:183], v165 offset:3072
	s_add_u32 s34, s76, 0xffea0080
	s_addc_u32 s35, s77, -1
	s_cmpk_eq_i32 s52, 0x54
	s_cselect_b32 s85, s5, s35
	s_cselect_b32 s84, s4, s34
	s_cselect_b32 s35, s83, s1
	s_cselect_b32 s34, s82, s0
	v_lshl_add_u64 v[218:219], s[76:77], 0, v[138:139]
	s_add_i32 m0, s33, 0xc000
	ds_read_b128 v[184:187], v166
	ds_read_b128 v[188:191], v166 offset:1024
	ds_read_b128 v[192:195], v166 offset:2048
	ds_read_b128 v[196:199], v166 offset:3072
	ds_read_b128 v[200:203], v166 offset:4096
	ds_read_b128 v[204:207], v166 offset:5120
	ds_read_b128 v[208:211], v166 offset:6144
	ds_read_b128 v[212:215], v166 offset:7168
	global_load_lds_dwordx4 v[218:219], off
	v_lshl_add_u64 v[218:219], s[76:77], 0, v[140:141]
	s_add_i32 m0, s33, 0xe000
	s_nop 0
	global_load_lds_dwordx4 v[218:219], off
	s_waitcnt vmcnt(8)
	s_waitcnt lgkmcnt(0)
	s_barrier
	s_setprio 1
	v_mfma_f32_16x16x32_bf16 v[126:129], v[146:149], v[184:187], v[126:129]
	v_mfma_f32_16x16x32_bf16 v[122:125], v[154:157], v[184:187], v[122:125]
	v_mfma_f32_16x16x32_bf16 v[110:113], v[146:149], v[192:195], v[110:113]
	v_mfma_f32_16x16x32_bf16 v[106:109], v[154:157], v[192:195], v[106:109]
	v_mfma_f32_16x16x32_bf16 v[94:97], v[146:149], v[200:203], v[94:97]
	v_mfma_f32_16x16x32_bf16 v[90:93], v[154:157], v[200:203], v[90:93]
	v_mfma_f32_16x16x32_bf16 v[78:81], v[146:149], v[208:211], v[78:81]
	v_mfma_f32_16x16x32_bf16 v[74:77], v[154:157], v[208:211], v[74:77]
	v_mfma_f32_16x16x32_bf16 v[126:129], v[150:153], v[188:191], v[126:129]
	v_mfma_f32_16x16x32_bf16 v[122:125], v[158:161], v[188:191], v[122:125]
	v_mfma_f32_16x16x32_bf16 v[110:113], v[150:153], v[196:199], v[110:113]
	v_mfma_f32_16x16x32_bf16 v[106:109], v[158:161], v[196:199], v[106:109]
	v_mfma_f32_16x16x32_bf16 v[94:97], v[150:153], v[204:207], v[94:97]
	v_mfma_f32_16x16x32_bf16 v[90:93], v[158:161], v[204:207], v[90:93]
	v_mfma_f32_16x16x32_bf16 v[78:81], v[150:153], v[212:215], v[78:81]
	v_mfma_f32_16x16x32_bf16 v[74:77], v[158:161], v[212:215], v[74:77]
	v_mfma_f32_16x16x32_bf16 v[118:121], v[168:171], v[184:187], v[118:121]
	v_mfma_f32_16x16x32_bf16 v[114:117], v[176:179], v[184:187], v[114:117]
	v_mfma_f32_16x16x32_bf16 v[102:105], v[168:171], v[192:195], v[102:105]
	v_mfma_f32_16x16x32_bf16 v[98:101], v[176:179], v[192:195], v[98:101]
	v_mfma_f32_16x16x32_bf16 v[86:89], v[168:171], v[200:203], v[86:89]
	v_mfma_f32_16x16x32_bf16 v[82:85], v[176:179], v[200:203], v[82:85]
	v_mfma_f32_16x16x32_bf16 v[70:73], v[168:171], v[208:211], v[70:73]
	v_mfma_f32_16x16x32_bf16 v[66:69], v[176:179], v[208:211], v[66:69]
	v_mfma_f32_16x16x32_bf16 v[118:121], v[172:175], v[188:191], v[118:121]
	v_mfma_f32_16x16x32_bf16 v[114:117], v[180:183], v[188:191], v[114:117]
	v_mfma_f32_16x16x32_bf16 v[102:105], v[172:175], v[196:199], v[102:105]
	v_mfma_f32_16x16x32_bf16 v[98:101], v[180:183], v[196:199], v[98:101]
	v_mfma_f32_16x16x32_bf16 v[86:89], v[172:175], v[204:207], v[86:89]
	v_mfma_f32_16x16x32_bf16 v[82:85], v[180:183], v[204:207], v[82:85]
	v_mfma_f32_16x16x32_bf16 v[70:73], v[172:175], v[212:215], v[70:73]
	s_barrier
	v_mfma_f32_16x16x32_bf16 v[66:69], v[180:183], v[212:215], v[66:69]
	s_setprio 0
	s_add_i32 s53, s71, s31
	v_lshl_add_u64 v[218:219], s[34:35], 0, v[132:133]
	s_mov_b32 m0, s53
	ds_read_b128 v[184:187], v166 offset:16384
	ds_read_b128 v[188:191], v166 offset:17408
	ds_read_b128 v[192:195], v166 offset:18432
	ds_read_b128 v[196:199], v166 offset:19456
	ds_read_b128 v[200:203], v166 offset:20480
	ds_read_b128 v[204:207], v166 offset:21504
	ds_read_b128 v[208:211], v166 offset:22528
	ds_read_b128 v[212:215], v166 offset:23552
	global_load_lds_dwordx4 v[218:219], off
	s_add_i32 m0, s53, 0x2000
	s_add_u32 s54, s34, 0x160000
	v_lshl_add_u64 v[220:221], s[34:35], 0, v[136:137]
	s_addc_u32 s55, s35, 0
	s_add_i32 s53, s72, s31
	global_load_lds_dwordx4 v[220:221], off
	v_lshl_add_u64 v[222:223], s[54:55], 0, v[132:133]
	s_mov_b32 m0, s53
	v_lshl_add_u64 v[224:225], s[84:85], 0, v[134:135]
	global_load_lds_dwordx4 v[222:223], off
	v_lshl_add_u64 v[222:223], s[54:55], 0, v[136:137]
	s_add_i32 m0, s53, 0x2000
	s_nop 0
	global_load_lds_dwordx4 v[222:223], off
	v_lshl_add_u64 v[222:223], s[84:85], 0, v[130:131]
	s_mov_b32 m0, s33
	s_nop 0
	global_load_lds_dwordx4 v[222:223], off
	s_mov_b32 m0, s56
	s_nop 0
	global_load_lds_dwordx4 v[224:225], off
	s_waitcnt vmcnt(8)
	s_waitcnt lgkmcnt(0)
	s_barrier
	s_setprio 1
	v_mfma_f32_16x16x32_bf16 v[62:65], v[146:149], v[184:187], v[62:65]
	v_mfma_f32_16x16x32_bf16 v[58:61], v[154:157], v[184:187], v[58:61]
	v_mfma_f32_16x16x32_bf16 v[46:49], v[146:149], v[192:195], v[46:49]
	v_mfma_f32_16x16x32_bf16 v[42:45], v[154:157], v[192:195], v[42:45]
	v_mfma_f32_16x16x32_bf16 v[30:33], v[146:149], v[200:203], v[30:33]
	v_mfma_f32_16x16x32_bf16 v[26:29], v[154:157], v[200:203], v[26:29]
	v_mfma_f32_16x16x32_bf16 v[14:17], v[146:149], v[208:211], v[14:17]
	v_mfma_f32_16x16x32_bf16 v[10:13], v[154:157], v[208:211], v[10:13]
	v_mfma_f32_16x16x32_bf16 v[62:65], v[150:153], v[188:191], v[62:65]
	v_mfma_f32_16x16x32_bf16 v[58:61], v[158:161], v[188:191], v[58:61]
	v_mfma_f32_16x16x32_bf16 v[46:49], v[150:153], v[196:199], v[46:49]
	v_mfma_f32_16x16x32_bf16 v[42:45], v[158:161], v[196:199], v[42:45]
	v_mfma_f32_16x16x32_bf16 v[30:33], v[150:153], v[204:207], v[30:33]
	v_mfma_f32_16x16x32_bf16 v[26:29], v[158:161], v[204:207], v[26:29]
	v_mfma_f32_16x16x32_bf16 v[14:17], v[150:153], v[212:215], v[14:17]
	v_mfma_f32_16x16x32_bf16 v[10:13], v[158:161], v[212:215], v[10:13]
	v_mfma_f32_16x16x32_bf16 v[54:57], v[168:171], v[184:187], v[54:57]
	v_mfma_f32_16x16x32_bf16 v[50:53], v[176:179], v[184:187], v[50:53]
	v_mfma_f32_16x16x32_bf16 v[38:41], v[168:171], v[192:195], v[38:41]
	v_mfma_f32_16x16x32_bf16 v[34:37], v[176:179], v[192:195], v[34:37]
	v_mfma_f32_16x16x32_bf16 v[22:25], v[168:171], v[200:203], v[22:25]
	v_mfma_f32_16x16x32_bf16 v[18:21], v[176:179], v[200:203], v[18:21]
	v_mfma_f32_16x16x32_bf16 v[6:9], v[168:171], v[208:211], v[6:9]
	v_mfma_f32_16x16x32_bf16 v[2:5], v[176:179], v[208:211], v[2:5]
	v_mfma_f32_16x16x32_bf16 v[54:57], v[172:175], v[188:191], v[54:57]
	v_mfma_f32_16x16x32_bf16 v[50:53], v[180:183], v[188:191], v[50:53]
	v_mfma_f32_16x16x32_bf16 v[38:41], v[172:175], v[196:199], v[38:41]
	v_mfma_f32_16x16x32_bf16 v[34:37], v[180:183], v[196:199], v[34:37]
	v_mfma_f32_16x16x32_bf16 v[22:25], v[172:175], v[204:207], v[22:25]
	v_mfma_f32_16x16x32_bf16 v[18:21], v[180:183], v[204:207], v[18:21]
	v_mfma_f32_16x16x32_bf16 v[6:9], v[172:175], v[212:215], v[6:9]
	s_barrier
	v_mfma_f32_16x16x32_bf16 v[2:5], v[180:183], v[212:215], v[2:5]
	s_setprio 0
	s_add_i32 s53, 0, 0x18000
	s_add_i32 s62, 0, 0x1c000
	v_add_u32_e32 v158, s53, v162
	v_add_u32_e32 v167, s62, v162
	ds_read_b128 v[146:149], v158
	ds_read_b128 v[150:153], v158 offset:1024
	ds_read_b128 v[154:157], v158 offset:2048
	ds_read_b128 v[158:161], v158 offset:3072
	ds_read_b128 v[168:171], v167
	ds_read_b128 v[172:175], v167 offset:1024
	ds_read_b128 v[176:179], v167 offset:2048
	ds_read_b128 v[180:183], v167 offset:3072
	s_add_u32 s54, s84, 0x160000
	s_addc_u32 s55, s85, 0
	s_mov_b32 m0, s57
	v_lshl_add_u64 v[226:227], s[54:55], 0, v[130:131]
	ds_read_b128 v[184:187], v166 offset:32768
	ds_read_b128 v[188:191], v166 offset:33792
	ds_read_b128 v[192:195], v166 offset:34816
	ds_read_b128 v[196:199], v166 offset:35840
	ds_read_b128 v[200:203], v166 offset:36864
	ds_read_b128 v[204:207], v166 offset:37888
	ds_read_b128 v[208:211], v166 offset:38912
	ds_read_b128 v[212:215], v166 offset:39936
	global_load_lds_dwordx4 v[226:227], off
	v_lshl_add_u64 v[226:227], s[54:55], 0, v[134:135]
	s_mov_b32 m0, s58
	s_nop 0
	global_load_lds_dwordx4 v[226:227], off
	s_waitcnt vmcnt(8)
	s_waitcnt lgkmcnt(0)
	s_barrier
	s_setprio 1
	v_mfma_f32_16x16x32_bf16 v[126:129], v[146:149], v[184:187], v[126:129]
	v_mfma_f32_16x16x32_bf16 v[122:125], v[154:157], v[184:187], v[122:125]
	v_mfma_f32_16x16x32_bf16 v[110:113], v[146:149], v[192:195], v[110:113]
	v_mfma_f32_16x16x32_bf16 v[106:109], v[154:157], v[192:195], v[106:109]
	v_mfma_f32_16x16x32_bf16 v[94:97], v[146:149], v[200:203], v[94:97]
	v_mfma_f32_16x16x32_bf16 v[90:93], v[154:157], v[200:203], v[90:93]
	v_mfma_f32_16x16x32_bf16 v[78:81], v[146:149], v[208:211], v[78:81]
	v_mfma_f32_16x16x32_bf16 v[74:77], v[154:157], v[208:211], v[74:77]
	v_mfma_f32_16x16x32_bf16 v[126:129], v[150:153], v[188:191], v[126:129]
	v_mfma_f32_16x16x32_bf16 v[122:125], v[158:161], v[188:191], v[122:125]
	v_mfma_f32_16x16x32_bf16 v[110:113], v[150:153], v[196:199], v[110:113]
	v_mfma_f32_16x16x32_bf16 v[106:109], v[158:161], v[196:199], v[106:109]
	v_mfma_f32_16x16x32_bf16 v[94:97], v[150:153], v[204:207], v[94:97]
	v_mfma_f32_16x16x32_bf16 v[90:93], v[158:161], v[204:207], v[90:93]
	v_mfma_f32_16x16x32_bf16 v[78:81], v[150:153], v[212:215], v[78:81]
	v_mfma_f32_16x16x32_bf16 v[74:77], v[158:161], v[212:215], v[74:77]
	v_mfma_f32_16x16x32_bf16 v[118:121], v[168:171], v[184:187], v[118:121]
	v_mfma_f32_16x16x32_bf16 v[114:117], v[176:179], v[184:187], v[114:117]
	v_mfma_f32_16x16x32_bf16 v[102:105], v[168:171], v[192:195], v[102:105]
	v_mfma_f32_16x16x32_bf16 v[98:101], v[176:179], v[192:195], v[98:101]
	v_mfma_f32_16x16x32_bf16 v[86:89], v[168:171], v[200:203], v[86:89]
	v_mfma_f32_16x16x32_bf16 v[82:85], v[176:179], v[200:203], v[82:85]
	v_mfma_f32_16x16x32_bf16 v[70:73], v[168:171], v[208:211], v[70:73]
	v_mfma_f32_16x16x32_bf16 v[66:69], v[176:179], v[208:211], v[66:69]
	v_mfma_f32_16x16x32_bf16 v[118:121], v[172:175], v[188:191], v[118:121]
	v_mfma_f32_16x16x32_bf16 v[114:117], v[180:183], v[188:191], v[114:117]
	v_mfma_f32_16x16x32_bf16 v[102:105], v[172:175], v[196:199], v[102:105]
	v_mfma_f32_16x16x32_bf16 v[98:101], v[180:183], v[196:199], v[98:101]
	v_mfma_f32_16x16x32_bf16 v[86:89], v[172:175], v[204:207], v[86:89]
	v_mfma_f32_16x16x32_bf16 v[82:85], v[180:183], v[204:207], v[82:85]
	v_mfma_f32_16x16x32_bf16 v[70:73], v[172:175], v[212:215], v[70:73]
	s_barrier
	v_mfma_f32_16x16x32_bf16 v[66:69], v[180:183], v[212:215], v[66:69]
	s_setprio 0
	s_add_i32 s53, s53, s31
	v_lshl_add_u64 v[218:219], v[218:219], 0, s[78:79]
	s_mov_b32 m0, s53
	ds_read_b128 v[184:187], v166 offset:49152
	ds_read_b128 v[188:191], v166 offset:50176
	ds_read_b128 v[192:195], v166 offset:51200
	ds_read_b128 v[196:199], v166 offset:52224
	ds_read_b128 v[200:203], v166 offset:53248
	ds_read_b128 v[204:207], v166 offset:54272
	ds_read_b128 v[208:211], v166 offset:55296
	ds_read_b128 v[212:215], v166 offset:56320
	global_load_lds_dwordx4 v[218:219], off
	s_add_i32 m0, s53, 0x2000
	s_add_u32 s34, s34, 0x160080
	v_lshl_add_u64 v[218:219], v[220:221], 0, s[78:79]
	s_addc_u32 s35, s35, 0
	s_add_i32 s53, s62, s31
	global_load_lds_dwordx4 v[218:219], off
	v_lshl_add_u64 v[218:219], s[34:35], 0, v[132:133]
	s_mov_b32 m0, s53
	s_nop 0
	global_load_lds_dwordx4 v[218:219], off
	v_lshl_add_u64 v[218:219], s[34:35], 0, v[136:137]
	s_add_i32 m0, s53, 0x2000
	s_nop 0
	global_load_lds_dwordx4 v[218:219], off
	v_lshl_add_u64 v[218:219], v[222:223], 0, s[78:79]
	s_mov_b32 m0, s60
	s_nop 0
	global_load_lds_dwordx4 v[218:219], off
	v_lshl_add_u64 v[218:219], v[224:225], 0, s[78:79]
	s_mov_b32 m0, s61
	s_nop 0
	global_load_lds_dwordx4 v[218:219], off
	s_waitcnt vmcnt(8)
	s_waitcnt lgkmcnt(0)
	s_barrier
	s_setprio 1
	v_mfma_f32_16x16x32_bf16 v[62:65], v[146:149], v[184:187], v[62:65]
	v_mfma_f32_16x16x32_bf16 v[58:61], v[154:157], v[184:187], v[58:61]
	v_mfma_f32_16x16x32_bf16 v[46:49], v[146:149], v[192:195], v[46:49]
	v_mfma_f32_16x16x32_bf16 v[42:45], v[154:157], v[192:195], v[42:45]
	v_mfma_f32_16x16x32_bf16 v[30:33], v[146:149], v[200:203], v[30:33]
	v_mfma_f32_16x16x32_bf16 v[26:29], v[154:157], v[200:203], v[26:29]
	v_mfma_f32_16x16x32_bf16 v[14:17], v[146:149], v[208:211], v[14:17]
	v_mfma_f32_16x16x32_bf16 v[10:13], v[154:157], v[208:211], v[10:13]
	v_mfma_f32_16x16x32_bf16 v[62:65], v[150:153], v[188:191], v[62:65]
	v_mfma_f32_16x16x32_bf16 v[58:61], v[158:161], v[188:191], v[58:61]
	v_mfma_f32_16x16x32_bf16 v[46:49], v[150:153], v[196:199], v[46:49]
	v_mfma_f32_16x16x32_bf16 v[42:45], v[158:161], v[196:199], v[42:45]
	v_mfma_f32_16x16x32_bf16 v[30:33], v[150:153], v[204:207], v[30:33]
	v_mfma_f32_16x16x32_bf16 v[26:29], v[158:161], v[204:207], v[26:29]
	v_mfma_f32_16x16x32_bf16 v[14:17], v[150:153], v[212:215], v[14:17]
	v_mfma_f32_16x16x32_bf16 v[10:13], v[158:161], v[212:215], v[10:13]
	v_mfma_f32_16x16x32_bf16 v[54:57], v[168:171], v[184:187], v[54:57]
	v_mfma_f32_16x16x32_bf16 v[50:53], v[176:179], v[184:187], v[50:53]
	v_mfma_f32_16x16x32_bf16 v[38:41], v[168:171], v[192:195], v[38:41]
	v_mfma_f32_16x16x32_bf16 v[34:37], v[176:179], v[192:195], v[34:37]
	v_mfma_f32_16x16x32_bf16 v[22:25], v[168:171], v[200:203], v[22:25]
	v_mfma_f32_16x16x32_bf16 v[18:21], v[176:179], v[200:203], v[18:21]
	v_mfma_f32_16x16x32_bf16 v[6:9], v[168:171], v[208:211], v[6:9]
	v_mfma_f32_16x16x32_bf16 v[2:5], v[176:179], v[208:211], v[2:5]
	v_mfma_f32_16x16x32_bf16 v[54:57], v[172:175], v[188:191], v[54:57]
	v_mfma_f32_16x16x32_bf16 v[50:53], v[180:183], v[188:191], v[50:53]
	v_mfma_f32_16x16x32_bf16 v[38:41], v[172:175], v[196:199], v[38:41]
	v_mfma_f32_16x16x32_bf16 v[34:37], v[180:183], v[196:199], v[34:37]
	v_mfma_f32_16x16x32_bf16 v[22:25], v[172:175], v[204:207], v[22:25]
	v_mfma_f32_16x16x32_bf16 v[18:21], v[180:183], v[204:207], v[18:21]
	v_mfma_f32_16x16x32_bf16 v[6:9], v[172:175], v[212:215], v[6:9]
	s_barrier
	v_mfma_f32_16x16x32_bf16 v[2:5], v[180:183], v[212:215], v[2:5]
	s_setprio 0
	s_add_i32 s52, s52, 2
	s_add_u32 s76, s76, 0x100
	s_addc_u32 s77, s77, 0
	s_add_u32 s0, s0, 0x100
	s_addc_u32 s1, s1, 0
	s_cmpk_gt_u32 s52, 0x55
	s_cbranch_scc0 .LBB0_1237
	s_and_b64 vcc, exec, s[80:81]
	s_cbranch_vccz .LBB0_1240
	s_barrier

.LBB0_1624:
	ds_read_b128 v[154:157], v151
	ds_read_b128 v[158:161], v151 offset:1024
	ds_read_b128 v[162:165], v151 offset:2048
	ds_read_b128 v[166:169], v151 offset:3072
	ds_read_b128 v[170:173], v152
	ds_read_b128 v[174:177], v152 offset:1024
	ds_read_b128 v[178:181], v152 offset:2048
	ds_read_b128 v[182:185], v152 offset:3072
	s_add_u32 s34, s88, 0xfff80080
	s_addc_u32 s35, s89, -1
	s_cmp_eq_u32 s83, 28
	s_cselect_b32 s91, s0, s35
	s_cselect_b32 s90, s1, s34
	s_cselect_b32 s35, s52, s81
	s_cselect_b32 s34, s75, s77
	v_lshl_add_u64 v[146:147], s[88:89], 0, v[138:139]
	s_add_i32 m0, s33, 0xc000
	ds_read_b128 v[186:189], v153
	ds_read_b128 v[190:193], v153 offset:1024
	ds_read_b128 v[194:197], v153 offset:2048
	ds_read_b128 v[198:201], v153 offset:3072
	ds_read_b128 v[202:205], v153 offset:4096
	ds_read_b128 v[206:209], v153 offset:5120
	ds_read_b128 v[210:213], v153 offset:6144
	ds_read_b128 v[218:221], v153 offset:7168
	global_load_lds_dwordx4 v[146:147], off
	v_lshl_add_u64 v[146:147], s[88:89], 0, v[140:141]
	s_add_i32 m0, s33, 0xe000
	s_nop 0
	global_load_lds_dwordx4 v[146:147], off
	s_waitcnt vmcnt(8)
	s_waitcnt lgkmcnt(0)
	s_barrier
	s_setprio 1
	v_mfma_f32_16x16x32_bf16 v[126:129], v[154:157], v[186:189], v[126:129]
	v_mfma_f32_16x16x32_bf16 v[122:125], v[162:165], v[186:189], v[122:125]
	v_mfma_f32_16x16x32_bf16 v[114:117], v[154:157], v[194:197], v[114:117]
	v_mfma_f32_16x16x32_bf16 v[106:109], v[162:165], v[194:197], v[106:109]
	v_mfma_f32_16x16x32_bf16 v[98:101], v[154:157], v[202:205], v[98:101]
	v_mfma_f32_16x16x32_bf16 v[90:93], v[162:165], v[202:205], v[90:93]
	v_mfma_f32_16x16x32_bf16 v[82:85], v[154:157], v[210:213], v[82:85]
	v_mfma_f32_16x16x32_bf16 v[74:77], v[162:165], v[210:213], v[74:77]
	v_mfma_f32_16x16x32_bf16 v[126:129], v[158:161], v[190:193], v[126:129]
	v_mfma_f32_16x16x32_bf16 v[122:125], v[166:169], v[190:193], v[122:125]
	v_mfma_f32_16x16x32_bf16 v[114:117], v[158:161], v[198:201], v[114:117]
	v_mfma_f32_16x16x32_bf16 v[106:109], v[166:169], v[198:201], v[106:109]
	v_mfma_f32_16x16x32_bf16 v[98:101], v[158:161], v[206:209], v[98:101]
	v_mfma_f32_16x16x32_bf16 v[90:93], v[166:169], v[206:209], v[90:93]
	v_mfma_f32_16x16x32_bf16 v[82:85], v[158:161], v[218:221], v[82:85]
	v_mfma_f32_16x16x32_bf16 v[74:77], v[166:169], v[218:221], v[74:77]
	v_mfma_f32_16x16x32_bf16 v[118:121], v[170:173], v[186:189], v[118:121]
	v_mfma_f32_16x16x32_bf16 v[110:113], v[178:181], v[186:189], v[110:113]
	v_mfma_f32_16x16x32_bf16 v[102:105], v[170:173], v[194:197], v[102:105]
	v_mfma_f32_16x16x32_bf16 v[94:97], v[178:181], v[194:197], v[94:97]
	v_mfma_f32_16x16x32_bf16 v[86:89], v[170:173], v[202:205], v[86:89]
	v_mfma_f32_16x16x32_bf16 v[78:81], v[178:181], v[202:205], v[78:81]
	v_mfma_f32_16x16x32_bf16 v[70:73], v[170:173], v[210:213], v[70:73]
	v_mfma_f32_16x16x32_bf16 v[66:69], v[178:181], v[210:213], v[66:69]
	v_mfma_f32_16x16x32_bf16 v[118:121], v[174:177], v[190:193], v[118:121]
	v_mfma_f32_16x16x32_bf16 v[110:113], v[182:185], v[190:193], v[110:113]
	v_mfma_f32_16x16x32_bf16 v[102:105], v[174:177], v[198:201], v[102:105]
	v_mfma_f32_16x16x32_bf16 v[94:97], v[182:185], v[198:201], v[94:97]
	v_mfma_f32_16x16x32_bf16 v[86:89], v[174:177], v[206:209], v[86:89]
	v_mfma_f32_16x16x32_bf16 v[78:81], v[182:185], v[206:209], v[78:81]
	v_mfma_f32_16x16x32_bf16 v[70:73], v[174:177], v[218:221], v[70:73]
	s_barrier
	v_mfma_f32_16x16x32_bf16 v[66:69], v[182:185], v[218:221], v[66:69]
	s_setprio 0
	s_add_i32 s53, s71, s12
	v_lshl_add_u64 v[146:147], s[34:35], 0, v[134:135]
	s_mov_b32 m0, s53
	ds_read_b128 v[186:189], v153 offset:16384
	ds_read_b128 v[190:193], v153 offset:17408
	ds_read_b128 v[194:197], v153 offset:18432
	ds_read_b128 v[198:201], v153 offset:19456
	ds_read_b128 v[202:205], v153 offset:20480
	ds_read_b128 v[206:209], v153 offset:21504
	ds_read_b128 v[210:213], v153 offset:22528
	ds_read_b128 v[218:221], v153 offset:23552
	global_load_lds_dwordx4 v[146:147], off
	s_add_i32 m0, s53, 0x2000
	s_add_u32 s54, s34, 0x80000
	v_lshl_add_u64 v[214:215], s[34:35], 0, v[130:131]
	s_addc_u32 s55, s35, 0
	s_add_i32 s53, s72, s12
	global_load_lds_dwordx4 v[214:215], off
	v_lshl_add_u64 v[222:223], s[54:55], 0, v[134:135]
	s_mov_b32 m0, s53
	v_lshl_add_u64 v[224:225], s[90:91], 0, v[132:133]
	global_load_lds_dwordx4 v[222:223], off
	v_lshl_add_u64 v[222:223], s[54:55], 0, v[130:131]
	s_add_i32 m0, s53, 0x2000
	s_nop 0
	global_load_lds_dwordx4 v[222:223], off
	v_lshl_add_u64 v[222:223], s[90:91], 0, v[136:137]
	s_mov_b32 m0, s33
	s_nop 0
	global_load_lds_dwordx4 v[222:223], off
	s_mov_b32 m0, s56
	s_nop 0
	global_load_lds_dwordx4 v[224:225], off
	s_waitcnt vmcnt(8)
	s_waitcnt lgkmcnt(0)
	s_barrier
	s_setprio 1
	v_mfma_f32_16x16x32_bf16 v[62:65], v[154:157], v[186:189], v[62:65]
	v_mfma_f32_16x16x32_bf16 v[58:61], v[162:165], v[186:189], v[58:61]
	v_mfma_f32_16x16x32_bf16 v[50:53], v[154:157], v[194:197], v[50:53]
	v_mfma_f32_16x16x32_bf16 v[42:45], v[162:165], v[194:197], v[42:45]
	v_mfma_f32_16x16x32_bf16 v[34:37], v[154:157], v[202:205], v[34:37]
	v_mfma_f32_16x16x32_bf16 v[26:29], v[162:165], v[202:205], v[26:29]
	v_mfma_f32_16x16x32_bf16 v[18:21], v[154:157], v[210:213], v[18:21]
	v_mfma_f32_16x16x32_bf16 v[10:13], v[162:165], v[210:213], v[10:13]
	v_mfma_f32_16x16x32_bf16 v[62:65], v[158:161], v[190:193], v[62:65]
	v_mfma_f32_16x16x32_bf16 v[58:61], v[166:169], v[190:193], v[58:61]
	v_mfma_f32_16x16x32_bf16 v[50:53], v[158:161], v[198:201], v[50:53]
	v_mfma_f32_16x16x32_bf16 v[42:45], v[166:169], v[198:201], v[42:45]
	v_mfma_f32_16x16x32_bf16 v[34:37], v[158:161], v[206:209], v[34:37]
	v_mfma_f32_16x16x32_bf16 v[26:29], v[166:169], v[206:209], v[26:29]
	v_mfma_f32_16x16x32_bf16 v[18:21], v[158:161], v[218:221], v[18:21]
	v_mfma_f32_16x16x32_bf16 v[10:13], v[166:169], v[218:221], v[10:13]
	v_mfma_f32_16x16x32_bf16 v[54:57], v[170:173], v[186:189], v[54:57]
	v_mfma_f32_16x16x32_bf16 v[46:49], v[178:181], v[186:189], v[46:49]
	v_mfma_f32_16x16x32_bf16 v[38:41], v[170:173], v[194:197], v[38:41]
	v_mfma_f32_16x16x32_bf16 v[30:33], v[178:181], v[194:197], v[30:33]
	v_mfma_f32_16x16x32_bf16 v[22:25], v[170:173], v[202:205], v[22:25]
	v_mfma_f32_16x16x32_bf16 v[14:17], v[178:181], v[202:205], v[14:17]
	v_mfma_f32_16x16x32_bf16 v[6:9], v[170:173], v[210:213], v[6:9]
	v_mfma_f32_16x16x32_bf16 v[2:5], v[178:181], v[210:213], v[2:5]
	v_mfma_f32_16x16x32_bf16 v[54:57], v[174:177], v[190:193], v[54:57]
	v_mfma_f32_16x16x32_bf16 v[46:49], v[182:185], v[190:193], v[46:49]
	v_mfma_f32_16x16x32_bf16 v[38:41], v[174:177], v[198:201], v[38:41]
	v_mfma_f32_16x16x32_bf16 v[30:33], v[182:185], v[198:201], v[30:33]
	v_mfma_f32_16x16x32_bf16 v[22:25], v[174:177], v[206:209], v[22:25]
	v_mfma_f32_16x16x32_bf16 v[14:17], v[182:185], v[206:209], v[14:17]
	v_mfma_f32_16x16x32_bf16 v[6:9], v[174:177], v[218:221], v[6:9]
	s_barrier
	v_mfma_f32_16x16x32_bf16 v[2:5], v[182:185], v[218:221], v[2:5]
	s_setprio 0
	s_add_i32 s53, 0, 0x18000
	s_add_i32 s62, 0, 0x1c000
	v_add_u32_e32 v166, s53, v149
	v_add_u32_e32 v182, s62, v149
	ds_read_b128 v[154:157], v166
	ds_read_b128 v[158:161], v166 offset:1024
	ds_read_b128 v[162:165], v166 offset:2048
	ds_read_b128 v[166:169], v166 offset:3072
	ds_read_b128 v[170:173], v182
	ds_read_b128 v[174:177], v182 offset:1024
	ds_read_b128 v[178:181], v182 offset:2048
	ds_read_b128 v[182:185], v182 offset:3072
	s_add_u32 s54, s90, 0x80000
	s_addc_u32 s55, s91, 0
	s_mov_b32 m0, s57
	v_lshl_add_u64 v[226:227], s[54:55], 0, v[136:137]
	ds_read_b128 v[186:189], v153 offset:32768
	ds_read_b128 v[190:193], v153 offset:33792
	ds_read_b128 v[194:197], v153 offset:34816
	ds_read_b128 v[198:201], v153 offset:35840
	ds_read_b128 v[202:205], v153 offset:36864
	ds_read_b128 v[206:209], v153 offset:37888
	ds_read_b128 v[210:213], v153 offset:38912
	ds_read_b128 v[218:221], v153 offset:39936
	global_load_lds_dwordx4 v[226:227], off
	v_lshl_add_u64 v[226:227], s[54:55], 0, v[132:133]
	s_mov_b32 m0, s58
	s_nop 0
	global_load_lds_dwordx4 v[226:227], off
	s_waitcnt vmcnt(8)
	s_waitcnt lgkmcnt(0)
	s_barrier
	s_setprio 1
	v_mfma_f32_16x16x32_bf16 v[126:129], v[154:157], v[186:189], v[126:129]
	v_mfma_f32_16x16x32_bf16 v[122:125], v[162:165], v[186:189], v[122:125]
	v_mfma_f32_16x16x32_bf16 v[114:117], v[154:157], v[194:197], v[114:117]
	v_mfma_f32_16x16x32_bf16 v[106:109], v[162:165], v[194:197], v[106:109]
	v_mfma_f32_16x16x32_bf16 v[98:101], v[154:157], v[202:205], v[98:101]
	v_mfma_f32_16x16x32_bf16 v[90:93], v[162:165], v[202:205], v[90:93]
	v_mfma_f32_16x16x32_bf16 v[82:85], v[154:157], v[210:213], v[82:85]
	v_mfma_f32_16x16x32_bf16 v[74:77], v[162:165], v[210:213], v[74:77]
	v_mfma_f32_16x16x32_bf16 v[126:129], v[158:161], v[190:193], v[126:129]
	v_mfma_f32_16x16x32_bf16 v[122:125], v[166:169], v[190:193], v[122:125]
	v_mfma_f32_16x16x32_bf16 v[114:117], v[158:161], v[198:201], v[114:117]
	v_mfma_f32_16x16x32_bf16 v[106:109], v[166:169], v[198:201], v[106:109]
	v_mfma_f32_16x16x32_bf16 v[98:101], v[158:161], v[206:209], v[98:101]
	v_mfma_f32_16x16x32_bf16 v[90:93], v[166:169], v[206:209], v[90:93]
	v_mfma_f32_16x16x32_bf16 v[82:85], v[158:161], v[218:221], v[82:85]
	v_mfma_f32_16x16x32_bf16 v[74:77], v[166:169], v[218:221], v[74:77]
	v_mfma_f32_16x16x32_bf16 v[118:121], v[170:173], v[186:189], v[118:121]
	v_mfma_f32_16x16x32_bf16 v[110:113], v[178:181], v[186:189], v[110:113]
	v_mfma_f32_16x16x32_bf16 v[102:105], v[170:173], v[194:197], v[102:105]
	v_mfma_f32_16x16x32_bf16 v[94:97], v[178:181], v[194:197], v[94:97]
	v_mfma_f32_16x16x32_bf16 v[86:89], v[170:173], v[202:205], v[86:89]
	v_mfma_f32_16x16x32_bf16 v[78:81], v[178:181], v[202:205], v[78:81]
	v_mfma_f32_16x16x32_bf16 v[70:73], v[170:173], v[210:213], v[70:73]
	v_mfma_f32_16x16x32_bf16 v[66:69], v[178:181], v[210:213], v[66:69]
	v_mfma_f32_16x16x32_bf16 v[118:121], v[174:177], v[190:193], v[118:121]
	v_mfma_f32_16x16x32_bf16 v[110:113], v[182:185], v[190:193], v[110:113]
	v_mfma_f32_16x16x32_bf16 v[102:105], v[174:177], v[198:201], v[102:105]
	v_mfma_f32_16x16x32_bf16 v[94:97], v[182:185], v[198:201], v[94:97]
	v_mfma_f32_16x16x32_bf16 v[86:89], v[174:177], v[206:209], v[86:89]
	v_mfma_f32_16x16x32_bf16 v[78:81], v[182:185], v[206:209], v[78:81]
	v_mfma_f32_16x16x32_bf16 v[70:73], v[174:177], v[218:221], v[70:73]
	s_barrier
	v_mfma_f32_16x16x32_bf16 v[66:69], v[182:185], v[218:221], v[66:69]
	s_setprio 0
	s_add_i32 s53, s53, s12
	v_lshl_add_u64 v[146:147], v[146:147], 0, s[8:9]
	s_mov_b32 m0, s53
	ds_read_b128 v[186:189], v153 offset:49152
	ds_read_b128 v[190:193], v153 offset:50176
	ds_read_b128 v[194:197], v153 offset:51200
	ds_read_b128 v[198:201], v153 offset:52224
	ds_read_b128 v[202:205], v153 offset:53248
	ds_read_b128 v[206:209], v153 offset:54272
	ds_read_b128 v[210:213], v153 offset:55296
	ds_read_b128 v[218:221], v153 offset:56320
	global_load_lds_dwordx4 v[146:147], off
	s_add_i32 m0, s53, 0x2000
	s_add_u32 s34, s34, 0x80080
	v_lshl_add_u64 v[146:147], v[214:215], 0, s[8:9]
	s_addc_u32 s35, s35, 0
	s_add_i32 s53, s62, s12
	global_load_lds_dwordx4 v[146:147], off
	v_lshl_add_u64 v[146:147], s[34:35], 0, v[134:135]
	s_mov_b32 m0, s53
	s_nop 0
	global_load_lds_dwordx4 v[146:147], off
	v_lshl_add_u64 v[146:147], s[34:35], 0, v[130:131]
	s_add_i32 m0, s53, 0x2000
	s_nop 0
	global_load_lds_dwordx4 v[146:147], off
	v_lshl_add_u64 v[146:147], v[222:223], 0, s[8:9]
	s_mov_b32 m0, s60
	s_nop 0
	global_load_lds_dwordx4 v[146:147], off
	v_lshl_add_u64 v[146:147], v[224:225], 0, s[8:9]
	s_mov_b32 m0, s61
	s_nop 0
	global_load_lds_dwordx4 v[146:147], off
	s_waitcnt vmcnt(8)
	s_waitcnt lgkmcnt(0)
	s_barrier
	s_setprio 1
	v_mfma_f32_16x16x32_bf16 v[62:65], v[154:157], v[186:189], v[62:65]
	v_mfma_f32_16x16x32_bf16 v[58:61], v[162:165], v[186:189], v[58:61]
	v_mfma_f32_16x16x32_bf16 v[50:53], v[154:157], v[194:197], v[50:53]
	v_mfma_f32_16x16x32_bf16 v[42:45], v[162:165], v[194:197], v[42:45]
	v_mfma_f32_16x16x32_bf16 v[34:37], v[154:157], v[202:205], v[34:37]
	v_mfma_f32_16x16x32_bf16 v[26:29], v[162:165], v[202:205], v[26:29]
	v_mfma_f32_16x16x32_bf16 v[18:21], v[154:157], v[210:213], v[18:21]
	v_mfma_f32_16x16x32_bf16 v[10:13], v[162:165], v[210:213], v[10:13]
	v_mfma_f32_16x16x32_bf16 v[62:65], v[158:161], v[190:193], v[62:65]
	v_mfma_f32_16x16x32_bf16 v[58:61], v[166:169], v[190:193], v[58:61]
	v_mfma_f32_16x16x32_bf16 v[50:53], v[158:161], v[198:201], v[50:53]
	v_mfma_f32_16x16x32_bf16 v[42:45], v[166:169], v[198:201], v[42:45]
	v_mfma_f32_16x16x32_bf16 v[34:37], v[158:161], v[206:209], v[34:37]
	v_mfma_f32_16x16x32_bf16 v[26:29], v[166:169], v[206:209], v[26:29]
	v_mfma_f32_16x16x32_bf16 v[18:21], v[158:161], v[218:221], v[18:21]
	v_mfma_f32_16x16x32_bf16 v[10:13], v[166:169], v[218:221], v[10:13]
	v_mfma_f32_16x16x32_bf16 v[54:57], v[170:173], v[186:189], v[54:57]
	v_mfma_f32_16x16x32_bf16 v[46:49], v[178:181], v[186:189], v[46:49]
	v_mfma_f32_16x16x32_bf16 v[38:41], v[170:173], v[194:197], v[38:41]
	v_mfma_f32_16x16x32_bf16 v[30:33], v[178:181], v[194:197], v[30:33]
	v_mfma_f32_16x16x32_bf16 v[22:25], v[170:173], v[202:205], v[22:25]
	v_mfma_f32_16x16x32_bf16 v[14:17], v[178:181], v[202:205], v[14:17]
	v_mfma_f32_16x16x32_bf16 v[6:9], v[170:173], v[210:213], v[6:9]
	v_mfma_f32_16x16x32_bf16 v[2:5], v[178:181], v[210:213], v[2:5]
	v_mfma_f32_16x16x32_bf16 v[54:57], v[174:177], v[190:193], v[54:57]
	v_mfma_f32_16x16x32_bf16 v[46:49], v[182:185], v[190:193], v[46:49]
	v_mfma_f32_16x16x32_bf16 v[38:41], v[174:177], v[198:201], v[38:41]
	v_mfma_f32_16x16x32_bf16 v[30:33], v[182:185], v[198:201], v[30:33]
	v_mfma_f32_16x16x32_bf16 v[22:25], v[174:177], v[206:209], v[22:25]
	v_mfma_f32_16x16x32_bf16 v[14:17], v[182:185], v[206:209], v[14:17]
	v_mfma_f32_16x16x32_bf16 v[6:9], v[174:177], v[218:221], v[6:9]
	s_barrier
	v_mfma_f32_16x16x32_bf16 v[2:5], v[182:185], v[218:221], v[2:5]
	s_setprio 0
	s_add_i32 s83, s83, 2
	s_add_u32 s88, s88, 0x100
	s_addc_u32 s89, s89, 0
	s_add_u32 s77, s77, 0x100
	s_addc_u32 s81, s81, 0
	s_cmp_gt_u32 s83, 29
	s_cbranch_scc0 .LBB0_1624
	s_and_b64 vcc, exec, s[78:79]
	s_cbranch_vccz .LBB0_1627
	s_barrier

.LBB0_2089:
	ds_read_b128 v[130:133], v178
	ds_read_b128 v[134:137], v178 offset:1024
	ds_read_b128 v[138:141], v178 offset:2048
	ds_read_b128 v[142:145], v178 offset:3072
	ds_read_b128 v[162:165], v179
	ds_read_b128 v[166:169], v179 offset:1024
	ds_read_b128 v[170:173], v179 offset:2048
	ds_read_b128 v[182:185], v179 offset:3072
	s_add_u32 s34, s38, 0xffea0080
	s_addc_u32 s35, s39, -1
	s_cmpk_eq_i32 s52, 0x54
	s_cselect_b32 s41, s5, s35
	s_cselect_b32 s40, s4, s34
	s_cselect_b32 s35, s37, s1
	s_cselect_b32 s34, s36, s0
	v_lshl_add_u64 v[174:175], s[38:39], 0, v[154:155]
	s_add_i32 m0, s33, 0xc000
	ds_read_b128 v[186:189], v180
	ds_read_b128 v[190:193], v180 offset:1024
	ds_read_b128 v[194:197], v180 offset:2048
	ds_read_b128 v[198:201], v180 offset:3072
	ds_read_b128 v[202:205], v180 offset:4096
	ds_read_b128 v[206:209], v180 offset:5120
	ds_read_b128 v[210:213], v180 offset:6144
	ds_read_b128 v[218:221], v180 offset:7168
	global_load_lds_dwordx4 v[174:175], off
	v_lshl_add_u64 v[174:175], s[38:39], 0, v[156:157]
	s_add_i32 m0, s33, 0xe000
	s_nop 0
	global_load_lds_dwordx4 v[174:175], off
	s_waitcnt vmcnt(8)
	s_waitcnt lgkmcnt(0)
	s_barrier
	s_setprio 1
	v_mfma_f32_16x16x32_bf16 v[126:129], v[130:133], v[186:189], v[126:129]
	v_mfma_f32_16x16x32_bf16 v[122:125], v[138:141], v[186:189], v[122:125]
	v_mfma_f32_16x16x32_bf16 v[110:113], v[130:133], v[194:197], v[110:113]
	v_mfma_f32_16x16x32_bf16 v[106:109], v[138:141], v[194:197], v[106:109]
	v_mfma_f32_16x16x32_bf16 v[94:97], v[130:133], v[202:205], v[94:97]
	v_mfma_f32_16x16x32_bf16 v[90:93], v[138:141], v[202:205], v[90:93]
	v_mfma_f32_16x16x32_bf16 v[78:81], v[130:133], v[210:213], v[78:81]
	v_mfma_f32_16x16x32_bf16 v[74:77], v[138:141], v[210:213], v[74:77]
	v_mfma_f32_16x16x32_bf16 v[126:129], v[134:137], v[190:193], v[126:129]
	v_mfma_f32_16x16x32_bf16 v[122:125], v[142:145], v[190:193], v[122:125]
	v_mfma_f32_16x16x32_bf16 v[110:113], v[134:137], v[198:201], v[110:113]
	v_mfma_f32_16x16x32_bf16 v[106:109], v[142:145], v[198:201], v[106:109]
	v_mfma_f32_16x16x32_bf16 v[94:97], v[134:137], v[206:209], v[94:97]
	v_mfma_f32_16x16x32_bf16 v[90:93], v[142:145], v[206:209], v[90:93]
	v_mfma_f32_16x16x32_bf16 v[78:81], v[134:137], v[218:221], v[78:81]
	v_mfma_f32_16x16x32_bf16 v[74:77], v[142:145], v[218:221], v[74:77]
	v_mfma_f32_16x16x32_bf16 v[118:121], v[162:165], v[186:189], v[118:121]
	v_mfma_f32_16x16x32_bf16 v[114:117], v[170:173], v[186:189], v[114:117]
	v_mfma_f32_16x16x32_bf16 v[102:105], v[162:165], v[194:197], v[102:105]
	v_mfma_f32_16x16x32_bf16 v[98:101], v[170:173], v[194:197], v[98:101]
	v_mfma_f32_16x16x32_bf16 v[86:89], v[162:165], v[202:205], v[86:89]
	v_mfma_f32_16x16x32_bf16 v[82:85], v[170:173], v[202:205], v[82:85]
	v_mfma_f32_16x16x32_bf16 v[70:73], v[162:165], v[210:213], v[70:73]
	v_mfma_f32_16x16x32_bf16 v[66:69], v[170:173], v[210:213], v[66:69]
	v_mfma_f32_16x16x32_bf16 v[118:121], v[166:169], v[190:193], v[118:121]
	v_mfma_f32_16x16x32_bf16 v[114:117], v[182:185], v[190:193], v[114:117]
	v_mfma_f32_16x16x32_bf16 v[102:105], v[166:169], v[198:201], v[102:105]
	v_mfma_f32_16x16x32_bf16 v[98:101], v[182:185], v[198:201], v[98:101]
	v_mfma_f32_16x16x32_bf16 v[86:89], v[166:169], v[206:209], v[86:89]
	v_mfma_f32_16x16x32_bf16 v[82:85], v[182:185], v[206:209], v[82:85]
	v_mfma_f32_16x16x32_bf16 v[70:73], v[166:169], v[218:221], v[70:73]
	s_barrier
	v_mfma_f32_16x16x32_bf16 v[66:69], v[182:185], v[218:221], v[66:69]
	s_setprio 0
	s_add_i32 s53, s61, s31
	v_lshl_add_u64 v[174:175], s[34:35], 0, v[148:149]
	s_mov_b32 m0, s53
	ds_read_b128 v[186:189], v180 offset:16384
	ds_read_b128 v[190:193], v180 offset:17408
	ds_read_b128 v[194:197], v180 offset:18432
	ds_read_b128 v[198:201], v180 offset:19456
	ds_read_b128 v[202:205], v180 offset:20480
	ds_read_b128 v[206:209], v180 offset:21504
	ds_read_b128 v[210:213], v180 offset:22528
	ds_read_b128 v[218:221], v180 offset:23552
	global_load_lds_dwordx4 v[174:175], off
	s_add_i32 m0, s53, 0x2000
	s_add_u32 s54, s34, 0x160000
	v_lshl_add_u64 v[214:215], s[34:35], 0, v[152:153]
	s_addc_u32 s55, s35, 0
	s_add_i32 s53, s70, s31
	global_load_lds_dwordx4 v[214:215], off
	v_lshl_add_u64 v[222:223], s[54:55], 0, v[148:149]
	s_mov_b32 m0, s53
	v_lshl_add_u64 v[224:225], s[40:41], 0, v[150:151]
	global_load_lds_dwordx4 v[222:223], off
	v_lshl_add_u64 v[222:223], s[54:55], 0, v[152:153]
	s_add_i32 m0, s53, 0x2000
	s_nop 0
	global_load_lds_dwordx4 v[222:223], off
	v_lshl_add_u64 v[222:223], s[40:41], 0, v[146:147]
	s_mov_b32 m0, s33
	s_nop 0
	global_load_lds_dwordx4 v[222:223], off
	s_mov_b32 m0, s46
	s_nop 0
	global_load_lds_dwordx4 v[224:225], off
	s_waitcnt vmcnt(8)
	s_waitcnt lgkmcnt(0)
	s_barrier
	s_setprio 1
	v_mfma_f32_16x16x32_bf16 v[62:65], v[130:133], v[186:189], v[62:65]
	v_mfma_f32_16x16x32_bf16 v[58:61], v[138:141], v[186:189], v[58:61]
	v_mfma_f32_16x16x32_bf16 v[50:53], v[130:133], v[194:197], v[50:53]
	v_mfma_f32_16x16x32_bf16 v[42:45], v[138:141], v[194:197], v[42:45]
	v_mfma_f32_16x16x32_bf16 v[38:41], v[130:133], v[202:205], v[38:41]
	v_mfma_f32_16x16x32_bf16 v[34:37], v[138:141], v[202:205], v[34:37]
	v_mfma_f32_16x16x32_bf16 v[14:17], v[130:133], v[210:213], v[14:17]
	v_mfma_f32_16x16x32_bf16 v[10:13], v[138:141], v[210:213], v[10:13]
	v_mfma_f32_16x16x32_bf16 v[62:65], v[134:137], v[190:193], v[62:65]
	v_mfma_f32_16x16x32_bf16 v[58:61], v[142:145], v[190:193], v[58:61]
	v_mfma_f32_16x16x32_bf16 v[50:53], v[134:137], v[198:201], v[50:53]
	v_mfma_f32_16x16x32_bf16 v[42:45], v[142:145], v[198:201], v[42:45]
	v_mfma_f32_16x16x32_bf16 v[38:41], v[134:137], v[206:209], v[38:41]
	v_mfma_f32_16x16x32_bf16 v[34:37], v[142:145], v[206:209], v[34:37]
	v_mfma_f32_16x16x32_bf16 v[14:17], v[134:137], v[218:221], v[14:17]
	v_mfma_f32_16x16x32_bf16 v[10:13], v[142:145], v[218:221], v[10:13]
	v_mfma_f32_16x16x32_bf16 v[54:57], v[162:165], v[186:189], v[54:57]
	v_mfma_f32_16x16x32_bf16 v[46:49], v[170:173], v[186:189], v[46:49]
	v_mfma_f32_16x16x32_bf16 v[30:33], v[162:165], v[194:197], v[30:33]
	v_mfma_f32_16x16x32_bf16 v[26:29], v[170:173], v[194:197], v[26:29]
	v_mfma_f32_16x16x32_bf16 v[22:25], v[162:165], v[202:205], v[22:25]
	v_mfma_f32_16x16x32_bf16 v[18:21], v[170:173], v[202:205], v[18:21]
	v_mfma_f32_16x16x32_bf16 v[6:9], v[162:165], v[210:213], v[6:9]
	v_mfma_f32_16x16x32_bf16 v[2:5], v[170:173], v[210:213], v[2:5]
	v_mfma_f32_16x16x32_bf16 v[54:57], v[166:169], v[190:193], v[54:57]
	v_mfma_f32_16x16x32_bf16 v[46:49], v[182:185], v[190:193], v[46:49]
	v_mfma_f32_16x16x32_bf16 v[30:33], v[166:169], v[198:201], v[30:33]
	v_mfma_f32_16x16x32_bf16 v[26:29], v[182:185], v[198:201], v[26:29]
	v_mfma_f32_16x16x32_bf16 v[22:25], v[166:169], v[206:209], v[22:25]
	v_mfma_f32_16x16x32_bf16 v[18:21], v[182:185], v[206:209], v[18:21]
	v_mfma_f32_16x16x32_bf16 v[6:9], v[166:169], v[218:221], v[6:9]
	s_barrier
	v_mfma_f32_16x16x32_bf16 v[2:5], v[182:185], v[218:221], v[2:5]
	s_setprio 0
	s_add_i32 s53, 0, 0x18000
	s_add_i32 s54, 0, 0x1c000
	v_add_u32_e32 v142, s53, v176
	v_add_u32_e32 v181, s54, v176
	ds_read_b128 v[130:133], v142
	ds_read_b128 v[134:137], v142 offset:1024
	ds_read_b128 v[138:141], v142 offset:2048
	ds_read_b128 v[142:145], v142 offset:3072
	ds_read_b128 v[162:165], v181
	ds_read_b128 v[166:169], v181 offset:1024
	ds_read_b128 v[170:173], v181 offset:2048
	ds_read_b128 v[182:185], v181 offset:3072
	s_add_u32 s40, s40, 0x160000
	s_addc_u32 s41, s41, 0
	s_mov_b32 m0, s47
	v_lshl_add_u64 v[226:227], s[40:41], 0, v[146:147]
	ds_read_b128 v[186:189], v180 offset:32768
	ds_read_b128 v[190:193], v180 offset:33792
	ds_read_b128 v[194:197], v180 offset:34816
	ds_read_b128 v[198:201], v180 offset:35840
	ds_read_b128 v[202:205], v180 offset:36864
	ds_read_b128 v[206:209], v180 offset:37888
	ds_read_b128 v[210:213], v180 offset:38912
	ds_read_b128 v[218:221], v180 offset:39936
	global_load_lds_dwordx4 v[226:227], off
	v_lshl_add_u64 v[226:227], s[40:41], 0, v[150:151]
	s_mov_b32 m0, s56
	s_nop 0
	global_load_lds_dwordx4 v[226:227], off
	s_waitcnt vmcnt(8)
	s_waitcnt lgkmcnt(0)
	s_barrier
	s_setprio 1
	v_mfma_f32_16x16x32_bf16 v[126:129], v[130:133], v[186:189], v[126:129]
	v_mfma_f32_16x16x32_bf16 v[122:125], v[138:141], v[186:189], v[122:125]
	v_mfma_f32_16x16x32_bf16 v[110:113], v[130:133], v[194:197], v[110:113]
	v_mfma_f32_16x16x32_bf16 v[106:109], v[138:141], v[194:197], v[106:109]
	v_mfma_f32_16x16x32_bf16 v[94:97], v[130:133], v[202:205], v[94:97]
	v_mfma_f32_16x16x32_bf16 v[90:93], v[138:141], v[202:205], v[90:93]
	v_mfma_f32_16x16x32_bf16 v[78:81], v[130:133], v[210:213], v[78:81]
	v_mfma_f32_16x16x32_bf16 v[74:77], v[138:141], v[210:213], v[74:77]
	v_mfma_f32_16x16x32_bf16 v[126:129], v[134:137], v[190:193], v[126:129]
	v_mfma_f32_16x16x32_bf16 v[122:125], v[142:145], v[190:193], v[122:125]
	v_mfma_f32_16x16x32_bf16 v[110:113], v[134:137], v[198:201], v[110:113]
	v_mfma_f32_16x16x32_bf16 v[106:109], v[142:145], v[198:201], v[106:109]
	v_mfma_f32_16x16x32_bf16 v[94:97], v[134:137], v[206:209], v[94:97]
	v_mfma_f32_16x16x32_bf16 v[90:93], v[142:145], v[206:209], v[90:93]
	v_mfma_f32_16x16x32_bf16 v[78:81], v[134:137], v[218:221], v[78:81]
	v_mfma_f32_16x16x32_bf16 v[74:77], v[142:145], v[218:221], v[74:77]
	v_mfma_f32_16x16x32_bf16 v[118:121], v[162:165], v[186:189], v[118:121]
	v_mfma_f32_16x16x32_bf16 v[114:117], v[170:173], v[186:189], v[114:117]
	v_mfma_f32_16x16x32_bf16 v[102:105], v[162:165], v[194:197], v[102:105]
	v_mfma_f32_16x16x32_bf16 v[98:101], v[170:173], v[194:197], v[98:101]
	v_mfma_f32_16x16x32_bf16 v[86:89], v[162:165], v[202:205], v[86:89]
	v_mfma_f32_16x16x32_bf16 v[82:85], v[170:173], v[202:205], v[82:85]
	v_mfma_f32_16x16x32_bf16 v[70:73], v[162:165], v[210:213], v[70:73]
	v_mfma_f32_16x16x32_bf16 v[66:69], v[170:173], v[210:213], v[66:69]
	v_mfma_f32_16x16x32_bf16 v[118:121], v[166:169], v[190:193], v[118:121]
	v_mfma_f32_16x16x32_bf16 v[114:117], v[182:185], v[190:193], v[114:117]
	v_mfma_f32_16x16x32_bf16 v[102:105], v[166:169], v[198:201], v[102:105]
	v_mfma_f32_16x16x32_bf16 v[98:101], v[182:185], v[198:201], v[98:101]
	v_mfma_f32_16x16x32_bf16 v[86:89], v[166:169], v[206:209], v[86:89]
	v_mfma_f32_16x16x32_bf16 v[82:85], v[182:185], v[206:209], v[82:85]
	v_mfma_f32_16x16x32_bf16 v[70:73], v[166:169], v[218:221], v[70:73]
	s_barrier
	v_mfma_f32_16x16x32_bf16 v[66:69], v[182:185], v[218:221], v[66:69]
	s_setprio 0
	s_add_i32 s40, s53, s31
	v_lshl_add_u64 v[174:175], v[174:175], 0, s[24:25]
	s_mov_b32 m0, s40
	ds_read_b128 v[186:189], v180 offset:49152
	ds_read_b128 v[190:193], v180 offset:50176
	ds_read_b128 v[194:197], v180 offset:51200
	ds_read_b128 v[198:201], v180 offset:52224
	ds_read_b128 v[202:205], v180 offset:53248
	ds_read_b128 v[206:209], v180 offset:54272
	ds_read_b128 v[210:213], v180 offset:55296
	ds_read_b128 v[218:221], v180 offset:56320
	global_load_lds_dwordx4 v[174:175], off
	s_add_i32 m0, s40, 0x2000
	s_add_u32 s34, s34, 0x160080
	v_lshl_add_u64 v[174:175], v[214:215], 0, s[24:25]
	s_addc_u32 s35, s35, 0
	s_add_i32 s40, s54, s31
	global_load_lds_dwordx4 v[174:175], off
	v_lshl_add_u64 v[174:175], s[34:35], 0, v[148:149]
	s_mov_b32 m0, s40
	s_nop 0
	global_load_lds_dwordx4 v[174:175], off
	v_lshl_add_u64 v[174:175], s[34:35], 0, v[152:153]
	s_add_i32 m0, s40, 0x2000
	s_nop 0
	global_load_lds_dwordx4 v[174:175], off
	v_lshl_add_u64 v[174:175], v[222:223], 0, s[24:25]
	s_mov_b32 m0, s58
	s_nop 0
	global_load_lds_dwordx4 v[174:175], off
	v_lshl_add_u64 v[174:175], v[224:225], 0, s[24:25]
	s_mov_b32 m0, s59
	s_nop 0
	global_load_lds_dwordx4 v[174:175], off
	s_waitcnt vmcnt(8)
	s_waitcnt lgkmcnt(0)
	s_barrier
	s_setprio 1
	v_mfma_f32_16x16x32_bf16 v[62:65], v[130:133], v[186:189], v[62:65]
	v_mfma_f32_16x16x32_bf16 v[58:61], v[138:141], v[186:189], v[58:61]
	v_mfma_f32_16x16x32_bf16 v[50:53], v[130:133], v[194:197], v[50:53]
	v_mfma_f32_16x16x32_bf16 v[42:45], v[138:141], v[194:197], v[42:45]
	v_mfma_f32_16x16x32_bf16 v[38:41], v[130:133], v[202:205], v[38:41]
	v_mfma_f32_16x16x32_bf16 v[34:37], v[138:141], v[202:205], v[34:37]
	v_mfma_f32_16x16x32_bf16 v[14:17], v[130:133], v[210:213], v[14:17]
	v_mfma_f32_16x16x32_bf16 v[10:13], v[138:141], v[210:213], v[10:13]
	v_mfma_f32_16x16x32_bf16 v[62:65], v[134:137], v[190:193], v[62:65]
	v_mfma_f32_16x16x32_bf16 v[58:61], v[142:145], v[190:193], v[58:61]
	v_mfma_f32_16x16x32_bf16 v[50:53], v[134:137], v[198:201], v[50:53]
	v_mfma_f32_16x16x32_bf16 v[42:45], v[142:145], v[198:201], v[42:45]
	v_mfma_f32_16x16x32_bf16 v[38:41], v[134:137], v[206:209], v[38:41]
	v_mfma_f32_16x16x32_bf16 v[34:37], v[142:145], v[206:209], v[34:37]
	v_mfma_f32_16x16x32_bf16 v[14:17], v[134:137], v[218:221], v[14:17]
	v_mfma_f32_16x16x32_bf16 v[10:13], v[142:145], v[218:221], v[10:13]
	v_mfma_f32_16x16x32_bf16 v[54:57], v[162:165], v[186:189], v[54:57]
	v_mfma_f32_16x16x32_bf16 v[46:49], v[170:173], v[186:189], v[46:49]
	v_mfma_f32_16x16x32_bf16 v[30:33], v[162:165], v[194:197], v[30:33]
	v_mfma_f32_16x16x32_bf16 v[26:29], v[170:173], v[194:197], v[26:29]
	v_mfma_f32_16x16x32_bf16 v[22:25], v[162:165], v[202:205], v[22:25]
	v_mfma_f32_16x16x32_bf16 v[18:21], v[170:173], v[202:205], v[18:21]
	v_mfma_f32_16x16x32_bf16 v[6:9], v[162:165], v[210:213], v[6:9]
	v_mfma_f32_16x16x32_bf16 v[2:5], v[170:173], v[210:213], v[2:5]
	v_mfma_f32_16x16x32_bf16 v[54:57], v[166:169], v[190:193], v[54:57]
	v_mfma_f32_16x16x32_bf16 v[46:49], v[182:185], v[190:193], v[46:49]
	v_mfma_f32_16x16x32_bf16 v[30:33], v[166:169], v[198:201], v[30:33]
	v_mfma_f32_16x16x32_bf16 v[26:29], v[182:185], v[198:201], v[26:29]
	v_mfma_f32_16x16x32_bf16 v[22:25], v[166:169], v[206:209], v[22:25]
	v_mfma_f32_16x16x32_bf16 v[18:21], v[182:185], v[206:209], v[18:21]
	v_mfma_f32_16x16x32_bf16 v[6:9], v[166:169], v[218:221], v[6:9]
	s_barrier
	v_mfma_f32_16x16x32_bf16 v[2:5], v[182:185], v[218:221], v[2:5]
	s_setprio 0
	s_add_i32 s52, s52, 2
	s_add_u32 s38, s38, 0x100
	s_addc_u32 s39, s39, 0
	s_add_u32 s0, s0, 0x100
	s_addc_u32 s1, s1, 0
	s_cmpk_gt_u32 s52, 0x55
	s_cbranch_scc0 .LBB0_2089
	s_and_b64 vcc, exec, s[26:27]
	s_cbranch_vccz .LBB0_2092
	s_barrier

.LBB0_2218:
	ds_read_b128 v[146:149], v153
	ds_read_b128 v[156:159], v153 offset:1024
	ds_read_b128 v[160:163], v153 offset:2048
	ds_read_b128 v[164:167], v153 offset:3072
	ds_read_b128 v[168:171], v154
	ds_read_b128 v[172:175], v154 offset:1024
	ds_read_b128 v[176:179], v154 offset:2048
	ds_read_b128 v[180:183], v154 offset:3072
	s_add_u32 s34, s76, 0xfff80080
	s_addc_u32 s35, s77, -1
	s_cmp_eq_u32 s80, 28
	s_cselect_b32 s79, s0, s35
	s_cselect_b32 s78, s1, s34
	s_cselect_b32 s35, s27, s75
	s_cselect_b32 s34, s37, s52
	v_lshl_add_u64 v[218:219], s[76:77], 0, v[138:139]
	s_add_i32 m0, s47, 0xc000
	ds_read_b128 v[184:187], v155
	ds_read_b128 v[188:191], v155 offset:1024
	ds_read_b128 v[192:195], v155 offset:2048
	ds_read_b128 v[196:199], v155 offset:3072
	ds_read_b128 v[200:203], v155 offset:4096
	ds_read_b128 v[204:207], v155 offset:5120
	ds_read_b128 v[208:211], v155 offset:6144
	ds_read_b128 v[212:215], v155 offset:7168
	global_load_lds_dwordx4 v[218:219], off
	v_lshl_add_u64 v[218:219], s[76:77], 0, v[140:141]
	s_add_i32 m0, s47, 0xe000
	s_nop 0
	global_load_lds_dwordx4 v[218:219], off
	s_waitcnt vmcnt(8)
	s_waitcnt lgkmcnt(0)
	s_barrier
	s_setprio 1
	v_mfma_f32_16x16x32_bf16 v[126:129], v[146:149], v[184:187], v[126:129]
	v_mfma_f32_16x16x32_bf16 v[118:121], v[160:163], v[184:187], v[118:121]
	v_mfma_f32_16x16x32_bf16 v[110:113], v[146:149], v[192:195], v[110:113]
	v_mfma_f32_16x16x32_bf16 v[102:105], v[160:163], v[192:195], v[102:105]
	v_mfma_f32_16x16x32_bf16 v[94:97], v[146:149], v[200:203], v[94:97]
	v_mfma_f32_16x16x32_bf16 v[86:89], v[160:163], v[200:203], v[86:89]
	v_mfma_f32_16x16x32_bf16 v[78:81], v[146:149], v[208:211], v[78:81]
	v_mfma_f32_16x16x32_bf16 v[70:73], v[160:163], v[208:211], v[70:73]
	v_mfma_f32_16x16x32_bf16 v[126:129], v[156:159], v[188:191], v[126:129]
	v_mfma_f32_16x16x32_bf16 v[118:121], v[164:167], v[188:191], v[118:121]
	v_mfma_f32_16x16x32_bf16 v[110:113], v[156:159], v[196:199], v[110:113]
	v_mfma_f32_16x16x32_bf16 v[102:105], v[164:167], v[196:199], v[102:105]
	v_mfma_f32_16x16x32_bf16 v[94:97], v[156:159], v[204:207], v[94:97]
	v_mfma_f32_16x16x32_bf16 v[86:89], v[164:167], v[204:207], v[86:89]
	v_mfma_f32_16x16x32_bf16 v[78:81], v[156:159], v[212:215], v[78:81]
	v_mfma_f32_16x16x32_bf16 v[70:73], v[164:167], v[212:215], v[70:73]
	v_mfma_f32_16x16x32_bf16 v[122:125], v[168:171], v[184:187], v[122:125]
	v_mfma_f32_16x16x32_bf16 v[114:117], v[176:179], v[184:187], v[114:117]
	v_mfma_f32_16x16x32_bf16 v[106:109], v[168:171], v[192:195], v[106:109]
	v_mfma_f32_16x16x32_bf16 v[98:101], v[176:179], v[192:195], v[98:101]
	v_mfma_f32_16x16x32_bf16 v[90:93], v[168:171], v[200:203], v[90:93]
	v_mfma_f32_16x16x32_bf16 v[82:85], v[176:179], v[200:203], v[82:85]
	v_mfma_f32_16x16x32_bf16 v[74:77], v[168:171], v[208:211], v[74:77]
	v_mfma_f32_16x16x32_bf16 v[66:69], v[176:179], v[208:211], v[66:69]
	v_mfma_f32_16x16x32_bf16 v[122:125], v[172:175], v[188:191], v[122:125]
	v_mfma_f32_16x16x32_bf16 v[114:117], v[180:183], v[188:191], v[114:117]
	v_mfma_f32_16x16x32_bf16 v[106:109], v[172:175], v[196:199], v[106:109]
	v_mfma_f32_16x16x32_bf16 v[98:101], v[180:183], v[196:199], v[98:101]
	v_mfma_f32_16x16x32_bf16 v[90:93], v[172:175], v[204:207], v[90:93]
	v_mfma_f32_16x16x32_bf16 v[82:85], v[180:183], v[204:207], v[82:85]
	v_mfma_f32_16x16x32_bf16 v[74:77], v[172:175], v[212:215], v[74:77]
	s_barrier
	v_mfma_f32_16x16x32_bf16 v[66:69], v[180:183], v[212:215], v[66:69]
	s_setprio 0
	s_add_i32 s53, s71, s30
	v_lshl_add_u64 v[218:219], s[34:35], 0, v[134:135]
	s_mov_b32 m0, s53
	ds_read_b128 v[184:187], v155 offset:16384
	ds_read_b128 v[188:191], v155 offset:17408
	ds_read_b128 v[192:195], v155 offset:18432
	ds_read_b128 v[196:199], v155 offset:19456
	ds_read_b128 v[200:203], v155 offset:20480
	ds_read_b128 v[204:207], v155 offset:21504
	ds_read_b128 v[208:211], v155 offset:22528
	ds_read_b128 v[212:215], v155 offset:23552
	global_load_lds_dwordx4 v[218:219], off
	s_add_i32 m0, s53, 0x2000
	s_add_u32 s54, s34, 0x80000
	v_lshl_add_u64 v[220:221], s[34:35], 0, v[130:131]
	s_addc_u32 s55, s35, 0
	s_add_i32 s53, s72, s30
	global_load_lds_dwordx4 v[220:221], off
	v_lshl_add_u64 v[222:223], s[54:55], 0, v[134:135]
	s_mov_b32 m0, s53
	v_lshl_add_u64 v[224:225], s[78:79], 0, v[132:133]
	global_load_lds_dwordx4 v[222:223], off
	v_lshl_add_u64 v[222:223], s[54:55], 0, v[130:131]
	s_add_i32 m0, s53, 0x2000
	s_nop 0
	global_load_lds_dwordx4 v[222:223], off
	v_lshl_add_u64 v[222:223], s[78:79], 0, v[136:137]
	s_mov_b32 m0, s47
	s_nop 0
	global_load_lds_dwordx4 v[222:223], off
	s_mov_b32 m0, s56
	s_nop 0
	global_load_lds_dwordx4 v[224:225], off
	s_waitcnt vmcnt(8)
	s_waitcnt lgkmcnt(0)
	s_barrier
	s_setprio 1
	v_mfma_f32_16x16x32_bf16 v[62:65], v[146:149], v[184:187], v[62:65]
	v_mfma_f32_16x16x32_bf16 v[54:57], v[160:163], v[184:187], v[54:57]
	v_mfma_f32_16x16x32_bf16 v[46:49], v[146:149], v[192:195], v[46:49]
	v_mfma_f32_16x16x32_bf16 v[38:41], v[160:163], v[192:195], v[38:41]
	v_mfma_f32_16x16x32_bf16 v[30:33], v[146:149], v[200:203], v[30:33]
	v_mfma_f32_16x16x32_bf16 v[22:25], v[160:163], v[200:203], v[22:25]
	v_mfma_f32_16x16x32_bf16 v[14:17], v[146:149], v[208:211], v[14:17]
	v_mfma_f32_16x16x32_bf16 v[6:9], v[160:163], v[208:211], v[6:9]
	v_mfma_f32_16x16x32_bf16 v[62:65], v[156:159], v[188:191], v[62:65]
	v_mfma_f32_16x16x32_bf16 v[54:57], v[164:167], v[188:191], v[54:57]
	v_mfma_f32_16x16x32_bf16 v[46:49], v[156:159], v[196:199], v[46:49]
	v_mfma_f32_16x16x32_bf16 v[38:41], v[164:167], v[196:199], v[38:41]
	v_mfma_f32_16x16x32_bf16 v[30:33], v[156:159], v[204:207], v[30:33]
	v_mfma_f32_16x16x32_bf16 v[22:25], v[164:167], v[204:207], v[22:25]
	v_mfma_f32_16x16x32_bf16 v[14:17], v[156:159], v[212:215], v[14:17]
	v_mfma_f32_16x16x32_bf16 v[6:9], v[164:167], v[212:215], v[6:9]
	v_mfma_f32_16x16x32_bf16 v[58:61], v[168:171], v[184:187], v[58:61]
	v_mfma_f32_16x16x32_bf16 v[50:53], v[176:179], v[184:187], v[50:53]
	v_mfma_f32_16x16x32_bf16 v[42:45], v[168:171], v[192:195], v[42:45]
	v_mfma_f32_16x16x32_bf16 v[34:37], v[176:179], v[192:195], v[34:37]
	v_mfma_f32_16x16x32_bf16 v[26:29], v[168:171], v[200:203], v[26:29]
	v_mfma_f32_16x16x32_bf16 v[18:21], v[176:179], v[200:203], v[18:21]
	v_mfma_f32_16x16x32_bf16 v[10:13], v[168:171], v[208:211], v[10:13]
	v_mfma_f32_16x16x32_bf16 v[2:5], v[176:179], v[208:211], v[2:5]
	v_mfma_f32_16x16x32_bf16 v[58:61], v[172:175], v[188:191], v[58:61]
	v_mfma_f32_16x16x32_bf16 v[50:53], v[180:183], v[188:191], v[50:53]
	v_mfma_f32_16x16x32_bf16 v[42:45], v[172:175], v[196:199], v[42:45]
	v_mfma_f32_16x16x32_bf16 v[34:37], v[180:183], v[196:199], v[34:37]
	v_mfma_f32_16x16x32_bf16 v[26:29], v[172:175], v[204:207], v[26:29]
	v_mfma_f32_16x16x32_bf16 v[18:21], v[180:183], v[204:207], v[18:21]
	v_mfma_f32_16x16x32_bf16 v[10:13], v[172:175], v[212:215], v[10:13]
	s_barrier
	v_mfma_f32_16x16x32_bf16 v[2:5], v[180:183], v[212:215], v[2:5]
	s_setprio 0
	s_add_i32 s53, 0, 0x18000
	s_add_i32 s62, 0, 0x1c000
	v_add_u32_e32 v164, s53, v151
	v_add_u32_e32 v180, s62, v151
	ds_read_b128 v[146:149], v164
	ds_read_b128 v[156:159], v164 offset:1024
	ds_read_b128 v[160:163], v164 offset:2048
	ds_read_b128 v[164:167], v164 offset:3072
	ds_read_b128 v[168:171], v180
	ds_read_b128 v[172:175], v180 offset:1024
	ds_read_b128 v[176:179], v180 offset:2048
	ds_read_b128 v[180:183], v180 offset:3072
	s_add_u32 s54, s78, 0x80000
	s_addc_u32 s55, s79, 0
	s_mov_b32 m0, s57
	v_lshl_add_u64 v[226:227], s[54:55], 0, v[136:137]
	ds_read_b128 v[184:187], v155 offset:32768
	ds_read_b128 v[188:191], v155 offset:33792
	ds_read_b128 v[192:195], v155 offset:34816
	ds_read_b128 v[196:199], v155 offset:35840
	ds_read_b128 v[200:203], v155 offset:36864
	ds_read_b128 v[204:207], v155 offset:37888
	ds_read_b128 v[208:211], v155 offset:38912
	ds_read_b128 v[212:215], v155 offset:39936
	global_load_lds_dwordx4 v[226:227], off
	v_lshl_add_u64 v[226:227], s[54:55], 0, v[132:133]
	s_mov_b32 m0, s58
	s_nop 0
	global_load_lds_dwordx4 v[226:227], off
	s_waitcnt vmcnt(8)
	s_waitcnt lgkmcnt(0)
	s_barrier
	s_setprio 1
	v_mfma_f32_16x16x32_bf16 v[126:129], v[146:149], v[184:187], v[126:129]
	v_mfma_f32_16x16x32_bf16 v[118:121], v[160:163], v[184:187], v[118:121]
	v_mfma_f32_16x16x32_bf16 v[110:113], v[146:149], v[192:195], v[110:113]
	v_mfma_f32_16x16x32_bf16 v[102:105], v[160:163], v[192:195], v[102:105]
	v_mfma_f32_16x16x32_bf16 v[94:97], v[146:149], v[200:203], v[94:97]
	v_mfma_f32_16x16x32_bf16 v[86:89], v[160:163], v[200:203], v[86:89]
	v_mfma_f32_16x16x32_bf16 v[78:81], v[146:149], v[208:211], v[78:81]
	v_mfma_f32_16x16x32_bf16 v[70:73], v[160:163], v[208:211], v[70:73]
	v_mfma_f32_16x16x32_bf16 v[126:129], v[156:159], v[188:191], v[126:129]
	v_mfma_f32_16x16x32_bf16 v[118:121], v[164:167], v[188:191], v[118:121]
	v_mfma_f32_16x16x32_bf16 v[110:113], v[156:159], v[196:199], v[110:113]
	v_mfma_f32_16x16x32_bf16 v[102:105], v[164:167], v[196:199], v[102:105]
	v_mfma_f32_16x16x32_bf16 v[94:97], v[156:159], v[204:207], v[94:97]
	v_mfma_f32_16x16x32_bf16 v[86:89], v[164:167], v[204:207], v[86:89]
	v_mfma_f32_16x16x32_bf16 v[78:81], v[156:159], v[212:215], v[78:81]
	v_mfma_f32_16x16x32_bf16 v[70:73], v[164:167], v[212:215], v[70:73]
	v_mfma_f32_16x16x32_bf16 v[122:125], v[168:171], v[184:187], v[122:125]
	v_mfma_f32_16x16x32_bf16 v[114:117], v[176:179], v[184:187], v[114:117]
	v_mfma_f32_16x16x32_bf16 v[106:109], v[168:171], v[192:195], v[106:109]
	v_mfma_f32_16x16x32_bf16 v[98:101], v[176:179], v[192:195], v[98:101]
	v_mfma_f32_16x16x32_bf16 v[90:93], v[168:171], v[200:203], v[90:93]
	v_mfma_f32_16x16x32_bf16 v[82:85], v[176:179], v[200:203], v[82:85]
	v_mfma_f32_16x16x32_bf16 v[74:77], v[168:171], v[208:211], v[74:77]
	v_mfma_f32_16x16x32_bf16 v[66:69], v[176:179], v[208:211], v[66:69]
	v_mfma_f32_16x16x32_bf16 v[122:125], v[172:175], v[188:191], v[122:125]
	v_mfma_f32_16x16x32_bf16 v[114:117], v[180:183], v[188:191], v[114:117]
	v_mfma_f32_16x16x32_bf16 v[106:109], v[172:175], v[196:199], v[106:109]
	v_mfma_f32_16x16x32_bf16 v[98:101], v[180:183], v[196:199], v[98:101]
	v_mfma_f32_16x16x32_bf16 v[90:93], v[172:175], v[204:207], v[90:93]
	v_mfma_f32_16x16x32_bf16 v[82:85], v[180:183], v[204:207], v[82:85]
	v_mfma_f32_16x16x32_bf16 v[74:77], v[172:175], v[212:215], v[74:77]
	s_barrier
	v_mfma_f32_16x16x32_bf16 v[66:69], v[180:183], v[212:215], v[66:69]
	s_setprio 0
	s_add_i32 s53, s53, s30
	v_lshl_add_u64 v[218:219], v[218:219], 0, s[8:9]
	s_mov_b32 m0, s53
	ds_read_b128 v[184:187], v155 offset:49152
	ds_read_b128 v[188:191], v155 offset:50176
	ds_read_b128 v[192:195], v155 offset:51200
	ds_read_b128 v[196:199], v155 offset:52224
	ds_read_b128 v[200:203], v155 offset:53248
	ds_read_b128 v[204:207], v155 offset:54272
	ds_read_b128 v[208:211], v155 offset:55296
	ds_read_b128 v[212:215], v155 offset:56320
	global_load_lds_dwordx4 v[218:219], off
	s_add_i32 m0, s53, 0x2000
	s_add_u32 s34, s34, 0x80080
	v_lshl_add_u64 v[218:219], v[220:221], 0, s[8:9]
	s_addc_u32 s35, s35, 0
	s_add_i32 s53, s62, s30
	global_load_lds_dwordx4 v[218:219], off
	v_lshl_add_u64 v[218:219], s[34:35], 0, v[134:135]
	s_mov_b32 m0, s53
	s_nop 0
	global_load_lds_dwordx4 v[218:219], off
	v_lshl_add_u64 v[218:219], s[34:35], 0, v[130:131]
	s_add_i32 m0, s53, 0x2000
	s_nop 0
	global_load_lds_dwordx4 v[218:219], off
	v_lshl_add_u64 v[218:219], v[222:223], 0, s[8:9]
	s_mov_b32 m0, s60
	s_nop 0
	global_load_lds_dwordx4 v[218:219], off
	v_lshl_add_u64 v[218:219], v[224:225], 0, s[8:9]
	s_mov_b32 m0, s61
	s_nop 0
	global_load_lds_dwordx4 v[218:219], off
	s_waitcnt vmcnt(8)
	s_waitcnt lgkmcnt(0)
	s_barrier
	s_setprio 1
	v_mfma_f32_16x16x32_bf16 v[62:65], v[146:149], v[184:187], v[62:65]
	v_mfma_f32_16x16x32_bf16 v[54:57], v[160:163], v[184:187], v[54:57]
	v_mfma_f32_16x16x32_bf16 v[46:49], v[146:149], v[192:195], v[46:49]
	v_mfma_f32_16x16x32_bf16 v[38:41], v[160:163], v[192:195], v[38:41]
	v_mfma_f32_16x16x32_bf16 v[30:33], v[146:149], v[200:203], v[30:33]
	v_mfma_f32_16x16x32_bf16 v[22:25], v[160:163], v[200:203], v[22:25]
	v_mfma_f32_16x16x32_bf16 v[14:17], v[146:149], v[208:211], v[14:17]
	v_mfma_f32_16x16x32_bf16 v[6:9], v[160:163], v[208:211], v[6:9]
	v_mfma_f32_16x16x32_bf16 v[62:65], v[156:159], v[188:191], v[62:65]
	v_mfma_f32_16x16x32_bf16 v[54:57], v[164:167], v[188:191], v[54:57]
	v_mfma_f32_16x16x32_bf16 v[46:49], v[156:159], v[196:199], v[46:49]
	v_mfma_f32_16x16x32_bf16 v[38:41], v[164:167], v[196:199], v[38:41]
	v_mfma_f32_16x16x32_bf16 v[30:33], v[156:159], v[204:207], v[30:33]
	v_mfma_f32_16x16x32_bf16 v[22:25], v[164:167], v[204:207], v[22:25]
	v_mfma_f32_16x16x32_bf16 v[14:17], v[156:159], v[212:215], v[14:17]
	v_mfma_f32_16x16x32_bf16 v[6:9], v[164:167], v[212:215], v[6:9]
	v_mfma_f32_16x16x32_bf16 v[58:61], v[168:171], v[184:187], v[58:61]
	v_mfma_f32_16x16x32_bf16 v[50:53], v[176:179], v[184:187], v[50:53]
	v_mfma_f32_16x16x32_bf16 v[42:45], v[168:171], v[192:195], v[42:45]
	v_mfma_f32_16x16x32_bf16 v[34:37], v[176:179], v[192:195], v[34:37]
	v_mfma_f32_16x16x32_bf16 v[26:29], v[168:171], v[200:203], v[26:29]
	v_mfma_f32_16x16x32_bf16 v[18:21], v[176:179], v[200:203], v[18:21]
	v_mfma_f32_16x16x32_bf16 v[10:13], v[168:171], v[208:211], v[10:13]
	v_mfma_f32_16x16x32_bf16 v[2:5], v[176:179], v[208:211], v[2:5]
	v_mfma_f32_16x16x32_bf16 v[58:61], v[172:175], v[188:191], v[58:61]
	v_mfma_f32_16x16x32_bf16 v[50:53], v[180:183], v[188:191], v[50:53]
	v_mfma_f32_16x16x32_bf16 v[42:45], v[172:175], v[196:199], v[42:45]
	v_mfma_f32_16x16x32_bf16 v[34:37], v[180:183], v[196:199], v[34:37]
	v_mfma_f32_16x16x32_bf16 v[26:29], v[172:175], v[204:207], v[26:29]
	v_mfma_f32_16x16x32_bf16 v[18:21], v[180:183], v[204:207], v[18:21]
	v_mfma_f32_16x16x32_bf16 v[10:13], v[172:175], v[212:215], v[10:13]
	s_barrier
	v_mfma_f32_16x16x32_bf16 v[2:5], v[180:183], v[212:215], v[2:5]
	s_setprio 0
	s_add_i32 s80, s80, 2
	s_add_u32 s76, s76, 0x100
	s_addc_u32 s77, s77, 0
	s_add_u32 s52, s52, 0x100
	s_addc_u32 s75, s75, 0
	s_cmp_gt_u32 s80, 29
	s_cbranch_scc0 .LBB0_2218
	s_and_b64 vcc, exec, s[24:25]
	s_cbranch_vccz .LBB0_2221
	s_barrier

.LBB0_2462:
	ds_read_b128 v[160:163], v155
	ds_read_b128 v[164:167], v155 offset:1024
	ds_read_b128 v[168:171], v155 offset:2048
	ds_read_b128 v[172:175], v155 offset:3072
	ds_read_b128 v[176:179], v156
	ds_read_b128 v[180:183], v156 offset:1024
	ds_read_b128 v[184:187], v156 offset:2048
	ds_read_b128 v[188:191], v156 offset:3072
	s_add_u32 s34, s76, 0xfff80080
	s_addc_u32 s35, s77, -1
	s_cmp_eq_u32 s74, 28
	s_cselect_b32 s89, s0, s35
	s_cselect_b32 s88, s1, s34
	s_cselect_b32 s35, s7, s52
	s_cselect_b32 s34, s9, s36
	v_lshl_add_u64 v[152:153], s[76:77], 0, v[144:145]
	s_add_i32 m0, s31, 0xc000
	ds_read_b128 v[192:195], v157
	ds_read_b128 v[196:199], v157 offset:1024
	ds_read_b128 v[200:203], v157 offset:2048
	ds_read_b128 v[204:207], v157 offset:3072
	ds_read_b128 v[208:211], v157 offset:4096
	ds_read_b128 v[212:215], v157 offset:5120
	ds_read_b128 v[218:221], v157 offset:6144
	ds_read_b128 v[222:225], v157 offset:7168
	global_load_lds_dwordx4 v[152:153], off
	v_lshl_add_u64 v[152:153], s[76:77], 0, v[146:147]
	s_add_i32 m0, s31, 0xe000
	s_nop 0
	global_load_lds_dwordx4 v[152:153], off
	s_waitcnt vmcnt(8)
	s_waitcnt lgkmcnt(0)
	s_barrier
	s_setprio 1
	v_mfma_f32_16x16x32_bf16 v[126:129], v[160:163], v[192:195], v[126:129]
	v_mfma_f32_16x16x32_bf16 v[122:125], v[168:171], v[192:195], v[122:125]
	v_mfma_f32_16x16x32_bf16 v[110:113], v[160:163], v[200:203], v[110:113]
	v_mfma_f32_16x16x32_bf16 v[106:109], v[168:171], v[200:203], v[106:109]
	v_mfma_f32_16x16x32_bf16 v[94:97], v[160:163], v[208:211], v[94:97]
	v_mfma_f32_16x16x32_bf16 v[90:93], v[168:171], v[208:211], v[90:93]
	v_mfma_f32_16x16x32_bf16 v[78:81], v[160:163], v[218:221], v[78:81]
	v_mfma_f32_16x16x32_bf16 v[74:77], v[168:171], v[218:221], v[74:77]
	v_mfma_f32_16x16x32_bf16 v[126:129], v[164:167], v[196:199], v[126:129]
	v_mfma_f32_16x16x32_bf16 v[122:125], v[172:175], v[196:199], v[122:125]
	v_mfma_f32_16x16x32_bf16 v[110:113], v[164:167], v[204:207], v[110:113]
	v_mfma_f32_16x16x32_bf16 v[106:109], v[172:175], v[204:207], v[106:109]
	v_mfma_f32_16x16x32_bf16 v[94:97], v[164:167], v[212:215], v[94:97]
	v_mfma_f32_16x16x32_bf16 v[90:93], v[172:175], v[212:215], v[90:93]
	v_mfma_f32_16x16x32_bf16 v[78:81], v[164:167], v[222:225], v[78:81]
	v_mfma_f32_16x16x32_bf16 v[74:77], v[172:175], v[222:225], v[74:77]
	v_mfma_f32_16x16x32_bf16 v[118:121], v[176:179], v[192:195], v[118:121]
	v_mfma_f32_16x16x32_bf16 v[114:117], v[184:187], v[192:195], v[114:117]
	v_mfma_f32_16x16x32_bf16 v[102:105], v[176:179], v[200:203], v[102:105]
	v_mfma_f32_16x16x32_bf16 v[98:101], v[184:187], v[200:203], v[98:101]
	v_mfma_f32_16x16x32_bf16 v[86:89], v[176:179], v[208:211], v[86:89]
	v_mfma_f32_16x16x32_bf16 v[82:85], v[184:187], v[208:211], v[82:85]
	v_mfma_f32_16x16x32_bf16 v[70:73], v[176:179], v[218:221], v[70:73]
	v_mfma_f32_16x16x32_bf16 v[66:69], v[184:187], v[218:221], v[66:69]
	v_mfma_f32_16x16x32_bf16 v[118:121], v[180:183], v[196:199], v[118:121]
	v_mfma_f32_16x16x32_bf16 v[114:117], v[188:191], v[196:199], v[114:117]
	v_mfma_f32_16x16x32_bf16 v[102:105], v[180:183], v[204:207], v[102:105]
	v_mfma_f32_16x16x32_bf16 v[98:101], v[188:191], v[204:207], v[98:101]
	v_mfma_f32_16x16x32_bf16 v[86:89], v[180:183], v[212:215], v[86:89]
	v_mfma_f32_16x16x32_bf16 v[82:85], v[188:191], v[212:215], v[82:85]
	v_mfma_f32_16x16x32_bf16 v[70:73], v[180:183], v[222:225], v[70:73]
	s_barrier
	v_mfma_f32_16x16x32_bf16 v[66:69], v[188:191], v[222:225], v[66:69]
	s_setprio 0
	s_add_i32 s53, s71, s12
	v_lshl_add_u64 v[152:153], s[34:35], 0, v[132:133]
	s_mov_b32 m0, s53
	ds_read_b128 v[192:195], v157 offset:16384
	ds_read_b128 v[196:199], v157 offset:17408
	ds_read_b128 v[200:203], v157 offset:18432
	ds_read_b128 v[204:207], v157 offset:19456
	ds_read_b128 v[208:211], v157 offset:20480
	ds_read_b128 v[212:215], v157 offset:21504
	ds_read_b128 v[218:221], v157 offset:22528
	ds_read_b128 v[222:225], v157 offset:23552
	global_load_lds_dwordx4 v[152:153], off
	s_add_i32 m0, s53, 0x2000
	s_add_u32 s54, s34, 0x80000
	v_lshl_add_u64 v[226:227], s[34:35], 0, v[136:137]
	s_addc_u32 s55, s35, 0
	s_add_i32 s53, s72, s12
	global_load_lds_dwordx4 v[226:227], off
	v_lshl_add_u64 v[228:229], s[54:55], 0, v[132:133]
	s_mov_b32 m0, s53
	v_lshl_add_u64 v[230:231], s[88:89], 0, v[134:135]
	global_load_lds_dwordx4 v[228:229], off
	v_lshl_add_u64 v[228:229], s[54:55], 0, v[136:137]
	s_add_i32 m0, s53, 0x2000
	s_nop 0
	global_load_lds_dwordx4 v[228:229], off
	v_lshl_add_u64 v[228:229], s[88:89], 0, v[130:131]
	s_mov_b32 m0, s31
	s_nop 0
	global_load_lds_dwordx4 v[228:229], off
	s_mov_b32 m0, s33
	s_nop 0
	global_load_lds_dwordx4 v[230:231], off
	s_waitcnt vmcnt(8)
	s_waitcnt lgkmcnt(0)
	s_barrier
	s_setprio 1
	v_mfma_f32_16x16x32_bf16 v[62:65], v[160:163], v[192:195], v[62:65]
	v_mfma_f32_16x16x32_bf16 v[58:61], v[168:171], v[192:195], v[58:61]
	v_mfma_f32_16x16x32_bf16 v[46:49], v[160:163], v[200:203], v[46:49]
	v_mfma_f32_16x16x32_bf16 v[42:45], v[168:171], v[200:203], v[42:45]
	v_mfma_f32_16x16x32_bf16 v[30:33], v[160:163], v[208:211], v[30:33]
	v_mfma_f32_16x16x32_bf16 v[26:29], v[168:171], v[208:211], v[26:29]
	v_mfma_f32_16x16x32_bf16 v[14:17], v[160:163], v[218:221], v[14:17]
	v_mfma_f32_16x16x32_bf16 v[10:13], v[168:171], v[218:221], v[10:13]
	v_mfma_f32_16x16x32_bf16 v[62:65], v[164:167], v[196:199], v[62:65]
	v_mfma_f32_16x16x32_bf16 v[58:61], v[172:175], v[196:199], v[58:61]
	v_mfma_f32_16x16x32_bf16 v[46:49], v[164:167], v[204:207], v[46:49]
	v_mfma_f32_16x16x32_bf16 v[42:45], v[172:175], v[204:207], v[42:45]
	v_mfma_f32_16x16x32_bf16 v[30:33], v[164:167], v[212:215], v[30:33]
	v_mfma_f32_16x16x32_bf16 v[26:29], v[172:175], v[212:215], v[26:29]
	v_mfma_f32_16x16x32_bf16 v[14:17], v[164:167], v[222:225], v[14:17]
	v_mfma_f32_16x16x32_bf16 v[10:13], v[172:175], v[222:225], v[10:13]
	v_mfma_f32_16x16x32_bf16 v[54:57], v[176:179], v[192:195], v[54:57]
	v_mfma_f32_16x16x32_bf16 v[50:53], v[184:187], v[192:195], v[50:53]
	v_mfma_f32_16x16x32_bf16 v[38:41], v[176:179], v[200:203], v[38:41]
	v_mfma_f32_16x16x32_bf16 v[34:37], v[184:187], v[200:203], v[34:37]
	v_mfma_f32_16x16x32_bf16 v[22:25], v[176:179], v[208:211], v[22:25]
	v_mfma_f32_16x16x32_bf16 v[18:21], v[184:187], v[208:211], v[18:21]
	v_mfma_f32_16x16x32_bf16 v[6:9], v[176:179], v[218:221], v[6:9]
	v_mfma_f32_16x16x32_bf16 v[2:5], v[184:187], v[218:221], v[2:5]
	v_mfma_f32_16x16x32_bf16 v[54:57], v[180:183], v[196:199], v[54:57]
	v_mfma_f32_16x16x32_bf16 v[50:53], v[188:191], v[196:199], v[50:53]
	v_mfma_f32_16x16x32_bf16 v[38:41], v[180:183], v[204:207], v[38:41]
	v_mfma_f32_16x16x32_bf16 v[34:37], v[188:191], v[204:207], v[34:37]
	v_mfma_f32_16x16x32_bf16 v[22:25], v[180:183], v[212:215], v[22:25]
	v_mfma_f32_16x16x32_bf16 v[18:21], v[188:191], v[212:215], v[18:21]
	v_mfma_f32_16x16x32_bf16 v[6:9], v[180:183], v[222:225], v[6:9]
	s_barrier
	v_mfma_f32_16x16x32_bf16 v[2:5], v[188:191], v[222:225], v[2:5]
	s_setprio 0
	s_add_i32 s53, 0, 0x18000
	v_add_u32_e32 v138, s53, v154
	s_add_i32 s62, 0, 0x1c000
	ds_read_b128 v[160:163], v138
	ds_read_b128 v[164:167], v138 offset:1024
	ds_read_b128 v[168:171], v138 offset:2048
	ds_read_b128 v[172:175], v138 offset:3072
	v_add_u32_e32 v138, s62, v154
	ds_read_b128 v[176:179], v138
	ds_read_b128 v[180:183], v138 offset:1024
	ds_read_b128 v[184:187], v138 offset:2048
	ds_read_b128 v[188:191], v138 offset:3072
	s_add_u32 s54, s88, 0x80000
	s_addc_u32 s55, s89, 0
	s_mov_b32 m0, s56
	v_lshl_add_u64 v[232:233], s[54:55], 0, v[130:131]
	ds_read_b128 v[192:195], v157 offset:32768
	ds_read_b128 v[196:199], v157 offset:33792
	ds_read_b128 v[200:203], v157 offset:34816
	ds_read_b128 v[204:207], v157 offset:35840
	ds_read_b128 v[208:211], v157 offset:36864
	ds_read_b128 v[212:215], v157 offset:37888
	ds_read_b128 v[218:221], v157 offset:38912
	ds_read_b128 v[222:225], v157 offset:39936
	global_load_lds_dwordx4 v[232:233], off
	v_lshl_add_u64 v[232:233], s[54:55], 0, v[134:135]
	s_mov_b32 m0, s57
	s_nop 0
	global_load_lds_dwordx4 v[232:233], off
	s_waitcnt vmcnt(8)
	s_waitcnt lgkmcnt(0)
	s_barrier
	s_setprio 1
	v_mfma_f32_16x16x32_bf16 v[126:129], v[160:163], v[192:195], v[126:129]
	v_mfma_f32_16x16x32_bf16 v[122:125], v[168:171], v[192:195], v[122:125]
	v_mfma_f32_16x16x32_bf16 v[110:113], v[160:163], v[200:203], v[110:113]
	v_mfma_f32_16x16x32_bf16 v[106:109], v[168:171], v[200:203], v[106:109]
	v_mfma_f32_16x16x32_bf16 v[94:97], v[160:163], v[208:211], v[94:97]
	v_mfma_f32_16x16x32_bf16 v[90:93], v[168:171], v[208:211], v[90:93]
	v_mfma_f32_16x16x32_bf16 v[78:81], v[160:163], v[218:221], v[78:81]
	v_mfma_f32_16x16x32_bf16 v[74:77], v[168:171], v[218:221], v[74:77]
	v_mfma_f32_16x16x32_bf16 v[126:129], v[164:167], v[196:199], v[126:129]
	v_mfma_f32_16x16x32_bf16 v[122:125], v[172:175], v[196:199], v[122:125]
	v_mfma_f32_16x16x32_bf16 v[110:113], v[164:167], v[204:207], v[110:113]
	v_mfma_f32_16x16x32_bf16 v[106:109], v[172:175], v[204:207], v[106:109]
	v_mfma_f32_16x16x32_bf16 v[94:97], v[164:167], v[212:215], v[94:97]
	v_mfma_f32_16x16x32_bf16 v[90:93], v[172:175], v[212:215], v[90:93]
	v_mfma_f32_16x16x32_bf16 v[78:81], v[164:167], v[222:225], v[78:81]
	v_mfma_f32_16x16x32_bf16 v[74:77], v[172:175], v[222:225], v[74:77]
	v_mfma_f32_16x16x32_bf16 v[118:121], v[176:179], v[192:195], v[118:121]
	v_mfma_f32_16x16x32_bf16 v[114:117], v[184:187], v[192:195], v[114:117]
	v_mfma_f32_16x16x32_bf16 v[102:105], v[176:179], v[200:203], v[102:105]
	v_mfma_f32_16x16x32_bf16 v[98:101], v[184:187], v[200:203], v[98:101]
	v_mfma_f32_16x16x32_bf16 v[86:89], v[176:179], v[208:211], v[86:89]
	v_mfma_f32_16x16x32_bf16 v[82:85], v[184:187], v[208:211], v[82:85]
	v_mfma_f32_16x16x32_bf16 v[70:73], v[176:179], v[218:221], v[70:73]
	v_mfma_f32_16x16x32_bf16 v[66:69], v[184:187], v[218:221], v[66:69]
	v_mfma_f32_16x16x32_bf16 v[118:121], v[180:183], v[196:199], v[118:121]
	v_mfma_f32_16x16x32_bf16 v[114:117], v[188:191], v[196:199], v[114:117]
	v_mfma_f32_16x16x32_bf16 v[102:105], v[180:183], v[204:207], v[102:105]
	v_mfma_f32_16x16x32_bf16 v[98:101], v[188:191], v[204:207], v[98:101]
	v_mfma_f32_16x16x32_bf16 v[86:89], v[180:183], v[212:215], v[86:89]
	v_mfma_f32_16x16x32_bf16 v[82:85], v[188:191], v[212:215], v[82:85]
	v_mfma_f32_16x16x32_bf16 v[70:73], v[180:183], v[222:225], v[70:73]
	s_barrier
	v_mfma_f32_16x16x32_bf16 v[66:69], v[188:191], v[222:225], v[66:69]
	s_setprio 0
	s_add_i32 s53, s53, s12
	v_lshl_add_u64 v[152:153], v[152:153], 0, s[40:41]
	s_mov_b32 m0, s53
	ds_read_b128 v[192:195], v157 offset:49152
	ds_read_b128 v[196:199], v157 offset:50176
	ds_read_b128 v[200:203], v157 offset:51200
	ds_read_b128 v[204:207], v157 offset:52224
	ds_read_b128 v[208:211], v157 offset:53248
	ds_read_b128 v[212:215], v157 offset:54272
	ds_read_b128 v[218:221], v157 offset:55296
	ds_read_b128 v[222:225], v157 offset:56320
	global_load_lds_dwordx4 v[152:153], off
	s_add_i32 m0, s53, 0x2000
	s_add_u32 s34, s34, 0x80080
	v_lshl_add_u64 v[152:153], v[226:227], 0, s[40:41]
	s_addc_u32 s35, s35, 0
	s_add_i32 s53, s62, s12
	global_load_lds_dwordx4 v[152:153], off
	v_lshl_add_u64 v[152:153], s[34:35], 0, v[132:133]
	s_mov_b32 m0, s53
	s_nop 0
	global_load_lds_dwordx4 v[152:153], off
	v_lshl_add_u64 v[152:153], s[34:35], 0, v[136:137]
	s_add_i32 m0, s53, 0x2000
	s_nop 0
	global_load_lds_dwordx4 v[152:153], off
	v_lshl_add_u64 v[152:153], v[228:229], 0, s[40:41]
	s_mov_b32 m0, s59
	s_nop 0
	global_load_lds_dwordx4 v[152:153], off
	v_lshl_add_u64 v[152:153], v[230:231], 0, s[40:41]
	s_mov_b32 m0, s60
	s_nop 0
	global_load_lds_dwordx4 v[152:153], off
	s_waitcnt vmcnt(8)
	s_waitcnt lgkmcnt(0)
	s_barrier
	s_setprio 1
	v_mfma_f32_16x16x32_bf16 v[62:65], v[160:163], v[192:195], v[62:65]
	v_mfma_f32_16x16x32_bf16 v[58:61], v[168:171], v[192:195], v[58:61]
	v_mfma_f32_16x16x32_bf16 v[46:49], v[160:163], v[200:203], v[46:49]
	v_mfma_f32_16x16x32_bf16 v[42:45], v[168:171], v[200:203], v[42:45]
	v_mfma_f32_16x16x32_bf16 v[30:33], v[160:163], v[208:211], v[30:33]
	v_mfma_f32_16x16x32_bf16 v[26:29], v[168:171], v[208:211], v[26:29]
	v_mfma_f32_16x16x32_bf16 v[14:17], v[160:163], v[218:221], v[14:17]
	v_mfma_f32_16x16x32_bf16 v[10:13], v[168:171], v[218:221], v[10:13]
	v_mfma_f32_16x16x32_bf16 v[62:65], v[164:167], v[196:199], v[62:65]
	v_mfma_f32_16x16x32_bf16 v[58:61], v[172:175], v[196:199], v[58:61]
	v_mfma_f32_16x16x32_bf16 v[46:49], v[164:167], v[204:207], v[46:49]
	v_mfma_f32_16x16x32_bf16 v[42:45], v[172:175], v[204:207], v[42:45]
	v_mfma_f32_16x16x32_bf16 v[30:33], v[164:167], v[212:215], v[30:33]
	v_mfma_f32_16x16x32_bf16 v[26:29], v[172:175], v[212:215], v[26:29]
	v_mfma_f32_16x16x32_bf16 v[14:17], v[164:167], v[222:225], v[14:17]
	v_mfma_f32_16x16x32_bf16 v[10:13], v[172:175], v[222:225], v[10:13]
	v_mfma_f32_16x16x32_bf16 v[54:57], v[176:179], v[192:195], v[54:57]
	v_mfma_f32_16x16x32_bf16 v[50:53], v[184:187], v[192:195], v[50:53]
	v_mfma_f32_16x16x32_bf16 v[38:41], v[176:179], v[200:203], v[38:41]
	v_mfma_f32_16x16x32_bf16 v[34:37], v[184:187], v[200:203], v[34:37]
	v_mfma_f32_16x16x32_bf16 v[22:25], v[176:179], v[208:211], v[22:25]
	v_mfma_f32_16x16x32_bf16 v[18:21], v[184:187], v[208:211], v[18:21]
	v_mfma_f32_16x16x32_bf16 v[6:9], v[176:179], v[218:221], v[6:9]
	v_mfma_f32_16x16x32_bf16 v[2:5], v[184:187], v[218:221], v[2:5]
	v_mfma_f32_16x16x32_bf16 v[54:57], v[180:183], v[196:199], v[54:57]
	v_mfma_f32_16x16x32_bf16 v[50:53], v[188:191], v[196:199], v[50:53]
	v_mfma_f32_16x16x32_bf16 v[38:41], v[180:183], v[204:207], v[38:41]
	v_mfma_f32_16x16x32_bf16 v[34:37], v[188:191], v[204:207], v[34:37]
	v_mfma_f32_16x16x32_bf16 v[22:25], v[180:183], v[212:215], v[22:25]
	v_mfma_f32_16x16x32_bf16 v[18:21], v[188:191], v[212:215], v[18:21]
	v_mfma_f32_16x16x32_bf16 v[6:9], v[180:183], v[222:225], v[6:9]
	s_barrier
	v_mfma_f32_16x16x32_bf16 v[2:5], v[188:191], v[222:225], v[2:5]
	s_setprio 0
	s_add_i32 s74, s74, 2
	s_add_u32 s76, s76, 0x100
	s_addc_u32 s77, s77, 0
	s_add_u32 s36, s36, 0x100
	s_addc_u32 s52, s52, 0
	s_cmp_gt_u32 s74, 29
	s_cbranch_scc0 .LBB0_2462
	s_and_b64 vcc, exec, s[46:47]
	s_cbranch_vccz .LBB0_2465
	s_barrier

.LBB0_2629:
	ds_read_b128 v[146:149], v165
	ds_read_b128 v[150:153], v165 offset:1024
	ds_read_b128 v[168:171], v165 offset:2048
	ds_read_b128 v[172:175], v165 offset:3072
	ds_read_b128 v[176:179], v166
	ds_read_b128 v[180:183], v166 offset:1024
	ds_read_b128 v[184:187], v166 offset:2048
	ds_read_b128 v[188:191], v166 offset:3072
	s_add_u32 s34, s74, 0xfffe0080
	s_addc_u32 s35, s75, -1
	s_cmp_eq_u32 s79, 4
	s_cselect_b32 s77, s0, s35
	s_cselect_b32 s76, s1, s34
	s_cselect_b32 s35, s27, s78
	s_cselect_b32 s34, s37, s52
	v_lshl_add_u64 v[226:227], s[74:75], 0, v[138:139]
	s_add_i32 m0, s33, 0xc000
	ds_read_b128 v[192:195], v167
	ds_read_b128 v[196:199], v167 offset:1024
	ds_read_b128 v[200:203], v167 offset:2048
	ds_read_b128 v[204:207], v167 offset:3072
	ds_read_b128 v[208:211], v167 offset:4096
	ds_read_b128 v[212:215], v167 offset:5120
	ds_read_b128 v[218:221], v167 offset:6144
	ds_read_b128 v[222:225], v167 offset:7168
	global_load_lds_dwordx4 v[226:227], off
	v_lshl_add_u64 v[226:227], s[74:75], 0, v[140:141]
	s_add_i32 m0, s33, 0xe000
	s_nop 0
	global_load_lds_dwordx4 v[226:227], off
	s_waitcnt vmcnt(8)
	s_waitcnt lgkmcnt(0)
	s_barrier
	s_setprio 1
	v_mfma_f32_16x16x32_bf16 v[126:129], v[146:149], v[192:195], v[126:129]
	v_mfma_f32_16x16x32_bf16 v[122:125], v[168:171], v[192:195], v[122:125]
	v_mfma_f32_16x16x32_bf16 v[114:117], v[146:149], v[200:203], v[114:117]
	v_mfma_f32_16x16x32_bf16 v[106:109], v[168:171], v[200:203], v[106:109]
	v_mfma_f32_16x16x32_bf16 v[98:101], v[146:149], v[208:211], v[98:101]
	v_mfma_f32_16x16x32_bf16 v[90:93], v[168:171], v[208:211], v[90:93]
	v_mfma_f32_16x16x32_bf16 v[82:85], v[146:149], v[218:221], v[82:85]
	v_mfma_f32_16x16x32_bf16 v[74:77], v[168:171], v[218:221], v[74:77]
	v_mfma_f32_16x16x32_bf16 v[126:129], v[150:153], v[196:199], v[126:129]
	v_mfma_f32_16x16x32_bf16 v[122:125], v[172:175], v[196:199], v[122:125]
	v_mfma_f32_16x16x32_bf16 v[114:117], v[150:153], v[204:207], v[114:117]
	v_mfma_f32_16x16x32_bf16 v[106:109], v[172:175], v[204:207], v[106:109]
	v_mfma_f32_16x16x32_bf16 v[98:101], v[150:153], v[212:215], v[98:101]
	v_mfma_f32_16x16x32_bf16 v[90:93], v[172:175], v[212:215], v[90:93]
	v_mfma_f32_16x16x32_bf16 v[82:85], v[150:153], v[222:225], v[82:85]
	v_mfma_f32_16x16x32_bf16 v[74:77], v[172:175], v[222:225], v[74:77]
	v_mfma_f32_16x16x32_bf16 v[118:121], v[176:179], v[192:195], v[118:121]
	v_mfma_f32_16x16x32_bf16 v[110:113], v[184:187], v[192:195], v[110:113]
	v_mfma_f32_16x16x32_bf16 v[102:105], v[176:179], v[200:203], v[102:105]
	v_mfma_f32_16x16x32_bf16 v[94:97], v[184:187], v[200:203], v[94:97]
	v_mfma_f32_16x16x32_bf16 v[86:89], v[176:179], v[208:211], v[86:89]
	v_mfma_f32_16x16x32_bf16 v[78:81], v[184:187], v[208:211], v[78:81]
	v_mfma_f32_16x16x32_bf16 v[70:73], v[176:179], v[218:221], v[70:73]
	v_mfma_f32_16x16x32_bf16 v[66:69], v[184:187], v[218:221], v[66:69]
	v_mfma_f32_16x16x32_bf16 v[118:121], v[180:183], v[196:199], v[118:121]
	v_mfma_f32_16x16x32_bf16 v[110:113], v[188:191], v[196:199], v[110:113]
	v_mfma_f32_16x16x32_bf16 v[102:105], v[180:183], v[204:207], v[102:105]
	v_mfma_f32_16x16x32_bf16 v[94:97], v[188:191], v[204:207], v[94:97]
	v_mfma_f32_16x16x32_bf16 v[86:89], v[180:183], v[212:215], v[86:89]
	v_mfma_f32_16x16x32_bf16 v[78:81], v[188:191], v[212:215], v[78:81]
	v_mfma_f32_16x16x32_bf16 v[70:73], v[180:183], v[222:225], v[70:73]
	s_barrier
	v_mfma_f32_16x16x32_bf16 v[66:69], v[188:191], v[222:225], v[66:69]
	s_setprio 0
	s_add_i32 s53, s70, s12
	v_lshl_add_u64 v[226:227], s[34:35], 0, v[132:133]
	s_mov_b32 m0, s53
	ds_read_b128 v[192:195], v167 offset:16384
	ds_read_b128 v[196:199], v167 offset:17408
	ds_read_b128 v[200:203], v167 offset:18432
	ds_read_b128 v[204:207], v167 offset:19456
	ds_read_b128 v[208:211], v167 offset:20480
	ds_read_b128 v[212:215], v167 offset:21504
	ds_read_b128 v[218:221], v167 offset:22528
	ds_read_b128 v[222:225], v167 offset:23552
	global_load_lds_dwordx4 v[226:227], off
	s_add_i32 m0, s53, 0x2000
	s_add_u32 s54, s34, 0x20000
	v_lshl_add_u64 v[228:229], s[34:35], 0, v[136:137]
	s_addc_u32 s55, s35, 0
	s_add_i32 s53, s71, s12
	global_load_lds_dwordx4 v[228:229], off
	v_lshl_add_u64 v[230:231], s[54:55], 0, v[132:133]
	s_mov_b32 m0, s53
	v_lshl_add_u64 v[232:233], s[76:77], 0, v[134:135]
	global_load_lds_dwordx4 v[230:231], off
	v_lshl_add_u64 v[230:231], s[54:55], 0, v[136:137]
	s_add_i32 m0, s53, 0x2000
	s_nop 0
	global_load_lds_dwordx4 v[230:231], off
	v_lshl_add_u64 v[230:231], s[76:77], 0, v[130:131]
	s_mov_b32 m0, s33
	s_nop 0
	global_load_lds_dwordx4 v[230:231], off
	s_mov_b32 m0, s47
	s_nop 0
	global_load_lds_dwordx4 v[232:233], off
	s_waitcnt vmcnt(8)
	s_waitcnt lgkmcnt(0)
	s_barrier
	s_setprio 1
	v_mfma_f32_16x16x32_bf16 v[62:65], v[146:149], v[192:195], v[62:65]
	v_mfma_f32_16x16x32_bf16 v[58:61], v[168:171], v[192:195], v[58:61]
	v_mfma_f32_16x16x32_bf16 v[50:53], v[146:149], v[200:203], v[50:53]
	v_mfma_f32_16x16x32_bf16 v[42:45], v[168:171], v[200:203], v[42:45]
	v_mfma_f32_16x16x32_bf16 v[34:37], v[146:149], v[208:211], v[34:37]
	v_mfma_f32_16x16x32_bf16 v[26:29], v[168:171], v[208:211], v[26:29]
	v_mfma_f32_16x16x32_bf16 v[18:21], v[146:149], v[218:221], v[18:21]
	v_mfma_f32_16x16x32_bf16 v[10:13], v[168:171], v[218:221], v[10:13]
	v_mfma_f32_16x16x32_bf16 v[62:65], v[150:153], v[196:199], v[62:65]
	v_mfma_f32_16x16x32_bf16 v[58:61], v[172:175], v[196:199], v[58:61]
	v_mfma_f32_16x16x32_bf16 v[50:53], v[150:153], v[204:207], v[50:53]
	v_mfma_f32_16x16x32_bf16 v[42:45], v[172:175], v[204:207], v[42:45]
	v_mfma_f32_16x16x32_bf16 v[34:37], v[150:153], v[212:215], v[34:37]
	v_mfma_f32_16x16x32_bf16 v[26:29], v[172:175], v[212:215], v[26:29]
	v_mfma_f32_16x16x32_bf16 v[18:21], v[150:153], v[222:225], v[18:21]
	v_mfma_f32_16x16x32_bf16 v[10:13], v[172:175], v[222:225], v[10:13]
	v_mfma_f32_16x16x32_bf16 v[54:57], v[176:179], v[192:195], v[54:57]
	v_mfma_f32_16x16x32_bf16 v[46:49], v[184:187], v[192:195], v[46:49]
	v_mfma_f32_16x16x32_bf16 v[38:41], v[176:179], v[200:203], v[38:41]
	v_mfma_f32_16x16x32_bf16 v[30:33], v[184:187], v[200:203], v[30:33]
	v_mfma_f32_16x16x32_bf16 v[22:25], v[176:179], v[208:211], v[22:25]
	v_mfma_f32_16x16x32_bf16 v[14:17], v[184:187], v[208:211], v[14:17]
	v_mfma_f32_16x16x32_bf16 v[6:9], v[176:179], v[218:221], v[6:9]
	v_mfma_f32_16x16x32_bf16 v[2:5], v[184:187], v[218:221], v[2:5]
	v_mfma_f32_16x16x32_bf16 v[54:57], v[180:183], v[196:199], v[54:57]
	v_mfma_f32_16x16x32_bf16 v[46:49], v[188:191], v[196:199], v[46:49]
	v_mfma_f32_16x16x32_bf16 v[38:41], v[180:183], v[204:207], v[38:41]
	v_mfma_f32_16x16x32_bf16 v[30:33], v[188:191], v[204:207], v[30:33]
	v_mfma_f32_16x16x32_bf16 v[22:25], v[180:183], v[212:215], v[22:25]
	v_mfma_f32_16x16x32_bf16 v[14:17], v[188:191], v[212:215], v[14:17]
	v_mfma_f32_16x16x32_bf16 v[6:9], v[180:183], v[222:225], v[6:9]
	s_barrier
	v_mfma_f32_16x16x32_bf16 v[2:5], v[188:191], v[222:225], v[2:5]
	s_setprio 0
	s_add_i32 s53, 0, 0x18000
	s_add_i32 s62, 0, 0x1c000
	v_add_u32_e32 v172, s53, v162
	v_add_u32_e32 v188, s62, v162
	ds_read_b128 v[146:149], v172
	ds_read_b128 v[150:153], v172 offset:1024
	ds_read_b128 v[168:171], v172 offset:2048
	ds_read_b128 v[172:175], v172 offset:3072
	ds_read_b128 v[176:179], v188
	ds_read_b128 v[180:183], v188 offset:1024
	ds_read_b128 v[184:187], v188 offset:2048
	ds_read_b128 v[188:191], v188 offset:3072
	s_add_u32 s54, s76, 0x20000
	s_addc_u32 s55, s77, 0
	s_mov_b32 m0, s56
	v_lshl_add_u64 v[234:235], s[54:55], 0, v[130:131]
	ds_read_b128 v[192:195], v167 offset:32768
	ds_read_b128 v[196:199], v167 offset:33792
	ds_read_b128 v[200:203], v167 offset:34816
	ds_read_b128 v[204:207], v167 offset:35840
	ds_read_b128 v[208:211], v167 offset:36864
	ds_read_b128 v[212:215], v167 offset:37888
	ds_read_b128 v[218:221], v167 offset:38912
	ds_read_b128 v[222:225], v167 offset:39936
	global_load_lds_dwordx4 v[234:235], off
	v_lshl_add_u64 v[234:235], s[54:55], 0, v[134:135]
	s_mov_b32 m0, s57
	s_nop 0
	global_load_lds_dwordx4 v[234:235], off
	s_waitcnt vmcnt(8)
	s_waitcnt lgkmcnt(0)
	s_barrier
	s_setprio 1
	v_mfma_f32_16x16x32_bf16 v[126:129], v[146:149], v[192:195], v[126:129]
	v_mfma_f32_16x16x32_bf16 v[122:125], v[168:171], v[192:195], v[122:125]
	v_mfma_f32_16x16x32_bf16 v[114:117], v[146:149], v[200:203], v[114:117]
	v_mfma_f32_16x16x32_bf16 v[106:109], v[168:171], v[200:203], v[106:109]
	v_mfma_f32_16x16x32_bf16 v[98:101], v[146:149], v[208:211], v[98:101]
	v_mfma_f32_16x16x32_bf16 v[90:93], v[168:171], v[208:211], v[90:93]
	v_mfma_f32_16x16x32_bf16 v[82:85], v[146:149], v[218:221], v[82:85]
	v_mfma_f32_16x16x32_bf16 v[74:77], v[168:171], v[218:221], v[74:77]
	v_mfma_f32_16x16x32_bf16 v[126:129], v[150:153], v[196:199], v[126:129]
	v_mfma_f32_16x16x32_bf16 v[122:125], v[172:175], v[196:199], v[122:125]
	v_mfma_f32_16x16x32_bf16 v[114:117], v[150:153], v[204:207], v[114:117]
	v_mfma_f32_16x16x32_bf16 v[106:109], v[172:175], v[204:207], v[106:109]
	v_mfma_f32_16x16x32_bf16 v[98:101], v[150:153], v[212:215], v[98:101]
	v_mfma_f32_16x16x32_bf16 v[90:93], v[172:175], v[212:215], v[90:93]
	v_mfma_f32_16x16x32_bf16 v[82:85], v[150:153], v[222:225], v[82:85]
	v_mfma_f32_16x16x32_bf16 v[74:77], v[172:175], v[222:225], v[74:77]
	v_mfma_f32_16x16x32_bf16 v[118:121], v[176:179], v[192:195], v[118:121]
	v_mfma_f32_16x16x32_bf16 v[110:113], v[184:187], v[192:195], v[110:113]
	v_mfma_f32_16x16x32_bf16 v[102:105], v[176:179], v[200:203], v[102:105]
	v_mfma_f32_16x16x32_bf16 v[94:97], v[184:187], v[200:203], v[94:97]
	v_mfma_f32_16x16x32_bf16 v[86:89], v[176:179], v[208:211], v[86:89]
	v_mfma_f32_16x16x32_bf16 v[78:81], v[184:187], v[208:211], v[78:81]
	v_mfma_f32_16x16x32_bf16 v[70:73], v[176:179], v[218:221], v[70:73]
	v_mfma_f32_16x16x32_bf16 v[66:69], v[184:187], v[218:221], v[66:69]
	v_mfma_f32_16x16x32_bf16 v[118:121], v[180:183], v[196:199], v[118:121]
	v_mfma_f32_16x16x32_bf16 v[110:113], v[188:191], v[196:199], v[110:113]
	v_mfma_f32_16x16x32_bf16 v[102:105], v[180:183], v[204:207], v[102:105]
	v_mfma_f32_16x16x32_bf16 v[94:97], v[188:191], v[204:207], v[94:97]
	v_mfma_f32_16x16x32_bf16 v[86:89], v[180:183], v[212:215], v[86:89]
	v_mfma_f32_16x16x32_bf16 v[78:81], v[188:191], v[212:215], v[78:81]
	v_mfma_f32_16x16x32_bf16 v[70:73], v[180:183], v[222:225], v[70:73]
	s_barrier
	v_mfma_f32_16x16x32_bf16 v[66:69], v[188:191], v[222:225], v[66:69]
	s_setprio 0
	s_add_i32 s53, s53, s12
	v_lshl_add_u64 v[226:227], v[226:227], 0, s[8:9]
	s_mov_b32 m0, s53
	ds_read_b128 v[192:195], v167 offset:49152
	ds_read_b128 v[196:199], v167 offset:50176
	ds_read_b128 v[200:203], v167 offset:51200
	ds_read_b128 v[204:207], v167 offset:52224
	ds_read_b128 v[208:211], v167 offset:53248
	ds_read_b128 v[212:215], v167 offset:54272
	ds_read_b128 v[218:221], v167 offset:55296
	ds_read_b128 v[222:225], v167 offset:56320
	global_load_lds_dwordx4 v[226:227], off
	s_add_i32 m0, s53, 0x2000
	s_add_u32 s34, s34, 0x20080
	v_lshl_add_u64 v[226:227], v[228:229], 0, s[8:9]
	s_addc_u32 s35, s35, 0
	s_add_i32 s53, s62, s12
	global_load_lds_dwordx4 v[226:227], off
	v_lshl_add_u64 v[226:227], s[34:35], 0, v[132:133]
	s_mov_b32 m0, s53
	s_nop 0
	global_load_lds_dwordx4 v[226:227], off
	v_lshl_add_u64 v[226:227], s[34:35], 0, v[136:137]
	s_add_i32 m0, s53, 0x2000
	s_nop 0
	global_load_lds_dwordx4 v[226:227], off
	v_lshl_add_u64 v[226:227], v[230:231], 0, s[8:9]
	s_mov_b32 m0, s59
	s_nop 0
	global_load_lds_dwordx4 v[226:227], off
	v_lshl_add_u64 v[226:227], v[232:233], 0, s[8:9]
	s_mov_b32 m0, s60
	s_nop 0
	global_load_lds_dwordx4 v[226:227], off
	s_waitcnt vmcnt(8)
	s_waitcnt lgkmcnt(0)
	s_barrier
	s_setprio 1
	v_mfma_f32_16x16x32_bf16 v[62:65], v[146:149], v[192:195], v[62:65]
	v_mfma_f32_16x16x32_bf16 v[58:61], v[168:171], v[192:195], v[58:61]
	v_mfma_f32_16x16x32_bf16 v[50:53], v[146:149], v[200:203], v[50:53]
	v_mfma_f32_16x16x32_bf16 v[42:45], v[168:171], v[200:203], v[42:45]
	v_mfma_f32_16x16x32_bf16 v[34:37], v[146:149], v[208:211], v[34:37]
	v_mfma_f32_16x16x32_bf16 v[26:29], v[168:171], v[208:211], v[26:29]
	v_mfma_f32_16x16x32_bf16 v[18:21], v[146:149], v[218:221], v[18:21]
	v_mfma_f32_16x16x32_bf16 v[10:13], v[168:171], v[218:221], v[10:13]
	v_mfma_f32_16x16x32_bf16 v[62:65], v[150:153], v[196:199], v[62:65]
	v_mfma_f32_16x16x32_bf16 v[58:61], v[172:175], v[196:199], v[58:61]
	v_mfma_f32_16x16x32_bf16 v[50:53], v[150:153], v[204:207], v[50:53]
	v_mfma_f32_16x16x32_bf16 v[42:45], v[172:175], v[204:207], v[42:45]
	v_mfma_f32_16x16x32_bf16 v[34:37], v[150:153], v[212:215], v[34:37]
	v_mfma_f32_16x16x32_bf16 v[26:29], v[172:175], v[212:215], v[26:29]
	v_mfma_f32_16x16x32_bf16 v[18:21], v[150:153], v[222:225], v[18:21]
	v_mfma_f32_16x16x32_bf16 v[10:13], v[172:175], v[222:225], v[10:13]
	v_mfma_f32_16x16x32_bf16 v[54:57], v[176:179], v[192:195], v[54:57]
	v_mfma_f32_16x16x32_bf16 v[46:49], v[184:187], v[192:195], v[46:49]
	v_mfma_f32_16x16x32_bf16 v[38:41], v[176:179], v[200:203], v[38:41]
	v_mfma_f32_16x16x32_bf16 v[30:33], v[184:187], v[200:203], v[30:33]
	v_mfma_f32_16x16x32_bf16 v[22:25], v[176:179], v[208:211], v[22:25]
	v_mfma_f32_16x16x32_bf16 v[14:17], v[184:187], v[208:211], v[14:17]
	v_mfma_f32_16x16x32_bf16 v[6:9], v[176:179], v[218:221], v[6:9]
	v_mfma_f32_16x16x32_bf16 v[2:5], v[184:187], v[218:221], v[2:5]
	v_mfma_f32_16x16x32_bf16 v[54:57], v[180:183], v[196:199], v[54:57]
	v_mfma_f32_16x16x32_bf16 v[46:49], v[188:191], v[196:199], v[46:49]
	v_mfma_f32_16x16x32_bf16 v[38:41], v[180:183], v[204:207], v[38:41]
	v_mfma_f32_16x16x32_bf16 v[30:33], v[188:191], v[204:207], v[30:33]
	v_mfma_f32_16x16x32_bf16 v[22:25], v[180:183], v[212:215], v[22:25]
	v_mfma_f32_16x16x32_bf16 v[14:17], v[188:191], v[212:215], v[14:17]
	v_mfma_f32_16x16x32_bf16 v[6:9], v[180:183], v[222:225], v[6:9]
	s_barrier
	v_mfma_f32_16x16x32_bf16 v[2:5], v[188:191], v[222:225], v[2:5]
	s_setprio 0
	s_add_i32 s79, s79, 2
	s_add_u32 s74, s74, 0x100
	s_addc_u32 s75, s75, 0
	s_add_u32 s52, s52, 0x100
	s_addc_u32 s78, s78, 0
	s_cmp_gt_u32 s79, 5
	s_cbranch_scc0 .LBB0_2629
	s_and_b64 vcc, exec, s[24:25]
	s_cbranch_vccz .LBB0_2632
	s_barrier

.LBB0_2659:
	ds_read_b128 v[146:149], v1
	ds_read_b128 v[160:163], v1 offset:1024
	ds_read_b128 v[164:167], v1 offset:2048
	ds_read_b128 v[168:171], v1 offset:3072
	ds_read_b128 v[172:175], v154
	ds_read_b128 v[176:179], v154 offset:1024
	ds_read_b128 v[180:183], v154 offset:2048
	ds_read_b128 v[184:187], v154 offset:3072
	s_add_u32 s34, s74, 0xfffe0080
	s_addc_u32 s35, s75, -1
	s_cmp_eq_u32 s72, 4
	s_cselect_b32 s77, s0, s35
	s_cselect_b32 s76, s1, s34
	s_cselect_b32 s35, s27, s71
	s_cselect_b32 s34, s37, s52
	v_lshl_add_u64 v[150:151], s[74:75], 0, v[138:139]
	s_add_i32 m0, s33, 0xc000
	ds_read_b128 v[188:191], v155
	ds_read_b128 v[192:195], v155 offset:1024
	ds_read_b128 v[196:199], v155 offset:2048
	ds_read_b128 v[200:203], v155 offset:3072
	ds_read_b128 v[204:207], v155 offset:4096
	ds_read_b128 v[208:211], v155 offset:5120
	ds_read_b128 v[212:215], v155 offset:6144
	ds_read_b128 v[218:221], v155 offset:7168
	global_load_lds_dwordx4 v[150:151], off
	v_lshl_add_u64 v[150:151], s[74:75], 0, v[140:141]
	s_add_i32 m0, s33, 0xe000
	s_nop 0
	global_load_lds_dwordx4 v[150:151], off
	s_waitcnt vmcnt(8)
	s_waitcnt lgkmcnt(0)
	s_barrier
	s_setprio 1
	v_mfma_f32_16x16x32_bf16 v[126:129], v[146:149], v[188:191], v[126:129]
	v_mfma_f32_16x16x32_bf16 v[122:125], v[164:167], v[188:191], v[122:125]
	v_mfma_f32_16x16x32_bf16 v[110:113], v[146:149], v[196:199], v[110:113]
	v_mfma_f32_16x16x32_bf16 v[106:109], v[164:167], v[196:199], v[106:109]
	v_mfma_f32_16x16x32_bf16 v[94:97], v[146:149], v[204:207], v[94:97]
	v_mfma_f32_16x16x32_bf16 v[90:93], v[164:167], v[204:207], v[90:93]
	v_mfma_f32_16x16x32_bf16 v[78:81], v[146:149], v[212:215], v[78:81]
	v_mfma_f32_16x16x32_bf16 v[74:77], v[164:167], v[212:215], v[74:77]
	v_mfma_f32_16x16x32_bf16 v[126:129], v[160:163], v[192:195], v[126:129]
	v_mfma_f32_16x16x32_bf16 v[122:125], v[168:171], v[192:195], v[122:125]
	v_mfma_f32_16x16x32_bf16 v[110:113], v[160:163], v[200:203], v[110:113]
	v_mfma_f32_16x16x32_bf16 v[106:109], v[168:171], v[200:203], v[106:109]
	v_mfma_f32_16x16x32_bf16 v[94:97], v[160:163], v[208:211], v[94:97]
	v_mfma_f32_16x16x32_bf16 v[90:93], v[168:171], v[208:211], v[90:93]
	v_mfma_f32_16x16x32_bf16 v[78:81], v[160:163], v[218:221], v[78:81]
	v_mfma_f32_16x16x32_bf16 v[74:77], v[168:171], v[218:221], v[74:77]
	v_mfma_f32_16x16x32_bf16 v[118:121], v[172:175], v[188:191], v[118:121]
	v_mfma_f32_16x16x32_bf16 v[114:117], v[180:183], v[188:191], v[114:117]
	v_mfma_f32_16x16x32_bf16 v[102:105], v[172:175], v[196:199], v[102:105]
	v_mfma_f32_16x16x32_bf16 v[98:101], v[180:183], v[196:199], v[98:101]
	v_mfma_f32_16x16x32_bf16 v[86:89], v[172:175], v[204:207], v[86:89]
	v_mfma_f32_16x16x32_bf16 v[82:85], v[180:183], v[204:207], v[82:85]
	v_mfma_f32_16x16x32_bf16 v[70:73], v[172:175], v[212:215], v[70:73]
	v_mfma_f32_16x16x32_bf16 v[66:69], v[180:183], v[212:215], v[66:69]
	v_mfma_f32_16x16x32_bf16 v[118:121], v[176:179], v[192:195], v[118:121]
	v_mfma_f32_16x16x32_bf16 v[114:117], v[184:187], v[192:195], v[114:117]
	v_mfma_f32_16x16x32_bf16 v[102:105], v[176:179], v[200:203], v[102:105]
	v_mfma_f32_16x16x32_bf16 v[98:101], v[184:187], v[200:203], v[98:101]
	v_mfma_f32_16x16x32_bf16 v[86:89], v[176:179], v[208:211], v[86:89]
	v_mfma_f32_16x16x32_bf16 v[82:85], v[184:187], v[208:211], v[82:85]
	v_mfma_f32_16x16x32_bf16 v[70:73], v[176:179], v[218:221], v[70:73]
	s_barrier
	v_mfma_f32_16x16x32_bf16 v[66:69], v[184:187], v[218:221], v[66:69]
	s_setprio 0
	s_add_i32 s53, s60, s13
	v_lshl_add_u64 v[150:151], s[34:35], 0, v[132:133]
	s_mov_b32 m0, s53
	ds_read_b128 v[188:191], v155 offset:16384
	ds_read_b128 v[192:195], v155 offset:17408
	ds_read_b128 v[196:199], v155 offset:18432
	ds_read_b128 v[200:203], v155 offset:19456
	ds_read_b128 v[204:207], v155 offset:20480
	ds_read_b128 v[208:211], v155 offset:21504
	ds_read_b128 v[212:215], v155 offset:22528
	ds_read_b128 v[218:221], v155 offset:23552
	global_load_lds_dwordx4 v[150:151], off
	s_add_i32 m0, s53, 0x2000
	s_add_u32 s62, s34, 0x20000
	v_lshl_add_u64 v[222:223], s[34:35], 0, v[136:137]
	s_addc_u32 s63, s35, 0
	s_add_i32 s53, s61, s13
	global_load_lds_dwordx4 v[222:223], off
	v_lshl_add_u64 v[224:225], s[62:63], 0, v[132:133]
	s_mov_b32 m0, s53
	v_lshl_add_u64 v[226:227], s[76:77], 0, v[134:135]
	global_load_lds_dwordx4 v[224:225], off
	v_lshl_add_u64 v[224:225], s[62:63], 0, v[136:137]
	s_add_i32 m0, s53, 0x2000
	s_nop 0
	global_load_lds_dwordx4 v[224:225], off
	v_lshl_add_u64 v[224:225], s[76:77], 0, v[130:131]
	s_mov_b32 m0, s33
	s_nop 0
	global_load_lds_dwordx4 v[224:225], off
	s_mov_b32 m0, s47
	s_nop 0
	global_load_lds_dwordx4 v[226:227], off
	s_waitcnt vmcnt(8)
	s_waitcnt lgkmcnt(0)
	s_barrier
	s_setprio 1
	v_mfma_f32_16x16x32_bf16 v[62:65], v[146:149], v[188:191], v[62:65]
	v_mfma_f32_16x16x32_bf16 v[58:61], v[164:167], v[188:191], v[58:61]
	v_mfma_f32_16x16x32_bf16 v[50:53], v[146:149], v[196:199], v[50:53]
	v_mfma_f32_16x16x32_bf16 v[42:45], v[164:167], v[196:199], v[42:45]
	v_mfma_f32_16x16x32_bf16 v[34:37], v[146:149], v[204:207], v[34:37]
	v_mfma_f32_16x16x32_bf16 v[26:29], v[164:167], v[204:207], v[26:29]
	v_mfma_f32_16x16x32_bf16 v[18:21], v[146:149], v[212:215], v[18:21]
	v_mfma_f32_16x16x32_bf16 v[10:13], v[164:167], v[212:215], v[10:13]
	v_mfma_f32_16x16x32_bf16 v[62:65], v[160:163], v[192:195], v[62:65]
	v_mfma_f32_16x16x32_bf16 v[58:61], v[168:171], v[192:195], v[58:61]
	v_mfma_f32_16x16x32_bf16 v[50:53], v[160:163], v[200:203], v[50:53]
	v_mfma_f32_16x16x32_bf16 v[42:45], v[168:171], v[200:203], v[42:45]
	v_mfma_f32_16x16x32_bf16 v[34:37], v[160:163], v[208:211], v[34:37]
	v_mfma_f32_16x16x32_bf16 v[26:29], v[168:171], v[208:211], v[26:29]
	v_mfma_f32_16x16x32_bf16 v[18:21], v[160:163], v[218:221], v[18:21]
	v_mfma_f32_16x16x32_bf16 v[10:13], v[168:171], v[218:221], v[10:13]
	v_mfma_f32_16x16x32_bf16 v[54:57], v[172:175], v[188:191], v[54:57]
	v_mfma_f32_16x16x32_bf16 v[46:49], v[180:183], v[188:191], v[46:49]
	v_mfma_f32_16x16x32_bf16 v[38:41], v[172:175], v[196:199], v[38:41]
	v_mfma_f32_16x16x32_bf16 v[30:33], v[180:183], v[196:199], v[30:33]
	v_mfma_f32_16x16x32_bf16 v[22:25], v[172:175], v[204:207], v[22:25]
	v_mfma_f32_16x16x32_bf16 v[14:17], v[180:183], v[204:207], v[14:17]
	v_mfma_f32_16x16x32_bf16 v[6:9], v[172:175], v[212:215], v[6:9]
	v_mfma_f32_16x16x32_bf16 v[2:5], v[180:183], v[212:215], v[2:5]
	v_mfma_f32_16x16x32_bf16 v[54:57], v[176:179], v[192:195], v[54:57]
	v_mfma_f32_16x16x32_bf16 v[46:49], v[184:187], v[192:195], v[46:49]
	v_mfma_f32_16x16x32_bf16 v[38:41], v[176:179], v[200:203], v[38:41]
	v_mfma_f32_16x16x32_bf16 v[30:33], v[184:187], v[200:203], v[30:33]
	v_mfma_f32_16x16x32_bf16 v[22:25], v[176:179], v[208:211], v[22:25]
	v_mfma_f32_16x16x32_bf16 v[14:17], v[184:187], v[208:211], v[14:17]
	v_mfma_f32_16x16x32_bf16 v[6:9], v[176:179], v[218:221], v[6:9]
	s_barrier
	v_mfma_f32_16x16x32_bf16 v[2:5], v[184:187], v[218:221], v[2:5]
	s_setprio 0
	s_add_i32 s53, 0, 0x18000
	v_add_u32_e32 v156, s53, v153
	s_add_i32 s66, 0, 0x1c000
	ds_read_b128 v[146:149], v156
	ds_read_b128 v[160:163], v156 offset:1024
	ds_read_b128 v[164:167], v156 offset:2048
	ds_read_b128 v[168:171], v156 offset:3072
	v_add_u32_e32 v156, s66, v153
	ds_read_b128 v[172:175], v156
	ds_read_b128 v[176:179], v156 offset:1024
	ds_read_b128 v[180:183], v156 offset:2048
	ds_read_b128 v[184:187], v156 offset:3072
	s_add_u32 s62, s76, 0x20000
	s_addc_u32 s63, s77, 0
	s_mov_b32 m0, s54
	v_lshl_add_u64 v[228:229], s[62:63], 0, v[130:131]
	ds_read_b128 v[188:191], v155 offset:32768
	ds_read_b128 v[192:195], v155 offset:33792
	ds_read_b128 v[196:199], v155 offset:34816
	ds_read_b128 v[200:203], v155 offset:35840
	ds_read_b128 v[204:207], v155 offset:36864
	ds_read_b128 v[208:211], v155 offset:37888
	ds_read_b128 v[212:215], v155 offset:38912
	ds_read_b128 v[218:221], v155 offset:39936
	global_load_lds_dwordx4 v[228:229], off
	v_lshl_add_u64 v[228:229], s[62:63], 0, v[134:135]
	s_mov_b32 m0, s55
	s_nop 0
	global_load_lds_dwordx4 v[228:229], off
	s_waitcnt vmcnt(8)
	s_waitcnt lgkmcnt(0)
	s_barrier
	s_setprio 1
	v_mfma_f32_16x16x32_bf16 v[126:129], v[146:149], v[188:191], v[126:129]
	v_mfma_f32_16x16x32_bf16 v[122:125], v[164:167], v[188:191], v[122:125]
	v_mfma_f32_16x16x32_bf16 v[110:113], v[146:149], v[196:199], v[110:113]
	v_mfma_f32_16x16x32_bf16 v[106:109], v[164:167], v[196:199], v[106:109]
	v_mfma_f32_16x16x32_bf16 v[94:97], v[146:149], v[204:207], v[94:97]
	v_mfma_f32_16x16x32_bf16 v[90:93], v[164:167], v[204:207], v[90:93]
	v_mfma_f32_16x16x32_bf16 v[78:81], v[146:149], v[212:215], v[78:81]
	v_mfma_f32_16x16x32_bf16 v[74:77], v[164:167], v[212:215], v[74:77]
	v_mfma_f32_16x16x32_bf16 v[126:129], v[160:163], v[192:195], v[126:129]
	v_mfma_f32_16x16x32_bf16 v[122:125], v[168:171], v[192:195], v[122:125]
	v_mfma_f32_16x16x32_bf16 v[110:113], v[160:163], v[200:203], v[110:113]
	v_mfma_f32_16x16x32_bf16 v[106:109], v[168:171], v[200:203], v[106:109]
	v_mfma_f32_16x16x32_bf16 v[94:97], v[160:163], v[208:211], v[94:97]
	v_mfma_f32_16x16x32_bf16 v[90:93], v[168:171], v[208:211], v[90:93]
	v_mfma_f32_16x16x32_bf16 v[78:81], v[160:163], v[218:221], v[78:81]
	v_mfma_f32_16x16x32_bf16 v[74:77], v[168:171], v[218:221], v[74:77]
	v_mfma_f32_16x16x32_bf16 v[118:121], v[172:175], v[188:191], v[118:121]
	v_mfma_f32_16x16x32_bf16 v[114:117], v[180:183], v[188:191], v[114:117]
	v_mfma_f32_16x16x32_bf16 v[102:105], v[172:175], v[196:199], v[102:105]
	v_mfma_f32_16x16x32_bf16 v[98:101], v[180:183], v[196:199], v[98:101]
	v_mfma_f32_16x16x32_bf16 v[86:89], v[172:175], v[204:207], v[86:89]
	v_mfma_f32_16x16x32_bf16 v[82:85], v[180:183], v[204:207], v[82:85]
	v_mfma_f32_16x16x32_bf16 v[70:73], v[172:175], v[212:215], v[70:73]
	v_mfma_f32_16x16x32_bf16 v[66:69], v[180:183], v[212:215], v[66:69]
	v_mfma_f32_16x16x32_bf16 v[118:121], v[176:179], v[192:195], v[118:121]
	v_mfma_f32_16x16x32_bf16 v[114:117], v[184:187], v[192:195], v[114:117]
	v_mfma_f32_16x16x32_bf16 v[102:105], v[176:179], v[200:203], v[102:105]
	v_mfma_f32_16x16x32_bf16 v[98:101], v[184:187], v[200:203], v[98:101]
	v_mfma_f32_16x16x32_bf16 v[86:89], v[176:179], v[208:211], v[86:89]
	v_mfma_f32_16x16x32_bf16 v[82:85], v[184:187], v[208:211], v[82:85]
	v_mfma_f32_16x16x32_bf16 v[70:73], v[176:179], v[218:221], v[70:73]
	s_barrier
	v_mfma_f32_16x16x32_bf16 v[66:69], v[184:187], v[218:221], v[66:69]
	s_setprio 0
	s_add_i32 s53, s53, s13
	v_lshl_add_u64 v[150:151], v[150:151], 0, s[8:9]
	s_mov_b32 m0, s53
	ds_read_b128 v[188:191], v155 offset:49152
	ds_read_b128 v[192:195], v155 offset:50176
	ds_read_b128 v[196:199], v155 offset:51200
	ds_read_b128 v[200:203], v155 offset:52224
	ds_read_b128 v[204:207], v155 offset:53248
	ds_read_b128 v[208:211], v155 offset:54272
	ds_read_b128 v[212:215], v155 offset:55296
	ds_read_b128 v[218:221], v155 offset:56320
	global_load_lds_dwordx4 v[150:151], off
	s_add_i32 m0, s53, 0x2000
	s_add_u32 s34, s34, 0x20080
	v_lshl_add_u64 v[150:151], v[222:223], 0, s[8:9]
	s_addc_u32 s35, s35, 0
	s_add_i32 s53, s66, s13
	global_load_lds_dwordx4 v[150:151], off
	v_lshl_add_u64 v[150:151], s[34:35], 0, v[132:133]
	s_mov_b32 m0, s53
	s_nop 0
	global_load_lds_dwordx4 v[150:151], off
	v_lshl_add_u64 v[150:151], s[34:35], 0, v[136:137]
	s_add_i32 m0, s53, 0x2000
	s_nop 0
	global_load_lds_dwordx4 v[150:151], off
	v_lshl_add_u64 v[150:151], v[224:225], 0, s[8:9]
	s_mov_b32 m0, s57
	s_nop 0
	global_load_lds_dwordx4 v[150:151], off
	v_lshl_add_u64 v[150:151], v[226:227], 0, s[8:9]
	s_mov_b32 m0, s58
	s_nop 0
	global_load_lds_dwordx4 v[150:151], off
	s_waitcnt vmcnt(8)
	s_waitcnt lgkmcnt(0)
	s_barrier
	s_setprio 1
	v_mfma_f32_16x16x32_bf16 v[62:65], v[146:149], v[188:191], v[62:65]
	v_mfma_f32_16x16x32_bf16 v[58:61], v[164:167], v[188:191], v[58:61]
	v_mfma_f32_16x16x32_bf16 v[50:53], v[146:149], v[196:199], v[50:53]
	v_mfma_f32_16x16x32_bf16 v[42:45], v[164:167], v[196:199], v[42:45]
	v_mfma_f32_16x16x32_bf16 v[34:37], v[146:149], v[204:207], v[34:37]
	v_mfma_f32_16x16x32_bf16 v[26:29], v[164:167], v[204:207], v[26:29]
	v_mfma_f32_16x16x32_bf16 v[18:21], v[146:149], v[212:215], v[18:21]
	v_mfma_f32_16x16x32_bf16 v[10:13], v[164:167], v[212:215], v[10:13]
	v_mfma_f32_16x16x32_bf16 v[62:65], v[160:163], v[192:195], v[62:65]
	v_mfma_f32_16x16x32_bf16 v[58:61], v[168:171], v[192:195], v[58:61]
	v_mfma_f32_16x16x32_bf16 v[50:53], v[160:163], v[200:203], v[50:53]
	v_mfma_f32_16x16x32_bf16 v[42:45], v[168:171], v[200:203], v[42:45]
	v_mfma_f32_16x16x32_bf16 v[34:37], v[160:163], v[208:211], v[34:37]
	v_mfma_f32_16x16x32_bf16 v[26:29], v[168:171], v[208:211], v[26:29]
	v_mfma_f32_16x16x32_bf16 v[18:21], v[160:163], v[218:221], v[18:21]
	v_mfma_f32_16x16x32_bf16 v[10:13], v[168:171], v[218:221], v[10:13]
	v_mfma_f32_16x16x32_bf16 v[54:57], v[172:175], v[188:191], v[54:57]
	v_mfma_f32_16x16x32_bf16 v[46:49], v[180:183], v[188:191], v[46:49]
	v_mfma_f32_16x16x32_bf16 v[38:41], v[172:175], v[196:199], v[38:41]
	v_mfma_f32_16x16x32_bf16 v[30:33], v[180:183], v[196:199], v[30:33]
	v_mfma_f32_16x16x32_bf16 v[22:25], v[172:175], v[204:207], v[22:25]
	v_mfma_f32_16x16x32_bf16 v[14:17], v[180:183], v[204:207], v[14:17]
	v_mfma_f32_16x16x32_bf16 v[6:9], v[172:175], v[212:215], v[6:9]
	v_mfma_f32_16x16x32_bf16 v[2:5], v[180:183], v[212:215], v[2:5]
	v_mfma_f32_16x16x32_bf16 v[54:57], v[176:179], v[192:195], v[54:57]
	v_mfma_f32_16x16x32_bf16 v[46:49], v[184:187], v[192:195], v[46:49]
	v_mfma_f32_16x16x32_bf16 v[38:41], v[176:179], v[200:203], v[38:41]
	v_mfma_f32_16x16x32_bf16 v[30:33], v[184:187], v[200:203], v[30:33]
	v_mfma_f32_16x16x32_bf16 v[22:25], v[176:179], v[208:211], v[22:25]
	v_mfma_f32_16x16x32_bf16 v[14:17], v[184:187], v[208:211], v[14:17]
	v_mfma_f32_16x16x32_bf16 v[6:9], v[176:179], v[218:221], v[6:9]
	s_barrier
	v_mfma_f32_16x16x32_bf16 v[2:5], v[184:187], v[218:221], v[2:5]
	s_setprio 0
	s_add_i32 s72, s72, 2
	s_add_u32 s74, s74, 0x100
	s_addc_u32 s75, s75, 0
	s_add_u32 s52, s52, 0x100
	s_addc_u32 s71, s71, 0
	s_cmp_gt_u32 s72, 5
	s_cbranch_scc0 .LBB0_2659
	s_and_b64 vcc, exec, s[24:25]
	s_cbranch_vccz .LBB0_2662
	s_barrier

.LBB0_2938:
	ds_read_b128 v[130:133], v174
	ds_read_b128 v[134:137], v174 offset:1024
	ds_read_b128 v[138:141], v174 offset:2048
	ds_read_b128 v[158:161], v174 offset:3072
	ds_read_b128 v[162:165], v175
	ds_read_b128 v[166:169], v175 offset:1024
	ds_read_b128 v[178:181], v175 offset:2048
	ds_read_b128 v[182:185], v175 offset:3072
	s_add_u32 s34, s46, 0xfff80080
	s_addc_u32 s35, s47, -1
	s_cmp_eq_u32 s72, 28
	s_cselect_b32 s69, s0, s35
	s_cselect_b32 s68, s1, s34
	s_cselect_b32 s35, s37, s71
	s_cselect_b32 s34, s39, s70
	v_lshl_add_u64 v[170:171], s[46:47], 0, v[150:151]
	s_add_i32 m0, s33, 0xc000
	ds_read_b128 v[186:189], v176
	ds_read_b128 v[190:193], v176 offset:1024
	ds_read_b128 v[194:197], v176 offset:2048
	ds_read_b128 v[198:201], v176 offset:3072
	ds_read_b128 v[202:205], v176 offset:4096
	ds_read_b128 v[206:209], v176 offset:5120
	ds_read_b128 v[210:213], v176 offset:6144
	ds_read_b128 v[218:221], v176 offset:7168
	global_load_lds_dwordx4 v[170:171], off
	v_lshl_add_u64 v[170:171], s[46:47], 0, v[152:153]
	s_add_i32 m0, s33, 0xe000
	s_nop 0
	global_load_lds_dwordx4 v[170:171], off
	s_waitcnt vmcnt(8)
	s_waitcnt lgkmcnt(0)
	s_barrier
	s_setprio 1
	v_mfma_f32_16x16x32_bf16 v[126:129], v[130:133], v[186:189], v[126:129]
	v_mfma_f32_16x16x32_bf16 v[122:125], v[138:141], v[186:189], v[122:125]
	v_mfma_f32_16x16x32_bf16 v[110:113], v[130:133], v[194:197], v[110:113]
	v_mfma_f32_16x16x32_bf16 v[106:109], v[138:141], v[194:197], v[106:109]
	v_mfma_f32_16x16x32_bf16 v[94:97], v[130:133], v[202:205], v[94:97]
	v_mfma_f32_16x16x32_bf16 v[90:93], v[138:141], v[202:205], v[90:93]
	v_mfma_f32_16x16x32_bf16 v[78:81], v[130:133], v[210:213], v[78:81]
	v_mfma_f32_16x16x32_bf16 v[74:77], v[138:141], v[210:213], v[74:77]
	v_mfma_f32_16x16x32_bf16 v[126:129], v[134:137], v[190:193], v[126:129]
	v_mfma_f32_16x16x32_bf16 v[122:125], v[158:161], v[190:193], v[122:125]
	v_mfma_f32_16x16x32_bf16 v[110:113], v[134:137], v[198:201], v[110:113]
	v_mfma_f32_16x16x32_bf16 v[106:109], v[158:161], v[198:201], v[106:109]
	v_mfma_f32_16x16x32_bf16 v[94:97], v[134:137], v[206:209], v[94:97]
	v_mfma_f32_16x16x32_bf16 v[90:93], v[158:161], v[206:209], v[90:93]
	v_mfma_f32_16x16x32_bf16 v[78:81], v[134:137], v[218:221], v[78:81]
	v_mfma_f32_16x16x32_bf16 v[74:77], v[158:161], v[218:221], v[74:77]
	v_mfma_f32_16x16x32_bf16 v[118:121], v[162:165], v[186:189], v[118:121]
	v_mfma_f32_16x16x32_bf16 v[114:117], v[178:181], v[186:189], v[114:117]
	v_mfma_f32_16x16x32_bf16 v[102:105], v[162:165], v[194:197], v[102:105]
	v_mfma_f32_16x16x32_bf16 v[98:101], v[178:181], v[194:197], v[98:101]
	v_mfma_f32_16x16x32_bf16 v[86:89], v[162:165], v[202:205], v[86:89]
	v_mfma_f32_16x16x32_bf16 v[82:85], v[178:181], v[202:205], v[82:85]
	v_mfma_f32_16x16x32_bf16 v[70:73], v[162:165], v[210:213], v[70:73]
	v_mfma_f32_16x16x32_bf16 v[66:69], v[178:181], v[210:213], v[66:69]
	v_mfma_f32_16x16x32_bf16 v[118:121], v[166:169], v[190:193], v[118:121]
	v_mfma_f32_16x16x32_bf16 v[114:117], v[182:185], v[190:193], v[114:117]
	v_mfma_f32_16x16x32_bf16 v[102:105], v[166:169], v[198:201], v[102:105]
	v_mfma_f32_16x16x32_bf16 v[98:101], v[182:185], v[198:201], v[98:101]
	v_mfma_f32_16x16x32_bf16 v[86:89], v[166:169], v[206:209], v[86:89]
	v_mfma_f32_16x16x32_bf16 v[82:85], v[182:185], v[206:209], v[82:85]
	v_mfma_f32_16x16x32_bf16 v[70:73], v[166:169], v[218:221], v[70:73]
	s_barrier
	v_mfma_f32_16x16x32_bf16 v[66:69], v[182:185], v[218:221], v[66:69]
	s_setprio 0
	s_add_i32 s62, s58, s31
	v_lshl_add_u64 v[170:171], s[34:35], 0, v[144:145]
	s_mov_b32 m0, s62
	ds_read_b128 v[186:189], v176 offset:16384
	ds_read_b128 v[190:193], v176 offset:17408
	ds_read_b128 v[194:197], v176 offset:18432
	ds_read_b128 v[198:201], v176 offset:19456
	ds_read_b128 v[202:205], v176 offset:20480
	ds_read_b128 v[206:209], v176 offset:21504
	ds_read_b128 v[210:213], v176 offset:22528
	ds_read_b128 v[218:221], v176 offset:23552
	global_load_lds_dwordx4 v[170:171], off
	s_add_i32 m0, s62, 0x2000
	s_add_u32 s62, s34, 0x80000
	v_lshl_add_u64 v[214:215], s[34:35], 0, v[148:149]
	s_addc_u32 s63, s35, 0
	s_add_i32 s66, s59, s31
	global_load_lds_dwordx4 v[214:215], off
	v_lshl_add_u64 v[222:223], s[62:63], 0, v[144:145]
	s_mov_b32 m0, s66
	v_lshl_add_u64 v[224:225], s[68:69], 0, v[146:147]
	global_load_lds_dwordx4 v[222:223], off
	v_lshl_add_u64 v[222:223], s[62:63], 0, v[148:149]
	s_add_i32 m0, s66, 0x2000
	s_nop 0
	global_load_lds_dwordx4 v[222:223], off
	v_lshl_add_u64 v[222:223], s[68:69], 0, v[142:143]
	s_mov_b32 m0, s33
	s_nop 0
	global_load_lds_dwordx4 v[222:223], off
	s_mov_b32 m0, s45
	s_nop 0
	global_load_lds_dwordx4 v[224:225], off
	s_waitcnt vmcnt(8)
	s_waitcnt lgkmcnt(0)
	s_barrier
	s_setprio 1
	v_mfma_f32_16x16x32_bf16 v[62:65], v[130:133], v[186:189], v[62:65]
	v_mfma_f32_16x16x32_bf16 v[58:61], v[138:141], v[186:189], v[58:61]
	v_mfma_f32_16x16x32_bf16 v[50:53], v[130:133], v[194:197], v[50:53]
	v_mfma_f32_16x16x32_bf16 v[42:45], v[138:141], v[194:197], v[42:45]
	v_mfma_f32_16x16x32_bf16 v[38:41], v[130:133], v[202:205], v[38:41]
	v_mfma_f32_16x16x32_bf16 v[34:37], v[138:141], v[202:205], v[34:37]
	v_mfma_f32_16x16x32_bf16 v[14:17], v[130:133], v[210:213], v[14:17]
	v_mfma_f32_16x16x32_bf16 v[10:13], v[138:141], v[210:213], v[10:13]
	v_mfma_f32_16x16x32_bf16 v[62:65], v[134:137], v[190:193], v[62:65]
	v_mfma_f32_16x16x32_bf16 v[58:61], v[158:161], v[190:193], v[58:61]
	v_mfma_f32_16x16x32_bf16 v[50:53], v[134:137], v[198:201], v[50:53]
	v_mfma_f32_16x16x32_bf16 v[42:45], v[158:161], v[198:201], v[42:45]
	v_mfma_f32_16x16x32_bf16 v[38:41], v[134:137], v[206:209], v[38:41]
	v_mfma_f32_16x16x32_bf16 v[34:37], v[158:161], v[206:209], v[34:37]
	v_mfma_f32_16x16x32_bf16 v[14:17], v[134:137], v[218:221], v[14:17]
	v_mfma_f32_16x16x32_bf16 v[10:13], v[158:161], v[218:221], v[10:13]
	v_mfma_f32_16x16x32_bf16 v[54:57], v[162:165], v[186:189], v[54:57]
	v_mfma_f32_16x16x32_bf16 v[46:49], v[178:181], v[186:189], v[46:49]
	v_mfma_f32_16x16x32_bf16 v[30:33], v[162:165], v[194:197], v[30:33]
	v_mfma_f32_16x16x32_bf16 v[26:29], v[178:181], v[194:197], v[26:29]
	v_mfma_f32_16x16x32_bf16 v[22:25], v[162:165], v[202:205], v[22:25]
	v_mfma_f32_16x16x32_bf16 v[18:21], v[178:181], v[202:205], v[18:21]
	v_mfma_f32_16x16x32_bf16 v[6:9], v[162:165], v[210:213], v[6:9]
	v_mfma_f32_16x16x32_bf16 v[2:5], v[178:181], v[210:213], v[2:5]
	v_mfma_f32_16x16x32_bf16 v[54:57], v[166:169], v[190:193], v[54:57]
	v_mfma_f32_16x16x32_bf16 v[46:49], v[182:185], v[190:193], v[46:49]
	v_mfma_f32_16x16x32_bf16 v[30:33], v[166:169], v[198:201], v[30:33]
	v_mfma_f32_16x16x32_bf16 v[26:29], v[182:185], v[198:201], v[26:29]
	v_mfma_f32_16x16x32_bf16 v[22:25], v[166:169], v[206:209], v[22:25]
	v_mfma_f32_16x16x32_bf16 v[18:21], v[182:185], v[206:209], v[18:21]
	v_mfma_f32_16x16x32_bf16 v[6:9], v[166:169], v[218:221], v[6:9]
	s_barrier
	v_mfma_f32_16x16x32_bf16 v[2:5], v[182:185], v[218:221], v[2:5]
	s_setprio 0
	s_add_i32 s66, 0, 0x18000
	s_add_i32 s67, 0, 0x1c000
	v_add_u32_e32 v158, s66, v172
	v_add_u32_e32 v177, s67, v172
	ds_read_b128 v[130:133], v158
	ds_read_b128 v[134:137], v158 offset:1024
	ds_read_b128 v[138:141], v158 offset:2048
	ds_read_b128 v[158:161], v158 offset:3072
	ds_read_b128 v[162:165], v177
	ds_read_b128 v[166:169], v177 offset:1024
	ds_read_b128 v[178:181], v177 offset:2048
	ds_read_b128 v[182:185], v177 offset:3072
	s_add_u32 s62, s68, 0x80000
	s_addc_u32 s63, s69, 0
	s_mov_b32 m0, s52
	v_lshl_add_u64 v[226:227], s[62:63], 0, v[142:143]
	ds_read_b128 v[186:189], v176 offset:32768
	ds_read_b128 v[190:193], v176 offset:33792
	ds_read_b128 v[194:197], v176 offset:34816
	ds_read_b128 v[198:201], v176 offset:35840
	ds_read_b128 v[202:205], v176 offset:36864
	ds_read_b128 v[206:209], v176 offset:37888
	ds_read_b128 v[210:213], v176 offset:38912
	ds_read_b128 v[218:221], v176 offset:39936
	global_load_lds_dwordx4 v[226:227], off
	v_lshl_add_u64 v[226:227], s[62:63], 0, v[146:147]
	s_mov_b32 m0, s53
	s_nop 0
	global_load_lds_dwordx4 v[226:227], off
	s_waitcnt vmcnt(8)
	s_waitcnt lgkmcnt(0)
	s_barrier
	s_setprio 1
	v_mfma_f32_16x16x32_bf16 v[126:129], v[130:133], v[186:189], v[126:129]
	v_mfma_f32_16x16x32_bf16 v[122:125], v[138:141], v[186:189], v[122:125]
	v_mfma_f32_16x16x32_bf16 v[110:113], v[130:133], v[194:197], v[110:113]
	v_mfma_f32_16x16x32_bf16 v[106:109], v[138:141], v[194:197], v[106:109]
	v_mfma_f32_16x16x32_bf16 v[94:97], v[130:133], v[202:205], v[94:97]
	v_mfma_f32_16x16x32_bf16 v[90:93], v[138:141], v[202:205], v[90:93]
	v_mfma_f32_16x16x32_bf16 v[78:81], v[130:133], v[210:213], v[78:81]
	v_mfma_f32_16x16x32_bf16 v[74:77], v[138:141], v[210:213], v[74:77]
	v_mfma_f32_16x16x32_bf16 v[126:129], v[134:137], v[190:193], v[126:129]
	v_mfma_f32_16x16x32_bf16 v[122:125], v[158:161], v[190:193], v[122:125]
	v_mfma_f32_16x16x32_bf16 v[110:113], v[134:137], v[198:201], v[110:113]
	v_mfma_f32_16x16x32_bf16 v[106:109], v[158:161], v[198:201], v[106:109]
	v_mfma_f32_16x16x32_bf16 v[94:97], v[134:137], v[206:209], v[94:97]
	v_mfma_f32_16x16x32_bf16 v[90:93], v[158:161], v[206:209], v[90:93]
	v_mfma_f32_16x16x32_bf16 v[78:81], v[134:137], v[218:221], v[78:81]
	v_mfma_f32_16x16x32_bf16 v[74:77], v[158:161], v[218:221], v[74:77]
	v_mfma_f32_16x16x32_bf16 v[118:121], v[162:165], v[186:189], v[118:121]
	v_mfma_f32_16x16x32_bf16 v[114:117], v[178:181], v[186:189], v[114:117]
	v_mfma_f32_16x16x32_bf16 v[102:105], v[162:165], v[194:197], v[102:105]
	v_mfma_f32_16x16x32_bf16 v[98:101], v[178:181], v[194:197], v[98:101]
	v_mfma_f32_16x16x32_bf16 v[86:89], v[162:165], v[202:205], v[86:89]
	v_mfma_f32_16x16x32_bf16 v[82:85], v[178:181], v[202:205], v[82:85]
	v_mfma_f32_16x16x32_bf16 v[70:73], v[162:165], v[210:213], v[70:73]
	v_mfma_f32_16x16x32_bf16 v[66:69], v[178:181], v[210:213], v[66:69]
	v_mfma_f32_16x16x32_bf16 v[118:121], v[166:169], v[190:193], v[118:121]
	v_mfma_f32_16x16x32_bf16 v[114:117], v[182:185], v[190:193], v[114:117]
	v_mfma_f32_16x16x32_bf16 v[102:105], v[166:169], v[198:201], v[102:105]
	v_mfma_f32_16x16x32_bf16 v[98:101], v[182:185], v[198:201], v[98:101]
	v_mfma_f32_16x16x32_bf16 v[86:89], v[166:169], v[206:209], v[86:89]
	v_mfma_f32_16x16x32_bf16 v[82:85], v[182:185], v[206:209], v[82:85]
	v_mfma_f32_16x16x32_bf16 v[70:73], v[166:169], v[218:221], v[70:73]
	s_barrier
	v_mfma_f32_16x16x32_bf16 v[66:69], v[182:185], v[218:221], v[66:69]
	s_setprio 0
	s_add_i32 s62, s66, s31
	v_lshl_add_u64 v[170:171], v[170:171], 0, s[24:25]
	s_mov_b32 m0, s62
	ds_read_b128 v[186:189], v176 offset:49152
	ds_read_b128 v[190:193], v176 offset:50176
	ds_read_b128 v[194:197], v176 offset:51200
	ds_read_b128 v[198:201], v176 offset:52224
	ds_read_b128 v[202:205], v176 offset:53248
	ds_read_b128 v[206:209], v176 offset:54272
	ds_read_b128 v[210:213], v176 offset:55296
	ds_read_b128 v[218:221], v176 offset:56320
	global_load_lds_dwordx4 v[170:171], off
	s_add_i32 m0, s62, 0x2000
	s_add_u32 s34, s34, 0x80080
	v_lshl_add_u64 v[170:171], v[214:215], 0, s[24:25]
	s_addc_u32 s35, s35, 0
	s_add_i32 s62, s67, s31
	global_load_lds_dwordx4 v[170:171], off
	v_lshl_add_u64 v[170:171], s[34:35], 0, v[144:145]
	s_mov_b32 m0, s62
	s_nop 0
	global_load_lds_dwordx4 v[170:171], off
	v_lshl_add_u64 v[170:171], s[34:35], 0, v[148:149]
	s_add_i32 m0, s62, 0x2000
	s_nop 0
	global_load_lds_dwordx4 v[170:171], off
	v_lshl_add_u64 v[170:171], v[222:223], 0, s[24:25]
	s_mov_b32 m0, s55
	s_nop 0
	global_load_lds_dwordx4 v[170:171], off
	v_lshl_add_u64 v[170:171], v[224:225], 0, s[24:25]
	s_mov_b32 m0, s56
	s_nop 0
	global_load_lds_dwordx4 v[170:171], off
	s_waitcnt vmcnt(8)
	s_waitcnt lgkmcnt(0)
	s_barrier
	s_setprio 1
	v_mfma_f32_16x16x32_bf16 v[62:65], v[130:133], v[186:189], v[62:65]
	v_mfma_f32_16x16x32_bf16 v[58:61], v[138:141], v[186:189], v[58:61]
	v_mfma_f32_16x16x32_bf16 v[50:53], v[130:133], v[194:197], v[50:53]
	v_mfma_f32_16x16x32_bf16 v[42:45], v[138:141], v[194:197], v[42:45]
	v_mfma_f32_16x16x32_bf16 v[38:41], v[130:133], v[202:205], v[38:41]
	v_mfma_f32_16x16x32_bf16 v[34:37], v[138:141], v[202:205], v[34:37]
	v_mfma_f32_16x16x32_bf16 v[14:17], v[130:133], v[210:213], v[14:17]
	v_mfma_f32_16x16x32_bf16 v[10:13], v[138:141], v[210:213], v[10:13]
	v_mfma_f32_16x16x32_bf16 v[62:65], v[134:137], v[190:193], v[62:65]
	v_mfma_f32_16x16x32_bf16 v[58:61], v[158:161], v[190:193], v[58:61]
	v_mfma_f32_16x16x32_bf16 v[50:53], v[134:137], v[198:201], v[50:53]
	v_mfma_f32_16x16x32_bf16 v[42:45], v[158:161], v[198:201], v[42:45]
	v_mfma_f32_16x16x32_bf16 v[38:41], v[134:137], v[206:209], v[38:41]
	v_mfma_f32_16x16x32_bf16 v[34:37], v[158:161], v[206:209], v[34:37]
	v_mfma_f32_16x16x32_bf16 v[14:17], v[134:137], v[218:221], v[14:17]
	v_mfma_f32_16x16x32_bf16 v[10:13], v[158:161], v[218:221], v[10:13]
	v_mfma_f32_16x16x32_bf16 v[54:57], v[162:165], v[186:189], v[54:57]
	v_mfma_f32_16x16x32_bf16 v[46:49], v[178:181], v[186:189], v[46:49]
	v_mfma_f32_16x16x32_bf16 v[30:33], v[162:165], v[194:197], v[30:33]
	v_mfma_f32_16x16x32_bf16 v[26:29], v[178:181], v[194:197], v[26:29]
	v_mfma_f32_16x16x32_bf16 v[22:25], v[162:165], v[202:205], v[22:25]
	v_mfma_f32_16x16x32_bf16 v[18:21], v[178:181], v[202:205], v[18:21]
	v_mfma_f32_16x16x32_bf16 v[6:9], v[162:165], v[210:213], v[6:9]
	v_mfma_f32_16x16x32_bf16 v[2:5], v[178:181], v[210:213], v[2:5]
	v_mfma_f32_16x16x32_bf16 v[54:57], v[166:169], v[190:193], v[54:57]
	v_mfma_f32_16x16x32_bf16 v[46:49], v[182:185], v[190:193], v[46:49]
	v_mfma_f32_16x16x32_bf16 v[30:33], v[166:169], v[198:201], v[30:33]
	v_mfma_f32_16x16x32_bf16 v[26:29], v[182:185], v[198:201], v[26:29]
	v_mfma_f32_16x16x32_bf16 v[22:25], v[166:169], v[206:209], v[22:25]
	v_mfma_f32_16x16x32_bf16 v[18:21], v[182:185], v[206:209], v[18:21]
	v_mfma_f32_16x16x32_bf16 v[6:9], v[166:169], v[218:221], v[6:9]
	s_barrier
	v_mfma_f32_16x16x32_bf16 v[2:5], v[182:185], v[218:221], v[2:5]
	s_setprio 0
	s_add_i32 s72, s72, 2
	s_add_u32 s46, s46, 0x100
	s_addc_u32 s47, s47, 0
	s_add_u32 s70, s70, 0x100
	s_addc_u32 s71, s71, 0
	s_cmp_gt_u32 s72, 29
	s_cbranch_scc0 .LBB0_2938
	s_and_b64 vcc, exec, s[26:27]
	s_cbranch_vccz .LBB0_2941
	s_barrier

.LBB0_3067:
	ds_read_b128 v[146:149], v153
	ds_read_b128 v[156:159], v153 offset:1024
	ds_read_b128 v[160:163], v153 offset:2048
	ds_read_b128 v[164:167], v153 offset:3072
	ds_read_b128 v[168:171], v154
	ds_read_b128 v[172:175], v154 offset:1024
	ds_read_b128 v[176:179], v154 offset:2048
	ds_read_b128 v[180:183], v154 offset:3072
	s_add_u32 s34, s44, 0xfff80080
	s_addc_u32 s35, s45, -1
	s_cmp_eq_u32 s71, 28
	s_cselect_b32 s47, s0, s35
	s_cselect_b32 s46, s1, s34
	s_cselect_b32 s35, s27, s70
	s_cselect_b32 s34, s37, s69
	v_lshl_add_u64 v[218:219], s[44:45], 0, v[138:139]
	s_add_i32 m0, s43, 0xc000
	ds_read_b128 v[184:187], v155
	ds_read_b128 v[188:191], v155 offset:1024
	ds_read_b128 v[192:195], v155 offset:2048
	ds_read_b128 v[196:199], v155 offset:3072
	ds_read_b128 v[200:203], v155 offset:4096
	ds_read_b128 v[204:207], v155 offset:5120
	ds_read_b128 v[208:211], v155 offset:6144
	ds_read_b128 v[212:215], v155 offset:7168
	global_load_lds_dwordx4 v[218:219], off
	v_lshl_add_u64 v[218:219], s[44:45], 0, v[140:141]
	s_add_i32 m0, s43, 0xe000
	s_nop 0
	global_load_lds_dwordx4 v[218:219], off
	s_waitcnt vmcnt(8)
	s_waitcnt lgkmcnt(0)
	s_barrier
	s_setprio 1
	v_mfma_f32_16x16x32_bf16 v[126:129], v[146:149], v[184:187], v[126:129]
	v_mfma_f32_16x16x32_bf16 v[118:121], v[160:163], v[184:187], v[118:121]
	v_mfma_f32_16x16x32_bf16 v[110:113], v[146:149], v[192:195], v[110:113]
	v_mfma_f32_16x16x32_bf16 v[102:105], v[160:163], v[192:195], v[102:105]
	v_mfma_f32_16x16x32_bf16 v[94:97], v[146:149], v[200:203], v[94:97]
	v_mfma_f32_16x16x32_bf16 v[86:89], v[160:163], v[200:203], v[86:89]
	v_mfma_f32_16x16x32_bf16 v[78:81], v[146:149], v[208:211], v[78:81]
	v_mfma_f32_16x16x32_bf16 v[70:73], v[160:163], v[208:211], v[70:73]
	v_mfma_f32_16x16x32_bf16 v[126:129], v[156:159], v[188:191], v[126:129]
	v_mfma_f32_16x16x32_bf16 v[118:121], v[164:167], v[188:191], v[118:121]
	v_mfma_f32_16x16x32_bf16 v[110:113], v[156:159], v[196:199], v[110:113]
	v_mfma_f32_16x16x32_bf16 v[102:105], v[164:167], v[196:199], v[102:105]
	v_mfma_f32_16x16x32_bf16 v[94:97], v[156:159], v[204:207], v[94:97]
	v_mfma_f32_16x16x32_bf16 v[86:89], v[164:167], v[204:207], v[86:89]
	v_mfma_f32_16x16x32_bf16 v[78:81], v[156:159], v[212:215], v[78:81]
	v_mfma_f32_16x16x32_bf16 v[70:73], v[164:167], v[212:215], v[70:73]
	v_mfma_f32_16x16x32_bf16 v[122:125], v[168:171], v[184:187], v[122:125]
	v_mfma_f32_16x16x32_bf16 v[114:117], v[176:179], v[184:187], v[114:117]
	v_mfma_f32_16x16x32_bf16 v[106:109], v[168:171], v[192:195], v[106:109]
	v_mfma_f32_16x16x32_bf16 v[98:101], v[176:179], v[192:195], v[98:101]
	v_mfma_f32_16x16x32_bf16 v[90:93], v[168:171], v[200:203], v[90:93]
	v_mfma_f32_16x16x32_bf16 v[82:85], v[176:179], v[200:203], v[82:85]
	v_mfma_f32_16x16x32_bf16 v[74:77], v[168:171], v[208:211], v[74:77]
	v_mfma_f32_16x16x32_bf16 v[66:69], v[176:179], v[208:211], v[66:69]
	v_mfma_f32_16x16x32_bf16 v[122:125], v[172:175], v[188:191], v[122:125]
	v_mfma_f32_16x16x32_bf16 v[114:117], v[180:183], v[188:191], v[114:117]
	v_mfma_f32_16x16x32_bf16 v[106:109], v[172:175], v[196:199], v[106:109]
	v_mfma_f32_16x16x32_bf16 v[98:101], v[180:183], v[196:199], v[98:101]
	v_mfma_f32_16x16x32_bf16 v[90:93], v[172:175], v[204:207], v[90:93]
	v_mfma_f32_16x16x32_bf16 v[82:85], v[180:183], v[204:207], v[82:85]
	v_mfma_f32_16x16x32_bf16 v[74:77], v[172:175], v[212:215], v[74:77]
	s_barrier
	v_mfma_f32_16x16x32_bf16 v[66:69], v[180:183], v[212:215], v[66:69]
	s_setprio 0
	s_add_i32 s62, s59, s30
	v_lshl_add_u64 v[218:219], s[34:35], 0, v[134:135]
	s_mov_b32 m0, s62
	ds_read_b128 v[184:187], v155 offset:16384
	ds_read_b128 v[188:191], v155 offset:17408
	ds_read_b128 v[192:195], v155 offset:18432
	ds_read_b128 v[196:199], v155 offset:19456
	ds_read_b128 v[200:203], v155 offset:20480
	ds_read_b128 v[204:207], v155 offset:21504
	ds_read_b128 v[208:211], v155 offset:22528
	ds_read_b128 v[212:215], v155 offset:23552
	global_load_lds_dwordx4 v[218:219], off
	s_add_i32 m0, s62, 0x2000
	s_add_u32 s62, s34, 0x80000
	v_lshl_add_u64 v[220:221], s[34:35], 0, v[130:131]
	s_addc_u32 s63, s35, 0
	s_add_i32 s66, s60, s30
	global_load_lds_dwordx4 v[220:221], off
	v_lshl_add_u64 v[222:223], s[62:63], 0, v[134:135]
	s_mov_b32 m0, s66
	v_lshl_add_u64 v[224:225], s[46:47], 0, v[132:133]
	global_load_lds_dwordx4 v[222:223], off
	v_lshl_add_u64 v[222:223], s[62:63], 0, v[130:131]
	s_add_i32 m0, s66, 0x2000
	s_nop 0
	global_load_lds_dwordx4 v[222:223], off
	v_lshl_add_u64 v[222:223], s[46:47], 0, v[136:137]
	s_mov_b32 m0, s43
	s_nop 0
	global_load_lds_dwordx4 v[222:223], off
	s_mov_b32 m0, s52
	s_nop 0
	global_load_lds_dwordx4 v[224:225], off
	s_waitcnt vmcnt(8)
	s_waitcnt lgkmcnt(0)
	s_barrier
	s_setprio 1
	v_mfma_f32_16x16x32_bf16 v[62:65], v[146:149], v[184:187], v[62:65]
	v_mfma_f32_16x16x32_bf16 v[54:57], v[160:163], v[184:187], v[54:57]
	v_mfma_f32_16x16x32_bf16 v[46:49], v[146:149], v[192:195], v[46:49]
	v_mfma_f32_16x16x32_bf16 v[38:41], v[160:163], v[192:195], v[38:41]
	v_mfma_f32_16x16x32_bf16 v[30:33], v[146:149], v[200:203], v[30:33]
	v_mfma_f32_16x16x32_bf16 v[22:25], v[160:163], v[200:203], v[22:25]
	v_mfma_f32_16x16x32_bf16 v[14:17], v[146:149], v[208:211], v[14:17]
	v_mfma_f32_16x16x32_bf16 v[6:9], v[160:163], v[208:211], v[6:9]
	v_mfma_f32_16x16x32_bf16 v[62:65], v[156:159], v[188:191], v[62:65]
	v_mfma_f32_16x16x32_bf16 v[54:57], v[164:167], v[188:191], v[54:57]
	v_mfma_f32_16x16x32_bf16 v[46:49], v[156:159], v[196:199], v[46:49]
	v_mfma_f32_16x16x32_bf16 v[38:41], v[164:167], v[196:199], v[38:41]
	v_mfma_f32_16x16x32_bf16 v[30:33], v[156:159], v[204:207], v[30:33]
	v_mfma_f32_16x16x32_bf16 v[22:25], v[164:167], v[204:207], v[22:25]
	v_mfma_f32_16x16x32_bf16 v[14:17], v[156:159], v[212:215], v[14:17]
	v_mfma_f32_16x16x32_bf16 v[6:9], v[164:167], v[212:215], v[6:9]
	v_mfma_f32_16x16x32_bf16 v[58:61], v[168:171], v[184:187], v[58:61]
	v_mfma_f32_16x16x32_bf16 v[50:53], v[176:179], v[184:187], v[50:53]
	v_mfma_f32_16x16x32_bf16 v[42:45], v[168:171], v[192:195], v[42:45]
	v_mfma_f32_16x16x32_bf16 v[34:37], v[176:179], v[192:195], v[34:37]
	v_mfma_f32_16x16x32_bf16 v[26:29], v[168:171], v[200:203], v[26:29]
	v_mfma_f32_16x16x32_bf16 v[18:21], v[176:179], v[200:203], v[18:21]
	v_mfma_f32_16x16x32_bf16 v[10:13], v[168:171], v[208:211], v[10:13]
	v_mfma_f32_16x16x32_bf16 v[2:5], v[176:179], v[208:211], v[2:5]
	v_mfma_f32_16x16x32_bf16 v[58:61], v[172:175], v[188:191], v[58:61]
	v_mfma_f32_16x16x32_bf16 v[50:53], v[180:183], v[188:191], v[50:53]
	v_mfma_f32_16x16x32_bf16 v[42:45], v[172:175], v[196:199], v[42:45]
	v_mfma_f32_16x16x32_bf16 v[34:37], v[180:183], v[196:199], v[34:37]
	v_mfma_f32_16x16x32_bf16 v[26:29], v[172:175], v[204:207], v[26:29]
	v_mfma_f32_16x16x32_bf16 v[18:21], v[180:183], v[204:207], v[18:21]
	v_mfma_f32_16x16x32_bf16 v[10:13], v[172:175], v[212:215], v[10:13]
	s_barrier
	v_mfma_f32_16x16x32_bf16 v[2:5], v[180:183], v[212:215], v[2:5]
	s_setprio 0
	s_add_i32 s62, 0, 0x18000
	s_add_i32 s63, 0, 0x1c000
	v_add_u32_e32 v164, s62, v151
	v_add_u32_e32 v180, s63, v151
	ds_read_b128 v[146:149], v164
	ds_read_b128 v[156:159], v164 offset:1024
	ds_read_b128 v[160:163], v164 offset:2048
	ds_read_b128 v[164:167], v164 offset:3072
	ds_read_b128 v[168:171], v180
	ds_read_b128 v[172:175], v180 offset:1024
	ds_read_b128 v[176:179], v180 offset:2048
	ds_read_b128 v[180:183], v180 offset:3072
	s_add_u32 s46, s46, 0x80000
	s_addc_u32 s47, s47, 0
	s_mov_b32 m0, s53
	v_lshl_add_u64 v[226:227], s[46:47], 0, v[136:137]
	ds_read_b128 v[184:187], v155 offset:32768
	ds_read_b128 v[188:191], v155 offset:33792
	ds_read_b128 v[192:195], v155 offset:34816
	ds_read_b128 v[196:199], v155 offset:35840
	ds_read_b128 v[200:203], v155 offset:36864
	ds_read_b128 v[204:207], v155 offset:37888
	ds_read_b128 v[208:211], v155 offset:38912
	ds_read_b128 v[212:215], v155 offset:39936
	global_load_lds_dwordx4 v[226:227], off
	v_lshl_add_u64 v[226:227], s[46:47], 0, v[132:133]
	s_mov_b32 m0, s54
	s_nop 0
	global_load_lds_dwordx4 v[226:227], off
	s_waitcnt vmcnt(8)
	s_waitcnt lgkmcnt(0)
	s_barrier
	s_setprio 1
	v_mfma_f32_16x16x32_bf16 v[126:129], v[146:149], v[184:187], v[126:129]
	v_mfma_f32_16x16x32_bf16 v[118:121], v[160:163], v[184:187], v[118:121]
	v_mfma_f32_16x16x32_bf16 v[110:113], v[146:149], v[192:195], v[110:113]
	v_mfma_f32_16x16x32_bf16 v[102:105], v[160:163], v[192:195], v[102:105]
	v_mfma_f32_16x16x32_bf16 v[94:97], v[146:149], v[200:203], v[94:97]
	v_mfma_f32_16x16x32_bf16 v[86:89], v[160:163], v[200:203], v[86:89]
	v_mfma_f32_16x16x32_bf16 v[78:81], v[146:149], v[208:211], v[78:81]
	v_mfma_f32_16x16x32_bf16 v[70:73], v[160:163], v[208:211], v[70:73]
	v_mfma_f32_16x16x32_bf16 v[126:129], v[156:159], v[188:191], v[126:129]
	v_mfma_f32_16x16x32_bf16 v[118:121], v[164:167], v[188:191], v[118:121]
	v_mfma_f32_16x16x32_bf16 v[110:113], v[156:159], v[196:199], v[110:113]
	v_mfma_f32_16x16x32_bf16 v[102:105], v[164:167], v[196:199], v[102:105]
	v_mfma_f32_16x16x32_bf16 v[94:97], v[156:159], v[204:207], v[94:97]
	v_mfma_f32_16x16x32_bf16 v[86:89], v[164:167], v[204:207], v[86:89]
	v_mfma_f32_16x16x32_bf16 v[78:81], v[156:159], v[212:215], v[78:81]
	v_mfma_f32_16x16x32_bf16 v[70:73], v[164:167], v[212:215], v[70:73]
	v_mfma_f32_16x16x32_bf16 v[122:125], v[168:171], v[184:187], v[122:125]
	v_mfma_f32_16x16x32_bf16 v[114:117], v[176:179], v[184:187], v[114:117]
	v_mfma_f32_16x16x32_bf16 v[106:109], v[168:171], v[192:195], v[106:109]
	v_mfma_f32_16x16x32_bf16 v[98:101], v[176:179], v[192:195], v[98:101]
	v_mfma_f32_16x16x32_bf16 v[90:93], v[168:171], v[200:203], v[90:93]
	v_mfma_f32_16x16x32_bf16 v[82:85], v[176:179], v[200:203], v[82:85]
	v_mfma_f32_16x16x32_bf16 v[74:77], v[168:171], v[208:211], v[74:77]
	v_mfma_f32_16x16x32_bf16 v[66:69], v[176:179], v[208:211], v[66:69]
	v_mfma_f32_16x16x32_bf16 v[122:125], v[172:175], v[188:191], v[122:125]
	v_mfma_f32_16x16x32_bf16 v[114:117], v[180:183], v[188:191], v[114:117]
	v_mfma_f32_16x16x32_bf16 v[106:109], v[172:175], v[196:199], v[106:109]
	v_mfma_f32_16x16x32_bf16 v[98:101], v[180:183], v[196:199], v[98:101]
	v_mfma_f32_16x16x32_bf16 v[90:93], v[172:175], v[204:207], v[90:93]
	v_mfma_f32_16x16x32_bf16 v[82:85], v[180:183], v[204:207], v[82:85]
	v_mfma_f32_16x16x32_bf16 v[74:77], v[172:175], v[212:215], v[74:77]
	s_barrier
	v_mfma_f32_16x16x32_bf16 v[66:69], v[180:183], v[212:215], v[66:69]
	s_setprio 0
	s_add_i32 s46, s62, s30
	v_lshl_add_u64 v[218:219], v[218:219], 0, s[8:9]
	s_mov_b32 m0, s46
	ds_read_b128 v[184:187], v155 offset:49152
	ds_read_b128 v[188:191], v155 offset:50176
	ds_read_b128 v[192:195], v155 offset:51200
	ds_read_b128 v[196:199], v155 offset:52224
	ds_read_b128 v[200:203], v155 offset:53248
	ds_read_b128 v[204:207], v155 offset:54272
	ds_read_b128 v[208:211], v155 offset:55296
	ds_read_b128 v[212:215], v155 offset:56320
	global_load_lds_dwordx4 v[218:219], off
	s_add_i32 m0, s46, 0x2000
	s_add_u32 s34, s34, 0x80080
	v_lshl_add_u64 v[218:219], v[220:221], 0, s[8:9]
	s_addc_u32 s35, s35, 0
	s_add_i32 s46, s63, s30
	global_load_lds_dwordx4 v[218:219], off
	v_lshl_add_u64 v[218:219], s[34:35], 0, v[134:135]
	s_mov_b32 m0, s46
	s_nop 0
	global_load_lds_dwordx4 v[218:219], off
	v_lshl_add_u64 v[218:219], s[34:35], 0, v[130:131]
	s_add_i32 m0, s46, 0x2000
	s_nop 0
	global_load_lds_dwordx4 v[218:219], off
	v_lshl_add_u64 v[218:219], v[222:223], 0, s[8:9]
	s_mov_b32 m0, s56
	s_nop 0
	global_load_lds_dwordx4 v[218:219], off
	v_lshl_add_u64 v[218:219], v[224:225], 0, s[8:9]
	s_mov_b32 m0, s57
	s_nop 0
	global_load_lds_dwordx4 v[218:219], off
	s_waitcnt vmcnt(8)
	s_waitcnt lgkmcnt(0)
	s_barrier
	s_setprio 1
	v_mfma_f32_16x16x32_bf16 v[62:65], v[146:149], v[184:187], v[62:65]
	v_mfma_f32_16x16x32_bf16 v[54:57], v[160:163], v[184:187], v[54:57]
	v_mfma_f32_16x16x32_bf16 v[46:49], v[146:149], v[192:195], v[46:49]
	v_mfma_f32_16x16x32_bf16 v[38:41], v[160:163], v[192:195], v[38:41]
	v_mfma_f32_16x16x32_bf16 v[30:33], v[146:149], v[200:203], v[30:33]
	v_mfma_f32_16x16x32_bf16 v[22:25], v[160:163], v[200:203], v[22:25]
	v_mfma_f32_16x16x32_bf16 v[14:17], v[146:149], v[208:211], v[14:17]
	v_mfma_f32_16x16x32_bf16 v[6:9], v[160:163], v[208:211], v[6:9]
	v_mfma_f32_16x16x32_bf16 v[62:65], v[156:159], v[188:191], v[62:65]
	v_mfma_f32_16x16x32_bf16 v[54:57], v[164:167], v[188:191], v[54:57]
	v_mfma_f32_16x16x32_bf16 v[46:49], v[156:159], v[196:199], v[46:49]
	v_mfma_f32_16x16x32_bf16 v[38:41], v[164:167], v[196:199], v[38:41]
	v_mfma_f32_16x16x32_bf16 v[30:33], v[156:159], v[204:207], v[30:33]
	v_mfma_f32_16x16x32_bf16 v[22:25], v[164:167], v[204:207], v[22:25]
	v_mfma_f32_16x16x32_bf16 v[14:17], v[156:159], v[212:215], v[14:17]
	v_mfma_f32_16x16x32_bf16 v[6:9], v[164:167], v[212:215], v[6:9]
	v_mfma_f32_16x16x32_bf16 v[58:61], v[168:171], v[184:187], v[58:61]
	v_mfma_f32_16x16x32_bf16 v[50:53], v[176:179], v[184:187], v[50:53]
	v_mfma_f32_16x16x32_bf16 v[42:45], v[168:171], v[192:195], v[42:45]
	v_mfma_f32_16x16x32_bf16 v[34:37], v[176:179], v[192:195], v[34:37]
	v_mfma_f32_16x16x32_bf16 v[26:29], v[168:171], v[200:203], v[26:29]
	v_mfma_f32_16x16x32_bf16 v[18:21], v[176:179], v[200:203], v[18:21]
	v_mfma_f32_16x16x32_bf16 v[10:13], v[168:171], v[208:211], v[10:13]
	v_mfma_f32_16x16x32_bf16 v[2:5], v[176:179], v[208:211], v[2:5]
	v_mfma_f32_16x16x32_bf16 v[58:61], v[172:175], v[188:191], v[58:61]
	v_mfma_f32_16x16x32_bf16 v[50:53], v[180:183], v[188:191], v[50:53]
	v_mfma_f32_16x16x32_bf16 v[42:45], v[172:175], v[196:199], v[42:45]
	v_mfma_f32_16x16x32_bf16 v[34:37], v[180:183], v[196:199], v[34:37]
	v_mfma_f32_16x16x32_bf16 v[26:29], v[172:175], v[204:207], v[26:29]
	v_mfma_f32_16x16x32_bf16 v[18:21], v[180:183], v[204:207], v[18:21]
	v_mfma_f32_16x16x32_bf16 v[10:13], v[172:175], v[212:215], v[10:13]
	s_barrier
	v_mfma_f32_16x16x32_bf16 v[2:5], v[180:183], v[212:215], v[2:5]
	s_setprio 0
	s_add_i32 s71, s71, 2
	s_add_u32 s44, s44, 0x100
	s_addc_u32 s45, s45, 0
	s_add_u32 s69, s69, 0x100
	s_addc_u32 s70, s70, 0
	s_cmp_gt_u32 s71, 29
	s_cbranch_scc0 .LBB0_3067
	s_and_b64 vcc, exec, s[24:25]
	s_cbranch_vccz .LBB0_3070
	s_barrier

.LBB0_3180:
	ds_read_b128 v[130:133], v174
	ds_read_b128 v[134:137], v174 offset:1024
	ds_read_b128 v[138:141], v174 offset:2048
	ds_read_b128 v[158:161], v174 offset:3072
	ds_read_b128 v[162:165], v175
	ds_read_b128 v[166:169], v175 offset:1024
	ds_read_b128 v[178:181], v175 offset:2048
	ds_read_b128 v[182:185], v175 offset:3072
	s_add_u32 s34, s40, 0xffea0080
	s_addc_u32 s35, s41, -1
	s_cmpk_eq_i32 s60, 0x54
	s_cselect_b32 s43, s5, s35
	s_cselect_b32 s42, s4, s34
	s_cselect_b32 s35, s39, s1
	s_cselect_b32 s34, s38, s0
	v_lshl_add_u64 v[170:171], s[40:41], 0, v[150:151]
	s_add_i32 m0, s33, 0xc000
	ds_read_b128 v[186:189], v176
	ds_read_b128 v[190:193], v176 offset:1024
	ds_read_b128 v[194:197], v176 offset:2048
	ds_read_b128 v[198:201], v176 offset:3072
	ds_read_b128 v[202:205], v176 offset:4096
	ds_read_b128 v[206:209], v176 offset:5120
	ds_read_b128 v[210:213], v176 offset:6144
	ds_read_b128 v[218:221], v176 offset:7168
	global_load_lds_dwordx4 v[170:171], off
	v_lshl_add_u64 v[170:171], s[40:41], 0, v[152:153]
	s_add_i32 m0, s33, 0xe000
	s_nop 0
	global_load_lds_dwordx4 v[170:171], off
	s_waitcnt vmcnt(8)
	s_waitcnt lgkmcnt(0)
	s_barrier
	s_setprio 1
	v_mfma_f32_16x16x32_bf16 v[126:129], v[130:133], v[186:189], v[126:129]
	v_mfma_f32_16x16x32_bf16 v[122:125], v[138:141], v[186:189], v[122:125]
	v_mfma_f32_16x16x32_bf16 v[110:113], v[130:133], v[194:197], v[110:113]
	v_mfma_f32_16x16x32_bf16 v[106:109], v[138:141], v[194:197], v[106:109]
	v_mfma_f32_16x16x32_bf16 v[94:97], v[130:133], v[202:205], v[94:97]
	v_mfma_f32_16x16x32_bf16 v[90:93], v[138:141], v[202:205], v[90:93]
	v_mfma_f32_16x16x32_bf16 v[78:81], v[130:133], v[210:213], v[78:81]
	v_mfma_f32_16x16x32_bf16 v[74:77], v[138:141], v[210:213], v[74:77]
	v_mfma_f32_16x16x32_bf16 v[126:129], v[134:137], v[190:193], v[126:129]
	v_mfma_f32_16x16x32_bf16 v[122:125], v[158:161], v[190:193], v[122:125]
	v_mfma_f32_16x16x32_bf16 v[110:113], v[134:137], v[198:201], v[110:113]
	v_mfma_f32_16x16x32_bf16 v[106:109], v[158:161], v[198:201], v[106:109]
	v_mfma_f32_16x16x32_bf16 v[94:97], v[134:137], v[206:209], v[94:97]
	v_mfma_f32_16x16x32_bf16 v[90:93], v[158:161], v[206:209], v[90:93]
	v_mfma_f32_16x16x32_bf16 v[78:81], v[134:137], v[218:221], v[78:81]
	v_mfma_f32_16x16x32_bf16 v[74:77], v[158:161], v[218:221], v[74:77]
	v_mfma_f32_16x16x32_bf16 v[118:121], v[162:165], v[186:189], v[118:121]
	v_mfma_f32_16x16x32_bf16 v[114:117], v[178:181], v[186:189], v[114:117]
	v_mfma_f32_16x16x32_bf16 v[102:105], v[162:165], v[194:197], v[102:105]
	v_mfma_f32_16x16x32_bf16 v[98:101], v[178:181], v[194:197], v[98:101]
	v_mfma_f32_16x16x32_bf16 v[86:89], v[162:165], v[202:205], v[86:89]
	v_mfma_f32_16x16x32_bf16 v[82:85], v[178:181], v[202:205], v[82:85]
	v_mfma_f32_16x16x32_bf16 v[70:73], v[162:165], v[210:213], v[70:73]
	v_mfma_f32_16x16x32_bf16 v[66:69], v[178:181], v[210:213], v[66:69]
	v_mfma_f32_16x16x32_bf16 v[118:121], v[166:169], v[190:193], v[118:121]
	v_mfma_f32_16x16x32_bf16 v[114:117], v[182:185], v[190:193], v[114:117]
	v_mfma_f32_16x16x32_bf16 v[102:105], v[166:169], v[198:201], v[102:105]
	v_mfma_f32_16x16x32_bf16 v[98:101], v[182:185], v[198:201], v[98:101]
	v_mfma_f32_16x16x32_bf16 v[86:89], v[166:169], v[206:209], v[86:89]
	v_mfma_f32_16x16x32_bf16 v[82:85], v[182:185], v[206:209], v[82:85]
	v_mfma_f32_16x16x32_bf16 v[70:73], v[166:169], v[218:221], v[70:73]
	s_barrier
	v_mfma_f32_16x16x32_bf16 v[66:69], v[182:185], v[218:221], v[66:69]
	s_setprio 0
	s_add_i32 s61, s53, s31
	v_lshl_add_u64 v[170:171], s[34:35], 0, v[144:145]
	s_mov_b32 m0, s61
	ds_read_b128 v[186:189], v176 offset:16384
	ds_read_b128 v[190:193], v176 offset:17408
	ds_read_b128 v[194:197], v176 offset:18432
	ds_read_b128 v[198:201], v176 offset:19456
	ds_read_b128 v[202:205], v176 offset:20480
	ds_read_b128 v[206:209], v176 offset:21504
	ds_read_b128 v[210:213], v176 offset:22528
	ds_read_b128 v[218:221], v176 offset:23552
	global_load_lds_dwordx4 v[170:171], off
	s_add_i32 m0, s61, 0x2000
	s_add_u32 s62, s34, 0x160000
	v_lshl_add_u64 v[214:215], s[34:35], 0, v[148:149]
	s_addc_u32 s63, s35, 0
	s_add_i32 s61, s54, s31
	global_load_lds_dwordx4 v[214:215], off
	v_lshl_add_u64 v[222:223], s[62:63], 0, v[144:145]
	s_mov_b32 m0, s61
	v_lshl_add_u64 v[224:225], s[42:43], 0, v[146:147]
	global_load_lds_dwordx4 v[222:223], off
	v_lshl_add_u64 v[222:223], s[62:63], 0, v[148:149]
	s_add_i32 m0, s61, 0x2000
	s_nop 0
	global_load_lds_dwordx4 v[222:223], off
	v_lshl_add_u64 v[222:223], s[42:43], 0, v[142:143]
	s_mov_b32 m0, s33
	s_nop 0
	global_load_lds_dwordx4 v[222:223], off
	s_mov_b32 m0, s44
	s_nop 0
	global_load_lds_dwordx4 v[224:225], off
	s_waitcnt vmcnt(8)
	s_waitcnt lgkmcnt(0)
	s_barrier
	s_setprio 1
	v_mfma_f32_16x16x32_bf16 v[62:65], v[130:133], v[186:189], v[62:65]
	v_mfma_f32_16x16x32_bf16 v[58:61], v[138:141], v[186:189], v[58:61]
	v_mfma_f32_16x16x32_bf16 v[50:53], v[130:133], v[194:197], v[50:53]
	v_mfma_f32_16x16x32_bf16 v[42:45], v[138:141], v[194:197], v[42:45]
	v_mfma_f32_16x16x32_bf16 v[38:41], v[130:133], v[202:205], v[38:41]
	v_mfma_f32_16x16x32_bf16 v[34:37], v[138:141], v[202:205], v[34:37]
	v_mfma_f32_16x16x32_bf16 v[14:17], v[130:133], v[210:213], v[14:17]
	v_mfma_f32_16x16x32_bf16 v[10:13], v[138:141], v[210:213], v[10:13]
	v_mfma_f32_16x16x32_bf16 v[62:65], v[134:137], v[190:193], v[62:65]
	v_mfma_f32_16x16x32_bf16 v[58:61], v[158:161], v[190:193], v[58:61]
	v_mfma_f32_16x16x32_bf16 v[50:53], v[134:137], v[198:201], v[50:53]
	v_mfma_f32_16x16x32_bf16 v[42:45], v[158:161], v[198:201], v[42:45]
	v_mfma_f32_16x16x32_bf16 v[38:41], v[134:137], v[206:209], v[38:41]
	v_mfma_f32_16x16x32_bf16 v[34:37], v[158:161], v[206:209], v[34:37]
	v_mfma_f32_16x16x32_bf16 v[14:17], v[134:137], v[218:221], v[14:17]
	v_mfma_f32_16x16x32_bf16 v[10:13], v[158:161], v[218:221], v[10:13]
	v_mfma_f32_16x16x32_bf16 v[54:57], v[162:165], v[186:189], v[54:57]
	v_mfma_f32_16x16x32_bf16 v[46:49], v[178:181], v[186:189], v[46:49]
	v_mfma_f32_16x16x32_bf16 v[30:33], v[162:165], v[194:197], v[30:33]
	v_mfma_f32_16x16x32_bf16 v[26:29], v[178:181], v[194:197], v[26:29]
	v_mfma_f32_16x16x32_bf16 v[22:25], v[162:165], v[202:205], v[22:25]
	v_mfma_f32_16x16x32_bf16 v[18:21], v[178:181], v[202:205], v[18:21]
	v_mfma_f32_16x16x32_bf16 v[6:9], v[162:165], v[210:213], v[6:9]
	v_mfma_f32_16x16x32_bf16 v[2:5], v[178:181], v[210:213], v[2:5]
	v_mfma_f32_16x16x32_bf16 v[54:57], v[166:169], v[190:193], v[54:57]
	v_mfma_f32_16x16x32_bf16 v[46:49], v[182:185], v[190:193], v[46:49]
	v_mfma_f32_16x16x32_bf16 v[30:33], v[166:169], v[198:201], v[30:33]
	v_mfma_f32_16x16x32_bf16 v[26:29], v[182:185], v[198:201], v[26:29]
	v_mfma_f32_16x16x32_bf16 v[22:25], v[166:169], v[206:209], v[22:25]
	v_mfma_f32_16x16x32_bf16 v[18:21], v[182:185], v[206:209], v[18:21]
	v_mfma_f32_16x16x32_bf16 v[6:9], v[166:169], v[218:221], v[6:9]
	s_barrier
	v_mfma_f32_16x16x32_bf16 v[2:5], v[182:185], v[218:221], v[2:5]
	s_setprio 0
	s_add_i32 s61, 0, 0x18000
	s_add_i32 s62, 0, 0x1c000
	v_add_u32_e32 v158, s61, v172
	v_add_u32_e32 v177, s62, v172
	ds_read_b128 v[130:133], v158
	ds_read_b128 v[134:137], v158 offset:1024
	ds_read_b128 v[138:141], v158 offset:2048
	ds_read_b128 v[158:161], v158 offset:3072
	ds_read_b128 v[162:165], v177
	ds_read_b128 v[166:169], v177 offset:1024
	ds_read_b128 v[178:181], v177 offset:2048
	ds_read_b128 v[182:185], v177 offset:3072
	s_add_u32 s42, s42, 0x160000
	s_addc_u32 s43, s43, 0
	s_mov_b32 m0, s45
	v_lshl_add_u64 v[226:227], s[42:43], 0, v[142:143]
	ds_read_b128 v[186:189], v176 offset:32768
	ds_read_b128 v[190:193], v176 offset:33792
	ds_read_b128 v[194:197], v176 offset:34816
	ds_read_b128 v[198:201], v176 offset:35840
	ds_read_b128 v[202:205], v176 offset:36864
	ds_read_b128 v[206:209], v176 offset:37888
	ds_read_b128 v[210:213], v176 offset:38912
	ds_read_b128 v[218:221], v176 offset:39936
	global_load_lds_dwordx4 v[226:227], off
	v_lshl_add_u64 v[226:227], s[42:43], 0, v[146:147]
	s_mov_b32 m0, s46
	s_nop 0
	global_load_lds_dwordx4 v[226:227], off
	s_waitcnt vmcnt(8)
	s_waitcnt lgkmcnt(0)
	s_barrier
	s_setprio 1
	v_mfma_f32_16x16x32_bf16 v[126:129], v[130:133], v[186:189], v[126:129]
	v_mfma_f32_16x16x32_bf16 v[122:125], v[138:141], v[186:189], v[122:125]
	v_mfma_f32_16x16x32_bf16 v[110:113], v[130:133], v[194:197], v[110:113]
	v_mfma_f32_16x16x32_bf16 v[106:109], v[138:141], v[194:197], v[106:109]
	v_mfma_f32_16x16x32_bf16 v[94:97], v[130:133], v[202:205], v[94:97]
	v_mfma_f32_16x16x32_bf16 v[90:93], v[138:141], v[202:205], v[90:93]
	v_mfma_f32_16x16x32_bf16 v[78:81], v[130:133], v[210:213], v[78:81]
	v_mfma_f32_16x16x32_bf16 v[74:77], v[138:141], v[210:213], v[74:77]
	v_mfma_f32_16x16x32_bf16 v[126:129], v[134:137], v[190:193], v[126:129]
	v_mfma_f32_16x16x32_bf16 v[122:125], v[158:161], v[190:193], v[122:125]
	v_mfma_f32_16x16x32_bf16 v[110:113], v[134:137], v[198:201], v[110:113]
	v_mfma_f32_16x16x32_bf16 v[106:109], v[158:161], v[198:201], v[106:109]
	v_mfma_f32_16x16x32_bf16 v[94:97], v[134:137], v[206:209], v[94:97]
	v_mfma_f32_16x16x32_bf16 v[90:93], v[158:161], v[206:209], v[90:93]
	v_mfma_f32_16x16x32_bf16 v[78:81], v[134:137], v[218:221], v[78:81]
	v_mfma_f32_16x16x32_bf16 v[74:77], v[158:161], v[218:221], v[74:77]
	v_mfma_f32_16x16x32_bf16 v[118:121], v[162:165], v[186:189], v[118:121]
	v_mfma_f32_16x16x32_bf16 v[114:117], v[178:181], v[186:189], v[114:117]
	v_mfma_f32_16x16x32_bf16 v[102:105], v[162:165], v[194:197], v[102:105]
	v_mfma_f32_16x16x32_bf16 v[98:101], v[178:181], v[194:197], v[98:101]
	v_mfma_f32_16x16x32_bf16 v[86:89], v[162:165], v[202:205], v[86:89]
	v_mfma_f32_16x16x32_bf16 v[82:85], v[178:181], v[202:205], v[82:85]
	v_mfma_f32_16x16x32_bf16 v[70:73], v[162:165], v[210:213], v[70:73]
	v_mfma_f32_16x16x32_bf16 v[66:69], v[178:181], v[210:213], v[66:69]
	v_mfma_f32_16x16x32_bf16 v[118:121], v[166:169], v[190:193], v[118:121]
	v_mfma_f32_16x16x32_bf16 v[114:117], v[182:185], v[190:193], v[114:117]
	v_mfma_f32_16x16x32_bf16 v[102:105], v[166:169], v[198:201], v[102:105]
	v_mfma_f32_16x16x32_bf16 v[98:101], v[182:185], v[198:201], v[98:101]
	v_mfma_f32_16x16x32_bf16 v[86:89], v[166:169], v[206:209], v[86:89]
	v_mfma_f32_16x16x32_bf16 v[82:85], v[182:185], v[206:209], v[82:85]
	v_mfma_f32_16x16x32_bf16 v[70:73], v[166:169], v[218:221], v[70:73]
	s_barrier
	v_mfma_f32_16x16x32_bf16 v[66:69], v[182:185], v[218:221], v[66:69]
	s_setprio 0
	s_add_i32 s42, s61, s31
	v_lshl_add_u64 v[170:171], v[170:171], 0, s[24:25]
	s_mov_b32 m0, s42
	ds_read_b128 v[186:189], v176 offset:49152
	ds_read_b128 v[190:193], v176 offset:50176
	ds_read_b128 v[194:197], v176 offset:51200
	ds_read_b128 v[198:201], v176 offset:52224
	ds_read_b128 v[202:205], v176 offset:53248
	ds_read_b128 v[206:209], v176 offset:54272
	ds_read_b128 v[210:213], v176 offset:55296
	ds_read_b128 v[218:221], v176 offset:56320
	global_load_lds_dwordx4 v[170:171], off
	s_add_i32 m0, s42, 0x2000
	s_add_u32 s34, s34, 0x160080
	v_lshl_add_u64 v[170:171], v[214:215], 0, s[24:25]
	s_addc_u32 s35, s35, 0
	s_add_i32 s42, s62, s31
	global_load_lds_dwordx4 v[170:171], off
	v_lshl_add_u64 v[170:171], s[34:35], 0, v[144:145]
	s_mov_b32 m0, s42
	s_nop 0
	global_load_lds_dwordx4 v[170:171], off
	v_lshl_add_u64 v[170:171], s[34:35], 0, v[148:149]
	s_add_i32 m0, s42, 0x2000
	s_nop 0
	global_load_lds_dwordx4 v[170:171], off
	v_lshl_add_u64 v[170:171], v[222:223], 0, s[24:25]
	s_mov_b32 m0, s48
	s_nop 0
	global_load_lds_dwordx4 v[170:171], off
	v_lshl_add_u64 v[170:171], v[224:225], 0, s[24:25]
	s_mov_b32 m0, s49
	s_nop 0
	global_load_lds_dwordx4 v[170:171], off
	s_waitcnt vmcnt(8)
	s_waitcnt lgkmcnt(0)
	s_barrier
	s_setprio 1
	v_mfma_f32_16x16x32_bf16 v[62:65], v[130:133], v[186:189], v[62:65]
	v_mfma_f32_16x16x32_bf16 v[58:61], v[138:141], v[186:189], v[58:61]
	v_mfma_f32_16x16x32_bf16 v[50:53], v[130:133], v[194:197], v[50:53]
	v_mfma_f32_16x16x32_bf16 v[42:45], v[138:141], v[194:197], v[42:45]
	v_mfma_f32_16x16x32_bf16 v[38:41], v[130:133], v[202:205], v[38:41]
	v_mfma_f32_16x16x32_bf16 v[34:37], v[138:141], v[202:205], v[34:37]
	v_mfma_f32_16x16x32_bf16 v[14:17], v[130:133], v[210:213], v[14:17]
	v_mfma_f32_16x16x32_bf16 v[10:13], v[138:141], v[210:213], v[10:13]
	v_mfma_f32_16x16x32_bf16 v[62:65], v[134:137], v[190:193], v[62:65]
	v_mfma_f32_16x16x32_bf16 v[58:61], v[158:161], v[190:193], v[58:61]
	v_mfma_f32_16x16x32_bf16 v[50:53], v[134:137], v[198:201], v[50:53]
	v_mfma_f32_16x16x32_bf16 v[42:45], v[158:161], v[198:201], v[42:45]
	v_mfma_f32_16x16x32_bf16 v[38:41], v[134:137], v[206:209], v[38:41]
	v_mfma_f32_16x16x32_bf16 v[34:37], v[158:161], v[206:209], v[34:37]
	v_mfma_f32_16x16x32_bf16 v[14:17], v[134:137], v[218:221], v[14:17]
	v_mfma_f32_16x16x32_bf16 v[10:13], v[158:161], v[218:221], v[10:13]
	v_mfma_f32_16x16x32_bf16 v[54:57], v[162:165], v[186:189], v[54:57]
	v_mfma_f32_16x16x32_bf16 v[46:49], v[178:181], v[186:189], v[46:49]
	v_mfma_f32_16x16x32_bf16 v[30:33], v[162:165], v[194:197], v[30:33]
	v_mfma_f32_16x16x32_bf16 v[26:29], v[178:181], v[194:197], v[26:29]
	v_mfma_f32_16x16x32_bf16 v[22:25], v[162:165], v[202:205], v[22:25]
	v_mfma_f32_16x16x32_bf16 v[18:21], v[178:181], v[202:205], v[18:21]
	v_mfma_f32_16x16x32_bf16 v[6:9], v[162:165], v[210:213], v[6:9]
	v_mfma_f32_16x16x32_bf16 v[2:5], v[178:181], v[210:213], v[2:5]
	v_mfma_f32_16x16x32_bf16 v[54:57], v[166:169], v[190:193], v[54:57]
	v_mfma_f32_16x16x32_bf16 v[46:49], v[182:185], v[190:193], v[46:49]
	v_mfma_f32_16x16x32_bf16 v[30:33], v[166:169], v[198:201], v[30:33]
	v_mfma_f32_16x16x32_bf16 v[26:29], v[182:185], v[198:201], v[26:29]
	v_mfma_f32_16x16x32_bf16 v[22:25], v[166:169], v[206:209], v[22:25]
	v_mfma_f32_16x16x32_bf16 v[18:21], v[182:185], v[206:209], v[18:21]
	v_mfma_f32_16x16x32_bf16 v[6:9], v[166:169], v[218:221], v[6:9]
	s_barrier
	v_mfma_f32_16x16x32_bf16 v[2:5], v[182:185], v[218:221], v[2:5]
	s_setprio 0
	s_add_i32 s60, s60, 2
	s_add_u32 s40, s40, 0x100
	s_addc_u32 s41, s41, 0
	s_add_u32 s0, s0, 0x100
	s_addc_u32 s1, s1, 0
	s_cmpk_gt_u32 s60, 0x55
	s_cbranch_scc0 .LBB0_3180
	s_and_b64 vcc, exec, s[26:27]
	s_cbranch_vccz .LBB0_3183
	s_barrier

.LBB0_3309:
	ds_read_b128 v[146:149], v153
	ds_read_b128 v[156:159], v153 offset:1024
	ds_read_b128 v[160:163], v153 offset:2048
	ds_read_b128 v[164:167], v153 offset:3072
	ds_read_b128 v[168:171], v154
	ds_read_b128 v[172:175], v154 offset:1024
	ds_read_b128 v[176:179], v154 offset:2048
	ds_read_b128 v[180:183], v154 offset:3072
	s_add_u32 s34, s44, 0xfff80080
	s_addc_u32 s35, s45, -1
	s_cmp_eq_u32 s69, 28
	s_cselect_b32 s47, s0, s35
	s_cselect_b32 s46, s1, s34
	s_cselect_b32 s35, s27, s68
	s_cselect_b32 s34, s37, s61
	v_lshl_add_u64 v[218:219], s[44:45], 0, v[138:139]
	s_add_i32 m0, s43, 0xc000
	ds_read_b128 v[184:187], v155
	ds_read_b128 v[188:191], v155 offset:1024
	ds_read_b128 v[192:195], v155 offset:2048
	ds_read_b128 v[196:199], v155 offset:3072
	ds_read_b128 v[200:203], v155 offset:4096
	ds_read_b128 v[204:207], v155 offset:5120
	ds_read_b128 v[208:211], v155 offset:6144
	ds_read_b128 v[212:215], v155 offset:7168
	global_load_lds_dwordx4 v[218:219], off
	v_lshl_add_u64 v[218:219], s[44:45], 0, v[140:141]
	s_add_i32 m0, s43, 0xe000
	s_nop 0
	global_load_lds_dwordx4 v[218:219], off
	s_waitcnt vmcnt(8)
	s_waitcnt lgkmcnt(0)
	s_barrier
	s_setprio 1
	v_mfma_f32_16x16x32_bf16 v[126:129], v[146:149], v[184:187], v[126:129]
	v_mfma_f32_16x16x32_bf16 v[118:121], v[160:163], v[184:187], v[118:121]
	v_mfma_f32_16x16x32_bf16 v[110:113], v[146:149], v[192:195], v[110:113]
	v_mfma_f32_16x16x32_bf16 v[102:105], v[160:163], v[192:195], v[102:105]
	v_mfma_f32_16x16x32_bf16 v[94:97], v[146:149], v[200:203], v[94:97]
	v_mfma_f32_16x16x32_bf16 v[86:89], v[160:163], v[200:203], v[86:89]
	v_mfma_f32_16x16x32_bf16 v[78:81], v[146:149], v[208:211], v[78:81]
	v_mfma_f32_16x16x32_bf16 v[70:73], v[160:163], v[208:211], v[70:73]
	v_mfma_f32_16x16x32_bf16 v[126:129], v[156:159], v[188:191], v[126:129]
	v_mfma_f32_16x16x32_bf16 v[118:121], v[164:167], v[188:191], v[118:121]
	v_mfma_f32_16x16x32_bf16 v[110:113], v[156:159], v[196:199], v[110:113]
	v_mfma_f32_16x16x32_bf16 v[102:105], v[164:167], v[196:199], v[102:105]
	v_mfma_f32_16x16x32_bf16 v[94:97], v[156:159], v[204:207], v[94:97]
	v_mfma_f32_16x16x32_bf16 v[86:89], v[164:167], v[204:207], v[86:89]
	v_mfma_f32_16x16x32_bf16 v[78:81], v[156:159], v[212:215], v[78:81]
	v_mfma_f32_16x16x32_bf16 v[70:73], v[164:167], v[212:215], v[70:73]
	v_mfma_f32_16x16x32_bf16 v[122:125], v[168:171], v[184:187], v[122:125]
	v_mfma_f32_16x16x32_bf16 v[114:117], v[176:179], v[184:187], v[114:117]
	v_mfma_f32_16x16x32_bf16 v[106:109], v[168:171], v[192:195], v[106:109]
	v_mfma_f32_16x16x32_bf16 v[98:101], v[176:179], v[192:195], v[98:101]
	v_mfma_f32_16x16x32_bf16 v[90:93], v[168:171], v[200:203], v[90:93]
	v_mfma_f32_16x16x32_bf16 v[82:85], v[176:179], v[200:203], v[82:85]
	v_mfma_f32_16x16x32_bf16 v[74:77], v[168:171], v[208:211], v[74:77]
	v_mfma_f32_16x16x32_bf16 v[66:69], v[176:179], v[208:211], v[66:69]
	v_mfma_f32_16x16x32_bf16 v[122:125], v[172:175], v[188:191], v[122:125]
	v_mfma_f32_16x16x32_bf16 v[114:117], v[180:183], v[188:191], v[114:117]
	v_mfma_f32_16x16x32_bf16 v[106:109], v[172:175], v[196:199], v[106:109]
	v_mfma_f32_16x16x32_bf16 v[98:101], v[180:183], v[196:199], v[98:101]
	v_mfma_f32_16x16x32_bf16 v[90:93], v[172:175], v[204:207], v[90:93]
	v_mfma_f32_16x16x32_bf16 v[82:85], v[180:183], v[204:207], v[82:85]
	v_mfma_f32_16x16x32_bf16 v[74:77], v[172:175], v[212:215], v[74:77]
	s_barrier
	v_mfma_f32_16x16x32_bf16 v[66:69], v[180:183], v[212:215], v[66:69]
	s_setprio 0
	s_add_i32 s62, s57, s30
	v_lshl_add_u64 v[218:219], s[34:35], 0, v[134:135]
	s_mov_b32 m0, s62
	ds_read_b128 v[184:187], v155 offset:16384
	ds_read_b128 v[188:191], v155 offset:17408
	ds_read_b128 v[192:195], v155 offset:18432
	ds_read_b128 v[196:199], v155 offset:19456
	ds_read_b128 v[200:203], v155 offset:20480
	ds_read_b128 v[204:207], v155 offset:21504
	ds_read_b128 v[208:211], v155 offset:22528
	ds_read_b128 v[212:215], v155 offset:23552
	global_load_lds_dwordx4 v[218:219], off
	s_add_i32 m0, s62, 0x2000
	s_add_u32 s62, s34, 0x80000
	v_lshl_add_u64 v[220:221], s[34:35], 0, v[130:131]
	s_addc_u32 s63, s35, 0
	s_add_i32 s66, s58, s30
	global_load_lds_dwordx4 v[220:221], off
	v_lshl_add_u64 v[222:223], s[62:63], 0, v[134:135]
	s_mov_b32 m0, s66
	v_lshl_add_u64 v[224:225], s[46:47], 0, v[132:133]
	global_load_lds_dwordx4 v[222:223], off
	v_lshl_add_u64 v[222:223], s[62:63], 0, v[130:131]
	s_add_i32 m0, s66, 0x2000
	s_nop 0
	global_load_lds_dwordx4 v[222:223], off
	v_lshl_add_u64 v[222:223], s[46:47], 0, v[136:137]
	s_mov_b32 m0, s43
	s_nop 0
	global_load_lds_dwordx4 v[222:223], off
	s_mov_b32 m0, s48
	s_nop 0
	global_load_lds_dwordx4 v[224:225], off
	s_waitcnt vmcnt(8)
	s_waitcnt lgkmcnt(0)
	s_barrier
	s_setprio 1
	v_mfma_f32_16x16x32_bf16 v[62:65], v[146:149], v[184:187], v[62:65]
	v_mfma_f32_16x16x32_bf16 v[54:57], v[160:163], v[184:187], v[54:57]
	v_mfma_f32_16x16x32_bf16 v[46:49], v[146:149], v[192:195], v[46:49]
	v_mfma_f32_16x16x32_bf16 v[38:41], v[160:163], v[192:195], v[38:41]
	v_mfma_f32_16x16x32_bf16 v[30:33], v[146:149], v[200:203], v[30:33]
	v_mfma_f32_16x16x32_bf16 v[22:25], v[160:163], v[200:203], v[22:25]
	v_mfma_f32_16x16x32_bf16 v[14:17], v[146:149], v[208:211], v[14:17]
	v_mfma_f32_16x16x32_bf16 v[6:9], v[160:163], v[208:211], v[6:9]
	v_mfma_f32_16x16x32_bf16 v[62:65], v[156:159], v[188:191], v[62:65]
	v_mfma_f32_16x16x32_bf16 v[54:57], v[164:167], v[188:191], v[54:57]
	v_mfma_f32_16x16x32_bf16 v[46:49], v[156:159], v[196:199], v[46:49]
	v_mfma_f32_16x16x32_bf16 v[38:41], v[164:167], v[196:199], v[38:41]
	v_mfma_f32_16x16x32_bf16 v[30:33], v[156:159], v[204:207], v[30:33]
	v_mfma_f32_16x16x32_bf16 v[22:25], v[164:167], v[204:207], v[22:25]
	v_mfma_f32_16x16x32_bf16 v[14:17], v[156:159], v[212:215], v[14:17]
	v_mfma_f32_16x16x32_bf16 v[6:9], v[164:167], v[212:215], v[6:9]
	v_mfma_f32_16x16x32_bf16 v[58:61], v[168:171], v[184:187], v[58:61]
	v_mfma_f32_16x16x32_bf16 v[50:53], v[176:179], v[184:187], v[50:53]
	v_mfma_f32_16x16x32_bf16 v[42:45], v[168:171], v[192:195], v[42:45]
	v_mfma_f32_16x16x32_bf16 v[34:37], v[176:179], v[192:195], v[34:37]
	v_mfma_f32_16x16x32_bf16 v[26:29], v[168:171], v[200:203], v[26:29]
	v_mfma_f32_16x16x32_bf16 v[18:21], v[176:179], v[200:203], v[18:21]
	v_mfma_f32_16x16x32_bf16 v[10:13], v[168:171], v[208:211], v[10:13]
	v_mfma_f32_16x16x32_bf16 v[2:5], v[176:179], v[208:211], v[2:5]
	v_mfma_f32_16x16x32_bf16 v[58:61], v[172:175], v[188:191], v[58:61]
	v_mfma_f32_16x16x32_bf16 v[50:53], v[180:183], v[188:191], v[50:53]
	v_mfma_f32_16x16x32_bf16 v[42:45], v[172:175], v[196:199], v[42:45]
	v_mfma_f32_16x16x32_bf16 v[34:37], v[180:183], v[196:199], v[34:37]
	v_mfma_f32_16x16x32_bf16 v[26:29], v[172:175], v[204:207], v[26:29]
	v_mfma_f32_16x16x32_bf16 v[18:21], v[180:183], v[204:207], v[18:21]
	v_mfma_f32_16x16x32_bf16 v[10:13], v[172:175], v[212:215], v[10:13]
	s_barrier
	v_mfma_f32_16x16x32_bf16 v[2:5], v[180:183], v[212:215], v[2:5]
	s_setprio 0
	s_add_i32 s62, 0, 0x18000
	s_add_i32 s63, 0, 0x1c000
	v_add_u32_e32 v164, s62, v151
	v_add_u32_e32 v180, s63, v151
	ds_read_b128 v[146:149], v164
	ds_read_b128 v[156:159], v164 offset:1024
	ds_read_b128 v[160:163], v164 offset:2048
	ds_read_b128 v[164:167], v164 offset:3072
	ds_read_b128 v[168:171], v180
	ds_read_b128 v[172:175], v180 offset:1024
	ds_read_b128 v[176:179], v180 offset:2048
	ds_read_b128 v[180:183], v180 offset:3072
	s_add_u32 s46, s46, 0x80000
	s_addc_u32 s47, s47, 0
	s_mov_b32 m0, s49
	v_lshl_add_u64 v[226:227], s[46:47], 0, v[136:137]
	ds_read_b128 v[184:187], v155 offset:32768
	ds_read_b128 v[188:191], v155 offset:33792
	ds_read_b128 v[192:195], v155 offset:34816
	ds_read_b128 v[196:199], v155 offset:35840
	ds_read_b128 v[200:203], v155 offset:36864
	ds_read_b128 v[204:207], v155 offset:37888
	ds_read_b128 v[208:211], v155 offset:38912
	ds_read_b128 v[212:215], v155 offset:39936
	global_load_lds_dwordx4 v[226:227], off
	v_lshl_add_u64 v[226:227], s[46:47], 0, v[132:133]
	s_mov_b32 m0, s52
	s_nop 0
	global_load_lds_dwordx4 v[226:227], off
	s_waitcnt vmcnt(8)
	s_waitcnt lgkmcnt(0)
	s_barrier
	s_setprio 1
	v_mfma_f32_16x16x32_bf16 v[126:129], v[146:149], v[184:187], v[126:129]
	v_mfma_f32_16x16x32_bf16 v[118:121], v[160:163], v[184:187], v[118:121]
	v_mfma_f32_16x16x32_bf16 v[110:113], v[146:149], v[192:195], v[110:113]
	v_mfma_f32_16x16x32_bf16 v[102:105], v[160:163], v[192:195], v[102:105]
	v_mfma_f32_16x16x32_bf16 v[94:97], v[146:149], v[200:203], v[94:97]
	v_mfma_f32_16x16x32_bf16 v[86:89], v[160:163], v[200:203], v[86:89]
	v_mfma_f32_16x16x32_bf16 v[78:81], v[146:149], v[208:211], v[78:81]
	v_mfma_f32_16x16x32_bf16 v[70:73], v[160:163], v[208:211], v[70:73]
	v_mfma_f32_16x16x32_bf16 v[126:129], v[156:159], v[188:191], v[126:129]
	v_mfma_f32_16x16x32_bf16 v[118:121], v[164:167], v[188:191], v[118:121]
	v_mfma_f32_16x16x32_bf16 v[110:113], v[156:159], v[196:199], v[110:113]
	v_mfma_f32_16x16x32_bf16 v[102:105], v[164:167], v[196:199], v[102:105]
	v_mfma_f32_16x16x32_bf16 v[94:97], v[156:159], v[204:207], v[94:97]
	v_mfma_f32_16x16x32_bf16 v[86:89], v[164:167], v[204:207], v[86:89]
	v_mfma_f32_16x16x32_bf16 v[78:81], v[156:159], v[212:215], v[78:81]
	v_mfma_f32_16x16x32_bf16 v[70:73], v[164:167], v[212:215], v[70:73]
	v_mfma_f32_16x16x32_bf16 v[122:125], v[168:171], v[184:187], v[122:125]
	v_mfma_f32_16x16x32_bf16 v[114:117], v[176:179], v[184:187], v[114:117]
	v_mfma_f32_16x16x32_bf16 v[106:109], v[168:171], v[192:195], v[106:109]
	v_mfma_f32_16x16x32_bf16 v[98:101], v[176:179], v[192:195], v[98:101]
	v_mfma_f32_16x16x32_bf16 v[90:93], v[168:171], v[200:203], v[90:93]
	v_mfma_f32_16x16x32_bf16 v[82:85], v[176:179], v[200:203], v[82:85]
	v_mfma_f32_16x16x32_bf16 v[74:77], v[168:171], v[208:211], v[74:77]
	v_mfma_f32_16x16x32_bf16 v[66:69], v[176:179], v[208:211], v[66:69]
	v_mfma_f32_16x16x32_bf16 v[122:125], v[172:175], v[188:191], v[122:125]
	v_mfma_f32_16x16x32_bf16 v[114:117], v[180:183], v[188:191], v[114:117]
	v_mfma_f32_16x16x32_bf16 v[106:109], v[172:175], v[196:199], v[106:109]
	v_mfma_f32_16x16x32_bf16 v[98:101], v[180:183], v[196:199], v[98:101]
	v_mfma_f32_16x16x32_bf16 v[90:93], v[172:175], v[204:207], v[90:93]
	v_mfma_f32_16x16x32_bf16 v[82:85], v[180:183], v[204:207], v[82:85]
	v_mfma_f32_16x16x32_bf16 v[74:77], v[172:175], v[212:215], v[74:77]
	s_barrier
	v_mfma_f32_16x16x32_bf16 v[66:69], v[180:183], v[212:215], v[66:69]
	s_setprio 0
	s_add_i32 s46, s62, s30
	v_lshl_add_u64 v[218:219], v[218:219], 0, s[8:9]
	s_mov_b32 m0, s46
	ds_read_b128 v[184:187], v155 offset:49152
	ds_read_b128 v[188:191], v155 offset:50176
	ds_read_b128 v[192:195], v155 offset:51200
	ds_read_b128 v[196:199], v155 offset:52224
	ds_read_b128 v[200:203], v155 offset:53248
	ds_read_b128 v[204:207], v155 offset:54272
	ds_read_b128 v[208:211], v155 offset:55296
	ds_read_b128 v[212:215], v155 offset:56320
	global_load_lds_dwordx4 v[218:219], off
	s_add_i32 m0, s46, 0x2000
	s_add_u32 s34, s34, 0x80080
	v_lshl_add_u64 v[218:219], v[220:221], 0, s[8:9]
	s_addc_u32 s35, s35, 0
	s_add_i32 s46, s63, s30
	global_load_lds_dwordx4 v[218:219], off
	v_lshl_add_u64 v[218:219], s[34:35], 0, v[134:135]
	s_mov_b32 m0, s46
	s_nop 0
	global_load_lds_dwordx4 v[218:219], off
	v_lshl_add_u64 v[218:219], s[34:35], 0, v[130:131]
	s_add_i32 m0, s46, 0x2000
	s_nop 0
	global_load_lds_dwordx4 v[218:219], off
	v_lshl_add_u64 v[218:219], v[222:223], 0, s[8:9]
	s_mov_b32 m0, s54
	s_nop 0
	global_load_lds_dwordx4 v[218:219], off
	v_lshl_add_u64 v[218:219], v[224:225], 0, s[8:9]
	s_mov_b32 m0, s55
	s_nop 0
	global_load_lds_dwordx4 v[218:219], off
	s_waitcnt vmcnt(8)
	s_waitcnt lgkmcnt(0)
	s_barrier
	s_setprio 1
	v_mfma_f32_16x16x32_bf16 v[62:65], v[146:149], v[184:187], v[62:65]
	v_mfma_f32_16x16x32_bf16 v[54:57], v[160:163], v[184:187], v[54:57]
	v_mfma_f32_16x16x32_bf16 v[46:49], v[146:149], v[192:195], v[46:49]
	v_mfma_f32_16x16x32_bf16 v[38:41], v[160:163], v[192:195], v[38:41]
	v_mfma_f32_16x16x32_bf16 v[30:33], v[146:149], v[200:203], v[30:33]
	v_mfma_f32_16x16x32_bf16 v[22:25], v[160:163], v[200:203], v[22:25]
	v_mfma_f32_16x16x32_bf16 v[14:17], v[146:149], v[208:211], v[14:17]
	v_mfma_f32_16x16x32_bf16 v[6:9], v[160:163], v[208:211], v[6:9]
	v_mfma_f32_16x16x32_bf16 v[62:65], v[156:159], v[188:191], v[62:65]
	v_mfma_f32_16x16x32_bf16 v[54:57], v[164:167], v[188:191], v[54:57]
	v_mfma_f32_16x16x32_bf16 v[46:49], v[156:159], v[196:199], v[46:49]
	v_mfma_f32_16x16x32_bf16 v[38:41], v[164:167], v[196:199], v[38:41]
	v_mfma_f32_16x16x32_bf16 v[30:33], v[156:159], v[204:207], v[30:33]
	v_mfma_f32_16x16x32_bf16 v[22:25], v[164:167], v[204:207], v[22:25]
	v_mfma_f32_16x16x32_bf16 v[14:17], v[156:159], v[212:215], v[14:17]
	v_mfma_f32_16x16x32_bf16 v[6:9], v[164:167], v[212:215], v[6:9]
	v_mfma_f32_16x16x32_bf16 v[58:61], v[168:171], v[184:187], v[58:61]
	v_mfma_f32_16x16x32_bf16 v[50:53], v[176:179], v[184:187], v[50:53]
	v_mfma_f32_16x16x32_bf16 v[42:45], v[168:171], v[192:195], v[42:45]
	v_mfma_f32_16x16x32_bf16 v[34:37], v[176:179], v[192:195], v[34:37]
	v_mfma_f32_16x16x32_bf16 v[26:29], v[168:171], v[200:203], v[26:29]
	v_mfma_f32_16x16x32_bf16 v[18:21], v[176:179], v[200:203], v[18:21]
	v_mfma_f32_16x16x32_bf16 v[10:13], v[168:171], v[208:211], v[10:13]
	v_mfma_f32_16x16x32_bf16 v[2:5], v[176:179], v[208:211], v[2:5]
	v_mfma_f32_16x16x32_bf16 v[58:61], v[172:175], v[188:191], v[58:61]
	v_mfma_f32_16x16x32_bf16 v[50:53], v[180:183], v[188:191], v[50:53]
	v_mfma_f32_16x16x32_bf16 v[42:45], v[172:175], v[196:199], v[42:45]
	v_mfma_f32_16x16x32_bf16 v[34:37], v[180:183], v[196:199], v[34:37]
	v_mfma_f32_16x16x32_bf16 v[26:29], v[172:175], v[204:207], v[26:29]
	v_mfma_f32_16x16x32_bf16 v[18:21], v[180:183], v[204:207], v[18:21]
	v_mfma_f32_16x16x32_bf16 v[10:13], v[172:175], v[212:215], v[10:13]
	s_barrier
	v_mfma_f32_16x16x32_bf16 v[2:5], v[180:183], v[212:215], v[2:5]
	s_setprio 0
	s_add_i32 s69, s69, 2
	s_add_u32 s44, s44, 0x100
	s_addc_u32 s45, s45, 0
	s_add_u32 s61, s61, 0x100
	s_addc_u32 s68, s68, 0
	s_cmp_gt_u32 s69, 29
	s_cbranch_scc0 .LBB0_3309
	s_and_b64 vcc, exec, s[24:25]
	s_cbranch_vccz .LBB0_3312
	s_barrier

.LBB0_3533:
	ds_read_b128 v[154:157], v151
	ds_read_b128 v[158:161], v151 offset:1024
	ds_read_b128 v[162:165], v151 offset:2048
	ds_read_b128 v[166:169], v151 offset:3072
	ds_read_b128 v[170:173], v152
	ds_read_b128 v[174:177], v152 offset:1024
	ds_read_b128 v[178:181], v152 offset:2048
	ds_read_b128 v[182:185], v152 offset:3072
	s_add_u32 s34, s44, 0xfff80080
	s_addc_u32 s35, s45, -1
	s_cmp_eq_u32 s68, 28
	s_cselect_b32 s47, s0, s35
	s_cselect_b32 s46, s1, s34
	s_cselect_b32 s35, s27, s61
	s_cselect_b32 s34, s37, s60
	v_lshl_add_u64 v[146:147], s[44:45], 0, v[138:139]
	s_add_i32 m0, s33, 0xc000
	ds_read_b128 v[186:189], v153
	ds_read_b128 v[190:193], v153 offset:1024
	ds_read_b128 v[194:197], v153 offset:2048
	ds_read_b128 v[198:201], v153 offset:3072
	ds_read_b128 v[202:205], v153 offset:4096
	ds_read_b128 v[206:209], v153 offset:5120
	ds_read_b128 v[210:213], v153 offset:6144
	ds_read_b128 v[218:221], v153 offset:7168
	global_load_lds_dwordx4 v[146:147], off
	v_lshl_add_u64 v[146:147], s[44:45], 0, v[140:141]
	s_add_i32 m0, s33, 0xe000
	s_nop 0
	global_load_lds_dwordx4 v[146:147], off
	s_waitcnt vmcnt(8)
	s_waitcnt lgkmcnt(0)
	s_barrier
	s_setprio 1
	v_mfma_f32_16x16x32_bf16 v[126:129], v[154:157], v[186:189], v[126:129]
	v_mfma_f32_16x16x32_bf16 v[122:125], v[162:165], v[186:189], v[122:125]
	v_mfma_f32_16x16x32_bf16 v[114:117], v[154:157], v[194:197], v[114:117]
	v_mfma_f32_16x16x32_bf16 v[106:109], v[162:165], v[194:197], v[106:109]
	v_mfma_f32_16x16x32_bf16 v[98:101], v[154:157], v[202:205], v[98:101]
	v_mfma_f32_16x16x32_bf16 v[90:93], v[162:165], v[202:205], v[90:93]
	v_mfma_f32_16x16x32_bf16 v[82:85], v[154:157], v[210:213], v[82:85]
	v_mfma_f32_16x16x32_bf16 v[74:77], v[162:165], v[210:213], v[74:77]
	v_mfma_f32_16x16x32_bf16 v[126:129], v[158:161], v[190:193], v[126:129]
	v_mfma_f32_16x16x32_bf16 v[122:125], v[166:169], v[190:193], v[122:125]
	v_mfma_f32_16x16x32_bf16 v[114:117], v[158:161], v[198:201], v[114:117]
	v_mfma_f32_16x16x32_bf16 v[106:109], v[166:169], v[198:201], v[106:109]
	v_mfma_f32_16x16x32_bf16 v[98:101], v[158:161], v[206:209], v[98:101]
	v_mfma_f32_16x16x32_bf16 v[90:93], v[166:169], v[206:209], v[90:93]
	v_mfma_f32_16x16x32_bf16 v[82:85], v[158:161], v[218:221], v[82:85]
	v_mfma_f32_16x16x32_bf16 v[74:77], v[166:169], v[218:221], v[74:77]
	v_mfma_f32_16x16x32_bf16 v[118:121], v[170:173], v[186:189], v[118:121]
	v_mfma_f32_16x16x32_bf16 v[110:113], v[178:181], v[186:189], v[110:113]
	v_mfma_f32_16x16x32_bf16 v[102:105], v[170:173], v[194:197], v[102:105]
	v_mfma_f32_16x16x32_bf16 v[94:97], v[178:181], v[194:197], v[94:97]
	v_mfma_f32_16x16x32_bf16 v[86:89], v[170:173], v[202:205], v[86:89]
	v_mfma_f32_16x16x32_bf16 v[78:81], v[178:181], v[202:205], v[78:81]
	v_mfma_f32_16x16x32_bf16 v[70:73], v[170:173], v[210:213], v[70:73]
	v_mfma_f32_16x16x32_bf16 v[66:69], v[178:181], v[210:213], v[66:69]
	v_mfma_f32_16x16x32_bf16 v[118:121], v[174:177], v[190:193], v[118:121]
	v_mfma_f32_16x16x32_bf16 v[110:113], v[182:185], v[190:193], v[110:113]
	v_mfma_f32_16x16x32_bf16 v[102:105], v[174:177], v[198:201], v[102:105]
	v_mfma_f32_16x16x32_bf16 v[94:97], v[182:185], v[198:201], v[94:97]
	v_mfma_f32_16x16x32_bf16 v[86:89], v[174:177], v[206:209], v[86:89]
	v_mfma_f32_16x16x32_bf16 v[78:81], v[182:185], v[206:209], v[78:81]
	v_mfma_f32_16x16x32_bf16 v[70:73], v[174:177], v[218:221], v[70:73]
	s_barrier
	v_mfma_f32_16x16x32_bf16 v[66:69], v[182:185], v[218:221], v[66:69]
	s_setprio 0
	s_add_i32 s62, s56, s12
	v_lshl_add_u64 v[146:147], s[34:35], 0, v[134:135]
	s_mov_b32 m0, s62
	ds_read_b128 v[186:189], v153 offset:16384
	ds_read_b128 v[190:193], v153 offset:17408
	ds_read_b128 v[194:197], v153 offset:18432
	ds_read_b128 v[198:201], v153 offset:19456
	ds_read_b128 v[202:205], v153 offset:20480
	ds_read_b128 v[206:209], v153 offset:21504
	ds_read_b128 v[210:213], v153 offset:22528
	ds_read_b128 v[218:221], v153 offset:23552
	global_load_lds_dwordx4 v[146:147], off
	s_add_i32 m0, s62, 0x2000
	s_add_u32 s62, s34, 0x80000
	v_lshl_add_u64 v[214:215], s[34:35], 0, v[130:131]
	s_addc_u32 s63, s35, 0
	s_add_i32 s66, s57, s12
	global_load_lds_dwordx4 v[214:215], off
	v_lshl_add_u64 v[222:223], s[62:63], 0, v[134:135]
	s_mov_b32 m0, s66
	v_lshl_add_u64 v[224:225], s[46:47], 0, v[132:133]
	global_load_lds_dwordx4 v[222:223], off
	v_lshl_add_u64 v[222:223], s[62:63], 0, v[130:131]
	s_add_i32 m0, s66, 0x2000
	s_nop 0
	global_load_lds_dwordx4 v[222:223], off
	v_lshl_add_u64 v[222:223], s[46:47], 0, v[136:137]
	s_mov_b32 m0, s33
	s_nop 0
	global_load_lds_dwordx4 v[222:223], off
	s_mov_b32 m0, s43
	s_nop 0
	global_load_lds_dwordx4 v[224:225], off
	s_waitcnt vmcnt(8)
	s_waitcnt lgkmcnt(0)
	s_barrier
	s_setprio 1
	v_mfma_f32_16x16x32_bf16 v[62:65], v[154:157], v[186:189], v[62:65]
	v_mfma_f32_16x16x32_bf16 v[58:61], v[162:165], v[186:189], v[58:61]
	v_mfma_f32_16x16x32_bf16 v[50:53], v[154:157], v[194:197], v[50:53]
	v_mfma_f32_16x16x32_bf16 v[42:45], v[162:165], v[194:197], v[42:45]
	v_mfma_f32_16x16x32_bf16 v[34:37], v[154:157], v[202:205], v[34:37]
	v_mfma_f32_16x16x32_bf16 v[26:29], v[162:165], v[202:205], v[26:29]
	v_mfma_f32_16x16x32_bf16 v[18:21], v[154:157], v[210:213], v[18:21]
	v_mfma_f32_16x16x32_bf16 v[10:13], v[162:165], v[210:213], v[10:13]
	v_mfma_f32_16x16x32_bf16 v[62:65], v[158:161], v[190:193], v[62:65]
	v_mfma_f32_16x16x32_bf16 v[58:61], v[166:169], v[190:193], v[58:61]
	v_mfma_f32_16x16x32_bf16 v[50:53], v[158:161], v[198:201], v[50:53]
	v_mfma_f32_16x16x32_bf16 v[42:45], v[166:169], v[198:201], v[42:45]
	v_mfma_f32_16x16x32_bf16 v[34:37], v[158:161], v[206:209], v[34:37]
	v_mfma_f32_16x16x32_bf16 v[26:29], v[166:169], v[206:209], v[26:29]
	v_mfma_f32_16x16x32_bf16 v[18:21], v[158:161], v[218:221], v[18:21]
	v_mfma_f32_16x16x32_bf16 v[10:13], v[166:169], v[218:221], v[10:13]
	v_mfma_f32_16x16x32_bf16 v[54:57], v[170:173], v[186:189], v[54:57]
	v_mfma_f32_16x16x32_bf16 v[46:49], v[178:181], v[186:189], v[46:49]
	v_mfma_f32_16x16x32_bf16 v[38:41], v[170:173], v[194:197], v[38:41]
	v_mfma_f32_16x16x32_bf16 v[30:33], v[178:181], v[194:197], v[30:33]
	v_mfma_f32_16x16x32_bf16 v[22:25], v[170:173], v[202:205], v[22:25]
	v_mfma_f32_16x16x32_bf16 v[14:17], v[178:181], v[202:205], v[14:17]
	v_mfma_f32_16x16x32_bf16 v[6:9], v[170:173], v[210:213], v[6:9]
	v_mfma_f32_16x16x32_bf16 v[2:5], v[178:181], v[210:213], v[2:5]
	v_mfma_f32_16x16x32_bf16 v[54:57], v[174:177], v[190:193], v[54:57]
	v_mfma_f32_16x16x32_bf16 v[46:49], v[182:185], v[190:193], v[46:49]
	v_mfma_f32_16x16x32_bf16 v[38:41], v[174:177], v[198:201], v[38:41]
	v_mfma_f32_16x16x32_bf16 v[30:33], v[182:185], v[198:201], v[30:33]
	v_mfma_f32_16x16x32_bf16 v[22:25], v[174:177], v[206:209], v[22:25]
	v_mfma_f32_16x16x32_bf16 v[14:17], v[182:185], v[206:209], v[14:17]
	v_mfma_f32_16x16x32_bf16 v[6:9], v[174:177], v[218:221], v[6:9]
	s_barrier
	v_mfma_f32_16x16x32_bf16 v[2:5], v[182:185], v[218:221], v[2:5]
	s_setprio 0
	s_add_i32 s62, 0, 0x18000
	s_add_i32 s63, 0, 0x1c000
	v_add_u32_e32 v166, s62, v149
	v_add_u32_e32 v182, s63, v149
	ds_read_b128 v[154:157], v166
	ds_read_b128 v[158:161], v166 offset:1024
	ds_read_b128 v[162:165], v166 offset:2048
	ds_read_b128 v[166:169], v166 offset:3072
	ds_read_b128 v[170:173], v182
	ds_read_b128 v[174:177], v182 offset:1024
	ds_read_b128 v[178:181], v182 offset:2048
	ds_read_b128 v[182:185], v182 offset:3072
	s_add_u32 s46, s46, 0x80000
	s_addc_u32 s47, s47, 0
	s_mov_b32 m0, s48
	v_lshl_add_u64 v[226:227], s[46:47], 0, v[136:137]
	ds_read_b128 v[186:189], v153 offset:32768
	ds_read_b128 v[190:193], v153 offset:33792
	ds_read_b128 v[194:197], v153 offset:34816
	ds_read_b128 v[198:201], v153 offset:35840
	ds_read_b128 v[202:205], v153 offset:36864
	ds_read_b128 v[206:209], v153 offset:37888
	ds_read_b128 v[210:213], v153 offset:38912
	ds_read_b128 v[218:221], v153 offset:39936
	global_load_lds_dwordx4 v[226:227], off
	v_lshl_add_u64 v[226:227], s[46:47], 0, v[132:133]
	s_mov_b32 m0, s49
	s_nop 0
	global_load_lds_dwordx4 v[226:227], off
	s_waitcnt vmcnt(8)
	s_waitcnt lgkmcnt(0)
	s_barrier
	s_setprio 1
	v_mfma_f32_16x16x32_bf16 v[126:129], v[154:157], v[186:189], v[126:129]
	v_mfma_f32_16x16x32_bf16 v[122:125], v[162:165], v[186:189], v[122:125]
	v_mfma_f32_16x16x32_bf16 v[114:117], v[154:157], v[194:197], v[114:117]
	v_mfma_f32_16x16x32_bf16 v[106:109], v[162:165], v[194:197], v[106:109]
	v_mfma_f32_16x16x32_bf16 v[98:101], v[154:157], v[202:205], v[98:101]
	v_mfma_f32_16x16x32_bf16 v[90:93], v[162:165], v[202:205], v[90:93]
	v_mfma_f32_16x16x32_bf16 v[82:85], v[154:157], v[210:213], v[82:85]
	v_mfma_f32_16x16x32_bf16 v[74:77], v[162:165], v[210:213], v[74:77]
	v_mfma_f32_16x16x32_bf16 v[126:129], v[158:161], v[190:193], v[126:129]
	v_mfma_f32_16x16x32_bf16 v[122:125], v[166:169], v[190:193], v[122:125]
	v_mfma_f32_16x16x32_bf16 v[114:117], v[158:161], v[198:201], v[114:117]
	v_mfma_f32_16x16x32_bf16 v[106:109], v[166:169], v[198:201], v[106:109]
	v_mfma_f32_16x16x32_bf16 v[98:101], v[158:161], v[206:209], v[98:101]
	v_mfma_f32_16x16x32_bf16 v[90:93], v[166:169], v[206:209], v[90:93]
	v_mfma_f32_16x16x32_bf16 v[82:85], v[158:161], v[218:221], v[82:85]
	v_mfma_f32_16x16x32_bf16 v[74:77], v[166:169], v[218:221], v[74:77]
	v_mfma_f32_16x16x32_bf16 v[118:121], v[170:173], v[186:189], v[118:121]
	v_mfma_f32_16x16x32_bf16 v[110:113], v[178:181], v[186:189], v[110:113]
	v_mfma_f32_16x16x32_bf16 v[102:105], v[170:173], v[194:197], v[102:105]
	v_mfma_f32_16x16x32_bf16 v[94:97], v[178:181], v[194:197], v[94:97]
	v_mfma_f32_16x16x32_bf16 v[86:89], v[170:173], v[202:205], v[86:89]
	v_mfma_f32_16x16x32_bf16 v[78:81], v[178:181], v[202:205], v[78:81]
	v_mfma_f32_16x16x32_bf16 v[70:73], v[170:173], v[210:213], v[70:73]
	v_mfma_f32_16x16x32_bf16 v[66:69], v[178:181], v[210:213], v[66:69]
	v_mfma_f32_16x16x32_bf16 v[118:121], v[174:177], v[190:193], v[118:121]
	v_mfma_f32_16x16x32_bf16 v[110:113], v[182:185], v[190:193], v[110:113]
	v_mfma_f32_16x16x32_bf16 v[102:105], v[174:177], v[198:201], v[102:105]
	v_mfma_f32_16x16x32_bf16 v[94:97], v[182:185], v[198:201], v[94:97]
	v_mfma_f32_16x16x32_bf16 v[86:89], v[174:177], v[206:209], v[86:89]
	v_mfma_f32_16x16x32_bf16 v[78:81], v[182:185], v[206:209], v[78:81]
	v_mfma_f32_16x16x32_bf16 v[70:73], v[174:177], v[218:221], v[70:73]
	s_barrier
	v_mfma_f32_16x16x32_bf16 v[66:69], v[182:185], v[218:221], v[66:69]
	s_setprio 0
	s_add_i32 s46, s62, s12
	v_lshl_add_u64 v[146:147], v[146:147], 0, s[8:9]
	s_mov_b32 m0, s46
	ds_read_b128 v[186:189], v153 offset:49152
	ds_read_b128 v[190:193], v153 offset:50176
	ds_read_b128 v[194:197], v153 offset:51200
	ds_read_b128 v[198:201], v153 offset:52224
	ds_read_b128 v[202:205], v153 offset:53248
	ds_read_b128 v[206:209], v153 offset:54272
	ds_read_b128 v[210:213], v153 offset:55296
	ds_read_b128 v[218:221], v153 offset:56320
	global_load_lds_dwordx4 v[146:147], off
	s_add_i32 m0, s46, 0x2000
	s_add_u32 s34, s34, 0x80080
	v_lshl_add_u64 v[146:147], v[214:215], 0, s[8:9]
	s_addc_u32 s35, s35, 0
	s_add_i32 s46, s63, s12
	global_load_lds_dwordx4 v[146:147], off
	v_lshl_add_u64 v[146:147], s[34:35], 0, v[134:135]
	s_mov_b32 m0, s46
	s_nop 0
	global_load_lds_dwordx4 v[146:147], off
	v_lshl_add_u64 v[146:147], s[34:35], 0, v[130:131]
	s_add_i32 m0, s46, 0x2000
	s_nop 0
	global_load_lds_dwordx4 v[146:147], off
	v_lshl_add_u64 v[146:147], v[222:223], 0, s[8:9]
	s_mov_b32 m0, s53
	s_nop 0
	global_load_lds_dwordx4 v[146:147], off
	v_lshl_add_u64 v[146:147], v[224:225], 0, s[8:9]
	s_mov_b32 m0, s54
	s_nop 0
	global_load_lds_dwordx4 v[146:147], off
	s_waitcnt vmcnt(8)
	s_waitcnt lgkmcnt(0)
	s_barrier
	s_setprio 1
	v_mfma_f32_16x16x32_bf16 v[62:65], v[154:157], v[186:189], v[62:65]
	v_mfma_f32_16x16x32_bf16 v[58:61], v[162:165], v[186:189], v[58:61]
	v_mfma_f32_16x16x32_bf16 v[50:53], v[154:157], v[194:197], v[50:53]
	v_mfma_f32_16x16x32_bf16 v[42:45], v[162:165], v[194:197], v[42:45]
	v_mfma_f32_16x16x32_bf16 v[34:37], v[154:157], v[202:205], v[34:37]
	v_mfma_f32_16x16x32_bf16 v[26:29], v[162:165], v[202:205], v[26:29]
	v_mfma_f32_16x16x32_bf16 v[18:21], v[154:157], v[210:213], v[18:21]
	v_mfma_f32_16x16x32_bf16 v[10:13], v[162:165], v[210:213], v[10:13]
	v_mfma_f32_16x16x32_bf16 v[62:65], v[158:161], v[190:193], v[62:65]
	v_mfma_f32_16x16x32_bf16 v[58:61], v[166:169], v[190:193], v[58:61]
	v_mfma_f32_16x16x32_bf16 v[50:53], v[158:161], v[198:201], v[50:53]
	v_mfma_f32_16x16x32_bf16 v[42:45], v[166:169], v[198:201], v[42:45]
	v_mfma_f32_16x16x32_bf16 v[34:37], v[158:161], v[206:209], v[34:37]
	v_mfma_f32_16x16x32_bf16 v[26:29], v[166:169], v[206:209], v[26:29]
	v_mfma_f32_16x16x32_bf16 v[18:21], v[158:161], v[218:221], v[18:21]
	v_mfma_f32_16x16x32_bf16 v[10:13], v[166:169], v[218:221], v[10:13]
	v_mfma_f32_16x16x32_bf16 v[54:57], v[170:173], v[186:189], v[54:57]
	v_mfma_f32_16x16x32_bf16 v[46:49], v[178:181], v[186:189], v[46:49]
	v_mfma_f32_16x16x32_bf16 v[38:41], v[170:173], v[194:197], v[38:41]
	v_mfma_f32_16x16x32_bf16 v[30:33], v[178:181], v[194:197], v[30:33]
	v_mfma_f32_16x16x32_bf16 v[22:25], v[170:173], v[202:205], v[22:25]
	v_mfma_f32_16x16x32_bf16 v[14:17], v[178:181], v[202:205], v[14:17]
	v_mfma_f32_16x16x32_bf16 v[6:9], v[170:173], v[210:213], v[6:9]
	v_mfma_f32_16x16x32_bf16 v[2:5], v[178:181], v[210:213], v[2:5]
	v_mfma_f32_16x16x32_bf16 v[54:57], v[174:177], v[190:193], v[54:57]
	v_mfma_f32_16x16x32_bf16 v[46:49], v[182:185], v[190:193], v[46:49]
	v_mfma_f32_16x16x32_bf16 v[38:41], v[174:177], v[198:201], v[38:41]
	v_mfma_f32_16x16x32_bf16 v[30:33], v[182:185], v[198:201], v[30:33]
	v_mfma_f32_16x16x32_bf16 v[22:25], v[174:177], v[206:209], v[22:25]
	v_mfma_f32_16x16x32_bf16 v[14:17], v[182:185], v[206:209], v[14:17]
	v_mfma_f32_16x16x32_bf16 v[6:9], v[174:177], v[218:221], v[6:9]
	s_barrier
	v_mfma_f32_16x16x32_bf16 v[2:5], v[182:185], v[218:221], v[2:5]
	s_setprio 0
	s_add_i32 s68, s68, 2
	s_add_u32 s44, s44, 0x100
	s_addc_u32 s45, s45, 0
	s_add_u32 s60, s60, 0x100
	s_addc_u32 s61, s61, 0
	s_cmp_gt_u32 s68, 29
	s_cbranch_scc0 .LBB0_3533
	s_and_b64 vcc, exec, s[24:25]
	s_cbranch_vccz .LBB0_3536
	s_barrier

.LBB0_3706:
	ds_read_b128 v[130:133], v174
	ds_read_b128 v[134:137], v174 offset:1024
	ds_read_b128 v[138:141], v174 offset:2048
	ds_read_b128 v[158:161], v174 offset:3072
	ds_read_b128 v[162:165], v175
	ds_read_b128 v[166:169], v175 offset:1024
	ds_read_b128 v[178:181], v175 offset:2048
	ds_read_b128 v[182:185], v175 offset:3072
	s_add_u32 s34, s42, 0xfff80080
	s_addc_u32 s35, s43, -1
	s_cmp_eq_u32 s60, 28
	s_cselect_b32 s45, s0, s35
	s_cselect_b32 s44, s1, s34
	s_cselect_b32 s35, s25, s59
	s_cselect_b32 s34, s27, s58
	v_lshl_add_u64 v[170:171], s[42:43], 0, v[150:151]
	s_add_i32 m0, s41, 0xc000
	ds_read_b128 v[186:189], v176
	ds_read_b128 v[190:193], v176 offset:1024
	ds_read_b128 v[194:197], v176 offset:2048
	ds_read_b128 v[198:201], v176 offset:3072
	ds_read_b128 v[202:205], v176 offset:4096
	ds_read_b128 v[206:209], v176 offset:5120
	ds_read_b128 v[210:213], v176 offset:6144
	ds_read_b128 v[218:221], v176 offset:7168
	global_load_lds_dwordx4 v[170:171], off
	v_lshl_add_u64 v[170:171], s[42:43], 0, v[152:153]
	s_add_i32 m0, s41, 0xe000
	s_nop 0
	global_load_lds_dwordx4 v[170:171], off
	s_waitcnt vmcnt(8)
	s_waitcnt lgkmcnt(0)
	s_barrier
	s_setprio 1
	v_mfma_f32_16x16x32_bf16 v[126:129], v[130:133], v[186:189], v[126:129]
	v_mfma_f32_16x16x32_bf16 v[122:125], v[138:141], v[186:189], v[122:125]
	v_mfma_f32_16x16x32_bf16 v[110:113], v[130:133], v[194:197], v[110:113]
	v_mfma_f32_16x16x32_bf16 v[106:109], v[138:141], v[194:197], v[106:109]
	v_mfma_f32_16x16x32_bf16 v[94:97], v[130:133], v[202:205], v[94:97]
	v_mfma_f32_16x16x32_bf16 v[90:93], v[138:141], v[202:205], v[90:93]
	v_mfma_f32_16x16x32_bf16 v[78:81], v[130:133], v[210:213], v[78:81]
	v_mfma_f32_16x16x32_bf16 v[74:77], v[138:141], v[210:213], v[74:77]
	v_mfma_f32_16x16x32_bf16 v[126:129], v[134:137], v[190:193], v[126:129]
	v_mfma_f32_16x16x32_bf16 v[122:125], v[158:161], v[190:193], v[122:125]
	v_mfma_f32_16x16x32_bf16 v[110:113], v[134:137], v[198:201], v[110:113]
	v_mfma_f32_16x16x32_bf16 v[106:109], v[158:161], v[198:201], v[106:109]
	v_mfma_f32_16x16x32_bf16 v[94:97], v[134:137], v[206:209], v[94:97]
	v_mfma_f32_16x16x32_bf16 v[90:93], v[158:161], v[206:209], v[90:93]
	v_mfma_f32_16x16x32_bf16 v[78:81], v[134:137], v[218:221], v[78:81]
	v_mfma_f32_16x16x32_bf16 v[74:77], v[158:161], v[218:221], v[74:77]
	v_mfma_f32_16x16x32_bf16 v[118:121], v[162:165], v[186:189], v[118:121]
	v_mfma_f32_16x16x32_bf16 v[114:117], v[178:181], v[186:189], v[114:117]
	v_mfma_f32_16x16x32_bf16 v[102:105], v[162:165], v[194:197], v[102:105]
	v_mfma_f32_16x16x32_bf16 v[98:101], v[178:181], v[194:197], v[98:101]
	v_mfma_f32_16x16x32_bf16 v[86:89], v[162:165], v[202:205], v[86:89]
	v_mfma_f32_16x16x32_bf16 v[82:85], v[178:181], v[202:205], v[82:85]
	v_mfma_f32_16x16x32_bf16 v[70:73], v[162:165], v[210:213], v[70:73]
	v_mfma_f32_16x16x32_bf16 v[66:69], v[178:181], v[210:213], v[66:69]
	v_mfma_f32_16x16x32_bf16 v[118:121], v[166:169], v[190:193], v[118:121]
	v_mfma_f32_16x16x32_bf16 v[114:117], v[182:185], v[190:193], v[114:117]
	v_mfma_f32_16x16x32_bf16 v[102:105], v[166:169], v[198:201], v[102:105]
	v_mfma_f32_16x16x32_bf16 v[98:101], v[182:185], v[198:201], v[98:101]
	v_mfma_f32_16x16x32_bf16 v[86:89], v[166:169], v[206:209], v[86:89]
	v_mfma_f32_16x16x32_bf16 v[82:85], v[182:185], v[206:209], v[82:85]
	v_mfma_f32_16x16x32_bf16 v[70:73], v[166:169], v[218:221], v[70:73]
	s_barrier
	v_mfma_f32_16x16x32_bf16 v[66:69], v[182:185], v[218:221], v[66:69]
	s_setprio 0
	s_add_i32 s61, s54, s46
	v_lshl_add_u64 v[170:171], s[34:35], 0, v[144:145]
	s_mov_b32 m0, s61
	ds_read_b128 v[186:189], v176 offset:16384
	ds_read_b128 v[190:193], v176 offset:17408
	ds_read_b128 v[194:197], v176 offset:18432
	ds_read_b128 v[198:201], v176 offset:19456
	ds_read_b128 v[202:205], v176 offset:20480
	ds_read_b128 v[206:209], v176 offset:21504
	ds_read_b128 v[210:213], v176 offset:22528
	ds_read_b128 v[218:221], v176 offset:23552
	global_load_lds_dwordx4 v[170:171], off
	s_add_i32 m0, s61, 0x2000
	s_add_u32 s62, s34, 0x80000
	v_lshl_add_u64 v[214:215], s[34:35], 0, v[148:149]
	s_addc_u32 s63, s35, 0
	s_add_i32 s61, s55, s46
	global_load_lds_dwordx4 v[214:215], off
	v_lshl_add_u64 v[222:223], s[62:63], 0, v[144:145]
	s_mov_b32 m0, s61
	v_lshl_add_u64 v[224:225], s[44:45], 0, v[146:147]
	global_load_lds_dwordx4 v[222:223], off
	v_lshl_add_u64 v[222:223], s[62:63], 0, v[148:149]
	s_add_i32 m0, s61, 0x2000
	s_nop 0
	global_load_lds_dwordx4 v[222:223], off
	v_lshl_add_u64 v[222:223], s[44:45], 0, v[142:143]
	s_mov_b32 m0, s41
	s_nop 0
	global_load_lds_dwordx4 v[222:223], off
	s_mov_b32 m0, s47
	s_nop 0
	global_load_lds_dwordx4 v[224:225], off
	s_waitcnt vmcnt(8)
	s_waitcnt lgkmcnt(0)
	s_barrier
	s_setprio 1
	v_mfma_f32_16x16x32_bf16 v[62:65], v[130:133], v[186:189], v[62:65]
	v_mfma_f32_16x16x32_bf16 v[58:61], v[138:141], v[186:189], v[58:61]
	v_mfma_f32_16x16x32_bf16 v[50:53], v[130:133], v[194:197], v[50:53]
	v_mfma_f32_16x16x32_bf16 v[42:45], v[138:141], v[194:197], v[42:45]
	v_mfma_f32_16x16x32_bf16 v[38:41], v[130:133], v[202:205], v[38:41]
	v_mfma_f32_16x16x32_bf16 v[34:37], v[138:141], v[202:205], v[34:37]
	v_mfma_f32_16x16x32_bf16 v[14:17], v[130:133], v[210:213], v[14:17]
	v_mfma_f32_16x16x32_bf16 v[10:13], v[138:141], v[210:213], v[10:13]
	v_mfma_f32_16x16x32_bf16 v[62:65], v[134:137], v[190:193], v[62:65]
	v_mfma_f32_16x16x32_bf16 v[58:61], v[158:161], v[190:193], v[58:61]
	v_mfma_f32_16x16x32_bf16 v[50:53], v[134:137], v[198:201], v[50:53]
	v_mfma_f32_16x16x32_bf16 v[42:45], v[158:161], v[198:201], v[42:45]
	v_mfma_f32_16x16x32_bf16 v[38:41], v[134:137], v[206:209], v[38:41]
	v_mfma_f32_16x16x32_bf16 v[34:37], v[158:161], v[206:209], v[34:37]
	v_mfma_f32_16x16x32_bf16 v[14:17], v[134:137], v[218:221], v[14:17]
	v_mfma_f32_16x16x32_bf16 v[10:13], v[158:161], v[218:221], v[10:13]
	v_mfma_f32_16x16x32_bf16 v[54:57], v[162:165], v[186:189], v[54:57]
	v_mfma_f32_16x16x32_bf16 v[46:49], v[178:181], v[186:189], v[46:49]
	v_mfma_f32_16x16x32_bf16 v[30:33], v[162:165], v[194:197], v[30:33]
	v_mfma_f32_16x16x32_bf16 v[26:29], v[178:181], v[194:197], v[26:29]
	v_mfma_f32_16x16x32_bf16 v[22:25], v[162:165], v[202:205], v[22:25]
	v_mfma_f32_16x16x32_bf16 v[18:21], v[178:181], v[202:205], v[18:21]
	v_mfma_f32_16x16x32_bf16 v[6:9], v[162:165], v[210:213], v[6:9]
	v_mfma_f32_16x16x32_bf16 v[2:5], v[178:181], v[210:213], v[2:5]
	v_mfma_f32_16x16x32_bf16 v[54:57], v[166:169], v[190:193], v[54:57]
	v_mfma_f32_16x16x32_bf16 v[46:49], v[182:185], v[190:193], v[46:49]
	v_mfma_f32_16x16x32_bf16 v[30:33], v[166:169], v[198:201], v[30:33]
	v_mfma_f32_16x16x32_bf16 v[26:29], v[182:185], v[198:201], v[26:29]
	v_mfma_f32_16x16x32_bf16 v[22:25], v[166:169], v[206:209], v[22:25]
	v_mfma_f32_16x16x32_bf16 v[18:21], v[182:185], v[206:209], v[18:21]
	v_mfma_f32_16x16x32_bf16 v[6:9], v[166:169], v[218:221], v[6:9]
	s_barrier
	v_mfma_f32_16x16x32_bf16 v[2:5], v[182:185], v[218:221], v[2:5]
	s_setprio 0
	s_add_i32 s61, 0, 0x18000
	s_add_i32 s62, 0, 0x1c000
	v_add_u32_e32 v158, s61, v172
	v_add_u32_e32 v177, s62, v172
	ds_read_b128 v[130:133], v158
	ds_read_b128 v[134:137], v158 offset:1024
	ds_read_b128 v[138:141], v158 offset:2048
	ds_read_b128 v[158:161], v158 offset:3072
	ds_read_b128 v[162:165], v177
	ds_read_b128 v[166:169], v177 offset:1024
	ds_read_b128 v[178:181], v177 offset:2048
	ds_read_b128 v[182:185], v177 offset:3072
	s_add_u32 s44, s44, 0x80000
	s_addc_u32 s45, s45, 0
	s_mov_b32 m0, s48
	v_lshl_add_u64 v[226:227], s[44:45], 0, v[142:143]
	ds_read_b128 v[186:189], v176 offset:32768
	ds_read_b128 v[190:193], v176 offset:33792
	ds_read_b128 v[194:197], v176 offset:34816
	ds_read_b128 v[198:201], v176 offset:35840
	ds_read_b128 v[202:205], v176 offset:36864
	ds_read_b128 v[206:209], v176 offset:37888
	ds_read_b128 v[210:213], v176 offset:38912
	ds_read_b128 v[218:221], v176 offset:39936
	global_load_lds_dwordx4 v[226:227], off
	v_lshl_add_u64 v[226:227], s[44:45], 0, v[146:147]
	s_mov_b32 m0, s49
	s_nop 0
	global_load_lds_dwordx4 v[226:227], off
	s_waitcnt vmcnt(8)
	s_waitcnt lgkmcnt(0)
	s_barrier
	s_setprio 1
	v_mfma_f32_16x16x32_bf16 v[126:129], v[130:133], v[186:189], v[126:129]
	v_mfma_f32_16x16x32_bf16 v[122:125], v[138:141], v[186:189], v[122:125]
	v_mfma_f32_16x16x32_bf16 v[110:113], v[130:133], v[194:197], v[110:113]
	v_mfma_f32_16x16x32_bf16 v[106:109], v[138:141], v[194:197], v[106:109]
	v_mfma_f32_16x16x32_bf16 v[94:97], v[130:133], v[202:205], v[94:97]
	v_mfma_f32_16x16x32_bf16 v[90:93], v[138:141], v[202:205], v[90:93]
	v_mfma_f32_16x16x32_bf16 v[78:81], v[130:133], v[210:213], v[78:81]
	v_mfma_f32_16x16x32_bf16 v[74:77], v[138:141], v[210:213], v[74:77]
	v_mfma_f32_16x16x32_bf16 v[126:129], v[134:137], v[190:193], v[126:129]
	v_mfma_f32_16x16x32_bf16 v[122:125], v[158:161], v[190:193], v[122:125]
	v_mfma_f32_16x16x32_bf16 v[110:113], v[134:137], v[198:201], v[110:113]
	v_mfma_f32_16x16x32_bf16 v[106:109], v[158:161], v[198:201], v[106:109]
	v_mfma_f32_16x16x32_bf16 v[94:97], v[134:137], v[206:209], v[94:97]
	v_mfma_f32_16x16x32_bf16 v[90:93], v[158:161], v[206:209], v[90:93]
	v_mfma_f32_16x16x32_bf16 v[78:81], v[134:137], v[218:221], v[78:81]
	v_mfma_f32_16x16x32_bf16 v[74:77], v[158:161], v[218:221], v[74:77]
	v_mfma_f32_16x16x32_bf16 v[118:121], v[162:165], v[186:189], v[118:121]
	v_mfma_f32_16x16x32_bf16 v[114:117], v[178:181], v[186:189], v[114:117]
	v_mfma_f32_16x16x32_bf16 v[102:105], v[162:165], v[194:197], v[102:105]
	v_mfma_f32_16x16x32_bf16 v[98:101], v[178:181], v[194:197], v[98:101]
	v_mfma_f32_16x16x32_bf16 v[86:89], v[162:165], v[202:205], v[86:89]
	v_mfma_f32_16x16x32_bf16 v[82:85], v[178:181], v[202:205], v[82:85]
	v_mfma_f32_16x16x32_bf16 v[70:73], v[162:165], v[210:213], v[70:73]
	v_mfma_f32_16x16x32_bf16 v[66:69], v[178:181], v[210:213], v[66:69]
	v_mfma_f32_16x16x32_bf16 v[118:121], v[166:169], v[190:193], v[118:121]
	v_mfma_f32_16x16x32_bf16 v[114:117], v[182:185], v[190:193], v[114:117]
	v_mfma_f32_16x16x32_bf16 v[102:105], v[166:169], v[198:201], v[102:105]
	v_mfma_f32_16x16x32_bf16 v[98:101], v[182:185], v[198:201], v[98:101]
	v_mfma_f32_16x16x32_bf16 v[86:89], v[166:169], v[206:209], v[86:89]
	v_mfma_f32_16x16x32_bf16 v[82:85], v[182:185], v[206:209], v[82:85]
	v_mfma_f32_16x16x32_bf16 v[70:73], v[166:169], v[218:221], v[70:73]
	s_barrier
	v_mfma_f32_16x16x32_bf16 v[66:69], v[182:185], v[218:221], v[66:69]
	s_setprio 0
	s_add_i32 s44, s61, s46
	v_lshl_add_u64 v[170:171], v[170:171], 0, s[12:13]
	s_mov_b32 m0, s44
	ds_read_b128 v[186:189], v176 offset:49152
	ds_read_b128 v[190:193], v176 offset:50176
	ds_read_b128 v[194:197], v176 offset:51200
	ds_read_b128 v[198:201], v176 offset:52224
	ds_read_b128 v[202:205], v176 offset:53248
	ds_read_b128 v[206:209], v176 offset:54272
	ds_read_b128 v[210:213], v176 offset:55296
	ds_read_b128 v[218:221], v176 offset:56320
	global_load_lds_dwordx4 v[170:171], off
	s_add_i32 m0, s44, 0x2000
	s_add_u32 s34, s34, 0x80080
	v_lshl_add_u64 v[170:171], v[214:215], 0, s[12:13]
	s_addc_u32 s35, s35, 0
	s_add_i32 s44, s62, s46
	global_load_lds_dwordx4 v[170:171], off
	v_lshl_add_u64 v[170:171], s[34:35], 0, v[144:145]
	s_mov_b32 m0, s44
	s_nop 0
	global_load_lds_dwordx4 v[170:171], off
	v_lshl_add_u64 v[170:171], s[34:35], 0, v[148:149]
	s_add_i32 m0, s44, 0x2000
	s_nop 0
	global_load_lds_dwordx4 v[170:171], off
	v_lshl_add_u64 v[170:171], v[222:223], 0, s[12:13]
	s_mov_b32 m0, s51
	s_nop 0
	global_load_lds_dwordx4 v[170:171], off
	v_lshl_add_u64 v[170:171], v[224:225], 0, s[12:13]
	s_mov_b32 m0, s52
	s_nop 0
	global_load_lds_dwordx4 v[170:171], off
	s_waitcnt vmcnt(8)
	s_waitcnt lgkmcnt(0)
	s_barrier
	s_setprio 1
	v_mfma_f32_16x16x32_bf16 v[62:65], v[130:133], v[186:189], v[62:65]
	v_mfma_f32_16x16x32_bf16 v[58:61], v[138:141], v[186:189], v[58:61]
	v_mfma_f32_16x16x32_bf16 v[50:53], v[130:133], v[194:197], v[50:53]
	v_mfma_f32_16x16x32_bf16 v[42:45], v[138:141], v[194:197], v[42:45]
	v_mfma_f32_16x16x32_bf16 v[38:41], v[130:133], v[202:205], v[38:41]
	v_mfma_f32_16x16x32_bf16 v[34:37], v[138:141], v[202:205], v[34:37]
	v_mfma_f32_16x16x32_bf16 v[14:17], v[130:133], v[210:213], v[14:17]
	v_mfma_f32_16x16x32_bf16 v[10:13], v[138:141], v[210:213], v[10:13]
	v_mfma_f32_16x16x32_bf16 v[62:65], v[134:137], v[190:193], v[62:65]
	v_mfma_f32_16x16x32_bf16 v[58:61], v[158:161], v[190:193], v[58:61]
	v_mfma_f32_16x16x32_bf16 v[50:53], v[134:137], v[198:201], v[50:53]
	v_mfma_f32_16x16x32_bf16 v[42:45], v[158:161], v[198:201], v[42:45]
	v_mfma_f32_16x16x32_bf16 v[38:41], v[134:137], v[206:209], v[38:41]
	v_mfma_f32_16x16x32_bf16 v[34:37], v[158:161], v[206:209], v[34:37]
	v_mfma_f32_16x16x32_bf16 v[14:17], v[134:137], v[218:221], v[14:17]
	v_mfma_f32_16x16x32_bf16 v[10:13], v[158:161], v[218:221], v[10:13]
	v_mfma_f32_16x16x32_bf16 v[54:57], v[162:165], v[186:189], v[54:57]
	v_mfma_f32_16x16x32_bf16 v[46:49], v[178:181], v[186:189], v[46:49]
	v_mfma_f32_16x16x32_bf16 v[30:33], v[162:165], v[194:197], v[30:33]
	v_mfma_f32_16x16x32_bf16 v[26:29], v[178:181], v[194:197], v[26:29]
	v_mfma_f32_16x16x32_bf16 v[22:25], v[162:165], v[202:205], v[22:25]
	v_mfma_f32_16x16x32_bf16 v[18:21], v[178:181], v[202:205], v[18:21]
	v_mfma_f32_16x16x32_bf16 v[6:9], v[162:165], v[210:213], v[6:9]
	v_mfma_f32_16x16x32_bf16 v[2:5], v[178:181], v[210:213], v[2:5]
	v_mfma_f32_16x16x32_bf16 v[54:57], v[166:169], v[190:193], v[54:57]
	v_mfma_f32_16x16x32_bf16 v[46:49], v[182:185], v[190:193], v[46:49]
	v_mfma_f32_16x16x32_bf16 v[30:33], v[166:169], v[198:201], v[30:33]
	v_mfma_f32_16x16x32_bf16 v[26:29], v[182:185], v[198:201], v[26:29]
	v_mfma_f32_16x16x32_bf16 v[22:25], v[166:169], v[206:209], v[22:25]
	v_mfma_f32_16x16x32_bf16 v[18:21], v[182:185], v[206:209], v[18:21]
	v_mfma_f32_16x16x32_bf16 v[6:9], v[166:169], v[218:221], v[6:9]
	s_barrier
	v_mfma_f32_16x16x32_bf16 v[2:5], v[182:185], v[218:221], v[2:5]
	s_setprio 0
	s_add_i32 s60, s60, 2
	s_add_u32 s42, s42, 0x100
	s_addc_u32 s43, s43, 0
	s_add_u32 s58, s58, 0x100
	s_addc_u32 s59, s59, 0
	s_cmp_gt_u32 s60, 29
	s_cbranch_scc0 .LBB0_3706
	s_and_b64 vcc, exec, s[14:15]
	s_cbranch_vccz .LBB0_3709
	s_barrier

.LBB0_3835:
	ds_read_b128 v[146:149], v153
	ds_read_b128 v[156:159], v153 offset:1024
	ds_read_b128 v[160:163], v153 offset:2048
	ds_read_b128 v[164:167], v153 offset:3072
	ds_read_b128 v[168:171], v154
	ds_read_b128 v[172:175], v154 offset:1024
	ds_read_b128 v[176:179], v154 offset:2048
	ds_read_b128 v[180:183], v154 offset:3072
	s_add_u32 s34, s38, 0xfff80080
	s_addc_u32 s35, s39, -1
	s_cmp_eq_u32 s57, 28
	s_cselect_b32 s41, s0, s35
	s_cselect_b32 s40, s1, s34
	s_cselect_b32 s35, s15, s56
	s_cselect_b32 s34, s17, s55
	v_lshl_add_u64 v[218:219], s[38:39], 0, v[138:139]
	s_add_i32 m0, s37, 0xc000
	ds_read_b128 v[184:187], v155
	ds_read_b128 v[188:191], v155 offset:1024
	ds_read_b128 v[192:195], v155 offset:2048
	ds_read_b128 v[196:199], v155 offset:3072
	ds_read_b128 v[200:203], v155 offset:4096
	ds_read_b128 v[204:207], v155 offset:5120
	ds_read_b128 v[208:211], v155 offset:6144
	ds_read_b128 v[212:215], v155 offset:7168
	global_load_lds_dwordx4 v[218:219], off
	v_lshl_add_u64 v[218:219], s[38:39], 0, v[140:141]
	s_add_i32 m0, s37, 0xe000
	s_nop 0
	global_load_lds_dwordx4 v[218:219], off
	s_waitcnt vmcnt(8)
	s_waitcnt lgkmcnt(0)
	s_barrier
	s_setprio 1
	v_mfma_f32_16x16x32_bf16 v[126:129], v[146:149], v[184:187], v[126:129]
	v_mfma_f32_16x16x32_bf16 v[118:121], v[160:163], v[184:187], v[118:121]
	v_mfma_f32_16x16x32_bf16 v[110:113], v[146:149], v[192:195], v[110:113]
	v_mfma_f32_16x16x32_bf16 v[102:105], v[160:163], v[192:195], v[102:105]
	v_mfma_f32_16x16x32_bf16 v[94:97], v[146:149], v[200:203], v[94:97]
	v_mfma_f32_16x16x32_bf16 v[86:89], v[160:163], v[200:203], v[86:89]
	v_mfma_f32_16x16x32_bf16 v[78:81], v[146:149], v[208:211], v[78:81]
	v_mfma_f32_16x16x32_bf16 v[70:73], v[160:163], v[208:211], v[70:73]
	v_mfma_f32_16x16x32_bf16 v[126:129], v[156:159], v[188:191], v[126:129]
	v_mfma_f32_16x16x32_bf16 v[118:121], v[164:167], v[188:191], v[118:121]
	v_mfma_f32_16x16x32_bf16 v[110:113], v[156:159], v[196:199], v[110:113]
	v_mfma_f32_16x16x32_bf16 v[102:105], v[164:167], v[196:199], v[102:105]
	v_mfma_f32_16x16x32_bf16 v[94:97], v[156:159], v[204:207], v[94:97]
	v_mfma_f32_16x16x32_bf16 v[86:89], v[164:167], v[204:207], v[86:89]
	v_mfma_f32_16x16x32_bf16 v[78:81], v[156:159], v[212:215], v[78:81]
	v_mfma_f32_16x16x32_bf16 v[70:73], v[164:167], v[212:215], v[70:73]
	v_mfma_f32_16x16x32_bf16 v[122:125], v[168:171], v[184:187], v[122:125]
	v_mfma_f32_16x16x32_bf16 v[114:117], v[176:179], v[184:187], v[114:117]
	v_mfma_f32_16x16x32_bf16 v[106:109], v[168:171], v[192:195], v[106:109]
	v_mfma_f32_16x16x32_bf16 v[98:101], v[176:179], v[192:195], v[98:101]
	v_mfma_f32_16x16x32_bf16 v[90:93], v[168:171], v[200:203], v[90:93]
	v_mfma_f32_16x16x32_bf16 v[82:85], v[176:179], v[200:203], v[82:85]
	v_mfma_f32_16x16x32_bf16 v[74:77], v[168:171], v[208:211], v[74:77]
	v_mfma_f32_16x16x32_bf16 v[66:69], v[176:179], v[208:211], v[66:69]
	v_mfma_f32_16x16x32_bf16 v[122:125], v[172:175], v[188:191], v[122:125]
	v_mfma_f32_16x16x32_bf16 v[114:117], v[180:183], v[188:191], v[114:117]
	v_mfma_f32_16x16x32_bf16 v[106:109], v[172:175], v[196:199], v[106:109]
	v_mfma_f32_16x16x32_bf16 v[98:101], v[180:183], v[196:199], v[98:101]
	v_mfma_f32_16x16x32_bf16 v[90:93], v[172:175], v[204:207], v[90:93]
	v_mfma_f32_16x16x32_bf16 v[82:85], v[180:183], v[204:207], v[82:85]
	v_mfma_f32_16x16x32_bf16 v[74:77], v[172:175], v[212:215], v[74:77]
	s_barrier
	v_mfma_f32_16x16x32_bf16 v[66:69], v[180:183], v[212:215], v[66:69]
	s_setprio 0
	s_add_i32 s58, s51, s33
	v_lshl_add_u64 v[218:219], s[34:35], 0, v[134:135]
	s_mov_b32 m0, s58
	ds_read_b128 v[184:187], v155 offset:16384
	ds_read_b128 v[188:191], v155 offset:17408
	ds_read_b128 v[192:195], v155 offset:18432
	ds_read_b128 v[196:199], v155 offset:19456
	ds_read_b128 v[200:203], v155 offset:20480
	ds_read_b128 v[204:207], v155 offset:21504
	ds_read_b128 v[208:211], v155 offset:22528
	ds_read_b128 v[212:215], v155 offset:23552
	global_load_lds_dwordx4 v[218:219], off
	s_add_i32 m0, s58, 0x2000
	s_add_u32 s58, s34, 0x80000
	v_lshl_add_u64 v[220:221], s[34:35], 0, v[130:131]
	s_addc_u32 s59, s35, 0
	s_add_i32 s60, s52, s33
	global_load_lds_dwordx4 v[220:221], off
	v_lshl_add_u64 v[222:223], s[58:59], 0, v[134:135]
	s_mov_b32 m0, s60
	v_lshl_add_u64 v[224:225], s[40:41], 0, v[132:133]
	global_load_lds_dwordx4 v[222:223], off
	v_lshl_add_u64 v[222:223], s[58:59], 0, v[130:131]
	s_add_i32 m0, s60, 0x2000
	s_nop 0
	global_load_lds_dwordx4 v[222:223], off
	v_lshl_add_u64 v[222:223], s[40:41], 0, v[136:137]
	s_mov_b32 m0, s37
	s_nop 0
	global_load_lds_dwordx4 v[222:223], off
	s_mov_b32 m0, s44
	s_nop 0
	global_load_lds_dwordx4 v[224:225], off
	s_waitcnt vmcnt(8)
	s_waitcnt lgkmcnt(0)
	s_barrier
	s_setprio 1
	v_mfma_f32_16x16x32_bf16 v[62:65], v[146:149], v[184:187], v[62:65]
	v_mfma_f32_16x16x32_bf16 v[54:57], v[160:163], v[184:187], v[54:57]
	v_mfma_f32_16x16x32_bf16 v[46:49], v[146:149], v[192:195], v[46:49]
	v_mfma_f32_16x16x32_bf16 v[38:41], v[160:163], v[192:195], v[38:41]
	v_mfma_f32_16x16x32_bf16 v[30:33], v[146:149], v[200:203], v[30:33]
	v_mfma_f32_16x16x32_bf16 v[22:25], v[160:163], v[200:203], v[22:25]
	v_mfma_f32_16x16x32_bf16 v[14:17], v[146:149], v[208:211], v[14:17]
	v_mfma_f32_16x16x32_bf16 v[6:9], v[160:163], v[208:211], v[6:9]
	v_mfma_f32_16x16x32_bf16 v[62:65], v[156:159], v[188:191], v[62:65]
	v_mfma_f32_16x16x32_bf16 v[54:57], v[164:167], v[188:191], v[54:57]
	v_mfma_f32_16x16x32_bf16 v[46:49], v[156:159], v[196:199], v[46:49]
	v_mfma_f32_16x16x32_bf16 v[38:41], v[164:167], v[196:199], v[38:41]
	v_mfma_f32_16x16x32_bf16 v[30:33], v[156:159], v[204:207], v[30:33]
	v_mfma_f32_16x16x32_bf16 v[22:25], v[164:167], v[204:207], v[22:25]
	v_mfma_f32_16x16x32_bf16 v[14:17], v[156:159], v[212:215], v[14:17]
	v_mfma_f32_16x16x32_bf16 v[6:9], v[164:167], v[212:215], v[6:9]
	v_mfma_f32_16x16x32_bf16 v[58:61], v[168:171], v[184:187], v[58:61]
	v_mfma_f32_16x16x32_bf16 v[50:53], v[176:179], v[184:187], v[50:53]
	v_mfma_f32_16x16x32_bf16 v[42:45], v[168:171], v[192:195], v[42:45]
	v_mfma_f32_16x16x32_bf16 v[34:37], v[176:179], v[192:195], v[34:37]
	v_mfma_f32_16x16x32_bf16 v[26:29], v[168:171], v[200:203], v[26:29]
	v_mfma_f32_16x16x32_bf16 v[18:21], v[176:179], v[200:203], v[18:21]
	v_mfma_f32_16x16x32_bf16 v[10:13], v[168:171], v[208:211], v[10:13]
	v_mfma_f32_16x16x32_bf16 v[2:5], v[176:179], v[208:211], v[2:5]
	v_mfma_f32_16x16x32_bf16 v[58:61], v[172:175], v[188:191], v[58:61]
	v_mfma_f32_16x16x32_bf16 v[50:53], v[180:183], v[188:191], v[50:53]
	v_mfma_f32_16x16x32_bf16 v[42:45], v[172:175], v[196:199], v[42:45]
	v_mfma_f32_16x16x32_bf16 v[34:37], v[180:183], v[196:199], v[34:37]
	v_mfma_f32_16x16x32_bf16 v[26:29], v[172:175], v[204:207], v[26:29]
	v_mfma_f32_16x16x32_bf16 v[18:21], v[180:183], v[204:207], v[18:21]
	v_mfma_f32_16x16x32_bf16 v[10:13], v[172:175], v[212:215], v[10:13]
	s_barrier
	v_mfma_f32_16x16x32_bf16 v[2:5], v[180:183], v[212:215], v[2:5]
	s_setprio 0
	s_add_i32 s58, 0, 0x18000
	s_add_i32 s59, 0, 0x1c000
	v_add_u32_e32 v164, s58, v151
	v_add_u32_e32 v180, s59, v151
	ds_read_b128 v[146:149], v164
	ds_read_b128 v[156:159], v164 offset:1024
	ds_read_b128 v[160:163], v164 offset:2048
	ds_read_b128 v[164:167], v164 offset:3072
	ds_read_b128 v[168:171], v180
	ds_read_b128 v[172:175], v180 offset:1024
	ds_read_b128 v[176:179], v180 offset:2048
	ds_read_b128 v[180:183], v180 offset:3072
	s_add_u32 s40, s40, 0x80000
	s_addc_u32 s41, s41, 0
	s_mov_b32 m0, s45
	v_lshl_add_u64 v[226:227], s[40:41], 0, v[136:137]
	ds_read_b128 v[184:187], v155 offset:32768
	ds_read_b128 v[188:191], v155 offset:33792
	ds_read_b128 v[192:195], v155 offset:34816
	ds_read_b128 v[196:199], v155 offset:35840
	ds_read_b128 v[200:203], v155 offset:36864
	ds_read_b128 v[204:207], v155 offset:37888
	ds_read_b128 v[208:211], v155 offset:38912
	ds_read_b128 v[212:215], v155 offset:39936
	global_load_lds_dwordx4 v[226:227], off
	v_lshl_add_u64 v[226:227], s[40:41], 0, v[132:133]
	s_mov_b32 m0, s46
	s_nop 0
	global_load_lds_dwordx4 v[226:227], off
	s_waitcnt vmcnt(8)
	s_waitcnt lgkmcnt(0)
	s_barrier
	s_setprio 1
	v_mfma_f32_16x16x32_bf16 v[126:129], v[146:149], v[184:187], v[126:129]
	v_mfma_f32_16x16x32_bf16 v[118:121], v[160:163], v[184:187], v[118:121]
	v_mfma_f32_16x16x32_bf16 v[110:113], v[146:149], v[192:195], v[110:113]
	v_mfma_f32_16x16x32_bf16 v[102:105], v[160:163], v[192:195], v[102:105]
	v_mfma_f32_16x16x32_bf16 v[94:97], v[146:149], v[200:203], v[94:97]
	v_mfma_f32_16x16x32_bf16 v[86:89], v[160:163], v[200:203], v[86:89]
	v_mfma_f32_16x16x32_bf16 v[78:81], v[146:149], v[208:211], v[78:81]
	v_mfma_f32_16x16x32_bf16 v[70:73], v[160:163], v[208:211], v[70:73]
	v_mfma_f32_16x16x32_bf16 v[126:129], v[156:159], v[188:191], v[126:129]
	v_mfma_f32_16x16x32_bf16 v[118:121], v[164:167], v[188:191], v[118:121]
	v_mfma_f32_16x16x32_bf16 v[110:113], v[156:159], v[196:199], v[110:113]
	v_mfma_f32_16x16x32_bf16 v[102:105], v[164:167], v[196:199], v[102:105]
	v_mfma_f32_16x16x32_bf16 v[94:97], v[156:159], v[204:207], v[94:97]
	v_mfma_f32_16x16x32_bf16 v[86:89], v[164:167], v[204:207], v[86:89]
	v_mfma_f32_16x16x32_bf16 v[78:81], v[156:159], v[212:215], v[78:81]
	v_mfma_f32_16x16x32_bf16 v[70:73], v[164:167], v[212:215], v[70:73]
	v_mfma_f32_16x16x32_bf16 v[122:125], v[168:171], v[184:187], v[122:125]
	v_mfma_f32_16x16x32_bf16 v[114:117], v[176:179], v[184:187], v[114:117]
	v_mfma_f32_16x16x32_bf16 v[106:109], v[168:171], v[192:195], v[106:109]
	v_mfma_f32_16x16x32_bf16 v[98:101], v[176:179], v[192:195], v[98:101]
	v_mfma_f32_16x16x32_bf16 v[90:93], v[168:171], v[200:203], v[90:93]
	v_mfma_f32_16x16x32_bf16 v[82:85], v[176:179], v[200:203], v[82:85]
	v_mfma_f32_16x16x32_bf16 v[74:77], v[168:171], v[208:211], v[74:77]
	v_mfma_f32_16x16x32_bf16 v[66:69], v[176:179], v[208:211], v[66:69]
	v_mfma_f32_16x16x32_bf16 v[122:125], v[172:175], v[188:191], v[122:125]
	v_mfma_f32_16x16x32_bf16 v[114:117], v[180:183], v[188:191], v[114:117]
	v_mfma_f32_16x16x32_bf16 v[106:109], v[172:175], v[196:199], v[106:109]
	v_mfma_f32_16x16x32_bf16 v[98:101], v[180:183], v[196:199], v[98:101]
	v_mfma_f32_16x16x32_bf16 v[90:93], v[172:175], v[204:207], v[90:93]
	v_mfma_f32_16x16x32_bf16 v[82:85], v[180:183], v[204:207], v[82:85]
	v_mfma_f32_16x16x32_bf16 v[74:77], v[172:175], v[212:215], v[74:77]
	s_barrier
	v_mfma_f32_16x16x32_bf16 v[66:69], v[180:183], v[212:215], v[66:69]
	s_setprio 0
	s_add_i32 s40, s58, s33
	v_lshl_add_u64 v[218:219], v[218:219], 0, s[8:9]
	s_mov_b32 m0, s40
	ds_read_b128 v[184:187], v155 offset:49152
	ds_read_b128 v[188:191], v155 offset:50176
	ds_read_b128 v[192:195], v155 offset:51200
	ds_read_b128 v[196:199], v155 offset:52224
	ds_read_b128 v[200:203], v155 offset:53248
	ds_read_b128 v[204:207], v155 offset:54272
	ds_read_b128 v[208:211], v155 offset:55296
	ds_read_b128 v[212:215], v155 offset:56320
	global_load_lds_dwordx4 v[218:219], off
	s_add_i32 m0, s40, 0x2000
	s_add_u32 s34, s34, 0x80080
	v_lshl_add_u64 v[218:219], v[220:221], 0, s[8:9]
	s_addc_u32 s35, s35, 0
	s_add_i32 s40, s59, s33
	global_load_lds_dwordx4 v[218:219], off
	v_lshl_add_u64 v[218:219], s[34:35], 0, v[134:135]
	s_mov_b32 m0, s40
	s_nop 0
	global_load_lds_dwordx4 v[218:219], off
	v_lshl_add_u64 v[218:219], s[34:35], 0, v[130:131]
	s_add_i32 m0, s40, 0x2000
	s_nop 0
	global_load_lds_dwordx4 v[218:219], off
	v_lshl_add_u64 v[218:219], v[222:223], 0, s[8:9]
	s_mov_b32 m0, s48
	s_nop 0
	global_load_lds_dwordx4 v[218:219], off
	v_lshl_add_u64 v[218:219], v[224:225], 0, s[8:9]
	s_mov_b32 m0, s49
	s_nop 0
	global_load_lds_dwordx4 v[218:219], off
	s_waitcnt vmcnt(8)
	s_waitcnt lgkmcnt(0)
	s_barrier
	s_setprio 1
	v_mfma_f32_16x16x32_bf16 v[62:65], v[146:149], v[184:187], v[62:65]
	v_mfma_f32_16x16x32_bf16 v[54:57], v[160:163], v[184:187], v[54:57]
	v_mfma_f32_16x16x32_bf16 v[46:49], v[146:149], v[192:195], v[46:49]
	v_mfma_f32_16x16x32_bf16 v[38:41], v[160:163], v[192:195], v[38:41]
	v_mfma_f32_16x16x32_bf16 v[30:33], v[146:149], v[200:203], v[30:33]
	v_mfma_f32_16x16x32_bf16 v[22:25], v[160:163], v[200:203], v[22:25]
	v_mfma_f32_16x16x32_bf16 v[14:17], v[146:149], v[208:211], v[14:17]
	v_mfma_f32_16x16x32_bf16 v[6:9], v[160:163], v[208:211], v[6:9]
	v_mfma_f32_16x16x32_bf16 v[62:65], v[156:159], v[188:191], v[62:65]
	v_mfma_f32_16x16x32_bf16 v[54:57], v[164:167], v[188:191], v[54:57]
	v_mfma_f32_16x16x32_bf16 v[46:49], v[156:159], v[196:199], v[46:49]
	v_mfma_f32_16x16x32_bf16 v[38:41], v[164:167], v[196:199], v[38:41]
	v_mfma_f32_16x16x32_bf16 v[30:33], v[156:159], v[204:207], v[30:33]
	v_mfma_f32_16x16x32_bf16 v[22:25], v[164:167], v[204:207], v[22:25]
	v_mfma_f32_16x16x32_bf16 v[14:17], v[156:159], v[212:215], v[14:17]
	v_mfma_f32_16x16x32_bf16 v[6:9], v[164:167], v[212:215], v[6:9]
	v_mfma_f32_16x16x32_bf16 v[58:61], v[168:171], v[184:187], v[58:61]
	v_mfma_f32_16x16x32_bf16 v[50:53], v[176:179], v[184:187], v[50:53]
	v_mfma_f32_16x16x32_bf16 v[42:45], v[168:171], v[192:195], v[42:45]
	v_mfma_f32_16x16x32_bf16 v[34:37], v[176:179], v[192:195], v[34:37]
	v_mfma_f32_16x16x32_bf16 v[26:29], v[168:171], v[200:203], v[26:29]
	v_mfma_f32_16x16x32_bf16 v[18:21], v[176:179], v[200:203], v[18:21]
	v_mfma_f32_16x16x32_bf16 v[10:13], v[168:171], v[208:211], v[10:13]
	v_mfma_f32_16x16x32_bf16 v[2:5], v[176:179], v[208:211], v[2:5]
	v_mfma_f32_16x16x32_bf16 v[58:61], v[172:175], v[188:191], v[58:61]
	v_mfma_f32_16x16x32_bf16 v[50:53], v[180:183], v[188:191], v[50:53]
	v_mfma_f32_16x16x32_bf16 v[42:45], v[172:175], v[196:199], v[42:45]
	v_mfma_f32_16x16x32_bf16 v[34:37], v[180:183], v[196:199], v[34:37]
	v_mfma_f32_16x16x32_bf16 v[26:29], v[172:175], v[204:207], v[26:29]
	v_mfma_f32_16x16x32_bf16 v[18:21], v[180:183], v[204:207], v[18:21]
	v_mfma_f32_16x16x32_bf16 v[10:13], v[172:175], v[212:215], v[10:13]
	s_barrier
	v_mfma_f32_16x16x32_bf16 v[2:5], v[180:183], v[212:215], v[2:5]
	s_setprio 0
	s_add_i32 s57, s57, 2
	s_add_u32 s38, s38, 0x100
	s_addc_u32 s39, s39, 0
	s_add_u32 s55, s55, 0x100
	s_addc_u32 s56, s56, 0
	s_cmp_gt_u32 s57, 29
	s_cbranch_scc0 .LBB0_3835
	s_and_b64 vcc, exec, s[12:13]
	s_cbranch_vccz .LBB0_3838
	s_barrier

.LBB0_3930:
	ds_read_b128 v[144:147], v155
	ds_read_b128 v[148:151], v155 offset:1024
	ds_read_b128 v[158:161], v155 offset:2048
	ds_read_b128 v[162:165], v155 offset:3072
	ds_read_b128 v[166:169], v156
	ds_read_b128 v[170:173], v156 offset:1024
	ds_read_b128 v[174:177], v156 offset:2048
	ds_read_b128 v[178:181], v156 offset:3072
	s_add_u32 s20, s18, 0xffea0080
	s_addc_u32 s21, s19, -1
	s_cmpk_eq_i32 s45, 0x54
	s_cselect_b32 s23, s5, s21
	s_cselect_b32 s22, s4, s20
	s_cselect_b32 s21, s17, s1
	s_cselect_b32 s20, s16, s0
	v_lshl_add_u64 v[214:215], s[18:19], 0, v[136:137]
	s_add_i32 m0, s30, 0xc000
	ds_read_b128 v[182:185], v157
	ds_read_b128 v[186:189], v157 offset:1024
	ds_read_b128 v[190:193], v157 offset:2048
	ds_read_b128 v[194:197], v157 offset:3072
	ds_read_b128 v[198:201], v157 offset:4096
	ds_read_b128 v[202:205], v157 offset:5120
	ds_read_b128 v[206:209], v157 offset:6144
	ds_read_b128 v[210:213], v157 offset:7168
	global_load_lds_dwordx4 v[214:215], off
	v_lshl_add_u64 v[214:215], s[18:19], 0, v[138:139]
	s_add_i32 m0, s30, 0xe000
	s_nop 0
	global_load_lds_dwordx4 v[214:215], off
	s_waitcnt vmcnt(8)
	s_waitcnt lgkmcnt(0)
	s_barrier
	s_setprio 1
	v_mfma_f32_16x16x32_bf16 v[124:127], v[144:147], v[182:185], v[124:127]
	v_mfma_f32_16x16x32_bf16 v[120:123], v[158:161], v[182:185], v[120:123]
	v_mfma_f32_16x16x32_bf16 v[116:119], v[144:147], v[190:193], v[116:119]
	v_mfma_f32_16x16x32_bf16 v[112:115], v[158:161], v[190:193], v[112:115]
	v_mfma_f32_16x16x32_bf16 v[92:95], v[144:147], v[198:201], v[92:95]
	v_mfma_f32_16x16x32_bf16 v[88:91], v[158:161], v[198:201], v[88:91]
	v_mfma_f32_16x16x32_bf16 v[84:87], v[144:147], v[206:209], v[84:87]
	v_mfma_f32_16x16x32_bf16 v[80:83], v[158:161], v[206:209], v[80:83]
	v_mfma_f32_16x16x32_bf16 v[124:127], v[148:151], v[186:189], v[124:127]
	v_mfma_f32_16x16x32_bf16 v[120:123], v[162:165], v[186:189], v[120:123]
	v_mfma_f32_16x16x32_bf16 v[116:119], v[148:151], v[194:197], v[116:119]
	v_mfma_f32_16x16x32_bf16 v[112:115], v[162:165], v[194:197], v[112:115]
	v_mfma_f32_16x16x32_bf16 v[92:95], v[148:151], v[202:205], v[92:95]
	v_mfma_f32_16x16x32_bf16 v[88:91], v[162:165], v[202:205], v[88:91]
	v_mfma_f32_16x16x32_bf16 v[84:87], v[148:151], v[210:213], v[84:87]
	v_mfma_f32_16x16x32_bf16 v[80:83], v[162:165], v[210:213], v[80:83]
	v_mfma_f32_16x16x32_bf16 v[108:111], v[166:169], v[182:185], v[108:111]
	v_mfma_f32_16x16x32_bf16 v[104:107], v[174:177], v[182:185], v[104:107]
	v_mfma_f32_16x16x32_bf16 v[100:103], v[166:169], v[190:193], v[100:103]
	v_mfma_f32_16x16x32_bf16 v[96:99], v[174:177], v[190:193], v[96:99]
	v_mfma_f32_16x16x32_bf16 v[76:79], v[166:169], v[198:201], v[76:79]
	v_mfma_f32_16x16x32_bf16 v[72:75], v[174:177], v[198:201], v[72:75]
	v_mfma_f32_16x16x32_bf16 v[68:71], v[166:169], v[206:209], v[68:71]
	v_mfma_f32_16x16x32_bf16 v[64:67], v[174:177], v[206:209], v[64:67]
	v_mfma_f32_16x16x32_bf16 v[108:111], v[170:173], v[186:189], v[108:111]
	v_mfma_f32_16x16x32_bf16 v[104:107], v[178:181], v[186:189], v[104:107]
	v_mfma_f32_16x16x32_bf16 v[100:103], v[170:173], v[194:197], v[100:103]
	v_mfma_f32_16x16x32_bf16 v[96:99], v[178:181], v[194:197], v[96:99]
	v_mfma_f32_16x16x32_bf16 v[76:79], v[170:173], v[202:205], v[76:79]
	v_mfma_f32_16x16x32_bf16 v[72:75], v[178:181], v[202:205], v[72:75]
	v_mfma_f32_16x16x32_bf16 v[68:71], v[170:173], v[210:213], v[68:71]
	s_barrier
	v_mfma_f32_16x16x32_bf16 v[64:67], v[178:181], v[210:213], v[64:67]
	s_setprio 0
	s_add_i32 s46, s39, s27
	v_lshl_add_u64 v[214:215], s[20:21], 0, v[130:131]
	s_mov_b32 m0, s46
	ds_read_b128 v[182:185], v157 offset:16384
	ds_read_b128 v[186:189], v157 offset:17408
	ds_read_b128 v[190:193], v157 offset:18432
	ds_read_b128 v[194:197], v157 offset:19456
	ds_read_b128 v[198:201], v157 offset:20480
	ds_read_b128 v[202:205], v157 offset:21504
	ds_read_b128 v[206:209], v157 offset:22528
	ds_read_b128 v[210:213], v157 offset:23552
	global_load_lds_dwordx4 v[214:215], off
	s_add_i32 m0, s46, 0x2000
	s_add_u32 s46, s20, 0x160000
	v_lshl_add_u64 v[216:217], s[20:21], 0, v[134:135]
	s_addc_u32 s47, s21, 0
	s_add_i32 s48, s40, s27
	global_load_lds_dwordx4 v[216:217], off
	v_lshl_add_u64 v[218:219], s[46:47], 0, v[130:131]
	s_mov_b32 m0, s48
	v_lshl_add_u64 v[220:221], s[22:23], 0, v[132:133]
	global_load_lds_dwordx4 v[218:219], off
	v_lshl_add_u64 v[218:219], s[46:47], 0, v[134:135]
	s_add_i32 m0, s48, 0x2000
	s_nop 0
	global_load_lds_dwordx4 v[218:219], off
	v_lshl_add_u64 v[218:219], s[22:23], 0, v[128:129]
	s_mov_b32 m0, s30
	s_nop 0
	global_load_lds_dwordx4 v[218:219], off
	s_mov_b32 m0, s31
	s_nop 0
	global_load_lds_dwordx4 v[220:221], off
	s_waitcnt vmcnt(8)
	s_waitcnt lgkmcnt(0)
	s_barrier
	s_setprio 1
	v_mfma_f32_16x16x32_bf16 v[60:63], v[144:147], v[182:185], v[60:63]
	v_mfma_f32_16x16x32_bf16 v[56:59], v[158:161], v[182:185], v[56:59]
	v_mfma_f32_16x16x32_bf16 v[52:55], v[144:147], v[190:193], v[52:55]
	v_mfma_f32_16x16x32_bf16 v[48:51], v[158:161], v[190:193], v[48:51]
	v_mfma_f32_16x16x32_bf16 v[28:31], v[144:147], v[198:201], v[28:31]
	v_mfma_f32_16x16x32_bf16 v[24:27], v[158:161], v[198:201], v[24:27]
	v_mfma_f32_16x16x32_bf16 v[20:23], v[144:147], v[206:209], v[20:23]
	v_mfma_f32_16x16x32_bf16 v[16:19], v[158:161], v[206:209], v[16:19]
	v_mfma_f32_16x16x32_bf16 v[60:63], v[148:151], v[186:189], v[60:63]
	v_mfma_f32_16x16x32_bf16 v[56:59], v[162:165], v[186:189], v[56:59]
	v_mfma_f32_16x16x32_bf16 v[52:55], v[148:151], v[194:197], v[52:55]
	v_mfma_f32_16x16x32_bf16 v[48:51], v[162:165], v[194:197], v[48:51]
	v_mfma_f32_16x16x32_bf16 v[28:31], v[148:151], v[202:205], v[28:31]
	v_mfma_f32_16x16x32_bf16 v[24:27], v[162:165], v[202:205], v[24:27]
	v_mfma_f32_16x16x32_bf16 v[20:23], v[148:151], v[210:213], v[20:23]
	v_mfma_f32_16x16x32_bf16 v[16:19], v[162:165], v[210:213], v[16:19]
	v_mfma_f32_16x16x32_bf16 v[44:47], v[166:169], v[182:185], v[44:47]
	v_mfma_f32_16x16x32_bf16 v[40:43], v[174:177], v[182:185], v[40:43]
	v_mfma_f32_16x16x32_bf16 v[36:39], v[166:169], v[190:193], v[36:39]
	v_mfma_f32_16x16x32_bf16 v[32:35], v[174:177], v[190:193], v[32:35]
	v_mfma_f32_16x16x32_bf16 v[12:15], v[166:169], v[198:201], v[12:15]
	v_mfma_f32_16x16x32_bf16 v[8:11], v[174:177], v[198:201], v[8:11]
	v_mfma_f32_16x16x32_bf16 v[4:7], v[166:169], v[206:209], v[4:7]
	v_mfma_f32_16x16x32_bf16 v[0:3], v[174:177], v[206:209], v[0:3]
	v_mfma_f32_16x16x32_bf16 v[44:47], v[170:173], v[186:189], v[44:47]
	v_mfma_f32_16x16x32_bf16 v[40:43], v[178:181], v[186:189], v[40:43]
	v_mfma_f32_16x16x32_bf16 v[36:39], v[170:173], v[194:197], v[36:39]
	v_mfma_f32_16x16x32_bf16 v[32:35], v[178:181], v[194:197], v[32:35]
	v_mfma_f32_16x16x32_bf16 v[12:15], v[170:173], v[202:205], v[12:15]
	v_mfma_f32_16x16x32_bf16 v[8:11], v[178:181], v[202:205], v[8:11]
	v_mfma_f32_16x16x32_bf16 v[4:7], v[170:173], v[210:213], v[4:7]
	s_barrier
	v_mfma_f32_16x16x32_bf16 v[0:3], v[178:181], v[210:213], v[0:3]
	s_setprio 0
	s_add_i32 s46, 0, 0x18000
	s_add_i32 s47, 0, 0x1c000
	v_add_u32_e32 v162, s46, v153
	v_add_u32_e32 v178, s47, v153
	ds_read_b128 v[144:147], v162
	ds_read_b128 v[148:151], v162 offset:1024
	ds_read_b128 v[158:161], v162 offset:2048
	ds_read_b128 v[162:165], v162 offset:3072
	ds_read_b128 v[166:169], v178
	ds_read_b128 v[170:173], v178 offset:1024
	ds_read_b128 v[174:177], v178 offset:2048
	ds_read_b128 v[178:181], v178 offset:3072
	s_add_u32 s22, s22, 0x160000
	s_addc_u32 s23, s23, 0
	s_mov_b32 m0, s33
	v_lshl_add_u64 v[222:223], s[22:23], 0, v[128:129]
	ds_read_b128 v[182:185], v157 offset:32768
	ds_read_b128 v[186:189], v157 offset:33792
	ds_read_b128 v[190:193], v157 offset:34816
	ds_read_b128 v[194:197], v157 offset:35840
	ds_read_b128 v[198:201], v157 offset:36864
	ds_read_b128 v[202:205], v157 offset:37888
	ds_read_b128 v[206:209], v157 offset:38912
	ds_read_b128 v[210:213], v157 offset:39936
	global_load_lds_dwordx4 v[222:223], off
	v_lshl_add_u64 v[222:223], s[22:23], 0, v[132:133]
	s_mov_b32 m0, s34
	s_nop 0
	global_load_lds_dwordx4 v[222:223], off
	s_waitcnt vmcnt(8)
	s_waitcnt lgkmcnt(0)
	s_barrier
	s_setprio 1
	v_mfma_f32_16x16x32_bf16 v[124:127], v[144:147], v[182:185], v[124:127]
	v_mfma_f32_16x16x32_bf16 v[120:123], v[158:161], v[182:185], v[120:123]
	v_mfma_f32_16x16x32_bf16 v[116:119], v[144:147], v[190:193], v[116:119]
	v_mfma_f32_16x16x32_bf16 v[112:115], v[158:161], v[190:193], v[112:115]
	v_mfma_f32_16x16x32_bf16 v[92:95], v[144:147], v[198:201], v[92:95]
	v_mfma_f32_16x16x32_bf16 v[88:91], v[158:161], v[198:201], v[88:91]
	v_mfma_f32_16x16x32_bf16 v[84:87], v[144:147], v[206:209], v[84:87]
	v_mfma_f32_16x16x32_bf16 v[80:83], v[158:161], v[206:209], v[80:83]
	v_mfma_f32_16x16x32_bf16 v[124:127], v[148:151], v[186:189], v[124:127]
	v_mfma_f32_16x16x32_bf16 v[120:123], v[162:165], v[186:189], v[120:123]
	v_mfma_f32_16x16x32_bf16 v[116:119], v[148:151], v[194:197], v[116:119]
	v_mfma_f32_16x16x32_bf16 v[112:115], v[162:165], v[194:197], v[112:115]
	v_mfma_f32_16x16x32_bf16 v[92:95], v[148:151], v[202:205], v[92:95]
	v_mfma_f32_16x16x32_bf16 v[88:91], v[162:165], v[202:205], v[88:91]
	v_mfma_f32_16x16x32_bf16 v[84:87], v[148:151], v[210:213], v[84:87]
	v_mfma_f32_16x16x32_bf16 v[80:83], v[162:165], v[210:213], v[80:83]
	v_mfma_f32_16x16x32_bf16 v[108:111], v[166:169], v[182:185], v[108:111]
	v_mfma_f32_16x16x32_bf16 v[104:107], v[174:177], v[182:185], v[104:107]
	v_mfma_f32_16x16x32_bf16 v[100:103], v[166:169], v[190:193], v[100:103]
	v_mfma_f32_16x16x32_bf16 v[96:99], v[174:177], v[190:193], v[96:99]
	v_mfma_f32_16x16x32_bf16 v[76:79], v[166:169], v[198:201], v[76:79]
	v_mfma_f32_16x16x32_bf16 v[72:75], v[174:177], v[198:201], v[72:75]
	v_mfma_f32_16x16x32_bf16 v[68:71], v[166:169], v[206:209], v[68:71]
	v_mfma_f32_16x16x32_bf16 v[64:67], v[174:177], v[206:209], v[64:67]
	v_mfma_f32_16x16x32_bf16 v[108:111], v[170:173], v[186:189], v[108:111]
	v_mfma_f32_16x16x32_bf16 v[104:107], v[178:181], v[186:189], v[104:107]
	v_mfma_f32_16x16x32_bf16 v[100:103], v[170:173], v[194:197], v[100:103]
	v_mfma_f32_16x16x32_bf16 v[96:99], v[178:181], v[194:197], v[96:99]
	v_mfma_f32_16x16x32_bf16 v[76:79], v[170:173], v[202:205], v[76:79]
	v_mfma_f32_16x16x32_bf16 v[72:75], v[178:181], v[202:205], v[72:75]
	v_mfma_f32_16x16x32_bf16 v[68:71], v[170:173], v[210:213], v[68:71]
	s_barrier
	v_mfma_f32_16x16x32_bf16 v[64:67], v[178:181], v[210:213], v[64:67]
	s_setprio 0
	s_add_i32 s22, s46, s27
	v_lshl_add_u64 v[214:215], v[214:215], 0, s[12:13]
	s_mov_b32 m0, s22
	ds_read_b128 v[182:185], v157 offset:49152
	ds_read_b128 v[186:189], v157 offset:50176
	ds_read_b128 v[190:193], v157 offset:51200
	ds_read_b128 v[194:197], v157 offset:52224
	ds_read_b128 v[198:201], v157 offset:53248
	ds_read_b128 v[202:205], v157 offset:54272
	ds_read_b128 v[206:209], v157 offset:55296
	ds_read_b128 v[210:213], v157 offset:56320
	global_load_lds_dwordx4 v[214:215], off
	s_add_i32 m0, s22, 0x2000
	s_add_u32 s20, s20, 0x160080
	v_lshl_add_u64 v[214:215], v[216:217], 0, s[12:13]
	s_addc_u32 s21, s21, 0
	s_add_i32 s22, s47, s27
	global_load_lds_dwordx4 v[214:215], off
	v_lshl_add_u64 v[214:215], s[20:21], 0, v[130:131]
	s_mov_b32 m0, s22
	s_nop 0
	global_load_lds_dwordx4 v[214:215], off
	v_lshl_add_u64 v[214:215], s[20:21], 0, v[134:135]
	s_add_i32 m0, s22, 0x2000
	s_nop 0
	global_load_lds_dwordx4 v[214:215], off
	v_lshl_add_u64 v[214:215], v[218:219], 0, s[12:13]
	s_mov_b32 m0, s36
	s_nop 0
	global_load_lds_dwordx4 v[214:215], off
	v_lshl_add_u64 v[214:215], v[220:221], 0, s[12:13]
	s_mov_b32 m0, s37
	s_nop 0
	global_load_lds_dwordx4 v[214:215], off
	s_waitcnt vmcnt(8)
	s_waitcnt lgkmcnt(0)
	s_barrier
	s_setprio 1
	v_mfma_f32_16x16x32_bf16 v[60:63], v[144:147], v[182:185], v[60:63]
	v_mfma_f32_16x16x32_bf16 v[56:59], v[158:161], v[182:185], v[56:59]
	v_mfma_f32_16x16x32_bf16 v[52:55], v[144:147], v[190:193], v[52:55]
	v_mfma_f32_16x16x32_bf16 v[48:51], v[158:161], v[190:193], v[48:51]
	v_mfma_f32_16x16x32_bf16 v[28:31], v[144:147], v[198:201], v[28:31]
	v_mfma_f32_16x16x32_bf16 v[24:27], v[158:161], v[198:201], v[24:27]
	v_mfma_f32_16x16x32_bf16 v[20:23], v[144:147], v[206:209], v[20:23]
	v_mfma_f32_16x16x32_bf16 v[16:19], v[158:161], v[206:209], v[16:19]
	v_mfma_f32_16x16x32_bf16 v[60:63], v[148:151], v[186:189], v[60:63]
	v_mfma_f32_16x16x32_bf16 v[56:59], v[162:165], v[186:189], v[56:59]
	v_mfma_f32_16x16x32_bf16 v[52:55], v[148:151], v[194:197], v[52:55]
	v_mfma_f32_16x16x32_bf16 v[48:51], v[162:165], v[194:197], v[48:51]
	v_mfma_f32_16x16x32_bf16 v[28:31], v[148:151], v[202:205], v[28:31]
	v_mfma_f32_16x16x32_bf16 v[24:27], v[162:165], v[202:205], v[24:27]
	v_mfma_f32_16x16x32_bf16 v[20:23], v[148:151], v[210:213], v[20:23]
	v_mfma_f32_16x16x32_bf16 v[16:19], v[162:165], v[210:213], v[16:19]
	v_mfma_f32_16x16x32_bf16 v[44:47], v[166:169], v[182:185], v[44:47]
	v_mfma_f32_16x16x32_bf16 v[40:43], v[174:177], v[182:185], v[40:43]
	v_mfma_f32_16x16x32_bf16 v[36:39], v[166:169], v[190:193], v[36:39]
	v_mfma_f32_16x16x32_bf16 v[32:35], v[174:177], v[190:193], v[32:35]
	v_mfma_f32_16x16x32_bf16 v[12:15], v[166:169], v[198:201], v[12:15]
	v_mfma_f32_16x16x32_bf16 v[8:11], v[174:177], v[198:201], v[8:11]
	v_mfma_f32_16x16x32_bf16 v[4:7], v[166:169], v[206:209], v[4:7]
	v_mfma_f32_16x16x32_bf16 v[0:3], v[174:177], v[206:209], v[0:3]
	v_mfma_f32_16x16x32_bf16 v[44:47], v[170:173], v[186:189], v[44:47]
	v_mfma_f32_16x16x32_bf16 v[40:43], v[178:181], v[186:189], v[40:43]
	v_mfma_f32_16x16x32_bf16 v[36:39], v[170:173], v[194:197], v[36:39]
	v_mfma_f32_16x16x32_bf16 v[32:35], v[178:181], v[194:197], v[32:35]
	v_mfma_f32_16x16x32_bf16 v[12:15], v[170:173], v[202:205], v[12:15]
	v_mfma_f32_16x16x32_bf16 v[8:11], v[178:181], v[202:205], v[8:11]
	v_mfma_f32_16x16x32_bf16 v[4:7], v[170:173], v[210:213], v[4:7]
	s_barrier
	v_mfma_f32_16x16x32_bf16 v[0:3], v[178:181], v[210:213], v[0:3]
	s_setprio 0
	s_add_i32 s45, s45, 2
	s_add_u32 s18, s18, 0x100
	s_addc_u32 s19, s19, 0
	s_add_u32 s0, s0, 0x100
	s_addc_u32 s1, s1, 0
	s_cmpk_gt_u32 s45, 0x55
	s_cbranch_scc0 .LBB0_3930
	s_and_b64 vcc, exec, s[14:15]
	s_cbranch_vccz .LBB0_3933
	s_barrier
